# attention: K-fragment and column-term LDS reads issued together with counted waits; packed f32 VALU ops written as per-element f32 ops (bitwise same math); plus in-place PV accumulation and scalar-bas
# baseline (speedup 1.0000x reference)
; __device__ __forceinline__ unsigned cvt_pk_bf16(float lo, float hi) { f32x2_t v = {lo, hi}; bf16x2_t b = __builtin_convertvector(v, bf16x2_t); return __builtin_bit_cast(unsigned, b); }
; __device__ __forceinline__ float bf_lo(unsigned w) { return __uint_as_float(w << 16); }
; __device__ __forceinline__ float bf_hi(unsigned w) { return __uint_as_float(w & 0xffff0000u); }
; __device__ __forceinline__ float fast_rcp(float x) { return __builtin_amdgcn_rcpf(x); }
; __device__ __forceinline__ float swap_sum(float v) { auto rr = __builtin_amdgcn_permlane32_swap(__float_as_uint(v), __float_as_uint(v), false, false); return __uint_as_float(rr[0]) + __uint_as_float(rr[1]); }
; __device__ __forceinline__ void attn_store_gated(const f32x16& o0, const f32x16& o1, float inv, const ZRegs& zr, bf16_t* urow, int hh) {
; #pragma unroll
;     for (int d0 = 0; d0 < 2; ++d0)
; #pragma unroll
;         for (int g = 0; g < 4; ++g) { const int d = 32 * d0 + 8 * g + 4 * hh; const u32x2 z = zr.z[d0][g]; const f32x16& o = d0 ? o1 : o0;
;             u32x2 w; w.x = cvt_pk_bf16(o[4 * g] * inv * bf_lo(z.x), o[4 * g + 1] * inv * bf_hi(z.x)); w.y = cvt_pk_bf16(o[4 * g + 2] * inv * bf_lo(z.y), o[4 * g + 3] * inv * bf_hi(z.y));
;             *(u32x2*)(urow + d) = w; }
; }
; __device__ __forceinline__ void fox_unit(LAS char* lds, int bh, int qb2, const bf16_t* H, const float* c, const unsigned* ctl, bf16_t* U, int tid) {
;     ...
;     { ZRegs zr; load_z(zr, Hb + (size_t)qposA * HQ + C_FZ + h * 64, hh); attn_store_gated(oA0, oA1, fast_rcp(swap_sum(lA)), zr, U + ((size_t)b * SEQ + qposA) * 2048 + U_FOX + h * 64, hh); }
;     { ZRegs zr; load_z(zr, Hb + (size_t)qposB * HQ + C_FZ + h * 64, hh); attn_store_gated(oB0, oB1, fast_rcp(swap_sum(lB)), zr, U + ((size_t)b * SEQ + qposB) * 2048 + U_FOX + h * 64, hh); }
.LBB0_369:
	v_lshlrev_b32_e32 v0, 1, v150
	s_waitcnt lgkmcnt(0)
	s_barrier
	v_lshl_add_u64 v[66:67], v[160:161], 0, v[0:1]
	global_load_dwordx2 v[78:79], v[66:67], off offset:3072
	global_load_dwordx2 v[80:81], v[66:67], off offset:3088
	global_load_dwordx2 v[82:83], v[66:67], off offset:3104
	global_load_dwordx2 v[76:77], v[66:67], off offset:3120
	global_load_dwordx2 v[74:75], v[66:67], off offset:3136
	global_load_dwordx2 v[72:73], v[66:67], off offset:3152
	global_load_dwordx2 v[70:71], v[66:67], off offset:3168
	s_nop 0
	global_load_dwordx2 v[66:67], v[66:67], off offset:3184
	v_mov_b32_e32 v68, v212
	s_nop 1
	v_permlane32_swap_b32_e32 v212, v68
	v_add_f32_e32 v68, v212, v68
	v_rcp_f32_e32 v68, v68
	s_mov_b32 s47, s31
	v_lshl_add_u64 v[84:85], v[158:159], 0, s[46:47]
	v_lshlrev_b64 v[84:85], 12, v[84:85]
	v_mul_f32_e32 v50, v50, v68
	v_mul_f32_e32 v51, v51, v68
	v_lshl_add_u64 v[84:85], s[36:37], 0, v[84:85]
	v_lshl_add_u64 v[84:85], v[84:85], 0, s[30:31]
	v_mul_f32_e32 v34, v34, v68
	v_mul_f32_e32 v35, v35, v68
	v_mul_f32_e32 v36, v36, v68
	v_mul_f32_e32 v37, v37, v68
	s_waitcnt vmcnt(0)
	v_lshlrev_b32_e32 v86, 16, v78
	v_and_b32_e32 v87, 0xffff0000, v78
	v_mul_f32_e32 v50, v50, v86
	v_mul_f32_e32 v51, v51, v87
	s_nop 0
	v_cvt_pk_bf16_f32 v78, v50, v51
	v_mul_f32_e32 v50, v52, v68
	v_mul_f32_e32 v51, v53, v68
	v_lshlrev_b32_e32 v52, 16, v79
	v_and_b32_e32 v53, 0xffff0000, v79
	v_mul_f32_e32 v50, v50, v52
	v_mul_f32_e32 v51, v51, v53
	v_mul_f32_e32 v52, v54, v68
	v_mul_f32_e32 v53, v55, v68
	v_lshlrev_b32_e32 v54, 16, v80
	v_and_b32_e32 v55, 0xffff0000, v80
	v_mul_f32_e32 v52, v52, v54
	v_mul_f32_e32 v53, v53, v55
	v_mul_f32_e32 v54, v56, v68
	v_mul_f32_e32 v55, v57, v68
	v_lshlrev_b32_e32 v56, 16, v81
	v_and_b32_e32 v57, 0xffff0000, v81
	v_mul_f32_e32 v54, v54, v56
	v_mul_f32_e32 v55, v55, v57
	v_cvt_pk_bf16_f32 v79, v50, v51
	v_lshl_add_u64 v[50:51], v[84:85], 0, v[0:1]
	v_cvt_pk_bf16_f32 v52, v52, v53
	v_cvt_pk_bf16_f32 v53, v54, v55
	global_store_dwordx2 v[50:51], v[52:53], off offset:16
	v_mul_f32_e32 v52, v58, v68
	v_mul_f32_e32 v53, v59, v68
	v_lshlrev_b32_e32 v54, 16, v82
	v_and_b32_e32 v55, 0xffff0000, v82
	v_mul_f32_e32 v52, v52, v54
	v_mul_f32_e32 v53, v53, v55
	v_mul_f32_e32 v54, v60, v68
	v_mul_f32_e32 v55, v61, v68
	v_lshlrev_b32_e32 v56, 16, v83
	v_and_b32_e32 v57, 0xffff0000, v83
	v_mul_f32_e32 v54, v54, v56
	v_mul_f32_e32 v55, v55, v57
	v_cvt_pk_bf16_f32 v52, v52, v53
	v_cvt_pk_bf16_f32 v53, v54, v55
	global_store_dwordx2 v[50:51], v[52:53], off offset:32
	v_mul_f32_e32 v52, v62, v68
	v_mul_f32_e32 v53, v63, v68
	v_lshlrev_b32_e32 v54, 16, v76
	v_and_b32_e32 v55, 0xffff0000, v76
	v_mul_f32_e32 v52, v52, v54
	v_mul_f32_e32 v53, v53, v55
	v_mul_f32_e32 v54, v64, v68
	v_mul_f32_e32 v55, v65, v68
	v_lshlrev_b32_e32 v56, 16, v77
	v_and_b32_e32 v57, 0xffff0000, v77
	v_mul_f32_e32 v54, v54, v56
	v_mul_f32_e32 v55, v55, v57
	v_cvt_pk_bf16_f32 v52, v52, v53
	v_cvt_pk_bf16_f32 v53, v54, v55
	global_store_dwordx2 v[50:51], v[52:53], off offset:48
	v_lshlrev_b32_e32 v52, 16, v74
	v_and_b32_e32 v53, 0xffff0000, v74
	v_mul_f32_e32 v34, v34, v52
	v_mul_f32_e32 v35, v35, v53
	v_lshlrev_b32_e32 v52, 16, v75
	v_and_b32_e32 v53, 0xffff0000, v75
	v_mul_f32_e32 v36, v36, v52
	v_mul_f32_e32 v37, v37, v53
	v_cvt_pk_bf16_f32 v34, v34, v35
	v_cvt_pk_bf16_f32 v35, v36, v37
	global_store_dwordx2 v[50:51], v[34:35], off offset:64
	v_mul_f32_e32 v34, v38, v68
	v_mul_f32_e32 v35, v39, v68
	v_lshlrev_b32_e32 v36, 16, v72
	v_and_b32_e32 v37, 0xffff0000, v72
	v_mul_f32_e32 v34, v34, v36
	v_mul_f32_e32 v35, v35, v37
	v_mul_f32_e32 v36, v40, v68
	v_mul_f32_e32 v37, v41, v68
	v_lshlrev_b32_e32 v38, 16, v73
	v_and_b32_e32 v39, 0xffff0000, v73
	v_mul_f32_e32 v36, v36, v38
	v_mul_f32_e32 v37, v37, v39
	v_cvt_pk_bf16_f32 v34, v34, v35
	v_cvt_pk_bf16_f32 v35, v36, v37
	global_store_dwordx2 v[50:51], v[34:35], off offset:80
	v_mul_f32_e32 v34, v42, v68
	v_mul_f32_e32 v35, v43, v68
	v_lshlrev_b32_e32 v36, 16, v70
	v_and_b32_e32 v37, 0xffff0000, v70
	v_mul_f32_e32 v34, v34, v36
	v_mul_f32_e32 v35, v35, v37
	v_mul_f32_e32 v36, v44, v68
	v_mul_f32_e32 v37, v45, v68
	v_lshlrev_b32_e32 v38, 16, v71
	v_and_b32_e32 v39, 0xffff0000, v71
	v_mul_f32_e32 v36, v36, v38
	v_mul_f32_e32 v37, v37, v39
	v_cvt_pk_bf16_f32 v34, v34, v35
	v_cvt_pk_bf16_f32 v35, v36, v37
	global_store_dwordx2 v[50:51], v[34:35], off offset:96
	v_mul_f32_e32 v34, v46, v68
	v_mul_f32_e32 v35, v47, v68
	v_lshlrev_b32_e32 v36, 16, v66
	v_and_b32_e32 v37, 0xffff0000, v66
	v_mul_f32_e32 v34, v34, v36
	v_mul_f32_e32 v35, v35, v37
	v_mul_f32_e32 v36, v48, v68
	v_mul_f32_e32 v37, v49, v68
	v_lshlrev_b32_e32 v38, 16, v67
	v_and_b32_e32 v39, 0xffff0000, v67
	v_mul_f32_e32 v36, v36, v38
	v_mul_f32_e32 v37, v37, v39
	v_cvt_pk_bf16_f32 v34, v34, v35
	v_cvt_pk_bf16_f32 v35, v36, v37
	global_store_dwordx2 v[50:51], v[78:79], off
	global_store_dwordx2 v[50:51], v[34:35], off offset:112
	v_lshl_add_u64 v[34:35], v[156:157], 0, v[0:1]
	global_load_dwordx2 v[46:47], v[34:35], off offset:3072
	global_load_dwordx2 v[48:49], v[34:35], off offset:3088
	global_load_dwordx2 v[50:51], v[34:35], off offset:3104
	global_load_dwordx2 v[44:45], v[34:35], off offset:3120
	global_load_dwordx2 v[42:43], v[34:35], off offset:3136
	global_load_dwordx2 v[40:41], v[34:35], off offset:3152
	global_load_dwordx2 v[38:39], v[34:35], off offset:3168
	s_nop 0
	global_load_dwordx2 v[34:35], v[34:35], off offset:3184
	v_mov_b32_e32 v36, v194
	s_nop 1
	v_permlane32_swap_b32_e32 v194, v36
	v_add_f32_e32 v36, v194, v36
	v_rcp_f32_e32 v36, v36
	v_lshl_add_u64 v[52:53], v[154:155], 0, s[46:47]
	v_lshlrev_b64 v[52:53], 12, v[52:53]
	v_lshl_add_u64 v[52:53], s[36:37], 0, v[52:53]
	v_mul_f32_e32 v18, v18, v36
	v_mul_f32_e32 v19, v19, v36
	v_lshl_add_u64 v[52:53], v[52:53], 0, s[30:31]
	v_mul_f32_e32 v2, v2, v36
	v_mul_f32_e32 v3, v3, v36
	v_mul_f32_e32 v4, v4, v36
	v_mul_f32_e32 v5, v5, v36
	s_waitcnt vmcnt(0)
; __device__ __forceinline__ unsigned cvt_pk_bf16(float lo, float hi) { f32x2_t v = {lo, hi}; bf16x2_t b = __builtin_convertvector(v, bf16x2_t); return __builtin_bit_cast(unsigned, b); }
; __device__ __forceinline__ float bf_lo(unsigned w) { return __uint_as_float(w << 16); }
; __device__ __forceinline__ float bf_hi(unsigned w) { return __uint_as_float(w & 0xffff0000u); }
; __device__ __forceinline__ float fast_rcp(float x) { return __builtin_amdgcn_rcpf(x); }
; __device__ __forceinline__ float swap_sum(float v) { auto rr = __builtin_amdgcn_permlane32_swap(__float_as_uint(v), __float_as_uint(v), false, false); return __uint_as_float(rr[0]) + __uint_as_float(rr[1]); }
; __device__ __forceinline__ void attn_store_gated(const f32x16& o0, const f32x16& o1, float inv, const ZRegs& zr, bf16_t* urow, int hh) {
; #pragma unroll
;     for (int d0 = 0; d0 < 2; ++d0)
; #pragma unroll
;         for (int g = 0; g < 4; ++g) { const int d = 32 * d0 + 8 * g + 4 * hh; const u32x2 z = zr.z[d0][g]; const f32x16& o = d0 ? o1 : o0;
;             u32x2 w; w.x = cvt_pk_bf16(o[4 * g] * inv * bf_lo(z.x), o[4 * g + 1] * inv * bf_hi(z.x)); w.y = cvt_pk_bf16(o[4 * g + 2] * inv * bf_lo(z.y), o[4 * g + 3] * inv * bf_hi(z.y));
;             *(u32x2*)(urow + d) = w; }
; }
; __device__ __forceinline__ void fox_unit(LAS char* lds, int bh, int qb2, const bf16_t* H, const float* c, const unsigned* ctl, bf16_t* U, int tid) {
;     ...
;     { ZRegs zr; load_z(zr, Hb + (size_t)qposB * HQ + C_FZ + h * 64, hh); attn_store_gated(oB0, oB1, fast_rcp(swap_sum(lB)), zr, U + ((size_t)b * SEQ + qposB) * 2048 + U_FOX + h * 64, hh); }
	v_lshlrev_b32_e32 v54, 16, v46
	v_and_b32_e32 v55, 0xffff0000, v46
	v_mul_f32_e32 v18, v18, v54
	v_mul_f32_e32 v19, v19, v55
	s_nop 0
	v_cvt_pk_bf16_f32 v46, v18, v19
	v_mul_f32_e32 v18, v20, v36
	v_mul_f32_e32 v19, v21, v36
	v_lshlrev_b32_e32 v20, 16, v47
	v_and_b32_e32 v21, 0xffff0000, v47
	v_mul_f32_e32 v18, v18, v20
	v_mul_f32_e32 v19, v19, v21
	v_mul_f32_e32 v20, v22, v36
	v_mul_f32_e32 v21, v23, v36
	v_lshlrev_b32_e32 v22, 16, v48
	v_and_b32_e32 v23, 0xffff0000, v48
	v_mul_f32_e32 v20, v20, v22
	v_mul_f32_e32 v21, v21, v23
	v_mul_f32_e32 v22, v24, v36
	v_mul_f32_e32 v23, v25, v36
	v_lshlrev_b32_e32 v24, 16, v49
	v_and_b32_e32 v25, 0xffff0000, v49
	v_mul_f32_e32 v22, v22, v24
	v_mul_f32_e32 v23, v23, v25
	v_cvt_pk_bf16_f32 v47, v18, v19
	v_lshl_add_u64 v[18:19], v[52:53], 0, v[0:1]
	v_cvt_pk_bf16_f32 v20, v20, v21
	v_cvt_pk_bf16_f32 v21, v22, v23
	global_store_dwordx2 v[18:19], v[20:21], off offset:16
	v_mul_f32_e32 v20, v26, v36
	v_mul_f32_e32 v21, v27, v36
	v_lshlrev_b32_e32 v22, 16, v50
	v_and_b32_e32 v23, 0xffff0000, v50
	v_mul_f32_e32 v20, v20, v22
	v_mul_f32_e32 v21, v21, v23
	v_mul_f32_e32 v22, v28, v36
	v_mul_f32_e32 v23, v29, v36
	v_lshlrev_b32_e32 v24, 16, v51
	v_and_b32_e32 v25, 0xffff0000, v51
	v_mul_f32_e32 v22, v22, v24
	v_mul_f32_e32 v23, v23, v25
	v_cvt_pk_bf16_f32 v20, v20, v21
	v_cvt_pk_bf16_f32 v21, v22, v23
	global_store_dwordx2 v[18:19], v[20:21], off offset:32
	v_mul_f32_e32 v20, v30, v36
	v_mul_f32_e32 v21, v31, v36
	v_lshlrev_b32_e32 v22, 16, v44
	v_and_b32_e32 v23, 0xffff0000, v44
	v_mul_f32_e32 v20, v20, v22
	v_mul_f32_e32 v21, v21, v23
	v_mul_f32_e32 v22, v32, v36
	v_mul_f32_e32 v23, v33, v36
	v_lshlrev_b32_e32 v24, 16, v45
	v_and_b32_e32 v25, 0xffff0000, v45
	v_mul_f32_e32 v22, v22, v24
	v_mul_f32_e32 v23, v23, v25
	v_cvt_pk_bf16_f32 v20, v20, v21
	v_cvt_pk_bf16_f32 v21, v22, v23
	global_store_dwordx2 v[18:19], v[20:21], off offset:48
	v_lshlrev_b32_e32 v20, 16, v42
	v_and_b32_e32 v21, 0xffff0000, v42
	v_mul_f32_e32 v2, v2, v20
	v_mul_f32_e32 v3, v3, v21
	v_lshlrev_b32_e32 v20, 16, v43
	v_and_b32_e32 v21, 0xffff0000, v43
	v_mul_f32_e32 v4, v4, v20
	v_mul_f32_e32 v5, v5, v21
	v_cvt_pk_bf16_f32 v2, v2, v3
	v_cvt_pk_bf16_f32 v3, v4, v5
	global_store_dwordx2 v[18:19], v[2:3], off offset:64
	v_mul_f32_e32 v2, v6, v36
	v_mul_f32_e32 v3, v7, v36
	v_lshlrev_b32_e32 v4, 16, v40
	v_and_b32_e32 v5, 0xffff0000, v40
	v_mul_f32_e32 v2, v2, v4
	v_mul_f32_e32 v3, v3, v5
	v_mul_f32_e32 v4, v8, v36
	v_mul_f32_e32 v5, v9, v36
	v_lshlrev_b32_e32 v6, 16, v41
	v_and_b32_e32 v7, 0xffff0000, v41
	v_mul_f32_e32 v4, v4, v6
	v_mul_f32_e32 v5, v5, v7
	v_cvt_pk_bf16_f32 v2, v2, v3
	v_cvt_pk_bf16_f32 v3, v4, v5
	global_store_dwordx2 v[18:19], v[2:3], off offset:80
	v_mul_f32_e32 v2, v10, v36
	v_mul_f32_e32 v3, v11, v36
	v_lshlrev_b32_e32 v4, 16, v38
	v_and_b32_e32 v5, 0xffff0000, v38
	v_mul_f32_e32 v2, v2, v4
	v_mul_f32_e32 v3, v3, v5
	v_mul_f32_e32 v4, v12, v36
	v_mul_f32_e32 v5, v13, v36
	v_lshlrev_b32_e32 v6, 16, v39
	v_and_b32_e32 v7, 0xffff0000, v39
	v_mul_f32_e32 v4, v4, v6
	v_mul_f32_e32 v5, v5, v7
	v_cvt_pk_bf16_f32 v2, v2, v3
	v_cvt_pk_bf16_f32 v3, v4, v5
	global_store_dwordx2 v[18:19], v[2:3], off offset:96
	v_mul_f32_e32 v2, v14, v36
	v_mul_f32_e32 v3, v15, v36
	v_lshlrev_b32_e32 v4, 16, v34
	v_and_b32_e32 v5, 0xffff0000, v34
	v_mul_f32_e32 v2, v2, v4
	v_mul_f32_e32 v3, v3, v5
	v_mul_f32_e32 v4, v16, v36
	v_mul_f32_e32 v5, v17, v36
	v_lshlrev_b32_e32 v6, 16, v35
	v_and_b32_e32 v7, 0xffff0000, v35
	v_mul_f32_e32 v4, v4, v6
	v_mul_f32_e32 v5, v5, v7
	v_cvt_pk_bf16_f32 v2, v2, v3
	v_cvt_pk_bf16_f32 v3, v4, v5
	global_store_dwordx2 v[18:19], v[46:47], off
	global_store_dwordx2 v[18:19], v[2:3], off offset:112

; #define LAS __attribute__((address_space(3)))
; template <bool MASK> ...
;     s16x4 l00, h00, l01, h01, l10, h10, l11, h11; { const unsigned a0 = va0 + sub * 4096, a1 = va1 + sub * 4096;
;       asm volatile("ds_read_b64_tr_b16 %0, %1" : "=&v"(l00) : "v"(a0) : "memory"); asm volatile("ds_read_b64_tr_b16 %0, %1 offset:1024" : "=&v"(h00) : "v"(a0) : "memory");
;       asm volatile("ds_read_b64_tr_b16 %0, %1" : "=&v"(l01) : "v"(a1) : "memory"); asm volatile("ds_read_b64_tr_b16 %0, %1 offset:1024" : "=&v"(h01) : "v"(a1) : "memory");
;       asm volatile("ds_read_b64_tr_b16 %0, %1 offset:2048" : "=&v"(l10) : "v"(a0) : "memory"); asm volatile("ds_read_b64_tr_b16 %0, %1 offset:3072" : "=&v"(h10) : "v"(a0) : "memory");
;       asm volatile("ds_read_b64_tr_b16 %0, %1 offset:2048" : "=&v"(l11) : "v"(a1) : "memory"); asm volatile("ds_read_b64_tr_b16 %0, %1 offset:3072" : "=&v"(h11) : "v"(a1) : "memory"); }
;     const int r = lane & 31, hh = lane >> 5;
;     f32x16 st = {0.f, 0.f, 0.f, 0.f, 0.f, 0.f, 0.f, 0.f, 0.f, 0.f, 0.f, 0.f, 0.f, 0.f, 0.f, 0.f};
;     { const int key = sub * 32 + r; const LAS char* kp = Kt + key * 128; const int ksw = (key >> 1) & 7;
; #pragma unroll
;       for (int d0 = 0; d0 < 4; ++d0) { const bf16x8 kf = *(const LAS bf16x8*)(kp + (((2 * d0 + hh) ^ ksw) << 4)); st = __builtin_amdgcn_mfma_f32_32x32x16_bf16(kf, qr[d0], st, 0, 0, 0); } }
;     f32x2_t sp[8]; const f32x2_t cs2 = {cscale, cscale};
; #pragma unroll
;     for (int g = 0; g < 4; ++g) { const f32x4 c4 = *(const LAS f32x4*)(cb + sub * 32 + 8 * g + 4 * hh);
;         sp[2 * g] = (f32x2_t){st[4 * g], st[4 * g + 1]} + cs2 * (f32x2_t){c4[0], c4[1]};
;         sp[2 * g + 1] = (f32x2_t){st[4 * g + 2], st[4 * g + 3]} + cs2 * (f32x2_t){c4[2], c4[3]};
;         if (MASK) {
; #pragma unroll
;             for (int e = 0; e < 4; ++e) { const int kpos = kpos_sub + 8 * g + 4 * hh + e; const bool ok = (kpos <= qpos && kpos >= qpos - win);
;                 sp[2 * g + (e >> 1)][e & 1] = ok ? sp[2 * g + (e >> 1)][e & 1] : -INFINITY; } } }
;     float rm = fmaxf(sp[0][0], sp[0][1]);
; #pragma unroll
;     for (int i = 1; i < 8; ++i) rm = fmaxf(fmaxf(rm, sp[i][0]), sp[i][1]);
;     rm = swap_max(rm);
;     if (__any(rm - m > 8.0f)) { const float mnew = fmaxf(m, rm); const float f = fast_exp2(m - mnew); l *= f; o0 = o0 * f; o1 = o1 * f; m = mnew; }
.LBB0_385:
	s_mul_hi_u32 s5, s1, 0xaaaaaaab
	s_lshr_b32 s5, s5, 1
	s_mul_i32 s5, s5, 3
	s_add_i32 s4, s1, s67
	s_sub_i32 s1, s1, s5
	s_lshl_b32 s5, s1, 13
	s_lshl_b32 s4, s4, 6
	s_add_i32 s20, s5, 0
	s_mulk_i32 s1, 0xe100
	s_add_i32 s4, s4, s30
	s_add_i32 s1, s20, s1
	s_cmp_gt_i32 s4, s33
	v_add_u32_e32 v216, s5, v189
	v_add_u32_e32 v217, s5, v190
	s_cselect_b64 s[16:17], -1, 0
	s_or_b32 s5, s4, 31
	s_cmp_lt_i32 s5, s66
	s_cselect_b64 s[18:19], -1, 0
	s_or_b64 s[16:17], s[16:17], s[18:19]
	v_add_u32_e32 v0, s20, v198
	s_and_b64 vcc, exec, s[16:17]
	v_add_u32_e32 v215, v0, v191
	v_add_u32_e32 v214, v0, v192
	v_add_u32_e32 v213, v0, v193
	v_add_u32_e32 v212, v0, v196
	s_cbranch_vccnz .LBB0_397
	s_cmp_gt_i32 s5, s35
	s_cselect_b64 s[16:17], -1, 0
	s_cmp_lt_i32 s4, s11
	s_cselect_b64 s[18:19], -1, 0
	s_or_b64 s[16:17], s[16:17], s[18:19]
	s_mov_b64 s[18:19], -1
	s_and_b64 vcc, exec, s[16:17]
	s_cbranch_vccnz .LBB0_391
	ds_read_b64_tr_b16 v[142:143], v216
	ds_read_b64_tr_b16 v[144:145], v216 offset:1024
	ds_read_b64_tr_b16 v[138:139], v217
	ds_read_b64_tr_b16 v[140:141], v217 offset:1024
	ds_read_b64_tr_b16 v[134:135], v216 offset:2048
	ds_read_b64_tr_b16 v[136:137], v216 offset:3072
	ds_read_b64_tr_b16 v[130:131], v217 offset:2048
	ds_read_b64_tr_b16 v[132:133], v217 offset:3072
	ds_read_b128 v[66:69], v215
	ds_read_b128 v[82:85], v214
	ds_read_b128 v[86:89], v213
	ds_read_b128 v[90:93], v212
	v_add_u32_e32 v0, s1, v197
	s_waitcnt lgkmcnt(2)
	v_mfma_f32_32x32x16_bf16 v[66:81], v[66:69], v[106:109], 0
	v_mfma_f32_32x32x16_bf16 v[66:81], v[82:85], v[98:101], v[66:81]
	s_waitcnt lgkmcnt(1)
	v_mfma_f32_32x32x16_bf16 v[66:81], v[86:89], v[102:105], v[66:81]
	s_waitcnt lgkmcnt(0)
	v_mfma_f32_32x32x16_bf16 v[66:81], v[90:93], v[110:113], v[66:81]
	ds_read_b128 v[82:85], v0 offset:49152
	ds_read_b128 v[86:89], v0 offset:49184
	ds_read_b128 v[90:93], v0 offset:49216
	ds_read_b128 v[94:97], v0 offset:49248
	s_waitcnt lgkmcnt(0)
	s_nop 8
	v_fma_f32 v178, v158, v82, v66
	v_fma_f32 v179, v159, v83, v67
	v_fma_f32 v176, v158, v84, v68
	v_fma_f32 v177, v159, v85, v69
	v_fma_f32 v170, v158, v86, v70
	v_fma_f32 v171, v159, v87, v71
	v_fma_f32 v168, v158, v88, v72
	v_fma_f32 v169, v159, v89, v73
	v_fma_f32 v174, v158, v90, v74
	v_fma_f32 v175, v159, v91, v75
	v_fma_f32 v172, v158, v92, v76
	v_fma_f32 v173, v159, v93, v77
	v_max_f32_e32 v0, v178, v179
	v_max3_f32 v0, v0, v176, v177
	v_max3_f32 v0, v0, v170, v171
	v_max3_f32 v0, v0, v168, v169
	v_max3_f32 v0, v0, v174, v175
	v_fma_f32 v180, v158, v94, v78
	v_fma_f32 v181, v159, v95, v79
	v_max3_f32 v0, v0, v172, v173
	v_fma_f32 v182, v158, v96, v80
	v_fma_f32 v183, v159, v97, v81
	v_max3_f32 v0, v0, v180, v181
	v_max3_f32 v0, v0, v182, v183
	v_mov_b32_e32 v66, v0
	s_nop 1
	v_permlane32_swap_b32_e32 v0, v66
	v_max_f32_e32 v66, v66, v66
	v_max_f32_e32 v0, v0, v0
	v_max_f32_e32 v0, v0, v66
	v_sub_f32_e32 v66, v0, v210
	v_cmp_lt_f32_e32 vcc, s9, v66
	s_cbranch_vccz .LBB0_389
	v_max_f32_e32 v0, v0, v0
	v_max_f32_e32 v66, v210, v210
	v_max_f32_e32 v243, v66, v0
	v_sub_f32_e32 v0, v210, v243
	v_exp_f32_e32 v0, v0
	s_nop 0
	v_mul_f32_e32 v244, v211, v0
	v_mul_f32_e32 v64, v64, v0
	v_mul_f32_e32 v65, v65, v0
	v_mul_f32_e32 v62, v62, v0
	v_mul_f32_e32 v63, v63, v0
	v_mul_f32_e32 v60, v60, v0
	v_mul_f32_e32 v61, v61, v0
	v_mul_f32_e32 v58, v58, v0
	v_mul_f32_e32 v59, v59, v0
	v_mul_f32_e32 v56, v56, v0
	v_mul_f32_e32 v57, v57, v0
	v_mul_f32_e32 v54, v54, v0
	v_mul_f32_e32 v55, v55, v0
	v_mul_f32_e32 v52, v52, v0
	v_mul_f32_e32 v53, v53, v0
	v_mul_f32_e32 v50, v50, v0
	v_mul_f32_e32 v51, v51, v0
	v_mul_f32_e32 v48, v48, v0
	v_mul_f32_e32 v49, v49, v0
	v_mul_f32_e32 v46, v46, v0
	v_mul_f32_e32 v47, v47, v0
	v_mul_f32_e32 v44, v44, v0
	v_mul_f32_e32 v45, v45, v0
	v_mul_f32_e32 v42, v42, v0
	v_mul_f32_e32 v43, v43, v0
	v_mul_f32_e32 v40, v40, v0
	v_mul_f32_e32 v41, v41, v0
	v_mul_f32_e32 v38, v38, v0
	v_mul_f32_e32 v39, v39, v0
	v_mul_f32_e32 v36, v36, v0
	v_mul_f32_e32 v37, v37, v0
	v_mul_f32_e32 v34, v34, v0
	v_mul_f32_e32 v35, v35, v0
	v_mov_b32_e32 v0, v243
	s_branch .LBB0_390

; __device__ __forceinline__ unsigned cvt_pk_bf16(float lo, float hi) { f32x2_t v = {lo, hi}; bf16x2_t b = __builtin_convertvector(v, bf16x2_t); return __builtin_bit_cast(unsigned, b); }
; __device__ __forceinline__ float fast_exp2(float x) { return __builtin_amdgcn_exp2f(x); }
; template <bool MASK> ...
;     ...
;     { const f32x2_t m2 = {m, m}; f32x2_t ps2 = {0.f, 0.f};
; #pragma unroll
;       for (int i = 0; i < 8; ++i) { f32x2_t t = sp[i] - m2; t[0] = fast_exp2(t[0]); t[1] = fast_exp2(t[1]); sp[i] = t; ps2 = ps2 + t; }
;       l += ps2[0] + ps2[1]; }
;     u32x4 pw0, pw1;
;     pw0.x = cvt_pk_bf16(sp[0][0], sp[0][1]); pw0.y = cvt_pk_bf16(sp[1][0], sp[1][1]); pw0.z = cvt_pk_bf16(sp[2][0], sp[2][1]); pw0.w = cvt_pk_bf16(sp[3][0], sp[3][1]);
;     pw1.x = cvt_pk_bf16(sp[4][0], sp[4][1]); pw1.y = cvt_pk_bf16(sp[5][0], sp[5][1]); pw1.z = cvt_pk_bf16(sp[6][0], sp[6][1]); pw1.w = cvt_pk_bf16(sp[7][0], sp[7][1]);
;     asm volatile("s_waitcnt lgkmcnt(0)" : "+v"(l00), "+v"(h00), "+v"(l01), "+v"(h01), "+v"(l10), "+v"(h10), "+v"(l11), "+v"(h11) :: "memory");
;     { const bf16x8 pb0 = __builtin_bit_cast(bf16x8, pw0), pb1 = __builtin_bit_cast(bf16x8, pw1);
;       const bf16x8 v00 = {l00[0], l00[1], l00[2], l00[3], h00[0], h00[1], h00[2], h00[3]}, v01 = {l01[0], l01[1], l01[2], l01[3], h01[0], h01[1], h01[2], h01[3]};
;       const bf16x8 v10 = {l10[0], l10[1], l10[2], l10[3], h10[0], h10[1], h10[2], h10[3]}, v11 = {l11[0], l11[1], l11[2], l11[3], h11[0], h11[1], h11[2], h11[3]};
;       o0 = __builtin_amdgcn_mfma_f32_32x32x16_bf16(v00, pb0, o0, 0, 0, 0); o1 = __builtin_amdgcn_mfma_f32_32x32x16_bf16(v01, pb0, o1, 0, 0, 0);
;       o0 = __builtin_amdgcn_mfma_f32_32x32x16_bf16(v10, pb1, o0, 0, 0, 0); o1 = __builtin_amdgcn_mfma_f32_32x32x16_bf16(v11, pb1, o1, 0, 0, 0); }
.LBB0_390:
	v_sub_f32_e32 v178, v178, v0
	v_sub_f32_e32 v179, v179, v0
	v_sub_f32_e32 v176, v176, v0
	v_sub_f32_e32 v177, v177, v0
	v_exp_f32_e32 v178, v178
	v_exp_f32_e32 v179, v179
	v_exp_f32_e32 v176, v176
	v_exp_f32_e32 v177, v177
	v_sub_f32_e32 v170, v170, v0
	v_sub_f32_e32 v171, v171, v0
	v_sub_f32_e32 v168, v168, v0
	v_sub_f32_e32 v169, v169, v0
	v_exp_f32_e32 v170, v170
	v_exp_f32_e32 v171, v171
	v_exp_f32_e32 v248, v168
	v_exp_f32_e32 v249, v169
	v_add_f32_e32 v246, 0, v178
	v_add_f32_e32 v247, 0, v179
	v_sub_f32_e32 v174, v174, v0
	v_sub_f32_e32 v175, v175, v0
	v_add_f32_e32 v246, v176, v246
	v_add_f32_e32 v247, v177, v247
	v_exp_f32_e32 v174, v174
	v_add_f32_e32 v246, v170, v246
	v_add_f32_e32 v247, v171, v247
	v_exp_f32_e32 v175, v175
	v_sub_f32_e32 v172, v172, v0
	v_sub_f32_e32 v173, v173, v0
	v_add_f32_e32 v168, v248, v246
	v_add_f32_e32 v169, v249, v247
	v_exp_f32_e32 v246, v172
	v_exp_f32_e32 v247, v173
	v_sub_f32_e32 v172, v180, v0
	v_sub_f32_e32 v173, v181, v0
	v_add_f32_e32 v168, v174, v168
	v_add_f32_e32 v169, v175, v169
	v_exp_f32_e32 v180, v172
	v_exp_f32_e32 v181, v173
	v_sub_f32_e32 v172, v182, v0
	v_sub_f32_e32 v173, v183, v0
	v_add_f32_e32 v168, v246, v168
	v_add_f32_e32 v169, v247, v169
	v_exp_f32_e32 v182, v172
	v_exp_f32_e32 v183, v173
	v_add_f32_e32 v168, v180, v168
	v_add_f32_e32 v169, v181, v169
	v_cvt_pk_bf16_f32 v170, v170, v171
	v_cvt_pk_bf16_f32 v171, v248, v249
	v_add_f32_e32 v168, v182, v168
	v_add_f32_e32 v169, v183, v169
	s_waitcnt lgkmcnt(0)
	v_cvt_pk_bf16_f32 v172, v174, v175
	v_add_f32_e32 v0, v168, v169
	v_cvt_pk_bf16_f32 v168, v178, v179
	v_cvt_pk_bf16_f32 v169, v176, v177
	v_cvt_pk_bf16_f32 v173, v246, v247
	v_cvt_pk_bf16_f32 v174, v180, v181
	v_mfma_f32_32x32x16_bf16 v[50:65], v[142:145], v[168:171], v[50:65]
	v_cvt_pk_bf16_f32 v175, v182, v183
	v_add_f32_e32 v0, v244, v0
	s_mov_b64 s[18:19], 0
	v_mfma_f32_32x32x16_bf16 v[34:49], v[138:141], v[168:171], v[34:49]
	v_mfma_f32_32x32x16_bf16 v[50:65], v[134:137], v[172:175], v[50:65]
	v_mfma_f32_32x32x16_bf16 v[34:49], v[130:133], v[172:175], v[34:49]
; #define LAS __attribute__((address_space(3)))
; template <bool MASK> ...
;     s16x4 l00, h00, l01, h01, l10, h10, l11, h11; { const unsigned a0 = va0 + sub * 4096, a1 = va1 + sub * 4096;
;       asm volatile("ds_read_b64_tr_b16 %0, %1" : "=&v"(l00) : "v"(a0) : "memory"); asm volatile("ds_read_b64_tr_b16 %0, %1 offset:1024" : "=&v"(h00) : "v"(a0) : "memory");
;       asm volatile("ds_read_b64_tr_b16 %0, %1" : "=&v"(l01) : "v"(a1) : "memory"); asm volatile("ds_read_b64_tr_b16 %0, %1 offset:1024" : "=&v"(h01) : "v"(a1) : "memory");
;       asm volatile("ds_read_b64_tr_b16 %0, %1 offset:2048" : "=&v"(l10) : "v"(a0) : "memory"); asm volatile("ds_read_b64_tr_b16 %0, %1 offset:3072" : "=&v"(h10) : "v"(a0) : "memory");
;       asm volatile("ds_read_b64_tr_b16 %0, %1 offset:2048" : "=&v"(l11) : "v"(a1) : "memory"); asm volatile("ds_read_b64_tr_b16 %0, %1 offset:3072" : "=&v"(h11) : "v"(a1) : "memory"); }
;     const int r = lane & 31, hh = lane >> 5;
;     f32x16 st = {0.f, 0.f, 0.f, 0.f, 0.f, 0.f, 0.f, 0.f, 0.f, 0.f, 0.f, 0.f, 0.f, 0.f, 0.f, 0.f};
;     { const int key = sub * 32 + r; const LAS char* kp = Kt + key * 128; const int ksw = (key >> 1) & 7;
; #pragma unroll
;       for (int d0 = 0; d0 < 4; ++d0) { const bf16x8 kf = *(const LAS bf16x8*)(kp + (((2 * d0 + hh) ^ ksw) << 4)); st = __builtin_amdgcn_mfma_f32_32x32x16_bf16(kf, qr[d0], st, 0, 0, 0); } }
;     f32x2_t sp[8]; const f32x2_t cs2 = {cscale, cscale};
; #pragma unroll
;     for (int g = 0; g < 4; ++g) { const f32x4 c4 = *(const LAS f32x4*)(cb + sub * 32 + 8 * g + 4 * hh);
;         sp[2 * g] = (f32x2_t){st[4 * g], st[4 * g + 1]} + cs2 * (f32x2_t){c4[0], c4[1]};
;         sp[2 * g + 1] = (f32x2_t){st[4 * g + 2], st[4 * g + 3]} + cs2 * (f32x2_t){c4[2], c4[3]};
;         if (MASK) {
; #pragma unroll
;             for (int e = 0; e < 4; ++e) { const int kpos = kpos_sub + 8 * g + 4 * hh + e; const bool ok = (kpos <= qpos && kpos >= qpos - win);
;                 sp[2 * g + (e >> 1)][e & 1] = ok ? sp[2 * g + (e >> 1)][e & 1] : -INFINITY; } } }
;     float rm = fmaxf(sp[0][0], sp[0][1]);
; #pragma unroll
;     for (int i = 1; i < 8; ++i) rm = fmaxf(fmaxf(rm, sp[i][0]), sp[i][1]);
;     rm = swap_max(rm);
;     if (__any(rm - m > 8.0f)) { const float mnew = fmaxf(m, rm); const float f = fast_exp2(m - mnew); l *= f; o0 = o0 * f; o1 = o1 * f; m = mnew; }
.LBB0_391:
	s_and_b64 vcc, exec, s[18:19]
	s_cbranch_vccz .LBB0_396
	ds_read_b64_tr_b16 v[94:95], v216
	ds_read_b64_tr_b16 v[96:97], v216 offset:1024
	ds_read_b64_tr_b16 v[90:91], v217
	ds_read_b64_tr_b16 v[92:93], v217 offset:1024
	ds_read_b64_tr_b16 v[86:87], v216 offset:2048
	ds_read_b64_tr_b16 v[88:89], v216 offset:3072
	ds_read_b64_tr_b16 v[82:83], v217 offset:2048
	ds_read_b64_tr_b16 v[84:85], v217 offset:3072
	s_nop 8
	ds_read_b128 v[66:69], v215
	ds_read_b128 v[130:133], v214
	v_add_u32_e32 v138, s1, v197
	v_or_b32_e32 v0, s4, v150
	v_cmp_le_i32_e32 vcc, v0, v160
	v_cmp_ge_i32_e64 s[44:45], v0, v208
	s_and_b64 vcc, vcc, s[44:45]
	s_waitcnt lgkmcnt(0)
	v_mfma_f32_32x32x16_bf16 v[66:81], v[66:69], v[106:109], 0
	v_mfma_f32_32x32x16_bf16 v[66:81], v[130:133], v[98:101], v[66:81]
	ds_read_b128 v[130:133], v213
	s_waitcnt lgkmcnt(0)
	v_mfma_f32_32x32x16_bf16 v[66:81], v[130:133], v[102:105], v[66:81]
	ds_read_b128 v[130:133], v212
	s_waitcnt lgkmcnt(0)
	v_mfma_f32_32x32x16_bf16 v[66:81], v[130:133], v[110:113], v[66:81]
	ds_read_b128 v[130:133], v138 offset:49152
	ds_read_b128 v[134:137], v138 offset:49184
	s_waitcnt lgkmcnt(0)
	s_nop 8
	v_fma_f32 v66, v158, v130, v66
	v_fma_f32 v67, v159, v131, v67
	v_or_b32_e32 v130, 1, v0
	v_cndmask_b32_e32 v66, v240, v66, vcc
	v_cmp_lt_i32_e32 vcc, v0, v160
	v_cmp_ge_i32_e64 s[44:45], v130, v208
	s_and_b64 vcc, vcc, s[44:45]
	v_or_b32_e32 v130, 2, v0
	v_cndmask_b32_e32 v67, v240, v67, vcc
	v_cmp_le_i32_e32 vcc, v130, v160
	v_cmp_ge_i32_e64 s[44:45], v130, v208
	v_fma_f32 v68, v158, v132, v68
	v_fma_f32 v69, v159, v133, v69
	s_and_b64 vcc, vcc, s[44:45]
	v_or_b32_e32 v130, 3, v0
	v_cndmask_b32_e32 v68, v240, v68, vcc
	v_cmp_le_i32_e32 vcc, v130, v160
	v_cmp_ge_i32_e64 s[44:45], v130, v208
	s_and_b64 vcc, vcc, s[44:45]
	v_or_b32_e32 v130, 8, v0
	v_cndmask_b32_e32 v69, v240, v69, vcc
	v_cmp_le_i32_e32 vcc, v130, v160
	v_cmp_ge_i32_e64 s[44:45], v130, v208
	v_fma_f32 v70, v158, v134, v70
	v_fma_f32 v71, v159, v135, v71
	s_and_b64 vcc, vcc, s[44:45]
	v_or_b32_e32 v130, 9, v0
	v_cndmask_b32_e32 v70, v240, v70, vcc
	v_cmp_le_i32_e32 vcc, v130, v160
	v_cmp_ge_i32_e64 s[44:45], v130, v208
	s_and_b64 vcc, vcc, s[44:45]
	v_or_b32_e32 v130, 10, v0
	v_cndmask_b32_e32 v71, v240, v71, vcc
	v_cmp_le_i32_e32 vcc, v130, v160
	v_cmp_ge_i32_e64 s[44:45], v130, v208
	v_fma_f32 v72, v158, v136, v72
	v_fma_f32 v73, v159, v137, v73
	s_and_b64 vcc, vcc, s[44:45]
	v_or_b32_e32 v130, 11, v0
	v_cndmask_b32_e32 v72, v240, v72, vcc
	v_cmp_le_i32_e32 vcc, v130, v160
	v_cmp_ge_i32_e64 s[44:45], v130, v208
	ds_read_b128 v[130:133], v138 offset:49216
	s_and_b64 vcc, vcc, s[44:45]
	v_cndmask_b32_e32 v73, v240, v73, vcc
	s_waitcnt lgkmcnt(0)
	v_fma_f32 v74, v158, v130, v74
	v_fma_f32 v75, v159, v131, v75
	v_or_b32_e32 v130, 16, v0
	v_cmp_le_i32_e32 vcc, v130, v160
	v_cmp_ge_i32_e64 s[44:45], v130, v208
	s_and_b64 vcc, vcc, s[44:45]
	v_or_b32_e32 v130, 17, v0
	v_cndmask_b32_e32 v74, v240, v74, vcc
	v_cmp_le_i32_e32 vcc, v130, v160
	v_cmp_ge_i32_e64 s[44:45], v130, v208
	s_and_b64 vcc, vcc, s[44:45]
	v_or_b32_e32 v130, 18, v0
	v_cndmask_b32_e32 v75, v240, v75, vcc
	v_cmp_le_i32_e32 vcc, v130, v160
	v_cmp_ge_i32_e64 s[44:45], v130, v208
	v_fma_f32 v76, v158, v132, v76
	v_fma_f32 v77, v159, v133, v77
	s_and_b64 vcc, vcc, s[44:45]
	v_or_b32_e32 v130, 19, v0
	v_cndmask_b32_e32 v76, v240, v76, vcc
	v_cmp_le_i32_e32 vcc, v130, v160
	v_cmp_ge_i32_e64 s[44:45], v130, v208
	ds_read_b128 v[130:133], v138 offset:49248
	s_and_b64 vcc, vcc, s[44:45]
	v_cndmask_b32_e32 v77, v240, v77, vcc
	s_waitcnt lgkmcnt(0)
	v_fma_f32 v78, v158, v130, v78
	v_fma_f32 v79, v159, v131, v79
	v_or_b32_e32 v130, 24, v0
	v_cmp_le_i32_e32 vcc, v130, v160
	v_cmp_ge_i32_e64 s[44:45], v130, v208
	s_and_b64 vcc, vcc, s[44:45]
	v_or_b32_e32 v130, 25, v0
	v_cndmask_b32_e32 v78, v240, v78, vcc
	v_cmp_le_i32_e32 vcc, v130, v160
	v_cmp_ge_i32_e64 s[44:45], v130, v208
	s_and_b64 vcc, vcc, s[44:45]
	v_or_b32_e32 v130, 26, v0
	v_cndmask_b32_e32 v79, v240, v79, vcc
	v_cmp_le_i32_e32 vcc, v130, v160
	v_cmp_ge_i32_e64 s[44:45], v130, v208
	v_fma_f32 v80, v158, v132, v80
	v_fma_f32 v81, v159, v133, v81
	s_and_b64 vcc, vcc, s[44:45]
	v_or_b32_e32 v0, 27, v0
	v_cndmask_b32_e32 v80, v240, v80, vcc
	v_cmp_le_i32_e32 vcc, v0, v160
	v_cmp_ge_i32_e64 s[44:45], v0, v208
	v_max_f32_e32 v0, v66, v67
	v_max3_f32 v0, v0, v68, v69
	v_max3_f32 v0, v0, v70, v71
	v_max3_f32 v0, v0, v72, v73
	v_max3_f32 v0, v0, v74, v75
	s_and_b64 vcc, vcc, s[44:45]
	v_max3_f32 v0, v0, v76, v77
	v_cndmask_b32_e32 v81, v240, v81, vcc
	v_max3_f32 v0, v0, v78, v79
	v_max3_f32 v0, v0, v80, v81
	v_mov_b32_e32 v130, v0
	s_nop 1
	v_permlane32_swap_b32_e32 v0, v130
	v_max_f32_e32 v130, v130, v130
	v_max_f32_e32 v0, v0, v0
	v_max_f32_e32 v0, v0, v130
	v_sub_f32_e32 v130, v0, v210
	v_cmp_lt_f32_e32 vcc, s9, v130
	s_cbranch_vccz .LBB0_394
	v_max_f32_e32 v0, v0, v0
	v_max_f32_e32 v130, v210, v210
	v_max_f32_e32 v0, v130, v0
	v_sub_f32_e32 v130, v210, v0
	v_exp_f32_e32 v130, v130
	v_mov_b32_e32 v210, v0
	v_mul_f32_e32 v211, v211, v130
	v_mul_f32_e32 v64, v64, v130
	v_mul_f32_e32 v65, v65, v130
	v_mul_f32_e32 v62, v62, v130
	v_mul_f32_e32 v63, v63, v130
	v_mul_f32_e32 v60, v60, v130
	v_mul_f32_e32 v61, v61, v130
	v_mul_f32_e32 v58, v58, v130
	v_mul_f32_e32 v59, v59, v130
	v_mul_f32_e32 v56, v56, v130
	v_mul_f32_e32 v57, v57, v130
	v_mul_f32_e32 v54, v54, v130
	v_mul_f32_e32 v55, v55, v130
	v_mul_f32_e32 v52, v52, v130
	v_mul_f32_e32 v53, v53, v130
	v_mul_f32_e32 v50, v50, v130
	v_mul_f32_e32 v51, v51, v130
	v_mul_f32_e32 v48, v48, v130
	v_mul_f32_e32 v49, v49, v130
	v_mul_f32_e32 v46, v46, v130
	v_mul_f32_e32 v47, v47, v130
	v_mul_f32_e32 v44, v44, v130
	v_mul_f32_e32 v45, v45, v130
	v_mul_f32_e32 v42, v42, v130
	v_mul_f32_e32 v43, v43, v130
	v_mul_f32_e32 v40, v40, v130
	v_mul_f32_e32 v41, v41, v130
	v_mul_f32_e32 v38, v38, v130
	v_mul_f32_e32 v39, v39, v130
	v_mul_f32_e32 v36, v36, v130
	v_mul_f32_e32 v37, v37, v130
	v_mul_f32_e32 v34, v34, v130
	v_mul_f32_e32 v35, v35, v130
	s_branch .LBB0_395

; __device__ __forceinline__ unsigned cvt_pk_bf16(float lo, float hi) { f32x2_t v = {lo, hi}; bf16x2_t b = __builtin_convertvector(v, bf16x2_t); return __builtin_bit_cast(unsigned, b); }
; __device__ __forceinline__ float fast_exp2(float x) { return __builtin_amdgcn_exp2f(x); }
; template <bool MASK> ...
;     ...
;     { const f32x2_t m2 = {m, m}; f32x2_t ps2 = {0.f, 0.f};
; #pragma unroll
;       for (int i = 0; i < 8; ++i) { f32x2_t t = sp[i] - m2; t[0] = fast_exp2(t[0]); t[1] = fast_exp2(t[1]); sp[i] = t; ps2 = ps2 + t; }
;       l += ps2[0] + ps2[1]; }
;     u32x4 pw0, pw1;
;     pw0.x = cvt_pk_bf16(sp[0][0], sp[0][1]); pw0.y = cvt_pk_bf16(sp[1][0], sp[1][1]); pw0.z = cvt_pk_bf16(sp[2][0], sp[2][1]); pw0.w = cvt_pk_bf16(sp[3][0], sp[3][1]);
;     pw1.x = cvt_pk_bf16(sp[4][0], sp[4][1]); pw1.y = cvt_pk_bf16(sp[5][0], sp[5][1]); pw1.z = cvt_pk_bf16(sp[6][0], sp[6][1]); pw1.w = cvt_pk_bf16(sp[7][0], sp[7][1]);
;     asm volatile("s_waitcnt lgkmcnt(0)" : "+v"(l00), "+v"(h00), "+v"(l01), "+v"(h01), "+v"(l10), "+v"(h10), "+v"(l11), "+v"(h11) :: "memory");
;     { const bf16x8 pb0 = __builtin_bit_cast(bf16x8, pw0), pb1 = __builtin_bit_cast(bf16x8, pw1);
;       const bf16x8 v00 = {l00[0], l00[1], l00[2], l00[3], h00[0], h00[1], h00[2], h00[3]}, v01 = {l01[0], l01[1], l01[2], l01[3], h01[0], h01[1], h01[2], h01[3]};
;       const bf16x8 v10 = {l10[0], l10[1], l10[2], l10[3], h10[0], h10[1], h10[2], h10[3]}, v11 = {l11[0], l11[1], l11[2], l11[3], h11[0], h11[1], h11[2], h11[3]};
;       o0 = __builtin_amdgcn_mfma_f32_32x32x16_bf16(v00, pb0, o0, 0, 0, 0); o1 = __builtin_amdgcn_mfma_f32_32x32x16_bf16(v01, pb0, o1, 0, 0, 0);
;       o0 = __builtin_amdgcn_mfma_f32_32x32x16_bf16(v10, pb1, o0, 0, 0, 0); o1 = __builtin_amdgcn_mfma_f32_32x32x16_bf16(v11, pb1, o1, 0, 0, 0); }
.LBB0_395:
	v_sub_f32_e32 v66, v66, v0
	v_sub_f32_e32 v67, v67, v0
	v_sub_f32_e32 v68, v68, v0
	v_sub_f32_e32 v69, v69, v0
	v_exp_f32_e32 v66, v66
	v_exp_f32_e32 v67, v67
	v_sub_f32_e32 v70, v70, v0
	v_sub_f32_e32 v71, v71, v0
	v_sub_f32_e32 v72, v72, v0
	v_sub_f32_e32 v73, v73, v0
	v_exp_f32_e32 v68, v68
	v_exp_f32_e32 v69, v69
	v_exp_f32_e32 v70, v70
	v_exp_f32_e32 v71, v71
	v_exp_f32_e32 v72, v72
	v_exp_f32_e32 v73, v73
	v_add_f32_e32 v130, 0, v66
	v_add_f32_e32 v131, 0, v67
	v_cvt_pk_bf16_f32 v66, v66, v67
	v_add_f32_e32 v130, v68, v130
	v_add_f32_e32 v131, v69, v131
	v_cvt_pk_bf16_f32 v67, v68, v69
	v_cvt_pk_bf16_f32 v68, v70, v71
	v_cvt_pk_bf16_f32 v69, v72, v73
	s_waitcnt lgkmcnt(0)
	v_sub_f32_e32 v74, v74, v0
	v_sub_f32_e32 v75, v75, v0
	v_sub_f32_e32 v76, v76, v0
	v_sub_f32_e32 v77, v77, v0
	v_mfma_f32_32x32x16_bf16 v[50:65], v[94:97], v[66:69], v[50:65]
	v_add_f32_e64 v78, v78, -v0
	v_add_f32_e64 v79, v79, -v0
	v_add_f32_e64 v80, v80, -v0
	v_add_f32_e64 v81, v81, -v0
	v_exp_f32_e32 v74, v74
	v_exp_f32_e32 v75, v75
	v_exp_f32_e32 v76, v76
	v_exp_f32_e32 v77, v77
	v_exp_f32_e32 v78, v78
	v_mfma_f32_32x32x16_bf16 v[34:49], v[90:93], v[66:69], v[34:49]
	v_exp_f32_e32 v79, v79
	v_exp_f32_e32 v80, v80
	v_exp_f32_e32 v81, v81
	v_add_f32_e32 v130, v70, v130
	v_add_f32_e32 v131, v71, v131
	v_cvt_pk_bf16_f32 v70, v74, v75
	v_add_f32_e32 v130, v72, v130
	v_add_f32_e32 v131, v73, v131
	v_cvt_pk_bf16_f32 v71, v76, v77
	v_cvt_pk_bf16_f32 v72, v78, v79
	v_cvt_pk_bf16_f32 v73, v80, v81
	v_add_f32_e32 v130, v74, v130
	v_add_f32_e32 v131, v75, v131
	v_mov_b32_e32 v243, v210
	v_mfma_f32_32x32x16_bf16 v[50:65], v[86:89], v[70:73], v[50:65]
	v_add_f32_e64 v130, v76, v130
	v_add_f32_e64 v131, v77, v131
	v_add_f32_e64 v130, v78, v130
	v_add_f32_e64 v131, v79, v131
	v_add_f32_e64 v130, v80, v130
	v_add_f32_e64 v131, v81, v131
	v_add_f32_e32 v0, v130, v131
	v_mfma_f32_32x32x16_bf16 v[34:49], v[82:85], v[70:73], v[34:49]
	s_nop 3
	v_add_f32_e32 v0, v211, v0
	s_nop 0

; #define LAS __attribute__((address_space(3)))
; template <bool MASK> ...
;     s16x4 l00, h00, l01, h01, l10, h10, l11, h11; { const unsigned a0 = va0 + sub * 4096, a1 = va1 + sub * 4096;
;       asm volatile("ds_read_b64_tr_b16 %0, %1" : "=&v"(l00) : "v"(a0) : "memory"); asm volatile("ds_read_b64_tr_b16 %0, %1 offset:1024" : "=&v"(h00) : "v"(a0) : "memory");
;       asm volatile("ds_read_b64_tr_b16 %0, %1" : "=&v"(l01) : "v"(a1) : "memory"); asm volatile("ds_read_b64_tr_b16 %0, %1 offset:1024" : "=&v"(h01) : "v"(a1) : "memory");
;       asm volatile("ds_read_b64_tr_b16 %0, %1 offset:2048" : "=&v"(l10) : "v"(a0) : "memory"); asm volatile("ds_read_b64_tr_b16 %0, %1 offset:3072" : "=&v"(h10) : "v"(a0) : "memory");
;       asm volatile("ds_read_b64_tr_b16 %0, %1 offset:2048" : "=&v"(l11) : "v"(a1) : "memory"); asm volatile("ds_read_b64_tr_b16 %0, %1 offset:3072" : "=&v"(h11) : "v"(a1) : "memory"); }
;     const int r = lane & 31, hh = lane >> 5;
;     f32x16 st = {0.f, 0.f, 0.f, 0.f, 0.f, 0.f, 0.f, 0.f, 0.f, 0.f, 0.f, 0.f, 0.f, 0.f, 0.f, 0.f};
;     { const int key = sub * 32 + r; const LAS char* kp = Kt + key * 128; const int ksw = (key >> 1) & 7;
; #pragma unroll
;       for (int d0 = 0; d0 < 4; ++d0) { const bf16x8 kf = *(const LAS bf16x8*)(kp + (((2 * d0 + hh) ^ ksw) << 4)); st = __builtin_amdgcn_mfma_f32_32x32x16_bf16(kf, qr[d0], st, 0, 0, 0); } }
;     f32x2_t sp[8]; const f32x2_t cs2 = {cscale, cscale};
; #pragma unroll
;     for (int g = 0; g < 4; ++g) { const f32x4 c4 = *(const LAS f32x4*)(cb + sub * 32 + 8 * g + 4 * hh);
;         sp[2 * g] = (f32x2_t){st[4 * g], st[4 * g + 1]} + cs2 * (f32x2_t){c4[0], c4[1]};
;         sp[2 * g + 1] = (f32x2_t){st[4 * g + 2], st[4 * g + 3]} + cs2 * (f32x2_t){c4[2], c4[3]};
;         if (MASK) {
; #pragma unroll
;             for (int e = 0; e < 4; ++e) { const int kpos = kpos_sub + 8 * g + 4 * hh + e; const bool ok = (kpos <= qpos && kpos >= qpos - win);
;                 sp[2 * g + (e >> 1)][e & 1] = ok ? sp[2 * g + (e >> 1)][e & 1] : -INFINITY; } } }
;     float rm = fmaxf(sp[0][0], sp[0][1]);
; #pragma unroll
;     for (int i = 1; i < 8; ++i) rm = fmaxf(fmaxf(rm, sp[i][0]), sp[i][1]);
;     rm = swap_max(rm);
;     if (__any(rm - m > 8.0f)) { const float mnew = fmaxf(m, rm); const float f = fast_exp2(m - mnew); l *= f; o0 = o0 * f; o1 = o1 * f; m = mnew; }
.LBB0_397:
	s_cmp_gt_i32 s4, s3
	s_cselect_b64 s[16:17], -1, 0
	s_cmp_lt_i32 s5, s22
	s_cselect_b64 s[18:19], -1, 0
	s_or_b64 s[16:17], s[16:17], s[18:19]
	s_and_b64 vcc, exec, s[16:17]
	s_cbranch_vccnz .LBB0_409
	s_cmp_gt_i32 s4, s12
	s_cselect_b64 s[16:17], -1, 0
	s_cmp_lt_i32 s4, s13
	s_cselect_b64 s[18:19], -1, 0
	s_or_b64 s[16:17], s[16:17], s[18:19]
	s_mov_b64 s[18:19], -1
	s_and_b64 vcc, exec, s[16:17]
	s_cbranch_vccnz .LBB0_403
	ds_read_b64_tr_b16 v[142:143], v216
	ds_read_b64_tr_b16 v[144:145], v216 offset:1024
	ds_read_b64_tr_b16 v[138:139], v217
	ds_read_b64_tr_b16 v[140:141], v217 offset:1024
	ds_read_b64_tr_b16 v[134:135], v216 offset:2048
	ds_read_b64_tr_b16 v[136:137], v216 offset:3072
	ds_read_b64_tr_b16 v[130:131], v217 offset:2048
	ds_read_b64_tr_b16 v[132:133], v217 offset:3072
	ds_read_b128 v[66:69], v215
	ds_read_b128 v[82:85], v214
	ds_read_b128 v[86:89], v213
	ds_read_b128 v[90:93], v212
	v_add_u32_e32 v0, s1, v197
	s_waitcnt lgkmcnt(2)
	v_mfma_f32_32x32x16_bf16 v[66:81], v[66:69], v[122:125], 0
	v_mfma_f32_32x32x16_bf16 v[66:81], v[82:85], v[114:117], v[66:81]
	s_waitcnt lgkmcnt(1)
	v_mfma_f32_32x32x16_bf16 v[66:81], v[86:89], v[118:121], v[66:81]
	s_waitcnt lgkmcnt(0)
	v_mfma_f32_32x32x16_bf16 v[66:81], v[90:93], v[126:129], v[66:81]
	ds_read_b128 v[82:85], v0 offset:49152
	ds_read_b128 v[86:89], v0 offset:49184
	ds_read_b128 v[90:93], v0 offset:49216
	ds_read_b128 v[94:97], v0 offset:49248
	s_waitcnt lgkmcnt(0)
	s_nop 8
	v_fma_f32 v178, v158, v82, v66
	v_fma_f32 v179, v159, v83, v67
	v_fma_f32 v176, v158, v84, v68
	v_fma_f32 v177, v159, v85, v69
	v_fma_f32 v170, v158, v86, v70
	v_fma_f32 v171, v159, v87, v71
	v_fma_f32 v168, v158, v88, v72
	v_fma_f32 v169, v159, v89, v73
	v_fma_f32 v174, v158, v90, v74
	v_fma_f32 v175, v159, v91, v75
	v_fma_f32 v172, v158, v92, v76
	v_fma_f32 v173, v159, v93, v77
	v_max_f32_e32 v0, v178, v179
	v_max3_f32 v0, v0, v176, v177
	v_max3_f32 v0, v0, v170, v171
	v_max3_f32 v0, v0, v168, v169
	v_max3_f32 v0, v0, v174, v175
	v_fma_f32 v180, v158, v94, v78
	v_fma_f32 v181, v159, v95, v79
	v_max3_f32 v0, v0, v172, v173
	v_fma_f32 v182, v158, v96, v80
	v_fma_f32 v183, v159, v97, v81
	v_max3_f32 v0, v0, v180, v181
	v_max3_f32 v0, v0, v182, v183
	v_mov_b32_e32 v66, v0
	s_nop 1
	v_permlane32_swap_b32_e32 v0, v66
	v_max_f32_e32 v66, v66, v66
	v_max_f32_e32 v0, v0, v0
	v_max_f32_e32 v0, v0, v66
	v_sub_f32_e32 v66, v0, v155
	v_cmp_lt_f32_e32 vcc, s9, v66
	s_cbranch_vccz .LBB0_401
	v_max_f32_e32 v0, v0, v0
	v_max_f32_e32 v66, v155, v155
	v_max_f32_e32 v243, v66, v0
	v_sub_f32_e32 v0, v155, v243
	v_exp_f32_e32 v0, v0
	s_nop 0
	v_mul_f32_e32 v244, v161, v0
	v_mul_f32_e32 v32, v32, v0
	v_mul_f32_e32 v33, v33, v0
	v_mul_f32_e32 v30, v30, v0
	v_mul_f32_e32 v31, v31, v0
	v_mul_f32_e32 v28, v28, v0
	v_mul_f32_e32 v29, v29, v0
	v_mul_f32_e32 v26, v26, v0
	v_mul_f32_e32 v27, v27, v0
	v_mul_f32_e32 v24, v24, v0
	v_mul_f32_e32 v25, v25, v0
	v_mul_f32_e32 v22, v22, v0
	v_mul_f32_e32 v23, v23, v0
	v_mul_f32_e32 v20, v20, v0
	v_mul_f32_e32 v21, v21, v0
	v_mul_f32_e32 v18, v18, v0
	v_mul_f32_e32 v19, v19, v0
	v_mul_f32_e32 v16, v16, v0
	v_mul_f32_e32 v17, v17, v0
	v_mul_f32_e32 v14, v14, v0
	v_mul_f32_e32 v15, v15, v0
	v_mul_f32_e32 v12, v12, v0
	v_mul_f32_e32 v13, v13, v0
	v_mul_f32_e32 v10, v10, v0
	v_mul_f32_e32 v11, v11, v0
	v_mul_f32_e32 v8, v8, v0
	v_mul_f32_e32 v9, v9, v0
	v_mul_f32_e32 v6, v6, v0
	v_mul_f32_e32 v7, v7, v0
	v_mul_f32_e32 v4, v4, v0
	v_mul_f32_e32 v5, v5, v0
	v_mul_f32_e32 v2, v2, v0
	v_mul_f32_e32 v3, v3, v0
	v_mov_b32_e32 v0, v243
	s_branch .LBB0_402

; __device__ __forceinline__ unsigned cvt_pk_bf16(float lo, float hi) { f32x2_t v = {lo, hi}; bf16x2_t b = __builtin_convertvector(v, bf16x2_t); return __builtin_bit_cast(unsigned, b); }
; __device__ __forceinline__ float fast_exp2(float x) { return __builtin_amdgcn_exp2f(x); }
; template <bool MASK> ...
;     ...
;     { const f32x2_t m2 = {m, m}; f32x2_t ps2 = {0.f, 0.f};
; #pragma unroll
;       for (int i = 0; i < 8; ++i) { f32x2_t t = sp[i] - m2; t[0] = fast_exp2(t[0]); t[1] = fast_exp2(t[1]); sp[i] = t; ps2 = ps2 + t; }
;       l += ps2[0] + ps2[1]; }
;     u32x4 pw0, pw1;
;     pw0.x = cvt_pk_bf16(sp[0][0], sp[0][1]); pw0.y = cvt_pk_bf16(sp[1][0], sp[1][1]); pw0.z = cvt_pk_bf16(sp[2][0], sp[2][1]); pw0.w = cvt_pk_bf16(sp[3][0], sp[3][1]);
;     pw1.x = cvt_pk_bf16(sp[4][0], sp[4][1]); pw1.y = cvt_pk_bf16(sp[5][0], sp[5][1]); pw1.z = cvt_pk_bf16(sp[6][0], sp[6][1]); pw1.w = cvt_pk_bf16(sp[7][0], sp[7][1]);
;     asm volatile("s_waitcnt lgkmcnt(0)" : "+v"(l00), "+v"(h00), "+v"(l01), "+v"(h01), "+v"(l10), "+v"(h10), "+v"(l11), "+v"(h11) :: "memory");
;     { const bf16x8 pb0 = __builtin_bit_cast(bf16x8, pw0), pb1 = __builtin_bit_cast(bf16x8, pw1);
;       const bf16x8 v00 = {l00[0], l00[1], l00[2], l00[3], h00[0], h00[1], h00[2], h00[3]}, v01 = {l01[0], l01[1], l01[2], l01[3], h01[0], h01[1], h01[2], h01[3]};
;       const bf16x8 v10 = {l10[0], l10[1], l10[2], l10[3], h10[0], h10[1], h10[2], h10[3]}, v11 = {l11[0], l11[1], l11[2], l11[3], h11[0], h11[1], h11[2], h11[3]};
;       o0 = __builtin_amdgcn_mfma_f32_32x32x16_bf16(v00, pb0, o0, 0, 0, 0); o1 = __builtin_amdgcn_mfma_f32_32x32x16_bf16(v01, pb0, o1, 0, 0, 0);
;       o0 = __builtin_amdgcn_mfma_f32_32x32x16_bf16(v10, pb1, o0, 0, 0, 0); o1 = __builtin_amdgcn_mfma_f32_32x32x16_bf16(v11, pb1, o1, 0, 0, 0); }
.LBB0_402:
	v_sub_f32_e32 v178, v178, v0
	v_sub_f32_e32 v179, v179, v0
	v_sub_f32_e32 v176, v176, v0
	v_sub_f32_e32 v177, v177, v0
	v_exp_f32_e32 v178, v178
	v_exp_f32_e32 v179, v179
	v_exp_f32_e32 v176, v176
	v_exp_f32_e32 v177, v177
	v_sub_f32_e32 v170, v170, v0
	v_sub_f32_e32 v171, v171, v0
	v_sub_f32_e32 v168, v168, v0
	v_sub_f32_e32 v169, v169, v0
	v_exp_f32_e32 v170, v170
	v_exp_f32_e32 v171, v171
	v_exp_f32_e32 v248, v168
	v_exp_f32_e32 v249, v169
	v_add_f32_e32 v246, 0, v178
	v_add_f32_e32 v247, 0, v179
	v_sub_f32_e32 v174, v174, v0
	v_sub_f32_e32 v175, v175, v0
	v_add_f32_e32 v246, v176, v246
	v_add_f32_e32 v247, v177, v247
	v_exp_f32_e32 v174, v174
	v_add_f32_e32 v246, v170, v246
	v_add_f32_e32 v247, v171, v247
	v_exp_f32_e32 v175, v175
	v_sub_f32_e32 v172, v172, v0
	v_sub_f32_e32 v173, v173, v0
	v_add_f32_e32 v168, v248, v246
	v_add_f32_e32 v169, v249, v247
	v_exp_f32_e32 v246, v172
	v_exp_f32_e32 v247, v173
	v_sub_f32_e32 v172, v180, v0
	v_sub_f32_e32 v173, v181, v0
	v_add_f32_e32 v168, v174, v168
	v_add_f32_e32 v169, v175, v169
	v_exp_f32_e32 v180, v172
	v_exp_f32_e32 v181, v173
	v_sub_f32_e32 v172, v182, v0
	v_sub_f32_e32 v173, v183, v0
	v_add_f32_e32 v168, v246, v168
	v_add_f32_e32 v169, v247, v169
	v_exp_f32_e32 v182, v172
	v_exp_f32_e32 v183, v173
	v_add_f32_e32 v168, v180, v168
	v_add_f32_e32 v169, v181, v169
	v_cvt_pk_bf16_f32 v170, v170, v171
	v_cvt_pk_bf16_f32 v171, v248, v249
	v_add_f32_e32 v168, v182, v168
	v_add_f32_e32 v169, v183, v169
	s_waitcnt lgkmcnt(0)
	v_cvt_pk_bf16_f32 v172, v174, v175
	v_add_f32_e32 v0, v168, v169
	v_cvt_pk_bf16_f32 v168, v178, v179
	v_cvt_pk_bf16_f32 v169, v176, v177
	v_cvt_pk_bf16_f32 v173, v246, v247
	v_cvt_pk_bf16_f32 v174, v180, v181
	v_mfma_f32_32x32x16_bf16 v[18:33], v[142:145], v[168:171], v[18:33]
	v_cvt_pk_bf16_f32 v175, v182, v183
	v_add_f32_e32 v0, v244, v0
	s_mov_b64 s[18:19], 0
	v_mfma_f32_32x32x16_bf16 v[2:17], v[138:141], v[168:171], v[2:17]
	v_mfma_f32_32x32x16_bf16 v[18:33], v[134:137], v[172:175], v[18:33]
	v_mfma_f32_32x32x16_bf16 v[2:17], v[130:133], v[172:175], v[2:17]
; #define LAS __attribute__((address_space(3)))
; template <bool MASK> ...
;     s16x4 l00, h00, l01, h01, l10, h10, l11, h11; { const unsigned a0 = va0 + sub * 4096, a1 = va1 + sub * 4096;
;       asm volatile("ds_read_b64_tr_b16 %0, %1" : "=&v"(l00) : "v"(a0) : "memory"); asm volatile("ds_read_b64_tr_b16 %0, %1 offset:1024" : "=&v"(h00) : "v"(a0) : "memory");
;       asm volatile("ds_read_b64_tr_b16 %0, %1" : "=&v"(l01) : "v"(a1) : "memory"); asm volatile("ds_read_b64_tr_b16 %0, %1 offset:1024" : "=&v"(h01) : "v"(a1) : "memory");
;       asm volatile("ds_read_b64_tr_b16 %0, %1 offset:2048" : "=&v"(l10) : "v"(a0) : "memory"); asm volatile("ds_read_b64_tr_b16 %0, %1 offset:3072" : "=&v"(h10) : "v"(a0) : "memory");
;       asm volatile("ds_read_b64_tr_b16 %0, %1 offset:2048" : "=&v"(l11) : "v"(a1) : "memory"); asm volatile("ds_read_b64_tr_b16 %0, %1 offset:3072" : "=&v"(h11) : "v"(a1) : "memory"); }
;     const int r = lane & 31, hh = lane >> 5;
;     f32x16 st = {0.f, 0.f, 0.f, 0.f, 0.f, 0.f, 0.f, 0.f, 0.f, 0.f, 0.f, 0.f, 0.f, 0.f, 0.f, 0.f};
;     { const int key = sub * 32 + r; const LAS char* kp = Kt + key * 128; const int ksw = (key >> 1) & 7;
; #pragma unroll
;       for (int d0 = 0; d0 < 4; ++d0) { const bf16x8 kf = *(const LAS bf16x8*)(kp + (((2 * d0 + hh) ^ ksw) << 4)); st = __builtin_amdgcn_mfma_f32_32x32x16_bf16(kf, qr[d0], st, 0, 0, 0); } }
;     f32x2_t sp[8]; const f32x2_t cs2 = {cscale, cscale};
; #pragma unroll
;     for (int g = 0; g < 4; ++g) { const f32x4 c4 = *(const LAS f32x4*)(cb + sub * 32 + 8 * g + 4 * hh);
;         sp[2 * g] = (f32x2_t){st[4 * g], st[4 * g + 1]} + cs2 * (f32x2_t){c4[0], c4[1]};
;         sp[2 * g + 1] = (f32x2_t){st[4 * g + 2], st[4 * g + 3]} + cs2 * (f32x2_t){c4[2], c4[3]};
;         if (MASK) {
; #pragma unroll
;             for (int e = 0; e < 4; ++e) { const int kpos = kpos_sub + 8 * g + 4 * hh + e; const bool ok = (kpos <= qpos && kpos >= qpos - win);
;                 sp[2 * g + (e >> 1)][e & 1] = ok ? sp[2 * g + (e >> 1)][e & 1] : -INFINITY; } } }
;     float rm = fmaxf(sp[0][0], sp[0][1]);
; #pragma unroll
;     for (int i = 1; i < 8; ++i) rm = fmaxf(fmaxf(rm, sp[i][0]), sp[i][1]);
;     rm = swap_max(rm);
;     if (__any(rm - m > 8.0f)) { const float mnew = fmaxf(m, rm); const float f = fast_exp2(m - mnew); l *= f; o0 = o0 * f; o1 = o1 * f; m = mnew; }
.LBB0_403:
	s_and_b64 vcc, exec, s[18:19]
	s_cbranch_vccz .LBB0_408
	ds_read_b64_tr_b16 v[94:95], v216
	ds_read_b64_tr_b16 v[96:97], v216 offset:1024
	ds_read_b64_tr_b16 v[90:91], v217
	ds_read_b64_tr_b16 v[92:93], v217 offset:1024
	ds_read_b64_tr_b16 v[86:87], v216 offset:2048
	ds_read_b64_tr_b16 v[88:89], v216 offset:3072
	ds_read_b64_tr_b16 v[82:83], v217 offset:2048
	ds_read_b64_tr_b16 v[84:85], v217 offset:3072
	s_nop 8
	ds_read_b128 v[66:69], v215
	ds_read_b128 v[130:133], v214
	v_add_u32_e32 v138, s1, v197
	v_or_b32_e32 v0, s4, v150
	v_cmp_le_i32_e32 vcc, v0, v154
	v_cmp_ge_i32_e64 s[44:45], v0, v209
	s_and_b64 vcc, vcc, s[44:45]
	s_waitcnt lgkmcnt(0)
	v_mfma_f32_32x32x16_bf16 v[66:81], v[66:69], v[122:125], 0
	v_mfma_f32_32x32x16_bf16 v[66:81], v[130:133], v[114:117], v[66:81]
	ds_read_b128 v[130:133], v213
	s_waitcnt lgkmcnt(0)
	v_mfma_f32_32x32x16_bf16 v[66:81], v[130:133], v[118:121], v[66:81]
	ds_read_b128 v[130:133], v212
	s_waitcnt lgkmcnt(0)
	v_mfma_f32_32x32x16_bf16 v[66:81], v[130:133], v[126:129], v[66:81]
	ds_read_b128 v[130:133], v138 offset:49152
	ds_read_b128 v[134:137], v138 offset:49184
	s_waitcnt lgkmcnt(0)
	s_nop 8
	v_fma_f32 v66, v158, v130, v66
	v_fma_f32 v67, v159, v131, v67
	v_or_b32_e32 v130, 1, v0
	v_cndmask_b32_e32 v66, v240, v66, vcc
	v_cmp_lt_i32_e32 vcc, v0, v154
	v_cmp_ge_i32_e64 s[44:45], v130, v209
	s_and_b64 vcc, vcc, s[44:45]
	v_or_b32_e32 v130, 2, v0
	v_cndmask_b32_e32 v67, v240, v67, vcc
	v_cmp_le_i32_e32 vcc, v130, v154
	v_cmp_ge_i32_e64 s[44:45], v130, v209
	v_fma_f32 v68, v158, v132, v68
	v_fma_f32 v69, v159, v133, v69
	s_and_b64 vcc, vcc, s[44:45]
	v_or_b32_e32 v130, 3, v0
	v_cndmask_b32_e32 v68, v240, v68, vcc
	v_cmp_le_i32_e32 vcc, v130, v154
	v_cmp_ge_i32_e64 s[44:45], v130, v209
	s_and_b64 vcc, vcc, s[44:45]
	v_or_b32_e32 v130, 8, v0
	v_cndmask_b32_e32 v69, v240, v69, vcc
	v_cmp_le_i32_e32 vcc, v130, v154
	v_cmp_ge_i32_e64 s[44:45], v130, v209
	v_fma_f32 v70, v158, v134, v70
	v_fma_f32 v71, v159, v135, v71
	s_and_b64 vcc, vcc, s[44:45]
	v_or_b32_e32 v130, 9, v0
	v_cndmask_b32_e32 v70, v240, v70, vcc
	v_cmp_le_i32_e32 vcc, v130, v154
	v_cmp_ge_i32_e64 s[44:45], v130, v209
	s_and_b64 vcc, vcc, s[44:45]
	v_or_b32_e32 v130, 10, v0
	v_cndmask_b32_e32 v71, v240, v71, vcc
	v_cmp_le_i32_e32 vcc, v130, v154
	v_cmp_ge_i32_e64 s[44:45], v130, v209
	v_fma_f32 v72, v158, v136, v72
	v_fma_f32 v73, v159, v137, v73
	s_and_b64 vcc, vcc, s[44:45]
	v_or_b32_e32 v130, 11, v0
	v_cndmask_b32_e32 v72, v240, v72, vcc
	v_cmp_le_i32_e32 vcc, v130, v154
	v_cmp_ge_i32_e64 s[44:45], v130, v209
	ds_read_b128 v[130:133], v138 offset:49216
	s_and_b64 vcc, vcc, s[44:45]
	v_cndmask_b32_e32 v73, v240, v73, vcc
	s_waitcnt lgkmcnt(0)
	v_fma_f32 v74, v158, v130, v74
	v_fma_f32 v75, v159, v131, v75
	v_or_b32_e32 v130, 16, v0
	v_cmp_le_i32_e32 vcc, v130, v154
	v_cmp_ge_i32_e64 s[44:45], v130, v209
	s_and_b64 vcc, vcc, s[44:45]
	v_or_b32_e32 v130, 17, v0
	v_cndmask_b32_e32 v74, v240, v74, vcc
	v_cmp_le_i32_e32 vcc, v130, v154
	v_cmp_ge_i32_e64 s[44:45], v130, v209
	s_and_b64 vcc, vcc, s[44:45]
	v_or_b32_e32 v130, 18, v0
	v_cndmask_b32_e32 v75, v240, v75, vcc
	v_cmp_le_i32_e32 vcc, v130, v154
	v_cmp_ge_i32_e64 s[44:45], v130, v209
	v_fma_f32 v76, v158, v132, v76
	v_fma_f32 v77, v159, v133, v77
	s_and_b64 vcc, vcc, s[44:45]
	v_or_b32_e32 v130, 19, v0
	v_cndmask_b32_e32 v76, v240, v76, vcc
	v_cmp_le_i32_e32 vcc, v130, v154
	v_cmp_ge_i32_e64 s[44:45], v130, v209
	ds_read_b128 v[130:133], v138 offset:49248
	s_and_b64 vcc, vcc, s[44:45]
	v_cndmask_b32_e32 v77, v240, v77, vcc
	s_waitcnt lgkmcnt(0)
	v_fma_f32 v78, v158, v130, v78
	v_fma_f32 v79, v159, v131, v79
	v_or_b32_e32 v130, 24, v0
	v_cmp_le_i32_e32 vcc, v130, v154
	v_cmp_ge_i32_e64 s[44:45], v130, v209
	s_and_b64 vcc, vcc, s[44:45]
	v_or_b32_e32 v130, 25, v0
	v_cndmask_b32_e32 v78, v240, v78, vcc
	v_cmp_le_i32_e32 vcc, v130, v154
	v_cmp_ge_i32_e64 s[44:45], v130, v209
	s_and_b64 vcc, vcc, s[44:45]
	v_or_b32_e32 v130, 26, v0
	v_cndmask_b32_e32 v79, v240, v79, vcc
	v_cmp_le_i32_e32 vcc, v130, v154
	v_cmp_ge_i32_e64 s[44:45], v130, v209
	v_fma_f32 v80, v158, v132, v80
	v_fma_f32 v81, v159, v133, v81
	s_and_b64 vcc, vcc, s[44:45]
	v_or_b32_e32 v0, 27, v0
	v_cndmask_b32_e32 v80, v240, v80, vcc
	v_cmp_le_i32_e32 vcc, v0, v154
	v_cmp_ge_i32_e64 s[44:45], v0, v209
	v_max_f32_e32 v0, v66, v67
	v_max3_f32 v0, v0, v68, v69
	v_max3_f32 v0, v0, v70, v71
	v_max3_f32 v0, v0, v72, v73
	v_max3_f32 v0, v0, v74, v75
	s_and_b64 vcc, vcc, s[44:45]
	v_max3_f32 v0, v0, v76, v77
	v_cndmask_b32_e32 v81, v240, v81, vcc
	v_max3_f32 v0, v0, v78, v79
	v_max3_f32 v0, v0, v80, v81
	v_mov_b32_e32 v130, v0
	s_nop 1
	v_permlane32_swap_b32_e32 v0, v130
	v_max_f32_e32 v130, v130, v130
	v_max_f32_e32 v0, v0, v0
	v_max_f32_e32 v0, v0, v130
	v_sub_f32_e32 v130, v0, v155
	v_cmp_lt_f32_e32 vcc, s9, v130
	s_cbranch_vccz .LBB0_406
	v_max_f32_e32 v0, v0, v0
	v_max_f32_e32 v130, v155, v155
	v_max_f32_e32 v0, v130, v0
	v_sub_f32_e32 v130, v155, v0
	v_exp_f32_e32 v130, v130
	v_mov_b32_e32 v155, v0
	v_mul_f32_e32 v161, v161, v130
	v_mul_f32_e32 v32, v32, v130
	v_mul_f32_e32 v33, v33, v130
	v_mul_f32_e32 v30, v30, v130
	v_mul_f32_e32 v31, v31, v130
	v_mul_f32_e32 v28, v28, v130
	v_mul_f32_e32 v29, v29, v130
	v_mul_f32_e32 v26, v26, v130
	v_mul_f32_e32 v27, v27, v130
	v_mul_f32_e32 v24, v24, v130
	v_mul_f32_e32 v25, v25, v130
	v_mul_f32_e32 v22, v22, v130
	v_mul_f32_e32 v23, v23, v130
	v_mul_f32_e32 v20, v20, v130
	v_mul_f32_e32 v21, v21, v130
	v_mul_f32_e32 v18, v18, v130
	v_mul_f32_e32 v19, v19, v130
	v_mul_f32_e32 v16, v16, v130
	v_mul_f32_e32 v17, v17, v130
	v_mul_f32_e32 v14, v14, v130
	v_mul_f32_e32 v15, v15, v130
	v_mul_f32_e32 v12, v12, v130
	v_mul_f32_e32 v13, v13, v130
	v_mul_f32_e32 v10, v10, v130
	v_mul_f32_e32 v11, v11, v130
	v_mul_f32_e32 v8, v8, v130
	v_mul_f32_e32 v9, v9, v130
	v_mul_f32_e32 v6, v6, v130
	v_mul_f32_e32 v7, v7, v130
	v_mul_f32_e32 v4, v4, v130
	v_mul_f32_e32 v5, v5, v130
	v_mul_f32_e32 v2, v2, v130
	v_mul_f32_e32 v3, v3, v130
	s_branch .LBB0_407

; __device__ __forceinline__ unsigned cvt_pk_bf16(float lo, float hi) { f32x2_t v = {lo, hi}; bf16x2_t b = __builtin_convertvector(v, bf16x2_t); return __builtin_bit_cast(unsigned, b); }
; __device__ __forceinline__ float fast_exp2(float x) { return __builtin_amdgcn_exp2f(x); }
; template <bool MASK> ...
;     ...
;     { const f32x2_t m2 = {m, m}; f32x2_t ps2 = {0.f, 0.f};
; #pragma unroll
;       for (int i = 0; i < 8; ++i) { f32x2_t t = sp[i] - m2; t[0] = fast_exp2(t[0]); t[1] = fast_exp2(t[1]); sp[i] = t; ps2 = ps2 + t; }
;       l += ps2[0] + ps2[1]; }
;     u32x4 pw0, pw1;
;     pw0.x = cvt_pk_bf16(sp[0][0], sp[0][1]); pw0.y = cvt_pk_bf16(sp[1][0], sp[1][1]); pw0.z = cvt_pk_bf16(sp[2][0], sp[2][1]); pw0.w = cvt_pk_bf16(sp[3][0], sp[3][1]);
;     pw1.x = cvt_pk_bf16(sp[4][0], sp[4][1]); pw1.y = cvt_pk_bf16(sp[5][0], sp[5][1]); pw1.z = cvt_pk_bf16(sp[6][0], sp[6][1]); pw1.w = cvt_pk_bf16(sp[7][0], sp[7][1]);
;     asm volatile("s_waitcnt lgkmcnt(0)" : "+v"(l00), "+v"(h00), "+v"(l01), "+v"(h01), "+v"(l10), "+v"(h10), "+v"(l11), "+v"(h11) :: "memory");
;     { const bf16x8 pb0 = __builtin_bit_cast(bf16x8, pw0), pb1 = __builtin_bit_cast(bf16x8, pw1);
;       const bf16x8 v00 = {l00[0], l00[1], l00[2], l00[3], h00[0], h00[1], h00[2], h00[3]}, v01 = {l01[0], l01[1], l01[2], l01[3], h01[0], h01[1], h01[2], h01[3]};
;       const bf16x8 v10 = {l10[0], l10[1], l10[2], l10[3], h10[0], h10[1], h10[2], h10[3]}, v11 = {l11[0], l11[1], l11[2], l11[3], h11[0], h11[1], h11[2], h11[3]};
;       o0 = __builtin_amdgcn_mfma_f32_32x32x16_bf16(v00, pb0, o0, 0, 0, 0); o1 = __builtin_amdgcn_mfma_f32_32x32x16_bf16(v01, pb0, o1, 0, 0, 0);
;       o0 = __builtin_amdgcn_mfma_f32_32x32x16_bf16(v10, pb1, o0, 0, 0, 0); o1 = __builtin_amdgcn_mfma_f32_32x32x16_bf16(v11, pb1, o1, 0, 0, 0); }
.LBB0_407:
	v_sub_f32_e32 v66, v66, v0
	v_sub_f32_e32 v67, v67, v0
	v_sub_f32_e32 v68, v68, v0
	v_sub_f32_e32 v69, v69, v0
	v_exp_f32_e32 v66, v66
	v_exp_f32_e32 v67, v67
	v_sub_f32_e32 v70, v70, v0
	v_sub_f32_e32 v71, v71, v0
	v_sub_f32_e32 v72, v72, v0
	v_sub_f32_e32 v73, v73, v0
	v_exp_f32_e32 v68, v68
	v_exp_f32_e32 v69, v69
	v_exp_f32_e32 v70, v70
	v_exp_f32_e32 v71, v71
	v_exp_f32_e32 v72, v72
	v_exp_f32_e32 v73, v73
	v_add_f32_e32 v130, 0, v66
	v_add_f32_e32 v131, 0, v67
	v_cvt_pk_bf16_f32 v66, v66, v67
	v_add_f32_e32 v130, v68, v130
	v_add_f32_e32 v131, v69, v131
	v_cvt_pk_bf16_f32 v67, v68, v69
	v_cvt_pk_bf16_f32 v68, v70, v71
	v_cvt_pk_bf16_f32 v69, v72, v73
	s_waitcnt lgkmcnt(0)
	v_sub_f32_e32 v74, v74, v0
	v_sub_f32_e32 v75, v75, v0
	v_sub_f32_e32 v76, v76, v0
	v_sub_f32_e32 v77, v77, v0
	v_mfma_f32_32x32x16_bf16 v[18:33], v[94:97], v[66:69], v[18:33]
	v_add_f32_e64 v78, v78, -v0
	v_add_f32_e64 v79, v79, -v0
	v_add_f32_e64 v80, v80, -v0
	v_add_f32_e64 v81, v81, -v0
	v_exp_f32_e32 v74, v74
	v_exp_f32_e32 v75, v75
	v_exp_f32_e32 v76, v76
	v_exp_f32_e32 v77, v77
	v_exp_f32_e32 v78, v78
	v_mfma_f32_32x32x16_bf16 v[2:17], v[90:93], v[66:69], v[2:17]
	v_exp_f32_e32 v79, v79
	v_exp_f32_e32 v80, v80
	v_exp_f32_e32 v81, v81
	v_add_f32_e32 v130, v70, v130
	v_add_f32_e32 v131, v71, v131
	v_cvt_pk_bf16_f32 v70, v74, v75
	v_add_f32_e32 v130, v72, v130
	v_add_f32_e32 v131, v73, v131
	v_cvt_pk_bf16_f32 v71, v76, v77
	v_cvt_pk_bf16_f32 v72, v78, v79
	v_cvt_pk_bf16_f32 v73, v80, v81
	v_add_f32_e32 v130, v74, v130
	v_add_f32_e32 v131, v75, v131
	v_mov_b32_e32 v243, v155
	v_mfma_f32_32x32x16_bf16 v[18:33], v[86:89], v[70:73], v[18:33]
	v_add_f32_e64 v130, v76, v130
	v_add_f32_e64 v131, v77, v131
	v_add_f32_e64 v130, v78, v130
	v_add_f32_e64 v131, v79, v131
	v_add_f32_e64 v130, v80, v130
	v_add_f32_e64 v131, v81, v131
	v_add_f32_e32 v0, v130, v131
	v_mfma_f32_32x32x16_bf16 v[2:17], v[82:85], v[70:73], v[2:17]
	s_nop 3
	v_add_f32_e32 v0, v161, v0
	s_nop 0

; #define LAS __attribute__((address_space(3)))
; template <bool MASK> ...
;     s16x4 l00, h00, l01, h01, l10, h10, l11, h11; { const unsigned a0 = va0 + sub * 4096, a1 = va1 + sub * 4096;
;       asm volatile("ds_read_b64_tr_b16 %0, %1" : "=&v"(l00) : "v"(a0) : "memory"); asm volatile("ds_read_b64_tr_b16 %0, %1 offset:1024" : "=&v"(h00) : "v"(a0) : "memory");
;       asm volatile("ds_read_b64_tr_b16 %0, %1" : "=&v"(l01) : "v"(a1) : "memory"); asm volatile("ds_read_b64_tr_b16 %0, %1 offset:1024" : "=&v"(h01) : "v"(a1) : "memory");
;       asm volatile("ds_read_b64_tr_b16 %0, %1 offset:2048" : "=&v"(l10) : "v"(a0) : "memory"); asm volatile("ds_read_b64_tr_b16 %0, %1 offset:3072" : "=&v"(h10) : "v"(a0) : "memory");
;       asm volatile("ds_read_b64_tr_b16 %0, %1 offset:2048" : "=&v"(l11) : "v"(a1) : "memory"); asm volatile("ds_read_b64_tr_b16 %0, %1 offset:3072" : "=&v"(h11) : "v"(a1) : "memory"); }
;     const int r = lane & 31, hh = lane >> 5;
;     f32x16 st = {0.f, 0.f, 0.f, 0.f, 0.f, 0.f, 0.f, 0.f, 0.f, 0.f, 0.f, 0.f, 0.f, 0.f, 0.f, 0.f};
;     { const int key = sub * 32 + r; const LAS char* kp = Kt + key * 128; const int ksw = (key >> 1) & 7;
; #pragma unroll
;       for (int d0 = 0; d0 < 4; ++d0) { const bf16x8 kf = *(const LAS bf16x8*)(kp + (((2 * d0 + hh) ^ ksw) << 4)); st = __builtin_amdgcn_mfma_f32_32x32x16_bf16(kf, qr[d0], st, 0, 0, 0); } }
;     f32x2_t sp[8]; const f32x2_t cs2 = {cscale, cscale};
; #pragma unroll
;     for (int g = 0; g < 4; ++g) { const f32x4 c4 = *(const LAS f32x4*)(cb + sub * 32 + 8 * g + 4 * hh);
;         sp[2 * g] = (f32x2_t){st[4 * g], st[4 * g + 1]} + cs2 * (f32x2_t){c4[0], c4[1]};
;         sp[2 * g + 1] = (f32x2_t){st[4 * g + 2], st[4 * g + 3]} + cs2 * (f32x2_t){c4[2], c4[3]};
;         if (MASK) {
; #pragma unroll
;             for (int e = 0; e < 4; ++e) { const int kpos = kpos_sub + 8 * g + 4 * hh + e; const bool ok = (kpos <= qpos && kpos >= qpos - win);
;                 sp[2 * g + (e >> 1)][e & 1] = ok ? sp[2 * g + (e >> 1)][e & 1] : -INFINITY; } } }
;     float rm = fmaxf(sp[0][0], sp[0][1]);
; #pragma unroll
;     for (int i = 1; i < 8; ++i) rm = fmaxf(fmaxf(rm, sp[i][0]), sp[i][1]);
;     rm = swap_max(rm);
;     if (__any(rm - m > 8.0f)) { const float mnew = fmaxf(m, rm); const float f = fast_exp2(m - mnew); l *= f; o0 = o0 * f; o1 = o1 * f; m = mnew; }
.LBB0_409:
	s_or_b32 s5, s4, 32
	s_cmp_gt_i32 s5, s33
	s_cselect_b64 s[16:17], -1, 0
	s_or_b32 s4, s4, 63
	s_cmp_lt_i32 s4, s66
	s_cselect_b64 s[18:19], -1, 0
	s_or_b64 s[16:17], s[16:17], s[18:19]
	s_and_b64 vcc, exec, s[16:17]
	v_add_u32_e32 v243, 0x1000, v216
	v_add_u32_e32 v216, 0x1000, v217
	s_cbranch_vccnz .LBB0_421
	s_cmp_gt_i32 s4, s35
	s_cselect_b64 s[16:17], -1, 0
	s_cmp_lt_i32 s5, s11
	s_cselect_b64 s[18:19], -1, 0
	s_or_b64 s[16:17], s[16:17], s[18:19]
	s_mov_b64 s[18:19], -1
	s_and_b64 vcc, exec, s[16:17]
	s_cbranch_vccnz .LBB0_415
	ds_read_b64_tr_b16 v[142:143], v243
	ds_read_b64_tr_b16 v[144:145], v243 offset:1024
	ds_read_b64_tr_b16 v[138:139], v216
	ds_read_b64_tr_b16 v[140:141], v216 offset:1024
	ds_read_b64_tr_b16 v[134:135], v243 offset:2048
	ds_read_b64_tr_b16 v[136:137], v243 offset:3072
	ds_read_b64_tr_b16 v[130:131], v216 offset:2048
	ds_read_b64_tr_b16 v[132:133], v216 offset:3072
	ds_read_b128 v[66:69], v215 offset:4096
	ds_read_b128 v[82:85], v214 offset:4096
	ds_read_b128 v[86:89], v213 offset:4096
	ds_read_b128 v[90:93], v212 offset:4096
	v_add_u32_e32 v0, s1, v197
	s_waitcnt lgkmcnt(2)
	v_mfma_f32_32x32x16_bf16 v[66:81], v[66:69], v[106:109], 0
	v_mfma_f32_32x32x16_bf16 v[66:81], v[82:85], v[98:101], v[66:81]
	s_waitcnt lgkmcnt(1)
	v_mfma_f32_32x32x16_bf16 v[66:81], v[86:89], v[102:105], v[66:81]
	s_waitcnt lgkmcnt(0)
	v_mfma_f32_32x32x16_bf16 v[66:81], v[90:93], v[110:113], v[66:81]
	ds_read_b128 v[82:85], v0 offset:49280
	ds_read_b128 v[86:89], v0 offset:49312
	ds_read_b128 v[90:93], v0 offset:49344
	ds_read_b128 v[94:97], v0 offset:49376
	s_waitcnt lgkmcnt(0)
	s_nop 8
	v_fma_f32 v178, v158, v82, v66
	v_fma_f32 v179, v159, v83, v67
	v_fma_f32 v176, v158, v84, v68
	v_fma_f32 v177, v159, v85, v69
	v_fma_f32 v170, v158, v86, v70
	v_fma_f32 v171, v159, v87, v71
	v_fma_f32 v168, v158, v88, v72
	v_fma_f32 v169, v159, v89, v73
	v_fma_f32 v174, v158, v90, v74
	v_fma_f32 v175, v159, v91, v75
	v_fma_f32 v172, v158, v92, v76
	v_fma_f32 v173, v159, v93, v77
	v_max_f32_e32 v0, v178, v179
	v_max3_f32 v0, v0, v176, v177
	v_max3_f32 v0, v0, v170, v171
	v_max3_f32 v0, v0, v168, v169
	v_max3_f32 v0, v0, v174, v175
	v_fma_f32 v180, v158, v94, v78
	v_fma_f32 v181, v159, v95, v79
	v_max3_f32 v0, v0, v172, v173
	v_fma_f32 v182, v158, v96, v80
	v_fma_f32 v183, v159, v97, v81
	v_max3_f32 v0, v0, v180, v181
	v_max3_f32 v0, v0, v182, v183
	v_mov_b32_e32 v66, v0
	s_nop 1
	v_permlane32_swap_b32_e32 v0, v66
	v_max_f32_e32 v66, v66, v66
	v_max_f32_e32 v0, v0, v0
	v_max_f32_e32 v0, v0, v66
	v_sub_f32_e32 v66, v0, v210
	v_cmp_lt_f32_e32 vcc, s9, v66
	s_cbranch_vccz .LBB0_413
	v_max_f32_e32 v0, v0, v0
	v_max_f32_e32 v66, v210, v210
	v_max_f32_e32 v217, v66, v0
	v_sub_f32_e32 v0, v210, v217
	v_exp_f32_e32 v0, v0
	s_nop 0
	v_mul_f32_e32 v244, v211, v0
	v_mul_f32_e32 v64, v64, v0
	v_mul_f32_e32 v65, v65, v0
	v_mul_f32_e32 v62, v62, v0
	v_mul_f32_e32 v63, v63, v0
	v_mul_f32_e32 v60, v60, v0
	v_mul_f32_e32 v61, v61, v0
	v_mul_f32_e32 v58, v58, v0
	v_mul_f32_e32 v59, v59, v0
	v_mul_f32_e32 v56, v56, v0
	v_mul_f32_e32 v57, v57, v0
	v_mul_f32_e32 v54, v54, v0
	v_mul_f32_e32 v55, v55, v0
	v_mul_f32_e32 v52, v52, v0
	v_mul_f32_e32 v53, v53, v0
	v_mul_f32_e32 v50, v50, v0
	v_mul_f32_e32 v51, v51, v0
	v_mul_f32_e32 v48, v48, v0
	v_mul_f32_e32 v49, v49, v0
	v_mul_f32_e32 v46, v46, v0
	v_mul_f32_e32 v47, v47, v0
	v_mul_f32_e32 v44, v44, v0
	v_mul_f32_e32 v45, v45, v0
	v_mul_f32_e32 v42, v42, v0
	v_mul_f32_e32 v43, v43, v0
	v_mul_f32_e32 v40, v40, v0
	v_mul_f32_e32 v41, v41, v0
	v_mul_f32_e32 v38, v38, v0
	v_mul_f32_e32 v39, v39, v0
	v_mul_f32_e32 v36, v36, v0
	v_mul_f32_e32 v37, v37, v0
	v_mul_f32_e32 v34, v34, v0
	v_mul_f32_e32 v35, v35, v0
	v_mov_b32_e32 v0, v217
	s_branch .LBB0_414

; #define LAS __attribute__((address_space(3)))
; template <bool MASK> ...
;     s16x4 l00, h00, l01, h01, l10, h10, l11, h11; { const unsigned a0 = va0 + sub * 4096, a1 = va1 + sub * 4096;
;       asm volatile("ds_read_b64_tr_b16 %0, %1" : "=&v"(l00) : "v"(a0) : "memory"); asm volatile("ds_read_b64_tr_b16 %0, %1 offset:1024" : "=&v"(h00) : "v"(a0) : "memory");
;       asm volatile("ds_read_b64_tr_b16 %0, %1" : "=&v"(l01) : "v"(a1) : "memory"); asm volatile("ds_read_b64_tr_b16 %0, %1 offset:1024" : "=&v"(h01) : "v"(a1) : "memory");
;       asm volatile("ds_read_b64_tr_b16 %0, %1 offset:2048" : "=&v"(l10) : "v"(a0) : "memory"); asm volatile("ds_read_b64_tr_b16 %0, %1 offset:3072" : "=&v"(h10) : "v"(a0) : "memory");
;       asm volatile("ds_read_b64_tr_b16 %0, %1 offset:2048" : "=&v"(l11) : "v"(a1) : "memory"); asm volatile("ds_read_b64_tr_b16 %0, %1 offset:3072" : "=&v"(h11) : "v"(a1) : "memory"); }
;     const int r = lane & 31, hh = lane >> 5;
;     f32x16 st = {0.f, 0.f, 0.f, 0.f, 0.f, 0.f, 0.f, 0.f, 0.f, 0.f, 0.f, 0.f, 0.f, 0.f, 0.f, 0.f};
;     { const int key = sub * 32 + r; const LAS char* kp = Kt + key * 128; const int ksw = (key >> 1) & 7;
; #pragma unroll
;       for (int d0 = 0; d0 < 4; ++d0) { const bf16x8 kf = *(const LAS bf16x8*)(kp + (((2 * d0 + hh) ^ ksw) << 4)); st = __builtin_amdgcn_mfma_f32_32x32x16_bf16(kf, qr[d0], st, 0, 0, 0); } }
;     f32x2_t sp[8]; const f32x2_t cs2 = {cscale, cscale};
; #pragma unroll
;     for (int g = 0; g < 4; ++g) { const f32x4 c4 = *(const LAS f32x4*)(cb + sub * 32 + 8 * g + 4 * hh);
;         sp[2 * g] = (f32x2_t){st[4 * g], st[4 * g + 1]} + cs2 * (f32x2_t){c4[0], c4[1]};
;         sp[2 * g + 1] = (f32x2_t){st[4 * g + 2], st[4 * g + 3]} + cs2 * (f32x2_t){c4[2], c4[3]};
;         if (MASK) {
; #pragma unroll
;             for (int e = 0; e < 4; ++e) { const int kpos = kpos_sub + 8 * g + 4 * hh + e; const bool ok = (kpos <= qpos && kpos >= qpos - win);
;                 sp[2 * g + (e >> 1)][e & 1] = ok ? sp[2 * g + (e >> 1)][e & 1] : -INFINITY; } } }
;     float rm = fmaxf(sp[0][0], sp[0][1]);
; #pragma unroll
;     for (int i = 1; i < 8; ++i) rm = fmaxf(fmaxf(rm, sp[i][0]), sp[i][1]);
;     rm = swap_max(rm);
;     if (__any(rm - m > 8.0f)) { const float mnew = fmaxf(m, rm); const float f = fast_exp2(m - mnew); l *= f; o0 = o0 * f; o1 = o1 * f; m = mnew; }
.LBB0_415:
	s_and_b64 vcc, exec, s[18:19]
	s_cbranch_vccz .LBB0_420
	ds_read_b64_tr_b16 v[94:95], v243
	ds_read_b64_tr_b16 v[96:97], v243 offset:1024
	ds_read_b64_tr_b16 v[90:91], v216
	ds_read_b64_tr_b16 v[92:93], v216 offset:1024
	ds_read_b64_tr_b16 v[86:87], v243 offset:2048
	ds_read_b64_tr_b16 v[88:89], v243 offset:3072
	ds_read_b64_tr_b16 v[82:83], v216 offset:2048
	ds_read_b64_tr_b16 v[84:85], v216 offset:3072
	s_nop 8
	ds_read_b128 v[66:69], v215 offset:4096
	ds_read_b128 v[130:133], v214 offset:4096
	v_add_u32_e32 v138, s1, v197
	v_or_b32_e32 v0, s5, v150
	v_cmp_le_i32_e32 vcc, v0, v160
	v_cmp_ge_i32_e64 s[44:45], v0, v208
	s_and_b64 vcc, vcc, s[44:45]
	s_waitcnt lgkmcnt(0)
	v_mfma_f32_32x32x16_bf16 v[66:81], v[66:69], v[106:109], 0
	v_mfma_f32_32x32x16_bf16 v[66:81], v[130:133], v[98:101], v[66:81]
	ds_read_b128 v[130:133], v213 offset:4096
	s_waitcnt lgkmcnt(0)
	v_mfma_f32_32x32x16_bf16 v[66:81], v[130:133], v[102:105], v[66:81]
	ds_read_b128 v[130:133], v212 offset:4096
	s_waitcnt lgkmcnt(0)
	v_mfma_f32_32x32x16_bf16 v[66:81], v[130:133], v[110:113], v[66:81]
	ds_read_b128 v[130:133], v138 offset:49280
	ds_read_b128 v[134:137], v138 offset:49312
	s_waitcnt lgkmcnt(0)
	s_nop 8
	v_fma_f32 v66, v158, v130, v66
	v_fma_f32 v67, v159, v131, v67
	v_or_b32_e32 v130, 1, v0
	v_cndmask_b32_e32 v66, v240, v66, vcc
	v_cmp_lt_i32_e32 vcc, v0, v160
	v_cmp_ge_i32_e64 s[44:45], v130, v208
	s_and_b64 vcc, vcc, s[44:45]
	v_or_b32_e32 v130, 2, v0
	v_cndmask_b32_e32 v67, v240, v67, vcc
	v_cmp_le_i32_e32 vcc, v130, v160
	v_cmp_ge_i32_e64 s[44:45], v130, v208
	v_fma_f32 v68, v158, v132, v68
	v_fma_f32 v69, v159, v133, v69
	s_and_b64 vcc, vcc, s[44:45]
	v_or_b32_e32 v130, 3, v0
	v_cndmask_b32_e32 v68, v240, v68, vcc
	v_cmp_le_i32_e32 vcc, v130, v160
	v_cmp_ge_i32_e64 s[44:45], v130, v208
	s_and_b64 vcc, vcc, s[44:45]
	v_or_b32_e32 v130, 8, v0
	v_cndmask_b32_e32 v69, v240, v69, vcc
	v_cmp_le_i32_e32 vcc, v130, v160
	v_cmp_ge_i32_e64 s[44:45], v130, v208
	v_fma_f32 v70, v158, v134, v70
	v_fma_f32 v71, v159, v135, v71
	s_and_b64 vcc, vcc, s[44:45]
	v_or_b32_e32 v130, 9, v0
	v_cndmask_b32_e32 v70, v240, v70, vcc
	v_cmp_le_i32_e32 vcc, v130, v160
	v_cmp_ge_i32_e64 s[44:45], v130, v208
	s_and_b64 vcc, vcc, s[44:45]
	v_or_b32_e32 v130, 10, v0
	v_cndmask_b32_e32 v71, v240, v71, vcc
	v_cmp_le_i32_e32 vcc, v130, v160
	v_cmp_ge_i32_e64 s[44:45], v130, v208
	v_fma_f32 v72, v158, v136, v72
	v_fma_f32 v73, v159, v137, v73
	s_and_b64 vcc, vcc, s[44:45]
	v_or_b32_e32 v130, 11, v0
	v_cndmask_b32_e32 v72, v240, v72, vcc
	v_cmp_le_i32_e32 vcc, v130, v160
	v_cmp_ge_i32_e64 s[44:45], v130, v208
	ds_read_b128 v[130:133], v138 offset:49344
	s_and_b64 vcc, vcc, s[44:45]
	v_cndmask_b32_e32 v73, v240, v73, vcc
	s_waitcnt lgkmcnt(0)
	v_fma_f32 v74, v158, v130, v74
	v_fma_f32 v75, v159, v131, v75
	v_or_b32_e32 v130, 16, v0
	v_cmp_le_i32_e32 vcc, v130, v160
	v_cmp_ge_i32_e64 s[44:45], v130, v208
	s_and_b64 vcc, vcc, s[44:45]
	v_or_b32_e32 v130, 17, v0
	v_cndmask_b32_e32 v74, v240, v74, vcc
	v_cmp_le_i32_e32 vcc, v130, v160
	v_cmp_ge_i32_e64 s[44:45], v130, v208
	s_and_b64 vcc, vcc, s[44:45]
	v_or_b32_e32 v130, 18, v0
	v_cndmask_b32_e32 v75, v240, v75, vcc
	v_cmp_le_i32_e32 vcc, v130, v160
	v_cmp_ge_i32_e64 s[44:45], v130, v208
	v_fma_f32 v76, v158, v132, v76
	v_fma_f32 v77, v159, v133, v77
	s_and_b64 vcc, vcc, s[44:45]
	v_or_b32_e32 v130, 19, v0
	v_cndmask_b32_e32 v76, v240, v76, vcc
	v_cmp_le_i32_e32 vcc, v130, v160
	v_cmp_ge_i32_e64 s[44:45], v130, v208
	ds_read_b128 v[130:133], v138 offset:49376
	s_and_b64 vcc, vcc, s[44:45]
	v_cndmask_b32_e32 v77, v240, v77, vcc
	s_waitcnt lgkmcnt(0)
	v_fma_f32 v78, v158, v130, v78
	v_fma_f32 v79, v159, v131, v79
	v_or_b32_e32 v130, 24, v0
	v_cmp_le_i32_e32 vcc, v130, v160
	v_cmp_ge_i32_e64 s[44:45], v130, v208
	s_and_b64 vcc, vcc, s[44:45]
	v_or_b32_e32 v130, 25, v0
	v_cndmask_b32_e32 v78, v240, v78, vcc
	v_cmp_le_i32_e32 vcc, v130, v160
	v_cmp_ge_i32_e64 s[44:45], v130, v208
	s_and_b64 vcc, vcc, s[44:45]
	v_or_b32_e32 v130, 26, v0
	v_cndmask_b32_e32 v79, v240, v79, vcc
	v_cmp_le_i32_e32 vcc, v130, v160
	v_cmp_ge_i32_e64 s[44:45], v130, v208
	v_fma_f32 v80, v158, v132, v80
	v_fma_f32 v81, v159, v133, v81
	s_and_b64 vcc, vcc, s[44:45]
	v_or_b32_e32 v0, 27, v0
	v_cndmask_b32_e32 v80, v240, v80, vcc
	v_cmp_le_i32_e32 vcc, v0, v160
	v_cmp_ge_i32_e64 s[44:45], v0, v208
	v_max_f32_e32 v0, v66, v67
	v_max3_f32 v0, v0, v68, v69
	v_max3_f32 v0, v0, v70, v71
	v_max3_f32 v0, v0, v72, v73
	v_max3_f32 v0, v0, v74, v75
	s_and_b64 vcc, vcc, s[44:45]
	v_max3_f32 v0, v0, v76, v77
	v_cndmask_b32_e32 v81, v240, v81, vcc
	v_max3_f32 v0, v0, v78, v79
	v_max3_f32 v0, v0, v80, v81
	v_mov_b32_e32 v130, v0
	s_nop 1
	v_permlane32_swap_b32_e32 v0, v130
	v_max_f32_e32 v130, v130, v130
	v_max_f32_e32 v0, v0, v0
	v_max_f32_e32 v0, v0, v130
	v_sub_f32_e32 v130, v0, v210
	v_cmp_lt_f32_e32 vcc, s9, v130
	s_cbranch_vccz .LBB0_418
	v_max_f32_e32 v0, v0, v0
	v_max_f32_e32 v130, v210, v210
	v_max_f32_e32 v0, v130, v0
	v_sub_f32_e32 v130, v210, v0
	v_exp_f32_e32 v130, v130
	v_mov_b32_e32 v210, v0
	v_mul_f32_e32 v211, v211, v130
	v_mul_f32_e32 v64, v64, v130
	v_mul_f32_e32 v65, v65, v130
	v_mul_f32_e32 v62, v62, v130
	v_mul_f32_e32 v63, v63, v130
	v_mul_f32_e32 v60, v60, v130
	v_mul_f32_e32 v61, v61, v130
	v_mul_f32_e32 v58, v58, v130
	v_mul_f32_e32 v59, v59, v130
	v_mul_f32_e32 v56, v56, v130
	v_mul_f32_e32 v57, v57, v130
	v_mul_f32_e32 v54, v54, v130
	v_mul_f32_e32 v55, v55, v130
	v_mul_f32_e32 v52, v52, v130
	v_mul_f32_e32 v53, v53, v130
	v_mul_f32_e32 v50, v50, v130
	v_mul_f32_e32 v51, v51, v130
	v_mul_f32_e32 v48, v48, v130
	v_mul_f32_e32 v49, v49, v130
	v_mul_f32_e32 v46, v46, v130
	v_mul_f32_e32 v47, v47, v130
	v_mul_f32_e32 v44, v44, v130
	v_mul_f32_e32 v45, v45, v130
	v_mul_f32_e32 v42, v42, v130
	v_mul_f32_e32 v43, v43, v130
	v_mul_f32_e32 v40, v40, v130
	v_mul_f32_e32 v41, v41, v130
	v_mul_f32_e32 v38, v38, v130
	v_mul_f32_e32 v39, v39, v130
	v_mul_f32_e32 v36, v36, v130
	v_mul_f32_e32 v37, v37, v130
	v_mul_f32_e32 v34, v34, v130
	v_mul_f32_e32 v35, v35, v130
	s_branch .LBB0_419

; __device__ __forceinline__ unsigned cvt_pk_bf16(float lo, float hi) { f32x2_t v = {lo, hi}; bf16x2_t b = __builtin_convertvector(v, bf16x2_t); return __builtin_bit_cast(unsigned, b); }
; __device__ __forceinline__ float fast_exp2(float x) { return __builtin_amdgcn_exp2f(x); }
; template <bool MASK> ...
;     ...
;     { const f32x2_t m2 = {m, m}; f32x2_t ps2 = {0.f, 0.f};
; #pragma unroll
;       for (int i = 0; i < 8; ++i) { f32x2_t t = sp[i] - m2; t[0] = fast_exp2(t[0]); t[1] = fast_exp2(t[1]); sp[i] = t; ps2 = ps2 + t; }
;       l += ps2[0] + ps2[1]; }
;     u32x4 pw0, pw1;
;     pw0.x = cvt_pk_bf16(sp[0][0], sp[0][1]); pw0.y = cvt_pk_bf16(sp[1][0], sp[1][1]); pw0.z = cvt_pk_bf16(sp[2][0], sp[2][1]); pw0.w = cvt_pk_bf16(sp[3][0], sp[3][1]);
;     pw1.x = cvt_pk_bf16(sp[4][0], sp[4][1]); pw1.y = cvt_pk_bf16(sp[5][0], sp[5][1]); pw1.z = cvt_pk_bf16(sp[6][0], sp[6][1]); pw1.w = cvt_pk_bf16(sp[7][0], sp[7][1]);
;     asm volatile("s_waitcnt lgkmcnt(0)" : "+v"(l00), "+v"(h00), "+v"(l01), "+v"(h01), "+v"(l10), "+v"(h10), "+v"(l11), "+v"(h11) :: "memory");
;     { const bf16x8 pb0 = __builtin_bit_cast(bf16x8, pw0), pb1 = __builtin_bit_cast(bf16x8, pw1);
;       const bf16x8 v00 = {l00[0], l00[1], l00[2], l00[3], h00[0], h00[1], h00[2], h00[3]}, v01 = {l01[0], l01[1], l01[2], l01[3], h01[0], h01[1], h01[2], h01[3]};
;       const bf16x8 v10 = {l10[0], l10[1], l10[2], l10[3], h10[0], h10[1], h10[2], h10[3]}, v11 = {l11[0], l11[1], l11[2], l11[3], h11[0], h11[1], h11[2], h11[3]};
;       o0 = __builtin_amdgcn_mfma_f32_32x32x16_bf16(v00, pb0, o0, 0, 0, 0); o1 = __builtin_amdgcn_mfma_f32_32x32x16_bf16(v01, pb0, o1, 0, 0, 0);
;       o0 = __builtin_amdgcn_mfma_f32_32x32x16_bf16(v10, pb1, o0, 0, 0, 0); o1 = __builtin_amdgcn_mfma_f32_32x32x16_bf16(v11, pb1, o1, 0, 0, 0); }
.LBB0_419:
	v_sub_f32_e32 v66, v66, v0
	v_sub_f32_e32 v67, v67, v0
	v_sub_f32_e32 v68, v68, v0
	v_sub_f32_e32 v69, v69, v0
	v_exp_f32_e32 v66, v66
	v_exp_f32_e32 v67, v67
	v_sub_f32_e32 v70, v70, v0
	v_sub_f32_e32 v71, v71, v0
	v_sub_f32_e32 v72, v72, v0
	v_sub_f32_e32 v73, v73, v0
	v_exp_f32_e32 v68, v68
	v_exp_f32_e32 v69, v69
	v_exp_f32_e32 v70, v70
	v_exp_f32_e32 v71, v71
	v_exp_f32_e32 v72, v72
	v_exp_f32_e32 v73, v73
	v_add_f32_e32 v130, 0, v66
	v_add_f32_e32 v131, 0, v67
	v_cvt_pk_bf16_f32 v66, v66, v67
	v_add_f32_e32 v130, v68, v130
	v_add_f32_e32 v131, v69, v131
	v_cvt_pk_bf16_f32 v67, v68, v69
	v_cvt_pk_bf16_f32 v68, v70, v71
	v_cvt_pk_bf16_f32 v69, v72, v73
	s_waitcnt lgkmcnt(0)
	v_sub_f32_e32 v74, v74, v0
	v_sub_f32_e32 v75, v75, v0
	v_sub_f32_e32 v76, v76, v0
	v_sub_f32_e32 v77, v77, v0
	v_mfma_f32_32x32x16_bf16 v[50:65], v[94:97], v[66:69], v[50:65]
	v_add_f32_e64 v78, v78, -v0
	v_add_f32_e64 v79, v79, -v0
	v_add_f32_e64 v80, v80, -v0
	v_add_f32_e64 v81, v81, -v0
	v_exp_f32_e32 v74, v74
	v_exp_f32_e32 v75, v75
	v_exp_f32_e32 v76, v76
	v_exp_f32_e32 v77, v77
	v_exp_f32_e32 v78, v78
	v_mfma_f32_32x32x16_bf16 v[34:49], v[90:93], v[66:69], v[34:49]
	v_exp_f32_e32 v79, v79
	v_exp_f32_e32 v80, v80
	v_exp_f32_e32 v81, v81
	v_add_f32_e32 v130, v70, v130
	v_add_f32_e32 v131, v71, v131
	v_cvt_pk_bf16_f32 v70, v74, v75
	v_add_f32_e32 v130, v72, v130
	v_add_f32_e32 v131, v73, v131
	v_cvt_pk_bf16_f32 v71, v76, v77
	v_cvt_pk_bf16_f32 v72, v78, v79
	v_cvt_pk_bf16_f32 v73, v80, v81
	v_add_f32_e32 v130, v74, v130
	v_add_f32_e32 v131, v75, v131
	v_mov_b32_e32 v217, v210
	v_mfma_f32_32x32x16_bf16 v[50:65], v[86:89], v[70:73], v[50:65]
	v_add_f32_e64 v130, v76, v130
	v_add_f32_e64 v131, v77, v131
	v_add_f32_e64 v130, v78, v130
	v_add_f32_e64 v131, v79, v131
	v_add_f32_e64 v130, v80, v130
	v_add_f32_e64 v131, v81, v131
	v_add_f32_e32 v0, v130, v131
	v_mfma_f32_32x32x16_bf16 v[34:49], v[82:85], v[70:73], v[34:49]
	s_nop 3
	v_add_f32_e32 v0, v211, v0
	s_nop 0

; #define LAS __attribute__((address_space(3)))
; template <bool MASK> ...
;     s16x4 l00, h00, l01, h01, l10, h10, l11, h11; { const unsigned a0 = va0 + sub * 4096, a1 = va1 + sub * 4096;
;       asm volatile("ds_read_b64_tr_b16 %0, %1" : "=&v"(l00) : "v"(a0) : "memory"); asm volatile("ds_read_b64_tr_b16 %0, %1 offset:1024" : "=&v"(h00) : "v"(a0) : "memory");
;       asm volatile("ds_read_b64_tr_b16 %0, %1" : "=&v"(l01) : "v"(a1) : "memory"); asm volatile("ds_read_b64_tr_b16 %0, %1 offset:1024" : "=&v"(h01) : "v"(a1) : "memory");
;       asm volatile("ds_read_b64_tr_b16 %0, %1 offset:2048" : "=&v"(l10) : "v"(a0) : "memory"); asm volatile("ds_read_b64_tr_b16 %0, %1 offset:3072" : "=&v"(h10) : "v"(a0) : "memory");
;       asm volatile("ds_read_b64_tr_b16 %0, %1 offset:2048" : "=&v"(l11) : "v"(a1) : "memory"); asm volatile("ds_read_b64_tr_b16 %0, %1 offset:3072" : "=&v"(h11) : "v"(a1) : "memory"); }
;     const int r = lane & 31, hh = lane >> 5;
;     f32x16 st = {0.f, 0.f, 0.f, 0.f, 0.f, 0.f, 0.f, 0.f, 0.f, 0.f, 0.f, 0.f, 0.f, 0.f, 0.f, 0.f};
;     { const int key = sub * 32 + r; const LAS char* kp = Kt + key * 128; const int ksw = (key >> 1) & 7;
; #pragma unroll
;       for (int d0 = 0; d0 < 4; ++d0) { const bf16x8 kf = *(const LAS bf16x8*)(kp + (((2 * d0 + hh) ^ ksw) << 4)); st = __builtin_amdgcn_mfma_f32_32x32x16_bf16(kf, qr[d0], st, 0, 0, 0); } }
;     f32x2_t sp[8]; const f32x2_t cs2 = {cscale, cscale};
; #pragma unroll
;     for (int g = 0; g < 4; ++g) { const f32x4 c4 = *(const LAS f32x4*)(cb + sub * 32 + 8 * g + 4 * hh);
;         sp[2 * g] = (f32x2_t){st[4 * g], st[4 * g + 1]} + cs2 * (f32x2_t){c4[0], c4[1]};
;         sp[2 * g + 1] = (f32x2_t){st[4 * g + 2], st[4 * g + 3]} + cs2 * (f32x2_t){c4[2], c4[3]};
;         if (MASK) {
; #pragma unroll
;             for (int e = 0; e < 4; ++e) { const int kpos = kpos_sub + 8 * g + 4 * hh + e; const bool ok = (kpos <= qpos && kpos >= qpos - win);
;                 sp[2 * g + (e >> 1)][e & 1] = ok ? sp[2 * g + (e >> 1)][e & 1] : -INFINITY; } } }
;     float rm = fmaxf(sp[0][0], sp[0][1]);
; #pragma unroll
;     for (int i = 1; i < 8; ++i) rm = fmaxf(fmaxf(rm, sp[i][0]), sp[i][1]);
;     rm = swap_max(rm);
;     if (__any(rm - m > 8.0f)) { const float mnew = fmaxf(m, rm); const float f = fast_exp2(m - mnew); l *= f; o0 = o0 * f; o1 = o1 * f; m = mnew; }
.LBB0_421:
	s_cmp_gt_i32 s5, s3
	s_cselect_b64 s[16:17], -1, 0
	s_cmp_lt_i32 s4, s22
	s_cselect_b64 s[18:19], -1, 0
	s_or_b64 s[16:17], s[16:17], s[18:19]
	s_and_b64 vcc, exec, s[16:17]
	s_cbranch_vccnz .LBB0_433
	s_cmp_gt_i32 s5, s12
	s_cselect_b64 s[16:17], -1, 0
	s_cmp_lt_i32 s5, s13
	s_cselect_b64 s[18:19], -1, 0
	s_or_b64 s[16:17], s[16:17], s[18:19]
	s_mov_b64 s[18:19], -1
	s_and_b64 vcc, exec, s[16:17]
	v_add_u32_e32 v217, s1, v197
	s_cbranch_vccnz .LBB0_427
	ds_read_b64_tr_b16 v[142:143], v243
	ds_read_b64_tr_b16 v[144:145], v243 offset:1024
	ds_read_b64_tr_b16 v[138:139], v216
	ds_read_b64_tr_b16 v[140:141], v216 offset:1024
	ds_read_b64_tr_b16 v[134:135], v243 offset:2048
	ds_read_b64_tr_b16 v[136:137], v243 offset:3072
	ds_read_b64_tr_b16 v[130:131], v216 offset:2048
	ds_read_b64_tr_b16 v[132:133], v216 offset:3072
	ds_read_b128 v[66:69], v215 offset:4096
	ds_read_b128 v[82:85], v214 offset:4096
	ds_read_b128 v[86:89], v213 offset:4096
	ds_read_b128 v[90:93], v212 offset:4096
	s_waitcnt lgkmcnt(2)
	v_mfma_f32_32x32x16_bf16 v[66:81], v[66:69], v[122:125], 0
	v_mfma_f32_32x32x16_bf16 v[66:81], v[82:85], v[114:117], v[66:81]
	s_waitcnt lgkmcnt(1)
	v_mfma_f32_32x32x16_bf16 v[66:81], v[86:89], v[118:121], v[66:81]
	s_waitcnt lgkmcnt(0)
	v_mfma_f32_32x32x16_bf16 v[66:81], v[90:93], v[126:129], v[66:81]
	ds_read_b128 v[82:85], v217 offset:49280
	ds_read_b128 v[86:89], v217 offset:49312
	ds_read_b128 v[90:93], v217 offset:49344
	ds_read_b128 v[94:97], v217 offset:49376
	s_waitcnt lgkmcnt(0)
	s_nop 8
	v_fma_f32 v178, v158, v82, v66
	v_fma_f32 v179, v159, v83, v67
	v_fma_f32 v176, v158, v84, v68
	v_fma_f32 v177, v159, v85, v69
	v_max_f32_e32 v0, v178, v179
	v_fma_f32 v170, v158, v86, v70
	v_fma_f32 v171, v159, v87, v71
	v_max3_f32 v0, v0, v176, v177
	v_fma_f32 v168, v158, v88, v72
	v_fma_f32 v169, v159, v89, v73
	v_fma_f32 v174, v158, v90, v74
	v_fma_f32 v175, v159, v91, v75
	v_fma_f32 v172, v158, v92, v76
	v_fma_f32 v173, v159, v93, v77
	v_max3_f32 v0, v0, v170, v171
	v_max3_f32 v0, v0, v168, v169
	v_max3_f32 v0, v0, v174, v175
	v_max3_f32 v0, v0, v172, v173
	v_fma_f32 v180, v158, v94, v78
	v_fma_f32 v181, v159, v95, v79
	v_fma_f32 v182, v158, v96, v80
	v_fma_f32 v183, v159, v97, v81
	v_max3_f32 v0, v0, v180, v181
	v_max3_f32 v0, v0, v182, v183
	v_mov_b32_e32 v66, v0
	s_nop 1
	v_permlane32_swap_b32_e32 v0, v66
	v_max_f32_e32 v66, v66, v66
	v_max_f32_e32 v0, v0, v0
	v_max_f32_e32 v0, v0, v66
	v_sub_f32_e32 v66, v0, v155
	v_cmp_lt_f32_e32 vcc, s9, v66
	s_cbranch_vccz .LBB0_425
	v_max_f32_e32 v0, v0, v0
	v_max_f32_e32 v66, v155, v155
	v_max_f32_e32 v244, v66, v0
	v_sub_f32_e32 v0, v155, v244
	v_exp_f32_e32 v0, v0
	s_nop 0
	v_mul_f32_e32 v245, v161, v0
	v_mul_f32_e32 v32, v32, v0
	v_mul_f32_e32 v33, v33, v0
	v_mul_f32_e32 v30, v30, v0
	v_mul_f32_e32 v31, v31, v0
	v_mul_f32_e32 v28, v28, v0
	v_mul_f32_e32 v29, v29, v0
	v_mul_f32_e32 v26, v26, v0
	v_mul_f32_e32 v27, v27, v0
	v_mul_f32_e32 v24, v24, v0
	v_mul_f32_e32 v25, v25, v0
	v_mul_f32_e32 v22, v22, v0
	v_mul_f32_e32 v23, v23, v0
	v_mul_f32_e32 v20, v20, v0
	v_mul_f32_e32 v21, v21, v0
	v_mul_f32_e32 v18, v18, v0
	v_mul_f32_e32 v19, v19, v0
	v_mul_f32_e32 v16, v16, v0
	v_mul_f32_e32 v17, v17, v0
	v_mul_f32_e32 v14, v14, v0
	v_mul_f32_e32 v15, v15, v0
	v_mul_f32_e32 v12, v12, v0
	v_mul_f32_e32 v13, v13, v0
	v_mul_f32_e32 v10, v10, v0
	v_mul_f32_e32 v11, v11, v0
	v_mul_f32_e32 v8, v8, v0
	v_mul_f32_e32 v9, v9, v0
	v_mul_f32_e32 v6, v6, v0
	v_mul_f32_e32 v7, v7, v0
	v_mul_f32_e32 v4, v4, v0
	v_mul_f32_e32 v5, v5, v0
	v_mul_f32_e32 v2, v2, v0
	v_mul_f32_e32 v3, v3, v0
	v_mov_b32_e32 v0, v244
	s_branch .LBB0_426

; __device__ __forceinline__ unsigned cvt_pk_bf16(float lo, float hi) { f32x2_t v = {lo, hi}; bf16x2_t b = __builtin_convertvector(v, bf16x2_t); return __builtin_bit_cast(unsigned, b); }
; __device__ __forceinline__ float fast_exp2(float x) { return __builtin_amdgcn_exp2f(x); }
; template <bool MASK> ...
;     ...
;     { const f32x2_t m2 = {m, m}; f32x2_t ps2 = {0.f, 0.f};
; #pragma unroll
;       for (int i = 0; i < 8; ++i) { f32x2_t t = sp[i] - m2; t[0] = fast_exp2(t[0]); t[1] = fast_exp2(t[1]); sp[i] = t; ps2 = ps2 + t; }
;       l += ps2[0] + ps2[1]; }
;     u32x4 pw0, pw1;
;     pw0.x = cvt_pk_bf16(sp[0][0], sp[0][1]); pw0.y = cvt_pk_bf16(sp[1][0], sp[1][1]); pw0.z = cvt_pk_bf16(sp[2][0], sp[2][1]); pw0.w = cvt_pk_bf16(sp[3][0], sp[3][1]);
;     pw1.x = cvt_pk_bf16(sp[4][0], sp[4][1]); pw1.y = cvt_pk_bf16(sp[5][0], sp[5][1]); pw1.z = cvt_pk_bf16(sp[6][0], sp[6][1]); pw1.w = cvt_pk_bf16(sp[7][0], sp[7][1]);
;     asm volatile("s_waitcnt lgkmcnt(0)" : "+v"(l00), "+v"(h00), "+v"(l01), "+v"(h01), "+v"(l10), "+v"(h10), "+v"(l11), "+v"(h11) :: "memory");
;     { const bf16x8 pb0 = __builtin_bit_cast(bf16x8, pw0), pb1 = __builtin_bit_cast(bf16x8, pw1);
;       const bf16x8 v00 = {l00[0], l00[1], l00[2], l00[3], h00[0], h00[1], h00[2], h00[3]}, v01 = {l01[0], l01[1], l01[2], l01[3], h01[0], h01[1], h01[2], h01[3]};
;       const bf16x8 v10 = {l10[0], l10[1], l10[2], l10[3], h10[0], h10[1], h10[2], h10[3]}, v11 = {l11[0], l11[1], l11[2], l11[3], h11[0], h11[1], h11[2], h11[3]};
;       o0 = __builtin_amdgcn_mfma_f32_32x32x16_bf16(v00, pb0, o0, 0, 0, 0); o1 = __builtin_amdgcn_mfma_f32_32x32x16_bf16(v01, pb0, o1, 0, 0, 0);
;       o0 = __builtin_amdgcn_mfma_f32_32x32x16_bf16(v10, pb1, o0, 0, 0, 0); o1 = __builtin_amdgcn_mfma_f32_32x32x16_bf16(v11, pb1, o1, 0, 0, 0); }
.LBB0_426:
	v_sub_f32_e32 v178, v178, v0
	v_sub_f32_e32 v179, v179, v0
	v_sub_f32_e32 v176, v176, v0
	v_sub_f32_e32 v177, v177, v0
	v_exp_f32_e32 v178, v178
	v_exp_f32_e32 v179, v179
	v_exp_f32_e32 v176, v176
	v_exp_f32_e32 v177, v177
	v_sub_f32_e32 v170, v170, v0
	v_sub_f32_e32 v171, v171, v0
	v_sub_f32_e32 v168, v168, v0
	v_sub_f32_e32 v169, v169, v0
	v_exp_f32_e32 v170, v170
	v_exp_f32_e32 v171, v171
	v_exp_f32_e32 v248, v168
	v_exp_f32_e32 v249, v169
	v_add_f32_e32 v246, 0, v178
	v_add_f32_e32 v247, 0, v179
	v_sub_f32_e32 v174, v174, v0
	v_sub_f32_e32 v175, v175, v0
	v_add_f32_e32 v246, v176, v246
	v_add_f32_e32 v247, v177, v247
	v_exp_f32_e32 v174, v174
	v_add_f32_e32 v246, v170, v246
	v_add_f32_e32 v247, v171, v247
	v_exp_f32_e32 v175, v175
	v_sub_f32_e32 v172, v172, v0
	v_sub_f32_e32 v173, v173, v0
	v_add_f32_e32 v168, v248, v246
	v_add_f32_e32 v169, v249, v247
	v_exp_f32_e32 v246, v172
	v_exp_f32_e32 v247, v173
	v_sub_f32_e32 v172, v180, v0
	v_sub_f32_e32 v173, v181, v0
	v_add_f32_e32 v168, v174, v168
	v_add_f32_e32 v169, v175, v169
	v_exp_f32_e32 v180, v172
	v_exp_f32_e32 v181, v173
	v_sub_f32_e32 v172, v182, v0
	v_sub_f32_e32 v173, v183, v0
	v_add_f32_e32 v168, v246, v168
	v_add_f32_e32 v169, v247, v169
	v_exp_f32_e32 v182, v172
	v_exp_f32_e32 v183, v173
	v_add_f32_e32 v168, v180, v168
	v_add_f32_e32 v169, v181, v169
	v_cvt_pk_bf16_f32 v170, v170, v171
	v_cvt_pk_bf16_f32 v171, v248, v249
	v_add_f32_e32 v168, v182, v168
	v_add_f32_e32 v169, v183, v169
	s_waitcnt lgkmcnt(0)
	v_cvt_pk_bf16_f32 v172, v174, v175
	v_add_f32_e32 v0, v168, v169
	v_cvt_pk_bf16_f32 v168, v178, v179
	v_cvt_pk_bf16_f32 v169, v176, v177
	v_cvt_pk_bf16_f32 v173, v246, v247
	v_cvt_pk_bf16_f32 v174, v180, v181
	v_mfma_f32_32x32x16_bf16 v[18:33], v[142:145], v[168:171], v[18:33]
	v_cvt_pk_bf16_f32 v175, v182, v183
	v_add_f32_e32 v0, v245, v0
	s_mov_b64 s[18:19], 0
	v_mfma_f32_32x32x16_bf16 v[2:17], v[138:141], v[168:171], v[2:17]
	v_mfma_f32_32x32x16_bf16 v[18:33], v[134:137], v[172:175], v[18:33]
	v_mfma_f32_32x32x16_bf16 v[2:17], v[130:133], v[172:175], v[2:17]
; #define LAS __attribute__((address_space(3)))
; template <bool MASK> ...
;     s16x4 l00, h00, l01, h01, l10, h10, l11, h11; { const unsigned a0 = va0 + sub * 4096, a1 = va1 + sub * 4096;
;       asm volatile("ds_read_b64_tr_b16 %0, %1" : "=&v"(l00) : "v"(a0) : "memory"); asm volatile("ds_read_b64_tr_b16 %0, %1 offset:1024" : "=&v"(h00) : "v"(a0) : "memory");
;       asm volatile("ds_read_b64_tr_b16 %0, %1" : "=&v"(l01) : "v"(a1) : "memory"); asm volatile("ds_read_b64_tr_b16 %0, %1 offset:1024" : "=&v"(h01) : "v"(a1) : "memory");
;       asm volatile("ds_read_b64_tr_b16 %0, %1 offset:2048" : "=&v"(l10) : "v"(a0) : "memory"); asm volatile("ds_read_b64_tr_b16 %0, %1 offset:3072" : "=&v"(h10) : "v"(a0) : "memory");
;       asm volatile("ds_read_b64_tr_b16 %0, %1 offset:2048" : "=&v"(l11) : "v"(a1) : "memory"); asm volatile("ds_read_b64_tr_b16 %0, %1 offset:3072" : "=&v"(h11) : "v"(a1) : "memory"); }
;     const int r = lane & 31, hh = lane >> 5;
;     f32x16 st = {0.f, 0.f, 0.f, 0.f, 0.f, 0.f, 0.f, 0.f, 0.f, 0.f, 0.f, 0.f, 0.f, 0.f, 0.f, 0.f};
;     { const int key = sub * 32 + r; const LAS char* kp = Kt + key * 128; const int ksw = (key >> 1) & 7;
; #pragma unroll
;       for (int d0 = 0; d0 < 4; ++d0) { const bf16x8 kf = *(const LAS bf16x8*)(kp + (((2 * d0 + hh) ^ ksw) << 4)); st = __builtin_amdgcn_mfma_f32_32x32x16_bf16(kf, qr[d0], st, 0, 0, 0); } }
;     f32x2_t sp[8]; const f32x2_t cs2 = {cscale, cscale};
; #pragma unroll
;     for (int g = 0; g < 4; ++g) { const f32x4 c4 = *(const LAS f32x4*)(cb + sub * 32 + 8 * g + 4 * hh);
;         sp[2 * g] = (f32x2_t){st[4 * g], st[4 * g + 1]} + cs2 * (f32x2_t){c4[0], c4[1]};
;         sp[2 * g + 1] = (f32x2_t){st[4 * g + 2], st[4 * g + 3]} + cs2 * (f32x2_t){c4[2], c4[3]};
;         if (MASK) {
; #pragma unroll
;             for (int e = 0; e < 4; ++e) { const int kpos = kpos_sub + 8 * g + 4 * hh + e; const bool ok = (kpos <= qpos && kpos >= qpos - win);
;                 sp[2 * g + (e >> 1)][e & 1] = ok ? sp[2 * g + (e >> 1)][e & 1] : -INFINITY; } } }
;     float rm = fmaxf(sp[0][0], sp[0][1]);
; #pragma unroll
;     for (int i = 1; i < 8; ++i) rm = fmaxf(fmaxf(rm, sp[i][0]), sp[i][1]);
;     rm = swap_max(rm);
;     if (__any(rm - m > 8.0f)) { const float mnew = fmaxf(m, rm); const float f = fast_exp2(m - mnew); l *= f; o0 = o0 * f; o1 = o1 * f; m = mnew; }
.LBB0_427:
	s_and_b64 vcc, exec, s[18:19]
	s_cbranch_vccz .LBB0_432
	ds_read_b64_tr_b16 v[94:95], v243
	ds_read_b64_tr_b16 v[96:97], v243 offset:1024
	ds_read_b64_tr_b16 v[90:91], v216
	ds_read_b64_tr_b16 v[92:93], v216 offset:1024
	ds_read_b64_tr_b16 v[86:87], v243 offset:2048
	ds_read_b64_tr_b16 v[88:89], v243 offset:3072
	ds_read_b64_tr_b16 v[82:83], v216 offset:2048
	ds_read_b64_tr_b16 v[84:85], v216 offset:3072
	s_nop 8
	ds_read_b128 v[66:69], v215 offset:4096
	ds_read_b128 v[130:133], v214 offset:4096
	v_or_b32_e32 v0, s5, v150
	v_cmp_le_i32_e32 vcc, v0, v154
	v_cmp_ge_i32_e64 s[44:45], v0, v209
	s_and_b64 vcc, vcc, s[44:45]
	s_waitcnt lgkmcnt(0)
	v_mfma_f32_32x32x16_bf16 v[66:81], v[66:69], v[122:125], 0
	v_mfma_f32_32x32x16_bf16 v[66:81], v[130:133], v[114:117], v[66:81]
	ds_read_b128 v[130:133], v213 offset:4096
	s_waitcnt lgkmcnt(0)
	v_mfma_f32_32x32x16_bf16 v[66:81], v[130:133], v[118:121], v[66:81]
	ds_read_b128 v[130:133], v212 offset:4096
	s_waitcnt lgkmcnt(0)
	v_mfma_f32_32x32x16_bf16 v[66:81], v[130:133], v[126:129], v[66:81]
	ds_read_b128 v[130:133], v217 offset:49280
	ds_read_b128 v[134:137], v217 offset:49312
	s_waitcnt lgkmcnt(0)
	s_nop 8
	v_fma_f32 v66, v158, v130, v66
	v_fma_f32 v67, v159, v131, v67
	v_or_b32_e32 v130, 1, v0
	v_cndmask_b32_e32 v66, v240, v66, vcc
	v_cmp_lt_i32_e32 vcc, v0, v154
	v_cmp_ge_i32_e64 s[44:45], v130, v209
	s_and_b64 vcc, vcc, s[44:45]
	v_or_b32_e32 v130, 2, v0
	v_cndmask_b32_e32 v67, v240, v67, vcc
	v_cmp_le_i32_e32 vcc, v130, v154
	v_cmp_ge_i32_e64 s[44:45], v130, v209
	v_fma_f32 v68, v158, v132, v68
	v_fma_f32 v69, v159, v133, v69
	s_and_b64 vcc, vcc, s[44:45]
	v_or_b32_e32 v130, 3, v0
	v_cndmask_b32_e32 v68, v240, v68, vcc
	v_cmp_le_i32_e32 vcc, v130, v154
	v_cmp_ge_i32_e64 s[44:45], v130, v209
	s_and_b64 vcc, vcc, s[44:45]
	v_or_b32_e32 v130, 8, v0
	v_cndmask_b32_e32 v69, v240, v69, vcc
	v_cmp_le_i32_e32 vcc, v130, v154
	v_cmp_ge_i32_e64 s[44:45], v130, v209
	v_fma_f32 v70, v158, v134, v70
	v_fma_f32 v71, v159, v135, v71
	s_and_b64 vcc, vcc, s[44:45]
	v_or_b32_e32 v130, 9, v0
	v_cndmask_b32_e32 v70, v240, v70, vcc
	v_cmp_le_i32_e32 vcc, v130, v154
	v_cmp_ge_i32_e64 s[44:45], v130, v209
	s_and_b64 vcc, vcc, s[44:45]
	v_or_b32_e32 v130, 10, v0
	v_cndmask_b32_e32 v71, v240, v71, vcc
	v_cmp_le_i32_e32 vcc, v130, v154
	v_cmp_ge_i32_e64 s[44:45], v130, v209
	v_fma_f32 v72, v158, v136, v72
	v_fma_f32 v73, v159, v137, v73
	s_and_b64 vcc, vcc, s[44:45]
	v_or_b32_e32 v130, 11, v0
	v_cndmask_b32_e32 v72, v240, v72, vcc
	v_cmp_le_i32_e32 vcc, v130, v154
	v_cmp_ge_i32_e64 s[44:45], v130, v209
	ds_read_b128 v[130:133], v217 offset:49344
	s_and_b64 vcc, vcc, s[44:45]
	v_cndmask_b32_e32 v73, v240, v73, vcc
	s_waitcnt lgkmcnt(0)
	v_fma_f32 v74, v158, v130, v74
	v_fma_f32 v75, v159, v131, v75
	v_or_b32_e32 v130, 16, v0
	v_cmp_le_i32_e32 vcc, v130, v154
	v_cmp_ge_i32_e64 s[44:45], v130, v209
	s_and_b64 vcc, vcc, s[44:45]
	v_or_b32_e32 v130, 17, v0
	v_cndmask_b32_e32 v74, v240, v74, vcc
	v_cmp_le_i32_e32 vcc, v130, v154
	v_cmp_ge_i32_e64 s[44:45], v130, v209
	s_and_b64 vcc, vcc, s[44:45]
	v_or_b32_e32 v130, 18, v0
	v_cndmask_b32_e32 v75, v240, v75, vcc
	v_cmp_le_i32_e32 vcc, v130, v154
	v_cmp_ge_i32_e64 s[44:45], v130, v209
	v_fma_f32 v76, v158, v132, v76
	v_fma_f32 v77, v159, v133, v77
	s_and_b64 vcc, vcc, s[44:45]
	v_or_b32_e32 v130, 19, v0
	v_cndmask_b32_e32 v76, v240, v76, vcc
	v_cmp_le_i32_e32 vcc, v130, v154
	v_cmp_ge_i32_e64 s[44:45], v130, v209
	ds_read_b128 v[130:133], v217 offset:49376
	s_and_b64 vcc, vcc, s[44:45]
	v_cndmask_b32_e32 v77, v240, v77, vcc
	s_waitcnt lgkmcnt(0)
	v_fma_f32 v78, v158, v130, v78
	v_fma_f32 v79, v159, v131, v79
	v_or_b32_e32 v130, 24, v0
	v_cmp_le_i32_e32 vcc, v130, v154
	v_cmp_ge_i32_e64 s[44:45], v130, v209
	s_and_b64 vcc, vcc, s[44:45]
	v_or_b32_e32 v130, 25, v0
	v_cndmask_b32_e32 v78, v240, v78, vcc
	v_cmp_le_i32_e32 vcc, v130, v154
	v_cmp_ge_i32_e64 s[44:45], v130, v209
	s_and_b64 vcc, vcc, s[44:45]
	v_or_b32_e32 v130, 26, v0
	v_cndmask_b32_e32 v79, v240, v79, vcc
	v_cmp_le_i32_e32 vcc, v130, v154
	v_cmp_ge_i32_e64 s[44:45], v130, v209
	v_fma_f32 v80, v158, v132, v80
	v_fma_f32 v81, v159, v133, v81
	s_and_b64 vcc, vcc, s[44:45]
	v_or_b32_e32 v0, 27, v0
	v_cndmask_b32_e32 v80, v240, v80, vcc
	v_cmp_le_i32_e32 vcc, v0, v154
	v_cmp_ge_i32_e64 s[44:45], v0, v209
	v_max_f32_e32 v0, v66, v67
	v_max3_f32 v0, v0, v68, v69
	v_max3_f32 v0, v0, v70, v71
	v_max3_f32 v0, v0, v72, v73
	v_max3_f32 v0, v0, v74, v75
	s_and_b64 vcc, vcc, s[44:45]
	v_max3_f32 v0, v0, v76, v77
	v_cndmask_b32_e32 v81, v240, v81, vcc
	v_max3_f32 v0, v0, v78, v79
	v_max3_f32 v0, v0, v80, v81
	v_mov_b32_e32 v130, v0
	s_nop 1
	v_permlane32_swap_b32_e32 v0, v130
	v_max_f32_e32 v130, v130, v130
	v_max_f32_e32 v0, v0, v0
	v_max_f32_e32 v0, v0, v130
	v_sub_f32_e32 v130, v0, v155
	v_cmp_lt_f32_e32 vcc, s9, v130
	s_cbranch_vccz .LBB0_430
	v_max_f32_e32 v0, v0, v0
	v_max_f32_e32 v130, v155, v155
	v_max_f32_e32 v0, v130, v0
	v_sub_f32_e32 v130, v155, v0
	v_exp_f32_e32 v130, v130
	v_mov_b32_e32 v155, v0
	v_mul_f32_e32 v161, v161, v130
	v_mul_f32_e32 v32, v32, v130
	v_mul_f32_e32 v33, v33, v130
	v_mul_f32_e32 v30, v30, v130
	v_mul_f32_e32 v31, v31, v130
	v_mul_f32_e32 v28, v28, v130
	v_mul_f32_e32 v29, v29, v130
	v_mul_f32_e32 v26, v26, v130
	v_mul_f32_e32 v27, v27, v130
	v_mul_f32_e32 v24, v24, v130
	v_mul_f32_e32 v25, v25, v130
	v_mul_f32_e32 v22, v22, v130
	v_mul_f32_e32 v23, v23, v130
	v_mul_f32_e32 v20, v20, v130
	v_mul_f32_e32 v21, v21, v130
	v_mul_f32_e32 v18, v18, v130
	v_mul_f32_e32 v19, v19, v130
	v_mul_f32_e32 v16, v16, v130
	v_mul_f32_e32 v17, v17, v130
	v_mul_f32_e32 v14, v14, v130
	v_mul_f32_e32 v15, v15, v130
	v_mul_f32_e32 v12, v12, v130
	v_mul_f32_e32 v13, v13, v130
	v_mul_f32_e32 v10, v10, v130
	v_mul_f32_e32 v11, v11, v130
	v_mul_f32_e32 v8, v8, v130
	v_mul_f32_e32 v9, v9, v130
	v_mul_f32_e32 v6, v6, v130
	v_mul_f32_e32 v7, v7, v130
	v_mul_f32_e32 v4, v4, v130
	v_mul_f32_e32 v5, v5, v130
	v_mul_f32_e32 v2, v2, v130
	v_mul_f32_e32 v3, v3, v130
	s_branch .LBB0_431

; __device__ __forceinline__ unsigned cvt_pk_bf16(float lo, float hi) { f32x2_t v = {lo, hi}; bf16x2_t b = __builtin_convertvector(v, bf16x2_t); return __builtin_bit_cast(unsigned, b); }
; __device__ __forceinline__ float fast_exp2(float x) { return __builtin_amdgcn_exp2f(x); }
; template <bool MASK> ...
;     ...
;     { const f32x2_t m2 = {m, m}; f32x2_t ps2 = {0.f, 0.f};
; #pragma unroll
;       for (int i = 0; i < 8; ++i) { f32x2_t t = sp[i] - m2; t[0] = fast_exp2(t[0]); t[1] = fast_exp2(t[1]); sp[i] = t; ps2 = ps2 + t; }
;       l += ps2[0] + ps2[1]; }
;     u32x4 pw0, pw1;
;     pw0.x = cvt_pk_bf16(sp[0][0], sp[0][1]); pw0.y = cvt_pk_bf16(sp[1][0], sp[1][1]); pw0.z = cvt_pk_bf16(sp[2][0], sp[2][1]); pw0.w = cvt_pk_bf16(sp[3][0], sp[3][1]);
;     pw1.x = cvt_pk_bf16(sp[4][0], sp[4][1]); pw1.y = cvt_pk_bf16(sp[5][0], sp[5][1]); pw1.z = cvt_pk_bf16(sp[6][0], sp[6][1]); pw1.w = cvt_pk_bf16(sp[7][0], sp[7][1]);
;     asm volatile("s_waitcnt lgkmcnt(0)" : "+v"(l00), "+v"(h00), "+v"(l01), "+v"(h01), "+v"(l10), "+v"(h10), "+v"(l11), "+v"(h11) :: "memory");
;     { const bf16x8 pb0 = __builtin_bit_cast(bf16x8, pw0), pb1 = __builtin_bit_cast(bf16x8, pw1);
;       const bf16x8 v00 = {l00[0], l00[1], l00[2], l00[3], h00[0], h00[1], h00[2], h00[3]}, v01 = {l01[0], l01[1], l01[2], l01[3], h01[0], h01[1], h01[2], h01[3]};
;       const bf16x8 v10 = {l10[0], l10[1], l10[2], l10[3], h10[0], h10[1], h10[2], h10[3]}, v11 = {l11[0], l11[1], l11[2], l11[3], h11[0], h11[1], h11[2], h11[3]};
;       o0 = __builtin_amdgcn_mfma_f32_32x32x16_bf16(v00, pb0, o0, 0, 0, 0); o1 = __builtin_amdgcn_mfma_f32_32x32x16_bf16(v01, pb0, o1, 0, 0, 0);
;       o0 = __builtin_amdgcn_mfma_f32_32x32x16_bf16(v10, pb1, o0, 0, 0, 0); o1 = __builtin_amdgcn_mfma_f32_32x32x16_bf16(v11, pb1, o1, 0, 0, 0); }
.LBB0_431:
	v_sub_f32_e32 v66, v66, v0
	v_sub_f32_e32 v67, v67, v0
	v_sub_f32_e32 v68, v68, v0
	v_sub_f32_e32 v69, v69, v0
	v_exp_f32_e32 v66, v66
	v_exp_f32_e32 v67, v67
	v_sub_f32_e32 v70, v70, v0
	v_sub_f32_e32 v71, v71, v0
	v_sub_f32_e32 v72, v72, v0
	v_sub_f32_e32 v73, v73, v0
	v_exp_f32_e32 v68, v68
	v_exp_f32_e32 v69, v69
	v_exp_f32_e32 v70, v70
	v_exp_f32_e32 v71, v71
	v_exp_f32_e32 v72, v72
	v_exp_f32_e32 v73, v73
	v_add_f32_e32 v130, 0, v66
	v_add_f32_e32 v131, 0, v67
	v_cvt_pk_bf16_f32 v66, v66, v67
	v_add_f32_e32 v130, v68, v130
	v_add_f32_e32 v131, v69, v131
	v_cvt_pk_bf16_f32 v67, v68, v69
	v_cvt_pk_bf16_f32 v68, v70, v71
	v_cvt_pk_bf16_f32 v69, v72, v73
	s_waitcnt lgkmcnt(0)
	v_sub_f32_e32 v74, v74, v0
	v_sub_f32_e32 v75, v75, v0
	v_sub_f32_e32 v76, v76, v0
	v_sub_f32_e32 v77, v77, v0
	v_mfma_f32_32x32x16_bf16 v[18:33], v[94:97], v[66:69], v[18:33]
	v_add_f32_e64 v78, v78, -v0
	v_add_f32_e64 v79, v79, -v0
	v_add_f32_e64 v80, v80, -v0
	v_add_f32_e64 v81, v81, -v0
	v_exp_f32_e32 v74, v74
	v_exp_f32_e32 v75, v75
	v_exp_f32_e32 v76, v76
	v_exp_f32_e32 v77, v77
	v_exp_f32_e32 v78, v78
	v_mfma_f32_32x32x16_bf16 v[2:17], v[90:93], v[66:69], v[2:17]
	v_exp_f32_e32 v79, v79
	v_exp_f32_e32 v80, v80
	v_exp_f32_e32 v81, v81
	v_add_f32_e32 v130, v70, v130
	v_add_f32_e32 v131, v71, v131
	v_cvt_pk_bf16_f32 v70, v74, v75
	v_add_f32_e32 v130, v72, v130
	v_add_f32_e32 v131, v73, v131
	v_cvt_pk_bf16_f32 v71, v76, v77
	v_cvt_pk_bf16_f32 v72, v78, v79
	v_cvt_pk_bf16_f32 v73, v80, v81
	v_add_f32_e32 v130, v74, v130
	v_add_f32_e32 v131, v75, v131
	v_mov_b32_e32 v244, v155
	v_mfma_f32_32x32x16_bf16 v[18:33], v[86:89], v[70:73], v[18:33]
	v_add_f32_e64 v130, v76, v130
	v_add_f32_e64 v131, v77, v131
	v_add_f32_e64 v130, v78, v130
	v_add_f32_e64 v131, v79, v131
	v_add_f32_e64 v130, v80, v130
	v_add_f32_e64 v131, v81, v131
	v_add_f32_e32 v0, v130, v131
	v_mfma_f32_32x32x16_bf16 v[2:17], v[82:85], v[70:73], v[2:17]
	s_nop 3
	v_add_f32_e32 v0, v161, v0
	s_nop 0

; __device__ __forceinline__ unsigned cvt_pk_bf16(float lo, float hi) { f32x2_t v = {lo, hi}; bf16x2_t b = __builtin_convertvector(v, bf16x2_t); return __builtin_bit_cast(unsigned, b); }
; __device__ __forceinline__ float bf_lo(unsigned w) { return __uint_as_float(w << 16); }
; __device__ __forceinline__ float bf_hi(unsigned w) { return __uint_as_float(w & 0xffff0000u); }
; __device__ __forceinline__ float fast_exp2(float x) { return __builtin_amdgcn_exp2f(x); }
; __device__ __forceinline__ float fast_rcp(float x) { return __builtin_amdgcn_rcpf(x); }
; __device__ __forceinline__ float swap_sum(float v) { auto rr = __builtin_amdgcn_permlane32_swap(__float_as_uint(v), __float_as_uint(v), false, false); return __uint_as_float(rr[0]) + __uint_as_float(rr[1]); }
; __device__ __forceinline__ void attn_store_gated(const f32x16& o0, const f32x16& o1, float inv, const ZRegs& zr, bf16_t* urow, int hh) {
; #pragma unroll
;     for (int d0 = 0; d0 < 2; ++d0)
; #pragma unroll
;         for (int g = 0; g < 4; ++g) { const int d = 32 * d0 + 8 * g + 4 * hh; const u32x2 z = zr.z[d0][g]; const f32x16& o = d0 ? o1 : o0;
;             u32x2 w; w.x = cvt_pk_bf16(o[4 * g] * inv * bf_lo(z.x), o[4 * g + 1] * inv * bf_hi(z.x)); w.y = cvt_pk_bf16(o[4 * g + 2] * inv * bf_lo(z.y), o[4 * g + 3] * inv * bf_hi(z.y));
;             *(u32x2*)(urow + d) = w; }
; }
; __device__ __forceinline__ void swa_unit(LAS char* lds, int b, int kvh, int qi, const bf16_t* H, const float* sinks, bf16_t* U, int tid) {
;     ...
;     { const float lt = swap_sum(lA), sinkp = sinkv * LOG2E + slope2 * (float)(qposA - q0);
;       const float mf = fmaxf(mA, sinkp), sc = fast_exp2(mA - mf), inv = sc * fast_rcp(lt * sc + fast_exp2(sinkp - mf));
;       ZRegs zr; load_z(zr, Hb + (size_t)qposA * HQ + C_SZ + hq * 64, hh); attn_store_gated(oA0, oA1, inv, zr, U + ((size_t)b * SEQ + qposA) * 2048 + U_SWA + hq * 64, hh); }
.LBB0_436:
	v_subrev_u32_e32 v66, s42, v160
	v_cvt_f32_i32_e32 v194, v66
	v_mov_b32_e32 v159, v207
	v_max_f32_e32 v68, v210, v210
	v_mov_b32_e32 v0, v211
	v_mul_f32_e32 v66, v158, v194
	v_mul_f32_e32 v67, v159, v195
	s_nop 0
	v_permlane32_swap_b32_e32 v211, v0
	v_add_f32_e32 v66, v66, v67
	v_max_f32_e32 v68, v68, v66
	v_sub_f32_e32 v69, v210, v68
	v_sub_f32_e32 v66, v66, v68
	v_exp_f32_e32 v69, v69
	v_exp_f32_e32 v66, v66
	v_add_f32_e32 v0, v211, v0
	s_mov_b64 s[0:1], 0x1600
	s_waitcnt lgkmcnt(0)
	s_barrier
	v_fmac_f32_e32 v66, v69, v0
	v_rcp_f32_e32 v0, v66
	s_lshl_b64 s[18:19], s[48:49], 14
	v_readlane_b32 s52, v254, 59
	v_readlane_b32 s53, v254, 60
	v_mul_f32_e32 v66, v69, v0
	v_lshlrev_b32_e32 v0, 1, v150
	v_lshl_add_u64 v[68:69], v[162:163], 0, v[0:1]
	v_lshl_add_u64 v[80:81], v[68:69], 0, s[0:1]
	v_add_co_u32_e32 v68, vcc, s75, v68
	v_mul_f32_e32 v50, v50, v66
	v_mul_f32_e32 v51, v51, v66
	s_nop 0
	v_addc_co_u32_e32 v69, vcc, 0, v69, vcc
	global_load_dwordx2 v[82:83], v[68:69], off offset:1536
	global_load_dwordx2 v[84:85], v[80:81], off offset:16
	global_load_dwordx2 v[78:79], v[80:81], off offset:32
	global_load_dwordx2 v[76:77], v[80:81], off offset:48
	global_load_dwordx2 v[74:75], v[80:81], off offset:64
	global_load_dwordx2 v[72:73], v[80:81], off offset:80
	global_load_dwordx2 v[70:71], v[80:81], off offset:96
	global_load_dwordx2 v[68:69], v[80:81], off offset:112
	v_mov_b32_e32 v81, s19
	v_or_b32_e32 v80, s18, v160
	v_lshlrev_b64 v[80:81], 12, v[80:81]
	v_lshl_add_u64 v[80:81], s[36:37], 0, v[80:81]
	v_lshl_add_u64 v[80:81], v[80:81], 0, s[46:47]
	v_mul_f32_e32 v34, v34, v66
	v_mul_f32_e32 v35, v35, v66
	v_mul_f32_e32 v36, v36, v66
	v_mul_f32_e32 v37, v37, v66
	s_mov_b32 s33, 0x42fc0000
	s_waitcnt vmcnt(0)
	v_lshlrev_b32_e32 v86, 16, v82
	v_and_b32_e32 v87, 0xffff0000, v82
	v_mul_f32_e32 v50, v50, v86
	v_mul_f32_e32 v51, v51, v87
	s_nop 0
	v_cvt_pk_bf16_f32 v82, v50, v51
	v_mul_f32_e32 v50, v52, v66
	v_mul_f32_e32 v51, v53, v66
	v_lshlrev_b32_e32 v52, 16, v83
	v_and_b32_e32 v53, 0xffff0000, v83
	v_mul_f32_e32 v50, v50, v52
	v_mul_f32_e32 v51, v51, v53
	v_mul_f32_e32 v52, v54, v66
	v_mul_f32_e32 v53, v55, v66
	v_lshlrev_b32_e32 v54, 16, v84
	v_and_b32_e32 v55, 0xffff0000, v84
	v_mul_f32_e32 v52, v52, v54
	v_mul_f32_e32 v53, v53, v55
	v_mul_f32_e32 v54, v56, v66
	v_mul_f32_e32 v55, v57, v66
	v_lshlrev_b32_e32 v56, 16, v85
	v_and_b32_e32 v57, 0xffff0000, v85
	v_mul_f32_e32 v54, v54, v56
	v_mul_f32_e32 v55, v55, v57
	v_cvt_pk_bf16_f32 v83, v50, v51
	v_lshl_add_u64 v[50:51], v[80:81], 0, v[0:1]
	v_cvt_pk_bf16_f32 v52, v52, v53
	v_cvt_pk_bf16_f32 v53, v54, v55
	global_store_dwordx2 v[50:51], v[52:53], off offset:1040
	v_mul_f32_e32 v52, v58, v66
	v_mul_f32_e32 v53, v59, v66
	v_lshlrev_b32_e32 v54, 16, v78
	v_and_b32_e32 v55, 0xffff0000, v78
	v_mul_f32_e32 v52, v52, v54
	v_mul_f32_e32 v53, v53, v55
	v_mul_f32_e32 v54, v60, v66
	v_mul_f32_e32 v55, v61, v66
	v_lshlrev_b32_e32 v56, 16, v79
	v_and_b32_e32 v57, 0xffff0000, v79
	v_mul_f32_e32 v54, v54, v56
	v_mul_f32_e32 v55, v55, v57
	v_cvt_pk_bf16_f32 v52, v52, v53
	v_cvt_pk_bf16_f32 v53, v54, v55
	global_store_dwordx2 v[50:51], v[52:53], off offset:1056
	v_mul_f32_e32 v52, v62, v66
	v_mul_f32_e32 v53, v63, v66
	v_lshlrev_b32_e32 v54, 16, v76
	v_and_b32_e32 v55, 0xffff0000, v76
	v_mul_f32_e32 v52, v52, v54
	v_mul_f32_e32 v53, v53, v55
	v_mul_f32_e32 v54, v64, v66
	v_mul_f32_e32 v55, v65, v66
	v_lshlrev_b32_e32 v56, 16, v77
	v_and_b32_e32 v57, 0xffff0000, v77
	v_mul_f32_e32 v54, v54, v56
	v_mul_f32_e32 v55, v55, v57
	v_cvt_pk_bf16_f32 v52, v52, v53
	v_cvt_pk_bf16_f32 v53, v54, v55
	global_store_dwordx2 v[50:51], v[52:53], off offset:1072
	v_lshlrev_b32_e32 v52, 16, v74
	v_and_b32_e32 v53, 0xffff0000, v74
	v_mul_f32_e32 v34, v34, v52
	v_mul_f32_e32 v35, v35, v53
	v_lshlrev_b32_e32 v52, 16, v75
	v_and_b32_e32 v53, 0xffff0000, v75
	v_mul_f32_e32 v36, v36, v52
	v_mul_f32_e32 v37, v37, v53
	v_cvt_pk_bf16_f32 v34, v34, v35
	v_cvt_pk_bf16_f32 v35, v36, v37
	global_store_dwordx2 v[50:51], v[34:35], off offset:1088
	v_mul_f32_e32 v34, v38, v66
	v_mul_f32_e32 v35, v39, v66
	v_lshlrev_b32_e32 v36, 16, v72
	v_and_b32_e32 v37, 0xffff0000, v72
	v_mul_f32_e32 v34, v34, v36
	v_mul_f32_e32 v35, v35, v37
	v_mul_f32_e32 v36, v40, v66
	v_mul_f32_e32 v37, v41, v66
	v_lshlrev_b32_e32 v38, 16, v73
	v_and_b32_e32 v39, 0xffff0000, v73
	v_mul_f32_e32 v36, v36, v38
	v_mul_f32_e32 v37, v37, v39
	v_cvt_pk_bf16_f32 v34, v34, v35
	v_cvt_pk_bf16_f32 v35, v36, v37
	global_store_dwordx2 v[50:51], v[34:35], off offset:1104
	v_mul_f32_e32 v34, v42, v66
	v_mul_f32_e32 v35, v43, v66
	v_lshlrev_b32_e32 v36, 16, v70
	v_and_b32_e32 v37, 0xffff0000, v70
	v_mul_f32_e32 v34, v34, v36
	v_mul_f32_e32 v35, v35, v37
	v_mul_f32_e32 v36, v44, v66
	v_mul_f32_e32 v37, v45, v66
	v_lshlrev_b32_e32 v38, 16, v71
	v_and_b32_e32 v39, 0xffff0000, v71
	v_mul_f32_e32 v36, v36, v38
	v_mul_f32_e32 v37, v37, v39
	v_cvt_pk_bf16_f32 v34, v34, v35
	v_cvt_pk_bf16_f32 v35, v36, v37
	global_store_dwordx2 v[50:51], v[34:35], off offset:1120
	v_mul_f32_e32 v34, v46, v66
	v_mul_f32_e32 v35, v47, v66
	v_lshlrev_b32_e32 v36, 16, v68
	v_and_b32_e32 v37, 0xffff0000, v68
	v_mul_f32_e32 v34, v34, v36
	v_mul_f32_e32 v35, v35, v37
	v_mul_f32_e32 v36, v48, v66
	v_mul_f32_e32 v37, v49, v66
	v_lshlrev_b32_e32 v38, 16, v69
	v_and_b32_e32 v39, 0xffff0000, v69
	v_mul_f32_e32 v36, v36, v38
	v_mul_f32_e32 v37, v37, v39
; __device__ __forceinline__ unsigned cvt_pk_bf16(float lo, float hi) { f32x2_t v = {lo, hi}; bf16x2_t b = __builtin_convertvector(v, bf16x2_t); return __builtin_bit_cast(unsigned, b); }
; __device__ __forceinline__ float bf_lo(unsigned w) { return __uint_as_float(w << 16); }
; __device__ __forceinline__ float bf_hi(unsigned w) { return __uint_as_float(w & 0xffff0000u); }
; __device__ __forceinline__ float fast_exp2(float x) { return __builtin_amdgcn_exp2f(x); }
; __device__ __forceinline__ float fast_rcp(float x) { return __builtin_amdgcn_rcpf(x); }
; __device__ __forceinline__ float swap_sum(float v) { auto rr = __builtin_amdgcn_permlane32_swap(__float_as_uint(v), __float_as_uint(v), false, false); return __uint_as_float(rr[0]) + __uint_as_float(rr[1]); }
; __device__ __forceinline__ void attn_store_gated(const f32x16& o0, const f32x16& o1, float inv, const ZRegs& zr, bf16_t* urow, int hh) {
; #pragma unroll
;     for (int d0 = 0; d0 < 2; ++d0)
; #pragma unroll
;         for (int g = 0; g < 4; ++g) { const int d = 32 * d0 + 8 * g + 4 * hh; const u32x2 z = zr.z[d0][g]; const f32x16& o = d0 ? o1 : o0;
;             u32x2 w; w.x = cvt_pk_bf16(o[4 * g] * inv * bf_lo(z.x), o[4 * g + 1] * inv * bf_hi(z.x)); w.y = cvt_pk_bf16(o[4 * g + 2] * inv * bf_lo(z.y), o[4 * g + 3] * inv * bf_hi(z.y));
;             *(u32x2*)(urow + d) = w; }
; }
; __device__ __forceinline__ void swa_unit(LAS char* lds, int b, int kvh, int qi, const bf16_t* H, const float* sinks, bf16_t* U, int tid) {
;     ...
;     { const float lt = swap_sum(lB), sinkp = sinkv * LOG2E + slope2 * (float)(qposB - q0);
;       const float mf = fmaxf(mB, sinkp), sc = fast_exp2(mB - mf), inv = sc * fast_rcp(lt * sc + fast_exp2(sinkp - mf));
;       ZRegs zr; load_z(zr, Hb + (size_t)qposB * HQ + C_SZ + hq * 64, hh); attn_store_gated(oB0, oB1, inv, zr, U + ((size_t)b * SEQ + qposB) * 2048 + U_SWA + hq * 64, hh); }
	v_cvt_pk_bf16_f32 v34, v34, v35
	v_cvt_pk_bf16_f32 v35, v36, v37
	global_store_dwordx2 v[50:51], v[34:35], off offset:1136
	v_subrev_u32_e32 v35, s42, v154
	v_cvt_f32_i32_e32 v35, v35
	v_mov_b32_e32 v34, v161
	s_nop 1
	v_permlane32_swap_b32_e32 v161, v34
	v_fmac_f32_e32 v67, v158, v35
	v_max_f32_e32 v35, v155, v155
	v_max_f32_e32 v35, v35, v67
	v_sub_f32_e32 v36, v155, v35
	v_sub_f32_e32 v35, v67, v35
	v_exp_f32_e32 v36, v36
	v_exp_f32_e32 v35, v35
	v_add_f32_e32 v34, v161, v34
	global_store_dwordx2 v[50:51], v[82:83], off offset:1024
	v_mov_b32_e32 v53, s19
	v_fmac_f32_e32 v35, v36, v34
	v_rcp_f32_e32 v34, v35
	v_or_b32_e32 v52, s18, v154
	v_lshlrev_b64 v[52:53], 12, v[52:53]
	v_lshl_add_u64 v[52:53], s[36:37], 0, v[52:53]
	v_mul_f32_e32 v34, v36, v34
	v_lshl_add_u64 v[36:37], v[156:157], 0, v[0:1]
	v_lshl_add_u64 v[38:39], v[36:37], 0, s[0:1]
	v_add_co_u32_e32 v36, vcc, s75, v36
	v_mul_f32_e32 v18, v18, v34
	v_mul_f32_e32 v19, v19, v34
	s_nop 0
	v_addc_co_u32_e32 v37, vcc, 0, v37, vcc
	global_load_dwordx2 v[36:37], v[36:37], off offset:1536
	s_nop 0
	global_load_dwordx2 v[40:41], v[38:39], off offset:16
	global_load_dwordx2 v[42:43], v[38:39], off offset:32
	global_load_dwordx2 v[44:45], v[38:39], off offset:48
	global_load_dwordx2 v[46:47], v[38:39], off offset:64
	global_load_dwordx2 v[48:49], v[38:39], off offset:80
	global_load_dwordx2 v[50:51], v[38:39], off offset:96
	s_nop 0
	global_load_dwordx2 v[38:39], v[38:39], off offset:112
	v_mul_f32_e32 v20, v20, v34
	v_mul_f32_e32 v21, v21, v34
	v_lshl_add_u64 v[52:53], v[52:53], 0, s[46:47]
	v_mul_f32_e32 v2, v2, v34
	v_mul_f32_e32 v3, v3, v34
	v_mul_f32_e32 v4, v4, v34
	v_mul_f32_e32 v5, v5, v34
	s_mov_b64 s[18:19], 0
	s_waitcnt vmcnt(0)
	v_lshlrev_b32_e32 v54, 16, v36
	v_and_b32_e32 v55, 0xffff0000, v36
	v_lshlrev_b32_e32 v36, 16, v37
	v_and_b32_e32 v37, 0xffff0000, v37
	v_mul_f32_e32 v18, v18, v54
	v_mul_f32_e32 v19, v19, v55
	v_mul_f32_e32 v20, v20, v36
	v_mul_f32_e32 v21, v21, v37
	v_cvt_pk_bf16_f32 v18, v18, v19
	v_cvt_pk_bf16_f32 v19, v20, v21
	v_lshl_add_u64 v[20:21], v[52:53], 0, v[0:1]
	global_store_dwordx2 v[20:21], v[18:19], off offset:1024
	v_mul_f32_e32 v18, v22, v34
	v_mul_f32_e32 v19, v23, v34
	v_lshlrev_b32_e32 v22, 16, v40
	v_and_b32_e32 v23, 0xffff0000, v40
	v_mul_f32_e32 v18, v18, v22
	v_mul_f32_e32 v19, v19, v23
	v_mul_f32_e32 v22, v24, v34
	v_mul_f32_e32 v23, v25, v34
	v_lshlrev_b32_e32 v24, 16, v41
	v_and_b32_e32 v25, 0xffff0000, v41
	v_mul_f32_e32 v22, v22, v24
	v_mul_f32_e32 v23, v23, v25
	v_cvt_pk_bf16_f32 v18, v18, v19
	v_cvt_pk_bf16_f32 v19, v22, v23
	global_store_dwordx2 v[20:21], v[18:19], off offset:1040
	v_mul_f32_e32 v18, v26, v34
	v_mul_f32_e32 v19, v27, v34
	v_lshlrev_b32_e32 v22, 16, v42
	v_and_b32_e32 v23, 0xffff0000, v42
	v_mul_f32_e32 v18, v18, v22
	v_mul_f32_e32 v19, v19, v23
	v_mul_f32_e32 v22, v28, v34
	v_mul_f32_e32 v23, v29, v34
	v_lshlrev_b32_e32 v24, 16, v43
	v_and_b32_e32 v25, 0xffff0000, v43
	v_mul_f32_e32 v22, v22, v24
	v_mul_f32_e32 v23, v23, v25
	v_cvt_pk_bf16_f32 v18, v18, v19
	v_cvt_pk_bf16_f32 v19, v22, v23
	global_store_dwordx2 v[20:21], v[18:19], off offset:1056
	v_mul_f32_e32 v18, v30, v34
	v_mul_f32_e32 v19, v31, v34
	v_lshlrev_b32_e32 v22, 16, v44
	v_and_b32_e32 v23, 0xffff0000, v44
	v_mul_f32_e32 v18, v18, v22
	v_mul_f32_e32 v19, v19, v23
	v_mul_f32_e32 v22, v32, v34
	v_mul_f32_e32 v23, v33, v34
	v_lshlrev_b32_e32 v24, 16, v45
	v_and_b32_e32 v25, 0xffff0000, v45
	v_mul_f32_e32 v22, v22, v24
	v_mul_f32_e32 v23, v23, v25
	v_cvt_pk_bf16_f32 v18, v18, v19
	v_cvt_pk_bf16_f32 v19, v22, v23
	global_store_dwordx2 v[20:21], v[18:19], off offset:1072
	v_lshlrev_b32_e32 v18, 16, v46
	v_and_b32_e32 v19, 0xffff0000, v46
	v_mul_f32_e32 v2, v2, v18
	v_mul_f32_e32 v3, v3, v19
	v_lshlrev_b32_e32 v18, 16, v47
	v_and_b32_e32 v19, 0xffff0000, v47
	v_mul_f32_e32 v4, v4, v18
	v_mul_f32_e32 v5, v5, v19
	v_cvt_pk_bf16_f32 v2, v2, v3
	v_cvt_pk_bf16_f32 v3, v4, v5
	global_store_dwordx2 v[20:21], v[2:3], off offset:1088
	v_mul_f32_e32 v2, v6, v34
	v_mul_f32_e32 v3, v7, v34
	v_lshlrev_b32_e32 v4, 16, v48
	v_and_b32_e32 v5, 0xffff0000, v48
	v_mul_f32_e32 v2, v2, v4
	v_mul_f32_e32 v3, v3, v5
	v_mul_f32_e32 v4, v8, v34
	v_mul_f32_e32 v5, v9, v34
	v_lshlrev_b32_e32 v6, 16, v49
	v_and_b32_e32 v7, 0xffff0000, v49
	v_mul_f32_e32 v4, v4, v6
	v_mul_f32_e32 v5, v5, v7
	v_cvt_pk_bf16_f32 v2, v2, v3
	v_cvt_pk_bf16_f32 v3, v4, v5
	global_store_dwordx2 v[20:21], v[2:3], off offset:1104
	v_mul_f32_e32 v2, v10, v34
	v_mul_f32_e32 v3, v11, v34
	v_lshlrev_b32_e32 v4, 16, v50
	v_and_b32_e32 v5, 0xffff0000, v50
	v_mul_f32_e32 v2, v2, v4
	v_mul_f32_e32 v3, v3, v5
	v_mul_f32_e32 v4, v12, v34
	v_mul_f32_e32 v5, v13, v34
	v_lshlrev_b32_e32 v6, 16, v51
	v_and_b32_e32 v7, 0xffff0000, v51
	v_mul_f32_e32 v4, v4, v6
	v_mul_f32_e32 v5, v5, v7
	v_cvt_pk_bf16_f32 v2, v2, v3
	v_cvt_pk_bf16_f32 v3, v4, v5
	global_store_dwordx2 v[20:21], v[2:3], off offset:1120
	v_mul_f32_e32 v2, v14, v34
	v_mul_f32_e32 v3, v15, v34
	v_lshlrev_b32_e32 v4, 16, v38
	v_and_b32_e32 v5, 0xffff0000, v38
	v_mul_f32_e32 v2, v2, v4
	v_mul_f32_e32 v3, v3, v5
	v_mul_f32_e32 v4, v16, v34
	v_mul_f32_e32 v5, v17, v34
	v_lshlrev_b32_e32 v6, 16, v39
	v_and_b32_e32 v7, 0xffff0000, v39
	v_mul_f32_e32 v4, v4, v6
	v_mul_f32_e32 v5, v5, v7
	v_cvt_pk_bf16_f32 v2, v2, v3
	v_cvt_pk_bf16_f32 v3, v4, v5
	global_store_dwordx2 v[20:21], v[2:3], off offset:1136

; #define LAS __attribute__((address_space(3)))
; template <bool MASK> ...
;     s16x4 l00, h00, l01, h01, l10, h10, l11, h11; { const unsigned a0 = va0 + sub * 4096, a1 = va1 + sub * 4096;
;       asm volatile("ds_read_b64_tr_b16 %0, %1" : "=&v"(l00) : "v"(a0) : "memory"); asm volatile("ds_read_b64_tr_b16 %0, %1 offset:1024" : "=&v"(h00) : "v"(a0) : "memory");
;       asm volatile("ds_read_b64_tr_b16 %0, %1" : "=&v"(l01) : "v"(a1) : "memory"); asm volatile("ds_read_b64_tr_b16 %0, %1 offset:1024" : "=&v"(h01) : "v"(a1) : "memory");
;       asm volatile("ds_read_b64_tr_b16 %0, %1 offset:2048" : "=&v"(l10) : "v"(a0) : "memory"); asm volatile("ds_read_b64_tr_b16 %0, %1 offset:3072" : "=&v"(h10) : "v"(a0) : "memory");
;       asm volatile("ds_read_b64_tr_b16 %0, %1 offset:2048" : "=&v"(l11) : "v"(a1) : "memory"); asm volatile("ds_read_b64_tr_b16 %0, %1 offset:3072" : "=&v"(h11) : "v"(a1) : "memory"); }
;     const int r = lane & 31, hh = lane >> 5;
;     f32x16 st = {0.f, 0.f, 0.f, 0.f, 0.f, 0.f, 0.f, 0.f, 0.f, 0.f, 0.f, 0.f, 0.f, 0.f, 0.f, 0.f};
;     { const int key = sub * 32 + r; const LAS char* kp = Kt + key * 128; const int ksw = (key >> 1) & 7;
; #pragma unroll
;       for (int d0 = 0; d0 < 4; ++d0) { const bf16x8 kf = *(const LAS bf16x8*)(kp + (((2 * d0 + hh) ^ ksw) << 4)); st = __builtin_amdgcn_mfma_f32_32x32x16_bf16(kf, qr[d0], st, 0, 0, 0); } }
;     f32x2_t sp[8]; const f32x2_t cs2 = {cscale, cscale};
; #pragma unroll
;     for (int g = 0; g < 4; ++g) { const f32x4 c4 = *(const LAS f32x4*)(cb + sub * 32 + 8 * g + 4 * hh);
;         sp[2 * g] = (f32x2_t){st[4 * g], st[4 * g + 1]} + cs2 * (f32x2_t){c4[0], c4[1]};
;         sp[2 * g + 1] = (f32x2_t){st[4 * g + 2], st[4 * g + 3]} + cs2 * (f32x2_t){c4[2], c4[3]};
;         if (MASK) {
; #pragma unroll
;             for (int e = 0; e < 4; ++e) { const int kpos = kpos_sub + 8 * g + 4 * hh + e; const bool ok = (kpos <= qpos && kpos >= qpos - win);
;                 sp[2 * g + (e >> 1)][e & 1] = ok ? sp[2 * g + (e >> 1)][e & 1] : -INFINITY; } } }
;     float rm = fmaxf(sp[0][0], sp[0][1]);
; #pragma unroll
;     for (int i = 1; i < 8; ++i) rm = fmaxf(fmaxf(rm, sp[i][0]), sp[i][1]);
;     rm = swap_max(rm);
;     if (__any(rm - m > 8.0f)) { const float mnew = fmaxf(m, rm); const float f = fast_exp2(m - mnew); l *= f; o0 = o0 * f; o1 = o1 * f; m = mnew; }
.LBB0_446:
	s_add_i32 s12, s0, 1
	v_cvt_f32_ubyte0_e32 v0, s12
	v_cmp_lt_f32_e32 vcc, s33, v0
	s_and_b64 s[12:13], vcc, exec
	s_cselect_b32 s12, 0xffffffc0, 0
	v_cndmask_b32_e32 v2, 0, v238, vcc
	v_sub_f32_e32 v0, v2, v0
	v_exp_f32_e32 v0, v0
	s_cmp_lt_i32 s5, s4
	s_cselect_b64 s[52:53], -1, 0
	s_cmp_ge_i32 s5, s4
	v_ldexp_f32 v0, v0, s12
	v_mul_f32_e32 v132, 0x3fb8aa3b, v0
	v_mov_b32_e32 v133, v132
	v_add_u32_e32 v159, v203, v191
	v_add_u32_e32 v158, v203, v192
	v_add_u32_e32 v157, v203, v193
	v_add_u32_e32 v156, v203, v196
	s_cbranch_scc1 .LBB0_449
	ds_read_b64_tr_b16 v[60:61], v189
	ds_read_b64_tr_b16 v[62:63], v189 offset:1024
	ds_read_b64_tr_b16 v[56:57], v190
	ds_read_b64_tr_b16 v[58:59], v190 offset:1024
	ds_read_b64_tr_b16 v[52:53], v189 offset:2048
	ds_read_b64_tr_b16 v[54:55], v189 offset:3072
	ds_read_b64_tr_b16 v[48:49], v190 offset:2048
	ds_read_b64_tr_b16 v[50:51], v190 offset:3072
	ds_read_b128 v[2:5], v159
	ds_read_b128 v[18:21], v158
	s_waitcnt lgkmcnt(0)
	v_mfma_f32_32x32x16_bf16 v[2:17], v[2:5], v[96:99], 0
	v_mfma_f32_32x32x16_bf16 v[2:17], v[18:21], v[100:103], v[2:17]
	ds_read_b128 v[18:21], v157
	s_waitcnt lgkmcnt(0)
	v_mfma_f32_32x32x16_bf16 v[2:17], v[18:21], v[104:107], v[2:17]
	ds_read_b128 v[18:21], v156
	s_waitcnt lgkmcnt(0)
	v_mfma_f32_32x32x16_bf16 v[2:17], v[18:21], v[108:111], v[2:17]
	ds_read_b128 v[18:21], v202 offset:49152
	ds_read_b128 v[22:25], v202 offset:49184
	s_waitcnt lgkmcnt(0)
	s_nop 8
	v_fma_f32 v34, v132, v18, v2
	v_fma_f32 v35, v133, v19, v3
	v_fma_f32 v32, v132, v20, v4
	v_fma_f32 v33, v133, v21, v5
	ds_read_b128 v[18:21], v202 offset:49216
	v_fma_f32 v2, v132, v24, v8
	v_fma_f32 v3, v133, v25, v9
	v_max_f32_e32 v0, v34, v35
	v_fma_f32 v6, v132, v22, v6
	v_fma_f32 v7, v133, v23, v7
	v_max3_f32 v0, v0, v32, v33
	s_waitcnt lgkmcnt(0)
	v_fma_f32 v8, v132, v18, v10
	v_fma_f32 v9, v133, v19, v11
	v_fma_f32 v4, v132, v20, v12
	v_fma_f32 v5, v133, v21, v13
	ds_read_b128 v[18:21], v202 offset:49248
	v_max3_f32 v0, v0, v6, v7
	v_max3_f32 v0, v0, v2, v3
	v_max3_f32 v0, v0, v8, v9
	v_max3_f32 v0, v0, v4, v5
	s_waitcnt lgkmcnt(0)
	v_fma_f32 v12, v132, v18, v14
	v_fma_f32 v13, v133, v19, v15
	v_fma_f32 v10, v132, v20, v16
	v_fma_f32 v11, v133, v21, v17
	v_max3_f32 v0, v0, v12, v13
	v_max3_f32 v0, v0, v10, v11
	v_mov_b32_e32 v14, v0
	s_nop 1
	v_permlane32_swap_b32_e32 v0, v14
	v_max_f32_e32 v14, v14, v14
	v_max_f32_e32 v0, v0, v0
	v_max_f32_e32 v0, v0, v14
	v_add_f32_e32 v14, 0x7149f2ca, v0
	v_cmp_lt_f32_e32 vcc, s9, v14
	s_cbranch_vccz .LBB0_450
	v_max_f32_e32 v0, v0, v0
	v_max_f32_e32 v134, 0xf149f2ca, v0
	v_sub_f32_e32 v0, 0xf149f2ca, v134
	v_exp_f32_e32 v0, v0
	s_nop 0
	v_mul_f32_e32 v16, 0, v0
	s_branch .LBB0_451

; template <bool MASK> ...
;     s16x4 l00, h00, l01, h01, l10, h10, l11, h11; { const unsigned a0 = va0 + sub * 4096, a1 = va1 + sub * 4096;
;       asm volatile("ds_read_b64_tr_b16 %0, %1" : "=&v"(l00) : "v"(a0) : "memory"); asm volatile("ds_read_b64_tr_b16 %0, %1 offset:1024" : "=&v"(h00) : "v"(a0) : "memory");
;       asm volatile("ds_read_b64_tr_b16 %0, %1" : "=&v"(l01) : "v"(a1) : "memory"); asm volatile("ds_read_b64_tr_b16 %0, %1 offset:1024" : "=&v"(h01) : "v"(a1) : "memory");
;       asm volatile("ds_read_b64_tr_b16 %0, %1 offset:2048" : "=&v"(l10) : "v"(a0) : "memory"); asm volatile("ds_read_b64_tr_b16 %0, %1 offset:3072" : "=&v"(h10) : "v"(a0) : "memory");
;       asm volatile("ds_read_b64_tr_b16 %0, %1 offset:2048" : "=&v"(l11) : "v"(a1) : "memory"); asm volatile("ds_read_b64_tr_b16 %0, %1 offset:3072" : "=&v"(h11) : "v"(a1) : "memory"); }
;     const int r = lane & 31, hh = lane >> 5;
;     f32x16 st = {0.f, 0.f, 0.f, 0.f, 0.f, 0.f, 0.f, 0.f, 0.f, 0.f, 0.f, 0.f, 0.f, 0.f, 0.f, 0.f};
;     { const int key = sub * 32 + r; const LAS char* kp = Kt + key * 128; const int ksw = (key >> 1) & 7;
; #pragma unroll
;       for (int d0 = 0; d0 < 4; ++d0) { const bf16x8 kf = *(const LAS bf16x8*)(kp + (((2 * d0 + hh) ^ ksw) << 4)); st = __builtin_amdgcn_mfma_f32_32x32x16_bf16(kf, qr[d0], st, 0, 0, 0); } }
;     f32x2_t sp[8]; const f32x2_t cs2 = {cscale, cscale};
; #pragma unroll
;     for (int g = 0; g < 4; ++g) { const f32x4 c4 = *(const LAS f32x4*)(cb + sub * 32 + 8 * g + 4 * hh);
;         sp[2 * g] = (f32x2_t){st[4 * g], st[4 * g + 1]} + cs2 * (f32x2_t){c4[0], c4[1]};
;         sp[2 * g + 1] = (f32x2_t){st[4 * g + 2], st[4 * g + 3]} + cs2 * (f32x2_t){c4[2], c4[3]};
;         if (MASK) {
; #pragma unroll
;             for (int e = 0; e < 4; ++e) { const int kpos = kpos_sub + 8 * g + 4 * hh + e; const bool ok = (kpos <= qpos && kpos >= qpos - win);
;                 sp[2 * g + (e >> 1)][e & 1] = ok ? sp[2 * g + (e >> 1)][e & 1] : -INFINITY; } } }
;     float rm = fmaxf(sp[0][0], sp[0][1]);
; #pragma unroll
;     for (int i = 1; i < 8; ++i) rm = fmaxf(fmaxf(rm, sp[i][0]), sp[i][1]);
;     rm = swap_max(rm);
;     if (__any(rm - m > 8.0f)) { const float mnew = fmaxf(m, rm); const float f = fast_exp2(m - mnew); l *= f; o0 = o0 * f; o1 = o1 * f; m = mnew; }
;     { const f32x2_t m2 = {m, m}; f32x2_t ps2 = {0.f, 0.f};
; #pragma unroll
.LBB0_451:
	v_sub_f32_e32 v14, v34, v134
	v_sub_f32_e32 v15, v35, v134
	v_sub_f32_e32 v32, v32, v134
	v_sub_f32_e32 v33, v33, v134
	v_exp_f32_e32 v14, v14
	v_exp_f32_e32 v15, v15
	v_exp_f32_e32 v32, v32
	v_exp_f32_e32 v33, v33
	v_sub_f32_e32 v6, v6, v134
	v_sub_f32_e32 v7, v7, v134
	v_sub_f32_e32 v2, v2, v134
	v_sub_f32_e32 v3, v3, v134
	v_exp_f32_e32 v6, v6
	v_exp_f32_e32 v7, v7
	v_exp_f32_e32 v36, v2
	v_exp_f32_e32 v37, v3
	v_add_f32_e32 v34, 0, v14
	v_add_f32_e32 v35, 0, v15
	v_sub_f32_e32 v8, v8, v134
	v_sub_f32_e32 v9, v9, v134
	v_add_f32_e32 v34, v32, v34
	v_add_f32_e32 v35, v33, v35
	v_exp_f32_e32 v8, v8
	v_add_f32_e32 v34, v6, v34
	v_add_f32_e32 v35, v7, v35
	v_exp_f32_e32 v9, v9
	v_sub_f32_e32 v4, v4, v134
	v_sub_f32_e32 v5, v5, v134
	v_add_f32_e32 v2, v36, v34
	v_add_f32_e32 v3, v37, v35
	v_exp_f32_e32 v34, v4
	v_exp_f32_e32 v35, v5
	v_sub_f32_e32 v4, v12, v134
	v_sub_f32_e32 v5, v13, v134
	v_add_f32_e32 v2, v8, v2
	v_add_f32_e32 v3, v9, v3
	v_exp_f32_e32 v12, v4
	v_exp_f32_e32 v13, v5
	v_sub_f32_e32 v4, v10, v134
	v_sub_f32_e32 v5, v11, v134
	v_add_f32_e32 v2, v34, v2
	v_add_f32_e32 v3, v35, v3
	v_exp_f32_e32 v10, v4
	v_exp_f32_e32 v11, v5
	v_add_f32_e32 v2, v12, v2
	v_add_f32_e32 v3, v13, v3
	v_mov_b32_e32 v17, v16
	v_mov_b32_e32 v18, v16
	v_add_f32_e32 v2, v10, v2
	v_add_f32_e32 v3, v11, v3
	v_mov_b32_e32 v19, v16
	v_mov_b32_e32 v20, v16
	v_mov_b32_e32 v21, v16
	v_mov_b32_e32 v22, v16
	v_mov_b32_e32 v23, v16
	v_mov_b32_e32 v24, v16
	v_mov_b32_e32 v25, v16
	v_mov_b32_e32 v26, v16
	v_mov_b32_e32 v27, v16
	v_mov_b32_e32 v28, v16
	v_mov_b32_e32 v29, v16
	v_mov_b32_e32 v30, v16
	v_mov_b32_e32 v31, v16
	v_add_f32_e32 v0, v2, v3
	v_cvt_pk_bf16_f32 v2, v14, v15
	v_cvt_pk_bf16_f32 v3, v32, v33
	v_cvt_pk_bf16_f32 v4, v6, v7
	v_cvt_pk_bf16_f32 v5, v36, v37
	v_add_f32_e32 v154, v16, v0
	v_cvt_pk_bf16_f32 v7, v34, v35
	s_waitcnt lgkmcnt(0)
	v_cvt_pk_bf16_f32 v6, v8, v9
	v_mfma_f32_32x32x16_bf16 v[32:47], v[60:63], v[2:5], v[16:31]
	v_cvt_pk_bf16_f32 v8, v12, v13
	v_cvt_pk_bf16_f32 v9, v10, v11
	v_mfma_f32_32x32x16_bf16 v[16:31], v[56:59], v[2:5], v[16:31]
	s_nop 0
	v_mfma_f32_32x32x16_bf16 v[32:47], v[52:55], v[6:9], v[32:47]
	v_mfma_f32_32x32x16_bf16 v[16:31], v[48:51], v[6:9], v[16:31]
.LBB0_452:
	s_ashr_i32 s29, s28, 31
	s_addk_i32 s5, 0x100
	s_cmp_lt_i32 s5, s4
	s_cselect_b64 s[18:19], -1, 0
	s_cmp_ge_i32 s5, s4
	s_cbranch_scc1 .LBB0_455
	ds_read_b64_tr_b16 v[80:81], v189
	ds_read_b64_tr_b16 v[82:83], v189 offset:1024
	ds_read_b64_tr_b16 v[10:11], v190
	ds_read_b64_tr_b16 v[12:13], v190 offset:1024
	ds_read_b64_tr_b16 v[6:7], v189 offset:2048
	ds_read_b64_tr_b16 v[8:9], v189 offset:3072
	ds_read_b64_tr_b16 v[2:3], v190 offset:2048
	ds_read_b64_tr_b16 v[4:5], v190 offset:3072
	ds_read_b128 v[48:51], v159
	ds_read_b128 v[64:67], v158
	s_waitcnt lgkmcnt(0)
	v_mfma_f32_32x32x16_bf16 v[48:63], v[48:51], v[112:115], 0
	v_mfma_f32_32x32x16_bf16 v[48:63], v[64:67], v[116:119], v[48:63]
	ds_read_b128 v[64:67], v157
	s_waitcnt lgkmcnt(0)
	v_mfma_f32_32x32x16_bf16 v[48:63], v[64:67], v[120:123], v[48:63]
	ds_read_b128 v[64:67], v156
	s_waitcnt lgkmcnt(0)
	v_mfma_f32_32x32x16_bf16 v[48:63], v[64:67], v[124:127], v[48:63]
	ds_read_b128 v[64:67], v202 offset:49152
	ds_read_b128 v[74:77], v202 offset:49184
	s_waitcnt lgkmcnt(0)
	s_nop 8
	v_fma_f32 v72, v132, v64, v48
	v_fma_f32 v73, v133, v65, v49
	v_fma_f32 v70, v132, v66, v50
	v_fma_f32 v71, v133, v67, v51
	ds_read_b128 v[48:51], v202 offset:49216
	v_max_f32_e32 v0, v72, v73
	v_fma_f32 v66, v132, v74, v52
	v_fma_f32 v67, v133, v75, v53
	v_max3_f32 v0, v0, v70, v71
	v_fma_f32 v14, v132, v76, v54
	v_fma_f32 v15, v133, v77, v55
	s_waitcnt lgkmcnt(0)
	v_fma_f32 v68, v132, v48, v56
	v_fma_f32 v69, v133, v49, v57
	v_fma_f32 v64, v132, v50, v58
	v_fma_f32 v65, v133, v51, v59
	ds_read_b128 v[48:51], v202 offset:49248
	v_max3_f32 v0, v0, v66, v67
	v_max3_f32 v0, v0, v14, v15
	v_max3_f32 v0, v0, v68, v69
	v_max3_f32 v0, v0, v64, v65
	s_waitcnt lgkmcnt(0)
	v_fma_f32 v76, v132, v48, v60
	v_fma_f32 v77, v133, v49, v61
	v_fma_f32 v74, v132, v50, v62
	v_fma_f32 v75, v133, v51, v63
	v_max3_f32 v0, v0, v76, v77
	v_max3_f32 v0, v0, v74, v75
	v_mov_b32_e32 v48, v0
	s_nop 1
	v_permlane32_swap_b32_e32 v0, v48
	v_max_f32_e32 v48, v48, v48
	v_max_f32_e32 v0, v0, v0
	v_max_f32_e32 v0, v0, v48
	v_add_f32_e32 v48, 0x7149f2ca, v0
	v_cmp_lt_f32_e32 vcc, s9, v48
	s_cbranch_vccz .LBB0_456
	v_max_f32_e32 v0, v0, v0
	v_max_f32_e32 v136, 0xf149f2ca, v0
	v_sub_f32_e32 v0, 0xf149f2ca, v136
	v_exp_f32_e32 v0, v0
	s_nop 0
	v_mul_f32_e32 v48, 0, v0
	s_branch .LBB0_457

; template <bool MASK> ...
;     s16x4 l00, h00, l01, h01, l10, h10, l11, h11; { const unsigned a0 = va0 + sub * 4096, a1 = va1 + sub * 4096;
;       asm volatile("ds_read_b64_tr_b16 %0, %1" : "=&v"(l00) : "v"(a0) : "memory"); asm volatile("ds_read_b64_tr_b16 %0, %1 offset:1024" : "=&v"(h00) : "v"(a0) : "memory");
;       asm volatile("ds_read_b64_tr_b16 %0, %1" : "=&v"(l01) : "v"(a1) : "memory"); asm volatile("ds_read_b64_tr_b16 %0, %1 offset:1024" : "=&v"(h01) : "v"(a1) : "memory");
;       asm volatile("ds_read_b64_tr_b16 %0, %1 offset:2048" : "=&v"(l10) : "v"(a0) : "memory"); asm volatile("ds_read_b64_tr_b16 %0, %1 offset:3072" : "=&v"(h10) : "v"(a0) : "memory");
;       asm volatile("ds_read_b64_tr_b16 %0, %1 offset:2048" : "=&v"(l11) : "v"(a1) : "memory"); asm volatile("ds_read_b64_tr_b16 %0, %1 offset:3072" : "=&v"(h11) : "v"(a1) : "memory"); }
;     const int r = lane & 31, hh = lane >> 5;
;     f32x16 st = {0.f, 0.f, 0.f, 0.f, 0.f, 0.f, 0.f, 0.f, 0.f, 0.f, 0.f, 0.f, 0.f, 0.f, 0.f, 0.f};
;     { const int key = sub * 32 + r; const LAS char* kp = Kt + key * 128; const int ksw = (key >> 1) & 7;
; #pragma unroll
;       for (int d0 = 0; d0 < 4; ++d0) { const bf16x8 kf = *(const LAS bf16x8*)(kp + (((2 * d0 + hh) ^ ksw) << 4)); st = __builtin_amdgcn_mfma_f32_32x32x16_bf16(kf, qr[d0], st, 0, 0, 0); } }
;     f32x2_t sp[8]; const f32x2_t cs2 = {cscale, cscale};
; #pragma unroll
;     for (int g = 0; g < 4; ++g) { const f32x4 c4 = *(const LAS f32x4*)(cb + sub * 32 + 8 * g + 4 * hh);
;         sp[2 * g] = (f32x2_t){st[4 * g], st[4 * g + 1]} + cs2 * (f32x2_t){c4[0], c4[1]};
;         sp[2 * g + 1] = (f32x2_t){st[4 * g + 2], st[4 * g + 3]} + cs2 * (f32x2_t){c4[2], c4[3]};
;         if (MASK) {
; #pragma unroll
;             for (int e = 0; e < 4; ++e) { const int kpos = kpos_sub + 8 * g + 4 * hh + e; const bool ok = (kpos <= qpos && kpos >= qpos - win);
;                 sp[2 * g + (e >> 1)][e & 1] = ok ? sp[2 * g + (e >> 1)][e & 1] : -INFINITY; } } }
;     float rm = fmaxf(sp[0][0], sp[0][1]);
; #pragma unroll
;     for (int i = 1; i < 8; ++i) rm = fmaxf(fmaxf(rm, sp[i][0]), sp[i][1]);
;     rm = swap_max(rm);
;     if (__any(rm - m > 8.0f)) { const float mnew = fmaxf(m, rm); const float f = fast_exp2(m - mnew); l *= f; o0 = o0 * f; o1 = o1 * f; m = mnew; }
;     { const f32x2_t m2 = {m, m}; f32x2_t ps2 = {0.f, 0.f};
; #pragma unroll
.LBB0_457:
	v_sub_f32_e32 v72, v72, v136
	v_sub_f32_e32 v73, v73, v136
	v_sub_f32_e32 v70, v70, v136
	v_sub_f32_e32 v71, v71, v136
	v_exp_f32_e32 v72, v72
	v_exp_f32_e32 v73, v73
	v_exp_f32_e32 v70, v70
	v_exp_f32_e32 v71, v71
	v_sub_f32_e32 v66, v66, v136
	v_sub_f32_e32 v67, v67, v136
	v_sub_f32_e32 v14, v14, v136
	v_sub_f32_e32 v15, v15, v136
	v_exp_f32_e32 v66, v66
	v_exp_f32_e32 v67, v67
	v_exp_f32_e32 v14, v14
	v_exp_f32_e32 v15, v15
	v_sub_f32_e32 v68, v68, v136
	v_sub_f32_e32 v69, v69, v136
	v_add_f32_e32 v78, 0, v72
	v_add_f32_e32 v79, 0, v73
	v_exp_f32_e32 v68, v68
	v_exp_f32_e32 v69, v69
	v_sub_f32_e32 v64, v64, v136
	v_sub_f32_e32 v65, v65, v136
	v_add_f32_e32 v78, v70, v78
	v_add_f32_e32 v79, v71, v79
	v_exp_f32_e32 v64, v64
	v_exp_f32_e32 v65, v65
	v_sub_f32_e32 v76, v76, v136
	v_sub_f32_e32 v77, v77, v136
	v_add_f32_e32 v78, v66, v78
	v_add_f32_e32 v79, v67, v79
	v_exp_f32_e32 v76, v76
	v_exp_f32_e32 v77, v77
	v_sub_f32_e32 v74, v74, v136
	v_sub_f32_e32 v75, v75, v136
	v_add_f32_e32 v78, v14, v78
	v_add_f32_e32 v79, v15, v79
	v_exp_f32_e32 v74, v74
	v_exp_f32_e32 v75, v75
	v_add_f32_e32 v78, v68, v78
	v_add_f32_e32 v79, v69, v79
	v_mov_b32_e32 v49, v48
	v_add_f32_e32 v78, v64, v78
	v_add_f32_e32 v79, v65, v79
	v_mov_b32_e32 v50, v48
	v_add_f32_e32 v78, v76, v78
	v_add_f32_e32 v79, v77, v79
	v_mov_b32_e32 v51, v48
	v_add_f32_e32 v78, v74, v78
	v_add_f32_e32 v79, v75, v79
	v_mov_b32_e32 v52, v48
	v_mov_b32_e32 v53, v48
	v_mov_b32_e32 v54, v48
	v_mov_b32_e32 v55, v48
	v_mov_b32_e32 v56, v48
	v_mov_b32_e32 v57, v48
	v_mov_b32_e32 v58, v48
	v_mov_b32_e32 v59, v48
	v_mov_b32_e32 v60, v48
	v_mov_b32_e32 v61, v48
	v_mov_b32_e32 v62, v48
	v_mov_b32_e32 v63, v48
	v_add_f32_e32 v0, v78, v79
	v_cvt_pk_bf16_f32 v84, v72, v73
	v_cvt_pk_bf16_f32 v85, v70, v71
	v_cvt_pk_bf16_f32 v86, v66, v67
	v_cvt_pk_bf16_f32 v87, v14, v15
	v_add_f32_e32 v155, v48, v0
	v_cvt_pk_bf16_f32 v88, v68, v69
	v_cvt_pk_bf16_f32 v89, v64, v65
	v_cvt_pk_bf16_f32 v90, v76, v77
	v_cvt_pk_bf16_f32 v91, v74, v75
	s_waitcnt lgkmcnt(0)
	s_nop 0
	v_mfma_f32_32x32x16_bf16 v[64:79], v[80:83], v[84:87], v[48:63]
	v_mfma_f32_32x32x16_bf16 v[48:63], v[10:13], v[84:87], v[48:63]
	v_mfma_f32_32x32x16_bf16 v[64:79], v[6:9], v[88:91], v[64:79]
	v_mfma_f32_32x32x16_bf16 v[48:63], v[2:5], v[88:91], v[48:63]
	v_cndmask_b32_e64 v0, 0, 1, s[52:53]
	v_cmp_ne_u32_e64 s[50:51], 1, v0
	s_andn2_b64 vcc, exec, s[52:53]
	s_cbranch_vccnz .LBB0_462
.LBB0_458:
	ds_read_b64_tr_b16 v[128:129], v204
	ds_read_b64_tr_b16 v[130:131], v204 offset:1024
	ds_read_b64_tr_b16 v[10:11], v205
	ds_read_b64_tr_b16 v[12:13], v205 offset:1024
	ds_read_b64_tr_b16 v[6:7], v204 offset:2048
	ds_read_b64_tr_b16 v[8:9], v204 offset:3072
	ds_read_b64_tr_b16 v[2:3], v205 offset:2048
	ds_read_b64_tr_b16 v[4:5], v205 offset:3072
	ds_read_b128 v[80:83], v159 offset:4096
	ds_read_b128 v[142:145], v158 offset:4096
	s_waitcnt lgkmcnt(0)
	v_mfma_f32_32x32x16_bf16 v[80:95], v[80:83], v[96:99], 0
	v_mfma_f32_32x32x16_bf16 v[80:95], v[142:145], v[100:103], v[80:95]
	ds_read_b128 v[142:145], v157 offset:4096
	s_waitcnt lgkmcnt(0)
	v_mfma_f32_32x32x16_bf16 v[80:95], v[142:145], v[104:107], v[80:95]
	ds_read_b128 v[142:145], v156 offset:4096
	ds_read_b128 v[160:163], v202 offset:49280
	ds_read_b128 v[164:167], v202 offset:49312
	s_waitcnt lgkmcnt(0)
	v_mfma_f32_32x32x16_bf16 v[80:95], v[142:145], v[108:111], v[80:95]
	s_nop 11
	v_fma_f32 v144, v132, v160, v80
	v_fma_f32 v145, v133, v161, v81
	v_fma_f32 v80, v132, v164, v84
	v_fma_f32 v81, v133, v165, v85
	v_fma_f32 v14, v132, v166, v86
	v_fma_f32 v15, v133, v167, v87
	ds_read_b128 v[84:87], v202 offset:49344
	v_fma_f32 v142, v132, v162, v82
	v_fma_f32 v143, v133, v163, v83
	v_max_f32_e32 v0, v144, v145
	v_max3_f32 v0, v0, v142, v143
	v_max3_f32 v0, v0, v80, v81
	s_waitcnt lgkmcnt(0)
	v_fma_f32 v84, v132, v84, v88
	v_fma_f32 v85, v133, v85, v89
	v_fma_f32 v82, v132, v86, v90
	v_fma_f32 v83, v133, v87, v91
	ds_read_b128 v[86:89], v202 offset:49376
	v_max3_f32 v0, v0, v14, v15
	v_max3_f32 v0, v0, v84, v85
	v_max3_f32 v0, v0, v82, v83
	s_waitcnt lgkmcnt(0)
	v_fma_f32 v86, v132, v86, v92
	v_fma_f32 v87, v133, v87, v93
	v_fma_f32 v88, v132, v88, v94
	v_fma_f32 v89, v133, v89, v95
	v_max3_f32 v0, v0, v86, v87
	v_max3_f32 v0, v0, v88, v89
	v_mov_b32_e32 v90, v0
	s_nop 1
	v_permlane32_swap_b32_e32 v0, v90
	v_max_f32_e32 v90, v90, v90
	v_max_f32_e32 v0, v0, v0
	v_max_f32_e32 v0, v0, v90
	v_sub_f32_e32 v90, v0, v134
	v_cmp_lt_f32_e32 vcc, s9, v90
	s_cbranch_vccz .LBB0_460
	v_max_f32_e32 v0, v0, v0
	v_max_f32_e32 v90, v134, v134
	v_max_f32_e32 v0, v90, v0
	v_sub_f32_e32 v90, v134, v0
	v_exp_f32_e32 v90, v90
	v_mov_b32_e32 v134, v0
	v_mul_f32_e32 v154, v154, v90
	v_mul_f32_e32 v46, v46, v90
	v_mul_f32_e32 v47, v47, v90
	v_mul_f32_e32 v44, v44, v90
	v_mul_f32_e32 v45, v45, v90
	v_mul_f32_e32 v42, v42, v90
	v_mul_f32_e32 v43, v43, v90
	v_mul_f32_e32 v40, v40, v90
	v_mul_f32_e32 v41, v41, v90
	v_mul_f32_e32 v38, v38, v90
	v_mul_f32_e32 v39, v39, v90
	v_mul_f32_e32 v36, v36, v90
	v_mul_f32_e32 v37, v37, v90
	v_mul_f32_e32 v34, v34, v90
	v_mul_f32_e32 v35, v35, v90
	v_mul_f32_e32 v32, v32, v90
	v_mul_f32_e32 v33, v33, v90
	v_mul_f32_e32 v30, v30, v90
	v_mul_f32_e32 v31, v31, v90
	v_mul_f32_e32 v28, v28, v90
	v_mul_f32_e32 v29, v29, v90
	v_mul_f32_e32 v26, v26, v90
	v_mul_f32_e32 v27, v27, v90
	v_mul_f32_e32 v24, v24, v90
	v_mul_f32_e32 v25, v25, v90
	v_mul_f32_e32 v22, v22, v90
	v_mul_f32_e32 v23, v23, v90
	v_mul_f32_e32 v20, v20, v90
	v_mul_f32_e32 v21, v21, v90
	v_mul_f32_e32 v18, v18, v90
	v_mul_f32_e32 v19, v19, v90
	v_mul_f32_e32 v16, v16, v90
	v_mul_f32_e32 v17, v17, v90
	s_branch .LBB0_461

; template <bool MASK> ...
;     s16x4 l00, h00, l01, h01, l10, h10, l11, h11; { const unsigned a0 = va0 + sub * 4096, a1 = va1 + sub * 4096;
;       asm volatile("ds_read_b64_tr_b16 %0, %1" : "=&v"(l00) : "v"(a0) : "memory"); asm volatile("ds_read_b64_tr_b16 %0, %1 offset:1024" : "=&v"(h00) : "v"(a0) : "memory");
;       asm volatile("ds_read_b64_tr_b16 %0, %1" : "=&v"(l01) : "v"(a1) : "memory"); asm volatile("ds_read_b64_tr_b16 %0, %1 offset:1024" : "=&v"(h01) : "v"(a1) : "memory");
;       asm volatile("ds_read_b64_tr_b16 %0, %1 offset:2048" : "=&v"(l10) : "v"(a0) : "memory"); asm volatile("ds_read_b64_tr_b16 %0, %1 offset:3072" : "=&v"(h10) : "v"(a0) : "memory");
;       asm volatile("ds_read_b64_tr_b16 %0, %1 offset:2048" : "=&v"(l11) : "v"(a1) : "memory"); asm volatile("ds_read_b64_tr_b16 %0, %1 offset:3072" : "=&v"(h11) : "v"(a1) : "memory"); }
;     const int r = lane & 31, hh = lane >> 5;
;     f32x16 st = {0.f, 0.f, 0.f, 0.f, 0.f, 0.f, 0.f, 0.f, 0.f, 0.f, 0.f, 0.f, 0.f, 0.f, 0.f, 0.f};
;     { const int key = sub * 32 + r; const LAS char* kp = Kt + key * 128; const int ksw = (key >> 1) & 7;
; #pragma unroll
;       for (int d0 = 0; d0 < 4; ++d0) { const bf16x8 kf = *(const LAS bf16x8*)(kp + (((2 * d0 + hh) ^ ksw) << 4)); st = __builtin_amdgcn_mfma_f32_32x32x16_bf16(kf, qr[d0], st, 0, 0, 0); } }
;     f32x2_t sp[8]; const f32x2_t cs2 = {cscale, cscale};
; #pragma unroll
;     for (int g = 0; g < 4; ++g) { const f32x4 c4 = *(const LAS f32x4*)(cb + sub * 32 + 8 * g + 4 * hh);
;         sp[2 * g] = (f32x2_t){st[4 * g], st[4 * g + 1]} + cs2 * (f32x2_t){c4[0], c4[1]};
;         sp[2 * g + 1] = (f32x2_t){st[4 * g + 2], st[4 * g + 3]} + cs2 * (f32x2_t){c4[2], c4[3]};
;         if (MASK) {
; #pragma unroll
;             for (int e = 0; e < 4; ++e) { const int kpos = kpos_sub + 8 * g + 4 * hh + e; const bool ok = (kpos <= qpos && kpos >= qpos - win);
;                 sp[2 * g + (e >> 1)][e & 1] = ok ? sp[2 * g + (e >> 1)][e & 1] : -INFINITY; } } }
;     float rm = fmaxf(sp[0][0], sp[0][1]);
; #pragma unroll
;     for (int i = 1; i < 8; ++i) rm = fmaxf(fmaxf(rm, sp[i][0]), sp[i][1]);
;     rm = swap_max(rm);
;     if (__any(rm - m > 8.0f)) { const float mnew = fmaxf(m, rm); const float f = fast_exp2(m - mnew); l *= f; o0 = o0 * f; o1 = o1 * f; m = mnew; }
;     { const f32x2_t m2 = {m, m}; f32x2_t ps2 = {0.f, 0.f};
; #pragma unroll
.LBB0_461:
	v_sub_f32_e32 v90, v144, v0
	v_sub_f32_e32 v91, v145, v0
	v_sub_f32_e32 v94, v142, v0
	v_sub_f32_e32 v95, v143, v0
	v_exp_f32_e32 v90, v90
	v_exp_f32_e32 v91, v91
	v_exp_f32_e32 v94, v94
	v_exp_f32_e32 v95, v95
	v_sub_f32_e32 v80, v80, v0
	v_sub_f32_e32 v81, v81, v0
	v_sub_f32_e32 v14, v14, v0
	v_sub_f32_e32 v15, v15, v0
	v_exp_f32_e32 v142, v80
	v_exp_f32_e32 v143, v81
	v_add_f32_e32 v92, 0, v90
	v_add_f32_e32 v93, 0, v91
	v_exp_f32_e32 v14, v14
	v_exp_f32_e32 v15, v15
	v_sub_f32_e32 v84, v84, v0
	v_sub_f32_e32 v85, v85, v0
	v_add_f32_e32 v92, v94, v92
	v_add_f32_e32 v93, v95, v93
	v_exp_f32_e32 v84, v84
	v_exp_f32_e32 v85, v85
	v_sub_f32_e32 v82, v82, v0
	v_sub_f32_e32 v83, v83, v0
	v_add_f32_e32 v80, v142, v92
	v_add_f32_e32 v81, v143, v93
	v_exp_f32_e32 v92, v82
	v_exp_f32_e32 v93, v83
	v_sub_f32_e32 v82, v86, v0
	v_sub_f32_e32 v83, v87, v0
	v_add_f32_e32 v80, v14, v80
	v_add_f32_e32 v81, v15, v81
	v_exp_f32_e32 v86, v82
	v_exp_f32_e32 v87, v83
	v_sub_f32_e32 v82, v88, v0
	v_sub_f32_e32 v83, v89, v0
	v_add_f32_e32 v80, v84, v80
	v_add_f32_e32 v81, v85, v81
	v_exp_f32_e32 v88, v82
	v_exp_f32_e32 v89, v83
	v_add_f32_e32 v80, v92, v80
	v_add_f32_e32 v81, v93, v81
	v_cvt_pk_bf16_f32 v82, v142, v143
	v_add_f32_e32 v80, v86, v80
	v_add_f32_e32 v81, v87, v81
	v_cvt_pk_bf16_f32 v83, v14, v15
	v_add_f32_e32 v80, v88, v80
	v_add_f32_e32 v81, v89, v81
	s_waitcnt lgkmcnt(0)
	v_cvt_pk_bf16_f32 v84, v84, v85
	v_add_f32_e32 v0, v80, v81
	v_cvt_pk_bf16_f32 v80, v90, v91
	v_cvt_pk_bf16_f32 v81, v94, v95
	v_cvt_pk_bf16_f32 v85, v92, v93
	v_cvt_pk_bf16_f32 v86, v86, v87
	v_mfma_f32_32x32x16_bf16 v[32:47], v[128:131], v[80:83], v[32:47]
	v_cvt_pk_bf16_f32 v87, v88, v89
	v_add_f32_e32 v154, v154, v0
	v_mfma_f32_32x32x16_bf16 v[16:31], v[10:13], v[80:83], v[16:31]
	v_mfma_f32_32x32x16_bf16 v[32:47], v[6:9], v[84:87], v[32:47]
	v_mfma_f32_32x32x16_bf16 v[16:31], v[2:5], v[84:87], v[16:31]
.LBB0_462:
	v_cndmask_b32_e64 v0, 0, 1, s[18:19]
	v_cmp_ne_u32_e64 s[52:53], 1, v0
	s_andn2_b64 vcc, exec, s[18:19]
	s_cbranch_vccnz .LBB0_467
	ds_read_b64_tr_b16 v[128:129], v204
	ds_read_b64_tr_b16 v[130:131], v204 offset:1024
	ds_read_b64_tr_b16 v[10:11], v205
	ds_read_b64_tr_b16 v[12:13], v205 offset:1024
	ds_read_b64_tr_b16 v[6:7], v204 offset:2048
	ds_read_b64_tr_b16 v[8:9], v204 offset:3072
	ds_read_b64_tr_b16 v[2:3], v205 offset:2048
	ds_read_b64_tr_b16 v[4:5], v205 offset:3072
	ds_read_b128 v[80:83], v159 offset:4096
	ds_read_b128 v[142:145], v158 offset:4096
	s_waitcnt lgkmcnt(0)
	v_mfma_f32_32x32x16_bf16 v[80:95], v[80:83], v[112:115], 0
	v_mfma_f32_32x32x16_bf16 v[80:95], v[142:145], v[116:119], v[80:95]
	ds_read_b128 v[142:145], v157 offset:4096
	s_waitcnt lgkmcnt(0)
	v_mfma_f32_32x32x16_bf16 v[80:95], v[142:145], v[120:123], v[80:95]
	ds_read_b128 v[142:145], v156 offset:4096
	ds_read_b128 v[156:159], v202 offset:49280
	ds_read_b128 v[160:163], v202 offset:49312
	s_waitcnt lgkmcnt(0)
	v_mfma_f32_32x32x16_bf16 v[80:95], v[142:145], v[124:127], v[80:95]
	s_nop 11
	v_fma_f32 v144, v132, v156, v80
	v_fma_f32 v145, v133, v157, v81
	v_fma_f32 v80, v132, v160, v84
	v_fma_f32 v81, v133, v161, v85
	v_fma_f32 v14, v132, v162, v86
	v_fma_f32 v15, v133, v163, v87
	ds_read_b128 v[84:87], v202 offset:49344
	v_fma_f32 v142, v132, v158, v82
	v_fma_f32 v143, v133, v159, v83
	v_max_f32_e32 v0, v144, v145
	v_max3_f32 v0, v0, v142, v143
	v_max3_f32 v0, v0, v80, v81
	s_waitcnt lgkmcnt(0)
	v_fma_f32 v84, v132, v84, v88
	v_fma_f32 v85, v133, v85, v89
	v_fma_f32 v82, v132, v86, v90
	v_fma_f32 v83, v133, v87, v91
	ds_read_b128 v[86:89], v202 offset:49376
	v_max3_f32 v0, v0, v14, v15
	v_max3_f32 v0, v0, v84, v85
	v_max3_f32 v0, v0, v82, v83
	s_waitcnt lgkmcnt(0)
	v_fma_f32 v86, v132, v86, v92
	v_fma_f32 v87, v133, v87, v93
	v_fma_f32 v88, v132, v88, v94
	v_fma_f32 v89, v133, v89, v95
	v_max3_f32 v0, v0, v86, v87
	v_max3_f32 v0, v0, v88, v89
	v_mov_b32_e32 v90, v0
	s_nop 1
	v_permlane32_swap_b32_e32 v0, v90
	v_max_f32_e32 v90, v90, v90
	v_max_f32_e32 v0, v0, v0
	v_max_f32_e32 v0, v0, v90
	v_sub_f32_e32 v90, v0, v136
	v_cmp_lt_f32_e32 vcc, s9, v90
	s_cbranch_vccz .LBB0_465
	v_max_f32_e32 v0, v0, v0
	v_max_f32_e32 v90, v136, v136
	v_max_f32_e32 v0, v90, v0
	v_sub_f32_e32 v90, v136, v0
	v_exp_f32_e32 v90, v90
	v_mov_b32_e32 v136, v0
	v_mul_f32_e32 v155, v155, v90
	v_mul_f32_e32 v78, v78, v90
	v_mul_f32_e32 v79, v79, v90
	v_mul_f32_e32 v76, v76, v90
	v_mul_f32_e32 v77, v77, v90
	v_mul_f32_e32 v74, v74, v90
	v_mul_f32_e32 v75, v75, v90
	v_mul_f32_e32 v72, v72, v90
	v_mul_f32_e32 v73, v73, v90
	v_mul_f32_e32 v70, v70, v90
	v_mul_f32_e32 v71, v71, v90
	v_mul_f32_e32 v68, v68, v90
	v_mul_f32_e32 v69, v69, v90
	v_mul_f32_e32 v66, v66, v90
	v_mul_f32_e32 v67, v67, v90
	v_mul_f32_e32 v64, v64, v90
	v_mul_f32_e32 v65, v65, v90
	v_mul_f32_e32 v62, v62, v90
	v_mul_f32_e32 v63, v63, v90
	v_mul_f32_e32 v60, v60, v90
	v_mul_f32_e32 v61, v61, v90
	v_mul_f32_e32 v58, v58, v90
	v_mul_f32_e32 v59, v59, v90
	v_mul_f32_e32 v56, v56, v90
	v_mul_f32_e32 v57, v57, v90
	v_mul_f32_e32 v54, v54, v90
	v_mul_f32_e32 v55, v55, v90
	v_mul_f32_e32 v52, v52, v90
	v_mul_f32_e32 v53, v53, v90
	v_mul_f32_e32 v50, v50, v90
	v_mul_f32_e32 v51, v51, v90
	v_mul_f32_e32 v48, v48, v90
	v_mul_f32_e32 v49, v49, v90
	s_branch .LBB0_466

; __device__ __forceinline__ unsigned cvt_pk_bf16(float lo, float hi) { f32x2_t v = {lo, hi}; bf16x2_t b = __builtin_convertvector(v, bf16x2_t); return __builtin_bit_cast(unsigned, b); }
; __device__ __forceinline__ float fast_exp2(float x) { return __builtin_amdgcn_exp2f(x); }
; template <bool MASK> ...
;     ...
;     { const f32x2_t m2 = {m, m}; f32x2_t ps2 = {0.f, 0.f};
; #pragma unroll
;       for (int i = 0; i < 8; ++i) { f32x2_t t = sp[i] - m2; t[0] = fast_exp2(t[0]); t[1] = fast_exp2(t[1]); sp[i] = t; ps2 = ps2 + t; }
;       l += ps2[0] + ps2[1]; }
;     u32x4 pw0, pw1;
;     pw0.x = cvt_pk_bf16(sp[0][0], sp[0][1]); pw0.y = cvt_pk_bf16(sp[1][0], sp[1][1]); pw0.z = cvt_pk_bf16(sp[2][0], sp[2][1]); pw0.w = cvt_pk_bf16(sp[3][0], sp[3][1]);
;     pw1.x = cvt_pk_bf16(sp[4][0], sp[4][1]); pw1.y = cvt_pk_bf16(sp[5][0], sp[5][1]); pw1.z = cvt_pk_bf16(sp[6][0], sp[6][1]); pw1.w = cvt_pk_bf16(sp[7][0], sp[7][1]);
;     asm volatile("s_waitcnt lgkmcnt(0)" : "+v"(l00), "+v"(h00), "+v"(l01), "+v"(h01), "+v"(l10), "+v"(h10), "+v"(l11), "+v"(h11) :: "memory");
;     { const bf16x8 pb0 = __builtin_bit_cast(bf16x8, pw0), pb1 = __builtin_bit_cast(bf16x8, pw1);
;       const bf16x8 v00 = {l00[0], l00[1], l00[2], l00[3], h00[0], h00[1], h00[2], h00[3]}, v01 = {l01[0], l01[1], l01[2], l01[3], h01[0], h01[1], h01[2], h01[3]};
;       const bf16x8 v10 = {l10[0], l10[1], l10[2], l10[3], h10[0], h10[1], h10[2], h10[3]}, v11 = {l11[0], l11[1], l11[2], l11[3], h11[0], h11[1], h11[2], h11[3]};
;       o0 = __builtin_amdgcn_mfma_f32_32x32x16_bf16(v00, pb0, o0, 0, 0, 0); o1 = __builtin_amdgcn_mfma_f32_32x32x16_bf16(v01, pb0, o1, 0, 0, 0);
;       o0 = __builtin_amdgcn_mfma_f32_32x32x16_bf16(v10, pb1, o0, 0, 0, 0); o1 = __builtin_amdgcn_mfma_f32_32x32x16_bf16(v11, pb1, o1, 0, 0, 0); }
.LBB0_466:
	v_sub_f32_e32 v90, v144, v0
	v_sub_f32_e32 v91, v145, v0
	v_sub_f32_e32 v94, v142, v0
	v_sub_f32_e32 v95, v143, v0
	v_exp_f32_e32 v90, v90
	v_exp_f32_e32 v91, v91
	v_exp_f32_e32 v94, v94
	v_exp_f32_e32 v95, v95
	v_sub_f32_e32 v80, v80, v0
	v_sub_f32_e32 v81, v81, v0
	v_sub_f32_e32 v14, v14, v0
	v_sub_f32_e32 v15, v15, v0
	v_exp_f32_e32 v142, v80
	v_exp_f32_e32 v143, v81
	v_add_f32_e32 v92, 0, v90
	v_add_f32_e32 v93, 0, v91
	v_exp_f32_e32 v14, v14
	v_exp_f32_e32 v15, v15
	v_sub_f32_e32 v84, v84, v0
	v_sub_f32_e32 v85, v85, v0
	v_add_f32_e32 v92, v94, v92
	v_add_f32_e32 v93, v95, v93
	v_exp_f32_e32 v84, v84
	v_exp_f32_e32 v85, v85
	v_sub_f32_e32 v82, v82, v0
	v_sub_f32_e32 v83, v83, v0
	v_add_f32_e32 v80, v142, v92
	v_add_f32_e32 v81, v143, v93
	v_exp_f32_e32 v92, v82
	v_exp_f32_e32 v93, v83
	v_sub_f32_e32 v82, v86, v0
	v_sub_f32_e32 v83, v87, v0
	v_add_f32_e32 v80, v14, v80
	v_add_f32_e32 v81, v15, v81
	v_exp_f32_e32 v86, v82
	v_exp_f32_e32 v87, v83
	v_sub_f32_e32 v82, v88, v0
	v_sub_f32_e32 v83, v89, v0
	v_add_f32_e32 v80, v84, v80
	v_add_f32_e32 v81, v85, v81
	v_exp_f32_e32 v88, v82
	v_exp_f32_e32 v89, v83
	v_add_f32_e32 v80, v92, v80
	v_add_f32_e32 v81, v93, v81
	v_cvt_pk_bf16_f32 v82, v142, v143
	v_add_f32_e32 v80, v86, v80
	v_add_f32_e32 v81, v87, v81
	v_cvt_pk_bf16_f32 v83, v14, v15
	v_add_f32_e32 v80, v88, v80
	v_add_f32_e32 v81, v89, v81
	s_waitcnt lgkmcnt(0)
	v_cvt_pk_bf16_f32 v84, v84, v85
	v_add_f32_e32 v0, v80, v81
	v_cvt_pk_bf16_f32 v80, v90, v91
	v_cvt_pk_bf16_f32 v81, v94, v95
	v_cvt_pk_bf16_f32 v85, v92, v93
	v_cvt_pk_bf16_f32 v86, v86, v87
	v_mfma_f32_32x32x16_bf16 v[64:79], v[128:131], v[80:83], v[64:79]
	v_cvt_pk_bf16_f32 v87, v88, v89
	v_add_f32_e32 v155, v155, v0
	v_mfma_f32_32x32x16_bf16 v[48:63], v[10:13], v[80:83], v[48:63]
	v_mfma_f32_32x32x16_bf16 v[64:79], v[6:9], v[84:87], v[64:79]
	v_mfma_f32_32x32x16_bf16 v[48:63], v[2:5], v[84:87], v[48:63]

; __device__ __forceinline__ unsigned cvt_pk_bf16(float lo, float hi) { f32x2_t v = {lo, hi}; bf16x2_t b = __builtin_convertvector(v, bf16x2_t); return __builtin_bit_cast(unsigned, b); }
; __device__ __forceinline__ float fast_exp2(float x) { return __builtin_amdgcn_exp2f(x); }
; template <bool MASK> ...
;     ...
;     if (__any(rm - m > 8.0f)) { const float mnew = fmaxf(m, rm); const float f = fast_exp2(m - mnew); l *= f; o0 = o0 * f; o1 = o1 * f; m = mnew; }
;     { const f32x2_t m2 = {m, m}; f32x2_t ps2 = {0.f, 0.f};
; #pragma unroll
;       for (int i = 0; i < 8; ++i) { f32x2_t t = sp[i] - m2; t[0] = fast_exp2(t[0]); t[1] = fast_exp2(t[1]); sp[i] = t; ps2 = ps2 + t; }
;       l += ps2[0] + ps2[1]; }
;     u32x4 pw0, pw1;
;     pw0.x = cvt_pk_bf16(sp[0][0], sp[0][1]); pw0.y = cvt_pk_bf16(sp[1][0], sp[1][1]); pw0.z = cvt_pk_bf16(sp[2][0], sp[2][1]); pw0.w = cvt_pk_bf16(sp[3][0], sp[3][1]);
;     pw1.x = cvt_pk_bf16(sp[4][0], sp[4][1]); pw1.y = cvt_pk_bf16(sp[5][0], sp[5][1]); pw1.z = cvt_pk_bf16(sp[6][0], sp[6][1]); pw1.w = cvt_pk_bf16(sp[7][0], sp[7][1]);
;     asm volatile("s_waitcnt lgkmcnt(0)" : "+v"(l00), "+v"(h00), "+v"(l01), "+v"(h01), "+v"(l10), "+v"(h10), "+v"(l11), "+v"(h11) :: "memory");
;     { const bf16x8 pb0 = __builtin_bit_cast(bf16x8, pw0), pb1 = __builtin_bit_cast(bf16x8, pw1);
;       const bf16x8 v00 = {l00[0], l00[1], l00[2], l00[3], h00[0], h00[1], h00[2], h00[3]}, v01 = {l01[0], l01[1], l01[2], l01[3], h01[0], h01[1], h01[2], h01[3]};
;       const bf16x8 v10 = {l10[0], l10[1], l10[2], l10[3], h10[0], h10[1], h10[2], h10[3]}, v11 = {l11[0], l11[1], l11[2], l11[3], h11[0], h11[1], h11[2], h11[3]};
;       o0 = __builtin_amdgcn_mfma_f32_32x32x16_bf16(v00, pb0, o0, 0, 0, 0); o1 = __builtin_amdgcn_mfma_f32_32x32x16_bf16(v01, pb0, o1, 0, 0, 0);
;       o0 = __builtin_amdgcn_mfma_f32_32x32x16_bf16(v10, pb1, o0, 0, 0, 0); o1 = __builtin_amdgcn_mfma_f32_32x32x16_bf16(v11, pb1, o1, 0, 0, 0); }
.LBB0_468:
	v_max_f32_e32 v0, v0, v0
	v_max_f32_e32 v92, v136, v136
	v_max_f32_e32 v0, v92, v0
	v_sub_f32_e32 v92, v136, v0
	v_exp_f32_e32 v92, v92
	v_mov_b32_e32 v136, v0
	v_mul_f32_e32 v155, v155, v92
	v_mul_f32_e32 v78, v78, v92
	v_mul_f32_e32 v79, v79, v92
	v_mul_f32_e32 v76, v76, v92
	v_mul_f32_e32 v77, v77, v92
	v_mul_f32_e32 v74, v74, v92
	v_mul_f32_e32 v75, v75, v92
	v_mul_f32_e32 v72, v72, v92
	v_mul_f32_e32 v73, v73, v92
	v_mul_f32_e32 v70, v70, v92
	v_mul_f32_e32 v71, v71, v92
	v_mul_f32_e32 v68, v68, v92
	v_mul_f32_e32 v69, v69, v92
	v_mul_f32_e32 v66, v66, v92
	v_mul_f32_e32 v67, v67, v92
	v_mul_f32_e32 v64, v64, v92
	v_mul_f32_e32 v65, v65, v92
	v_mul_f32_e32 v62, v62, v92
	v_mul_f32_e32 v63, v63, v92
	v_mul_f32_e32 v60, v60, v92
	v_mul_f32_e32 v61, v61, v92
	v_mul_f32_e32 v58, v58, v92
	v_mul_f32_e32 v59, v59, v92
	v_mul_f32_e32 v56, v56, v92
	v_mul_f32_e32 v57, v57, v92
	v_mul_f32_e32 v54, v54, v92
	v_mul_f32_e32 v55, v55, v92
	v_mul_f32_e32 v52, v52, v92
	v_mul_f32_e32 v53, v53, v92
	v_mul_f32_e32 v50, v50, v92
	v_mul_f32_e32 v51, v51, v92
	v_mul_f32_e32 v48, v48, v92
	v_mul_f32_e32 v49, v49, v92
.LBB0_469:
	v_sub_f32_e32 v92, v142, v0
	v_sub_f32_e32 v93, v143, v0
	v_sub_f32_e32 v140, v140, v0
	v_sub_f32_e32 v141, v141, v0
	v_exp_f32_e32 v92, v92
	v_exp_f32_e32 v93, v93
	v_exp_f32_e32 v140, v140
	v_exp_f32_e32 v141, v141
	v_sub_f32_e32 v82, v82, v0
	v_sub_f32_e32 v83, v83, v0
	v_sub_f32_e32 v80, v80, v0
	v_sub_f32_e32 v81, v81, v0
	v_exp_f32_e32 v82, v82
	v_exp_f32_e32 v83, v83
	v_exp_f32_e32 v142, v80
	v_exp_f32_e32 v143, v81
	v_add_f32_e32 v94, 0, v92
	v_add_f32_e32 v95, 0, v93
	v_sub_f32_e32 v86, v86, v0
	v_sub_f32_e32 v87, v87, v0
	v_add_f32_e32 v94, v140, v94
	v_add_f32_e32 v95, v141, v95
	v_exp_f32_e32 v86, v86
	v_add_f32_e32 v94, v82, v94
	v_add_f32_e32 v95, v83, v95
	v_exp_f32_e32 v87, v87
	v_sub_f32_e32 v84, v84, v0
	v_sub_f32_e32 v85, v85, v0
	v_add_f32_e32 v80, v142, v94
	v_add_f32_e32 v81, v143, v95
	v_exp_f32_e32 v94, v84
	v_exp_f32_e32 v95, v85
	v_sub_f32_e32 v84, v88, v0
	v_sub_f32_e32 v85, v89, v0
	v_add_f32_e32 v80, v86, v80
	v_add_f32_e32 v81, v87, v81
	v_exp_f32_e32 v88, v84
	v_exp_f32_e32 v89, v85
	v_sub_f32_e32 v84, v90, v0
	v_sub_f32_e32 v85, v91, v0
	v_add_f32_e32 v80, v94, v80
	v_add_f32_e32 v81, v95, v81
	v_exp_f32_e32 v90, v84
	v_exp_f32_e32 v91, v85
	v_add_f32_e32 v80, v88, v80
	v_add_f32_e32 v81, v89, v81
	v_cvt_pk_bf16_f32 v82, v82, v83
	v_cvt_pk_bf16_f32 v83, v142, v143
	v_add_f32_e32 v80, v90, v80
	v_add_f32_e32 v81, v91, v81
	s_waitcnt lgkmcnt(0)
	v_cvt_pk_bf16_f32 v84, v86, v87
	v_add_f32_e32 v0, v80, v81
	v_cvt_pk_bf16_f32 v80, v92, v93
	v_cvt_pk_bf16_f32 v81, v140, v141
	v_cvt_pk_bf16_f32 v85, v94, v95
	v_cvt_pk_bf16_f32 v86, v88, v89
	v_mfma_f32_32x32x16_bf16 v[64:79], v[128:131], v[80:83], v[64:79]
	v_cvt_pk_bf16_f32 v87, v90, v91
	v_add_f32_e32 v155, v155, v0
	v_mfma_f32_32x32x16_bf16 v[48:63], v[10:13], v[80:83], v[48:63]
	v_mfma_f32_32x32x16_bf16 v[64:79], v[6:9], v[84:87], v[64:79]
	v_mfma_f32_32x32x16_bf16 v[48:63], v[2:5], v[84:87], v[48:63]

; #define LAS __attribute__((address_space(3)))
; template <bool MASK> ...
;     s16x4 l00, h00, l01, h01, l10, h10, l11, h11; { const unsigned a0 = va0 + sub * 4096, a1 = va1 + sub * 4096;
;       asm volatile("ds_read_b64_tr_b16 %0, %1" : "=&v"(l00) : "v"(a0) : "memory"); asm volatile("ds_read_b64_tr_b16 %0, %1 offset:1024" : "=&v"(h00) : "v"(a0) : "memory");
;       asm volatile("ds_read_b64_tr_b16 %0, %1" : "=&v"(l01) : "v"(a1) : "memory"); asm volatile("ds_read_b64_tr_b16 %0, %1 offset:1024" : "=&v"(h01) : "v"(a1) : "memory");
;       asm volatile("ds_read_b64_tr_b16 %0, %1 offset:2048" : "=&v"(l10) : "v"(a0) : "memory"); asm volatile("ds_read_b64_tr_b16 %0, %1 offset:3072" : "=&v"(h10) : "v"(a0) : "memory");
;       asm volatile("ds_read_b64_tr_b16 %0, %1 offset:2048" : "=&v"(l11) : "v"(a1) : "memory"); asm volatile("ds_read_b64_tr_b16 %0, %1 offset:3072" : "=&v"(h11) : "v"(a1) : "memory"); }
;     const int r = lane & 31, hh = lane >> 5;
;     f32x16 st = {0.f, 0.f, 0.f, 0.f, 0.f, 0.f, 0.f, 0.f, 0.f, 0.f, 0.f, 0.f, 0.f, 0.f, 0.f, 0.f};
;     { const int key = sub * 32 + r; const LAS char* kp = Kt + key * 128; const int ksw = (key >> 1) & 7;
; #pragma unroll
;       for (int d0 = 0; d0 < 4; ++d0) { const bf16x8 kf = *(const LAS bf16x8*)(kp + (((2 * d0 + hh) ^ ksw) << 4)); st = __builtin_amdgcn_mfma_f32_32x32x16_bf16(kf, qr[d0], st, 0, 0, 0); } }
;     f32x2_t sp[8]; const f32x2_t cs2 = {cscale, cscale};
; #pragma unroll
;     for (int g = 0; g < 4; ++g) { const f32x4 c4 = *(const LAS f32x4*)(cb + sub * 32 + 8 * g + 4 * hh);
;         sp[2 * g] = (f32x2_t){st[4 * g], st[4 * g + 1]} + cs2 * (f32x2_t){c4[0], c4[1]};
;         sp[2 * g + 1] = (f32x2_t){st[4 * g + 2], st[4 * g + 3]} + cs2 * (f32x2_t){c4[2], c4[3]};
;         if (MASK) {
; #pragma unroll
;             for (int e = 0; e < 4; ++e) { const int kpos = kpos_sub + 8 * g + 4 * hh + e; const bool ok = (kpos <= qpos && kpos >= qpos - win);
;                 sp[2 * g + (e >> 1)][e & 1] = ok ? sp[2 * g + (e >> 1)][e & 1] : -INFINITY; } } }
;     float rm = fmaxf(sp[0][0], sp[0][1]);
; #pragma unroll
;     for (int i = 1; i < 8; ++i) rm = fmaxf(fmaxf(rm, sp[i][0]), sp[i][1]);
;     rm = swap_max(rm);
;     if (__any(rm - m > 8.0f)) { const float mnew = fmaxf(m, rm); const float f = fast_exp2(m - mnew); l *= f; o0 = o0 * f; o1 = o1 * f; m = mnew; }
.LBB0_478:
	s_and_b64 s[12:13], exec, s[18:19]
	s_cselect_b32 s5, 0, s4
	s_lshl_b32 s12, s5, 13
	s_add_i32 s13, s12, 0
	s_lshl_b32 s5, s5, 8
	v_add_u32_e32 v0, s13, v198
	v_add_u32_e32 v159, s12, v189
	v_add_u32_e32 v160, s12, v190
	s_and_b64 vcc, exec, s[50:51]
	v_add_u32_e32 v144, s5, v202
	v_add_u32_e32 v158, v0, v191
	v_add_u32_e32 v157, v0, v192
	v_add_u32_e32 v156, v0, v193
	v_add_u32_e32 v145, v0, v196
	s_cbranch_vccnz .LBB0_481
	ds_read_b64_tr_b16 v[128:129], v159
	ds_read_b64_tr_b16 v[130:131], v159 offset:1024
	ds_read_b64_tr_b16 v[10:11], v160
	ds_read_b64_tr_b16 v[12:13], v160 offset:1024
	ds_read_b64_tr_b16 v[6:7], v159 offset:2048
	ds_read_b64_tr_b16 v[8:9], v159 offset:3072
	ds_read_b64_tr_b16 v[2:3], v160 offset:2048
	ds_read_b64_tr_b16 v[4:5], v160 offset:3072
	ds_read_b128 v[80:83], v158
	ds_read_b128 v[140:143], v157
	s_waitcnt lgkmcnt(0)
	v_mfma_f32_32x32x16_bf16 v[80:95], v[80:83], v[96:99], 0
	v_mfma_f32_32x32x16_bf16 v[80:95], v[140:143], v[100:103], v[80:95]
	ds_read_b128 v[140:143], v156
	s_waitcnt lgkmcnt(0)
	v_mfma_f32_32x32x16_bf16 v[80:95], v[140:143], v[104:107], v[80:95]
	ds_read_b128 v[140:143], v145
	ds_read_b128 v[162:165], v144 offset:49152
	ds_read_b128 v[166:169], v144 offset:49184
	s_waitcnt lgkmcnt(0)
	v_mfma_f32_32x32x16_bf16 v[80:95], v[140:143], v[108:111], v[80:95]
	s_nop 11
	v_fma_f32 v142, v132, v162, v80
	v_fma_f32 v143, v133, v163, v81
	v_fma_f32 v140, v132, v164, v82
	v_fma_f32 v141, v133, v165, v83
	ds_read_b128 v[162:165], v144 offset:49216
	v_fma_f32 v82, v132, v166, v84
	v_fma_f32 v83, v133, v167, v85
	v_fma_f32 v80, v132, v168, v86
	v_fma_f32 v81, v133, v169, v87
	v_max_f32_e32 v0, v142, v143
	v_max3_f32 v0, v0, v140, v141
	s_waitcnt lgkmcnt(0)
	v_fma_f32 v86, v132, v162, v88
	v_fma_f32 v87, v133, v163, v89
	v_fma_f32 v84, v132, v164, v90
	v_fma_f32 v85, v133, v165, v91
	ds_read_b128 v[88:91], v144 offset:49248
	v_max3_f32 v0, v0, v82, v83
	v_max3_f32 v0, v0, v80, v81
	v_max3_f32 v0, v0, v86, v87
	v_max3_f32 v0, v0, v84, v85
	s_waitcnt lgkmcnt(0)
	v_fma_f32 v88, v132, v88, v92
	v_fma_f32 v89, v133, v89, v93
	v_fma_f32 v90, v132, v90, v94
	v_fma_f32 v91, v133, v91, v95
	v_max3_f32 v0, v0, v88, v89
	v_max3_f32 v0, v0, v90, v91
	v_mov_b32_e32 v92, v0
	s_nop 1
	v_permlane32_swap_b32_e32 v0, v92
	v_max_f32_e32 v92, v92, v92
	v_max_f32_e32 v0, v0, v0
	v_max_f32_e32 v0, v0, v92
	v_sub_f32_e32 v92, v0, v134
	v_cmp_lt_f32_e32 vcc, s9, v92
	s_cbranch_vccz .LBB0_484
	v_max_f32_e32 v0, v0, v0
	v_max_f32_e32 v92, v134, v134
	v_max_f32_e32 v0, v92, v0
	v_sub_f32_e32 v92, v134, v0
	v_exp_f32_e32 v92, v92
	v_mov_b32_e32 v134, v0
	v_mul_f32_e32 v154, v154, v92
	v_mul_f32_e32 v46, v46, v92
	v_mul_f32_e32 v47, v47, v92
	v_mul_f32_e32 v44, v44, v92
	v_mul_f32_e32 v45, v45, v92
	v_mul_f32_e32 v42, v42, v92
	v_mul_f32_e32 v43, v43, v92
	v_mul_f32_e32 v40, v40, v92
	v_mul_f32_e32 v41, v41, v92
	v_mul_f32_e32 v38, v38, v92
	v_mul_f32_e32 v39, v39, v92
	v_mul_f32_e32 v36, v36, v92
	v_mul_f32_e32 v37, v37, v92
	v_mul_f32_e32 v34, v34, v92
	v_mul_f32_e32 v35, v35, v92
	v_mul_f32_e32 v32, v32, v92
	v_mul_f32_e32 v33, v33, v92
	v_mul_f32_e32 v30, v30, v92
	v_mul_f32_e32 v31, v31, v92
	v_mul_f32_e32 v28, v28, v92
	v_mul_f32_e32 v29, v29, v92
	v_mul_f32_e32 v26, v26, v92
	v_mul_f32_e32 v27, v27, v92
	v_mul_f32_e32 v24, v24, v92
	v_mul_f32_e32 v25, v25, v92
	v_mul_f32_e32 v22, v22, v92
	v_mul_f32_e32 v23, v23, v92
	v_mul_f32_e32 v20, v20, v92
	v_mul_f32_e32 v21, v21, v92
	v_mul_f32_e32 v18, v18, v92
	v_mul_f32_e32 v19, v19, v92
	v_mul_f32_e32 v16, v16, v92
	v_mul_f32_e32 v17, v17, v92
	s_branch .LBB0_485

; #define LAS __attribute__((address_space(3)))
; template <bool MASK> ...
;     s16x4 l00, h00, l01, h01, l10, h10, l11, h11; { const unsigned a0 = va0 + sub * 4096, a1 = va1 + sub * 4096;
;       asm volatile("ds_read_b64_tr_b16 %0, %1" : "=&v"(l00) : "v"(a0) : "memory"); asm volatile("ds_read_b64_tr_b16 %0, %1 offset:1024" : "=&v"(h00) : "v"(a0) : "memory");
;       asm volatile("ds_read_b64_tr_b16 %0, %1" : "=&v"(l01) : "v"(a1) : "memory"); asm volatile("ds_read_b64_tr_b16 %0, %1 offset:1024" : "=&v"(h01) : "v"(a1) : "memory");
;       asm volatile("ds_read_b64_tr_b16 %0, %1 offset:2048" : "=&v"(l10) : "v"(a0) : "memory"); asm volatile("ds_read_b64_tr_b16 %0, %1 offset:3072" : "=&v"(h10) : "v"(a0) : "memory");
;       asm volatile("ds_read_b64_tr_b16 %0, %1 offset:2048" : "=&v"(l11) : "v"(a1) : "memory"); asm volatile("ds_read_b64_tr_b16 %0, %1 offset:3072" : "=&v"(h11) : "v"(a1) : "memory"); }
;     const int r = lane & 31, hh = lane >> 5;
;     f32x16 st = {0.f, 0.f, 0.f, 0.f, 0.f, 0.f, 0.f, 0.f, 0.f, 0.f, 0.f, 0.f, 0.f, 0.f, 0.f, 0.f};
;     { const int key = sub * 32 + r; const LAS char* kp = Kt + key * 128; const int ksw = (key >> 1) & 7;
; #pragma unroll
;       for (int d0 = 0; d0 < 4; ++d0) { const bf16x8 kf = *(const LAS bf16x8*)(kp + (((2 * d0 + hh) ^ ksw) << 4)); st = __builtin_amdgcn_mfma_f32_32x32x16_bf16(kf, qr[d0], st, 0, 0, 0); } }
;     f32x2_t sp[8]; const f32x2_t cs2 = {cscale, cscale};
; #pragma unroll
;     for (int g = 0; g < 4; ++g) { const f32x4 c4 = *(const LAS f32x4*)(cb + sub * 32 + 8 * g + 4 * hh);
;         sp[2 * g] = (f32x2_t){st[4 * g], st[4 * g + 1]} + cs2 * (f32x2_t){c4[0], c4[1]};
;         sp[2 * g + 1] = (f32x2_t){st[4 * g + 2], st[4 * g + 3]} + cs2 * (f32x2_t){c4[2], c4[3]};
;         if (MASK) {
; #pragma unroll
;             for (int e = 0; e < 4; ++e) { const int kpos = kpos_sub + 8 * g + 4 * hh + e; const bool ok = (kpos <= qpos && kpos >= qpos - win);
;                 sp[2 * g + (e >> 1)][e & 1] = ok ? sp[2 * g + (e >> 1)][e & 1] : -INFINITY; } } }
;     float rm = fmaxf(sp[0][0], sp[0][1]);
; #pragma unroll
;     for (int i = 1; i < 8; ++i) rm = fmaxf(fmaxf(rm, sp[i][0]), sp[i][1]);
;     rm = swap_max(rm);
;     if (__any(rm - m > 8.0f)) { const float mnew = fmaxf(m, rm); const float f = fast_exp2(m - mnew); l *= f; o0 = o0 * f; o1 = o1 * f; m = mnew; }
.LBB0_482:
	ds_read_b64_tr_b16 v[128:129], v159
	ds_read_b64_tr_b16 v[130:131], v159 offset:1024
	ds_read_b64_tr_b16 v[10:11], v160
	ds_read_b64_tr_b16 v[12:13], v160 offset:1024
	ds_read_b64_tr_b16 v[6:7], v159 offset:2048
	ds_read_b64_tr_b16 v[8:9], v159 offset:3072
	ds_read_b64_tr_b16 v[2:3], v160 offset:2048
	ds_read_b64_tr_b16 v[4:5], v160 offset:3072
	ds_read_b128 v[80:83], v158
	ds_read_b128 v[140:143], v157
	s_waitcnt lgkmcnt(0)
	v_mfma_f32_32x32x16_bf16 v[80:95], v[80:83], v[112:115], 0
	v_mfma_f32_32x32x16_bf16 v[80:95], v[140:143], v[116:119], v[80:95]
	ds_read_b128 v[140:143], v156
	s_waitcnt lgkmcnt(0)
	v_mfma_f32_32x32x16_bf16 v[80:95], v[140:143], v[120:123], v[80:95]
	ds_read_b128 v[140:143], v145
	ds_read_b128 v[162:165], v144 offset:49152
	ds_read_b128 v[166:169], v144 offset:49184
	s_waitcnt lgkmcnt(0)
	v_mfma_f32_32x32x16_bf16 v[80:95], v[140:143], v[124:127], v[80:95]
	s_nop 11
	v_fma_f32 v142, v132, v162, v80
	v_fma_f32 v143, v133, v163, v81
	v_fma_f32 v140, v132, v164, v82
	v_fma_f32 v141, v133, v165, v83
	ds_read_b128 v[162:165], v144 offset:49216
	v_fma_f32 v82, v132, v166, v84
	v_fma_f32 v83, v133, v167, v85
	v_fma_f32 v80, v132, v168, v86
	v_fma_f32 v81, v133, v169, v87
	v_max_f32_e32 v0, v142, v143
	v_max3_f32 v0, v0, v140, v141
	s_waitcnt lgkmcnt(0)
	v_fma_f32 v86, v132, v162, v88
	v_fma_f32 v87, v133, v163, v89
	v_fma_f32 v84, v132, v164, v90
	v_fma_f32 v85, v133, v165, v91
	ds_read_b128 v[88:91], v144 offset:49248
	v_max3_f32 v0, v0, v82, v83
	v_max3_f32 v0, v0, v80, v81
	v_max3_f32 v0, v0, v86, v87
	v_max3_f32 v0, v0, v84, v85
	s_waitcnt lgkmcnt(0)
	v_fma_f32 v88, v132, v88, v92
	v_fma_f32 v89, v133, v89, v93
	v_fma_f32 v90, v132, v90, v94
	v_fma_f32 v91, v133, v91, v95
	v_max3_f32 v0, v0, v88, v89
	v_max3_f32 v0, v0, v90, v91
	v_mov_b32_e32 v92, v0
	s_nop 1
	v_permlane32_swap_b32_e32 v0, v92
	v_max_f32_e32 v92, v92, v92
	v_max_f32_e32 v0, v0, v0
	v_max_f32_e32 v0, v0, v92
	v_sub_f32_e32 v92, v0, v136
	v_cmp_lt_f32_e32 vcc, s9, v92
	s_cbranch_vccz .LBB0_489
	v_max_f32_e32 v0, v0, v0
	v_max_f32_e32 v92, v136, v136
	v_max_f32_e32 v0, v92, v0
	v_sub_f32_e32 v92, v136, v0
	v_exp_f32_e32 v92, v92
	v_mov_b32_e32 v136, v0
	v_mul_f32_e32 v155, v155, v92
	v_mul_f32_e32 v78, v78, v92
	v_mul_f32_e32 v79, v79, v92
	v_mul_f32_e32 v76, v76, v92
	v_mul_f32_e32 v77, v77, v92
	v_mul_f32_e32 v74, v74, v92
	v_mul_f32_e32 v75, v75, v92
	v_mul_f32_e32 v72, v72, v92
	v_mul_f32_e32 v73, v73, v92
	v_mul_f32_e32 v70, v70, v92
	v_mul_f32_e32 v71, v71, v92
	v_mul_f32_e32 v68, v68, v92
	v_mul_f32_e32 v69, v69, v92
	v_mul_f32_e32 v66, v66, v92
	v_mul_f32_e32 v67, v67, v92
	v_mul_f32_e32 v64, v64, v92
	v_mul_f32_e32 v65, v65, v92
	v_mul_f32_e32 v62, v62, v92
	v_mul_f32_e32 v63, v63, v92
	v_mul_f32_e32 v60, v60, v92
	v_mul_f32_e32 v61, v61, v92
	v_mul_f32_e32 v58, v58, v92
	v_mul_f32_e32 v59, v59, v92
	v_mul_f32_e32 v56, v56, v92
	v_mul_f32_e32 v57, v57, v92
	v_mul_f32_e32 v54, v54, v92
	v_mul_f32_e32 v55, v55, v92
	v_mul_f32_e32 v52, v52, v92
	v_mul_f32_e32 v53, v53, v92
	v_mul_f32_e32 v50, v50, v92
	v_mul_f32_e32 v51, v51, v92
	v_mul_f32_e32 v48, v48, v92
	v_mul_f32_e32 v49, v49, v92
	s_branch .LBB0_490

; __device__ __forceinline__ unsigned cvt_pk_bf16(float lo, float hi) { f32x2_t v = {lo, hi}; bf16x2_t b = __builtin_convertvector(v, bf16x2_t); return __builtin_bit_cast(unsigned, b); }
; __device__ __forceinline__ float fast_exp2(float x) { return __builtin_amdgcn_exp2f(x); }
; template <bool MASK> ...
;     ...
;     { const f32x2_t m2 = {m, m}; f32x2_t ps2 = {0.f, 0.f};
; #pragma unroll
;       for (int i = 0; i < 8; ++i) { f32x2_t t = sp[i] - m2; t[0] = fast_exp2(t[0]); t[1] = fast_exp2(t[1]); sp[i] = t; ps2 = ps2 + t; }
;       l += ps2[0] + ps2[1]; }
;     u32x4 pw0, pw1;
;     pw0.x = cvt_pk_bf16(sp[0][0], sp[0][1]); pw0.y = cvt_pk_bf16(sp[1][0], sp[1][1]); pw0.z = cvt_pk_bf16(sp[2][0], sp[2][1]); pw0.w = cvt_pk_bf16(sp[3][0], sp[3][1]);
;     pw1.x = cvt_pk_bf16(sp[4][0], sp[4][1]); pw1.y = cvt_pk_bf16(sp[5][0], sp[5][1]); pw1.z = cvt_pk_bf16(sp[6][0], sp[6][1]); pw1.w = cvt_pk_bf16(sp[7][0], sp[7][1]);
;     asm volatile("s_waitcnt lgkmcnt(0)" : "+v"(l00), "+v"(h00), "+v"(l01), "+v"(h01), "+v"(l10), "+v"(h10), "+v"(l11), "+v"(h11) :: "memory");
;     { const bf16x8 pb0 = __builtin_bit_cast(bf16x8, pw0), pb1 = __builtin_bit_cast(bf16x8, pw1);
;       const bf16x8 v00 = {l00[0], l00[1], l00[2], l00[3], h00[0], h00[1], h00[2], h00[3]}, v01 = {l01[0], l01[1], l01[2], l01[3], h01[0], h01[1], h01[2], h01[3]};
;       const bf16x8 v10 = {l10[0], l10[1], l10[2], l10[3], h10[0], h10[1], h10[2], h10[3]}, v11 = {l11[0], l11[1], l11[2], l11[3], h11[0], h11[1], h11[2], h11[3]};
;       o0 = __builtin_amdgcn_mfma_f32_32x32x16_bf16(v00, pb0, o0, 0, 0, 0); o1 = __builtin_amdgcn_mfma_f32_32x32x16_bf16(v01, pb0, o1, 0, 0, 0);
;       o0 = __builtin_amdgcn_mfma_f32_32x32x16_bf16(v10, pb1, o0, 0, 0, 0); o1 = __builtin_amdgcn_mfma_f32_32x32x16_bf16(v11, pb1, o1, 0, 0, 0); }
.LBB0_485:
	v_sub_f32_e32 v92, v142, v0
	v_sub_f32_e32 v93, v143, v0
	v_sub_f32_e32 v140, v140, v0
	v_sub_f32_e32 v141, v141, v0
	v_exp_f32_e32 v92, v92
	v_exp_f32_e32 v93, v93
	v_exp_f32_e32 v140, v140
	v_exp_f32_e32 v141, v141
	v_sub_f32_e32 v82, v82, v0
	v_sub_f32_e32 v83, v83, v0
	v_sub_f32_e32 v80, v80, v0
	v_sub_f32_e32 v81, v81, v0
	v_exp_f32_e32 v82, v82
	v_exp_f32_e32 v83, v83
	v_exp_f32_e32 v142, v80
	v_exp_f32_e32 v143, v81
	v_add_f32_e32 v94, 0, v92
	v_add_f32_e32 v95, 0, v93
	v_sub_f32_e32 v86, v86, v0
	v_sub_f32_e32 v87, v87, v0
	v_add_f32_e32 v94, v140, v94
	v_add_f32_e32 v95, v141, v95
	v_exp_f32_e32 v86, v86
	v_add_f32_e32 v94, v82, v94
	v_add_f32_e32 v95, v83, v95
	v_exp_f32_e32 v87, v87
	v_sub_f32_e32 v84, v84, v0
	v_sub_f32_e32 v85, v85, v0
	v_add_f32_e32 v80, v142, v94
	v_add_f32_e32 v81, v143, v95
	v_exp_f32_e32 v94, v84
	v_exp_f32_e32 v95, v85
	v_sub_f32_e32 v84, v88, v0
	v_sub_f32_e32 v85, v89, v0
	v_add_f32_e32 v80, v86, v80
	v_add_f32_e32 v81, v87, v81
	v_exp_f32_e32 v88, v84
	v_exp_f32_e32 v89, v85
	v_sub_f32_e32 v84, v90, v0
	v_sub_f32_e32 v85, v91, v0
	v_add_f32_e32 v80, v94, v80
	v_add_f32_e32 v81, v95, v81
	v_exp_f32_e32 v90, v84
	v_exp_f32_e32 v91, v85
	v_add_f32_e32 v80, v88, v80
	v_add_f32_e32 v81, v89, v81
	v_cvt_pk_bf16_f32 v82, v82, v83
	v_cvt_pk_bf16_f32 v83, v142, v143
	v_add_f32_e32 v80, v90, v80
	v_add_f32_e32 v81, v91, v81
	s_waitcnt lgkmcnt(0)
	v_cvt_pk_bf16_f32 v84, v86, v87
	v_add_f32_e32 v0, v80, v81
	v_cvt_pk_bf16_f32 v80, v92, v93
	v_cvt_pk_bf16_f32 v81, v140, v141
	v_cvt_pk_bf16_f32 v85, v94, v95
	v_cvt_pk_bf16_f32 v86, v88, v89
	v_mfma_f32_32x32x16_bf16 v[32:47], v[128:131], v[80:83], v[32:47]
	v_cvt_pk_bf16_f32 v87, v90, v91
	v_add_f32_e32 v154, v154, v0
	v_mfma_f32_32x32x16_bf16 v[16:31], v[10:13], v[80:83], v[16:31]
	v_mfma_f32_32x32x16_bf16 v[32:47], v[6:9], v[84:87], v[32:47]
	v_mfma_f32_32x32x16_bf16 v[16:31], v[2:5], v[84:87], v[16:31]
	s_and_b64 vcc, exec, s[52:53]
	s_cbranch_vccz .LBB0_482

; #define LAS __attribute__((address_space(3)))
; template <bool MASK> ...
;     s16x4 l00, h00, l01, h01, l10, h10, l11, h11; { const unsigned a0 = va0 + sub * 4096, a1 = va1 + sub * 4096;
;       asm volatile("ds_read_b64_tr_b16 %0, %1" : "=&v"(l00) : "v"(a0) : "memory"); asm volatile("ds_read_b64_tr_b16 %0, %1 offset:1024" : "=&v"(h00) : "v"(a0) : "memory");
;       asm volatile("ds_read_b64_tr_b16 %0, %1" : "=&v"(l01) : "v"(a1) : "memory"); asm volatile("ds_read_b64_tr_b16 %0, %1 offset:1024" : "=&v"(h01) : "v"(a1) : "memory");
;       asm volatile("ds_read_b64_tr_b16 %0, %1 offset:2048" : "=&v"(l10) : "v"(a0) : "memory"); asm volatile("ds_read_b64_tr_b16 %0, %1 offset:3072" : "=&v"(h10) : "v"(a0) : "memory");
;       asm volatile("ds_read_b64_tr_b16 %0, %1 offset:2048" : "=&v"(l11) : "v"(a1) : "memory"); asm volatile("ds_read_b64_tr_b16 %0, %1 offset:3072" : "=&v"(h11) : "v"(a1) : "memory"); }
;     const int r = lane & 31, hh = lane >> 5;
;     f32x16 st = {0.f, 0.f, 0.f, 0.f, 0.f, 0.f, 0.f, 0.f, 0.f, 0.f, 0.f, 0.f, 0.f, 0.f, 0.f, 0.f};
;     { const int key = sub * 32 + r; const LAS char* kp = Kt + key * 128; const int ksw = (key >> 1) & 7;
; #pragma unroll
;       for (int d0 = 0; d0 < 4; ++d0) { const bf16x8 kf = *(const LAS bf16x8*)(kp + (((2 * d0 + hh) ^ ksw) << 4)); st = __builtin_amdgcn_mfma_f32_32x32x16_bf16(kf, qr[d0], st, 0, 0, 0); } }
;     f32x2_t sp[8]; const f32x2_t cs2 = {cscale, cscale};
; #pragma unroll
;     for (int g = 0; g < 4; ++g) { const f32x4 c4 = *(const LAS f32x4*)(cb + sub * 32 + 8 * g + 4 * hh);
;         sp[2 * g] = (f32x2_t){st[4 * g], st[4 * g + 1]} + cs2 * (f32x2_t){c4[0], c4[1]};
;         sp[2 * g + 1] = (f32x2_t){st[4 * g + 2], st[4 * g + 3]} + cs2 * (f32x2_t){c4[2], c4[3]};
;         if (MASK) {
; #pragma unroll
;             for (int e = 0; e < 4; ++e) { const int kpos = kpos_sub + 8 * g + 4 * hh + e; const bool ok = (kpos <= qpos && kpos >= qpos - win);
;                 sp[2 * g + (e >> 1)][e & 1] = ok ? sp[2 * g + (e >> 1)][e & 1] : -INFINITY; } } }
;     float rm = fmaxf(sp[0][0], sp[0][1]);
; #pragma unroll
;     for (int i = 1; i < 8; ++i) rm = fmaxf(fmaxf(rm, sp[i][0]), sp[i][1]);
;     rm = swap_max(rm);
;     if (__any(rm - m > 8.0f)) { const float mnew = fmaxf(m, rm); const float f = fast_exp2(m - mnew); l *= f; o0 = o0 * f; o1 = o1 * f; m = mnew; }
.LBB0_487:
	ds_read_b64_tr_b16 v[128:129], v161
	ds_read_b64_tr_b16 v[130:131], v161 offset:1024
	ds_read_b64_tr_b16 v[10:11], v159
	ds_read_b64_tr_b16 v[12:13], v159 offset:1024
	ds_read_b64_tr_b16 v[6:7], v161 offset:2048
	ds_read_b64_tr_b16 v[8:9], v161 offset:3072
	ds_read_b64_tr_b16 v[2:3], v159 offset:2048
	ds_read_b64_tr_b16 v[4:5], v159 offset:3072
	ds_read_b128 v[80:83], v158 offset:4096
	ds_read_b128 v[140:143], v157 offset:4096
	s_waitcnt lgkmcnt(0)
	v_mfma_f32_32x32x16_bf16 v[80:95], v[80:83], v[96:99], 0
	v_mfma_f32_32x32x16_bf16 v[80:95], v[140:143], v[100:103], v[80:95]
	ds_read_b128 v[140:143], v156 offset:4096
	s_waitcnt lgkmcnt(0)
	v_mfma_f32_32x32x16_bf16 v[80:95], v[140:143], v[104:107], v[80:95]
	ds_read_b128 v[140:143], v145 offset:4096
	ds_read_b128 v[162:165], v144 offset:49280
	ds_read_b128 v[166:169], v144 offset:49312
	s_waitcnt lgkmcnt(0)
	v_mfma_f32_32x32x16_bf16 v[80:95], v[140:143], v[108:111], v[80:95]
	s_nop 11
	v_fma_f32 v142, v132, v162, v80
	v_fma_f32 v143, v133, v163, v81
	v_fma_f32 v140, v132, v164, v82
	v_fma_f32 v141, v133, v165, v83
	ds_read_b128 v[162:165], v144 offset:49344
	v_fma_f32 v82, v132, v166, v84
	v_fma_f32 v83, v133, v167, v85
	v_fma_f32 v80, v132, v168, v86
	v_fma_f32 v81, v133, v169, v87
	v_max_f32_e32 v0, v142, v143
	v_max3_f32 v0, v0, v140, v141
	s_waitcnt lgkmcnt(0)
	v_fma_f32 v86, v132, v162, v88
	v_fma_f32 v87, v133, v163, v89
	v_fma_f32 v84, v132, v164, v90
	v_fma_f32 v85, v133, v165, v91
	ds_read_b128 v[88:91], v144 offset:49376
	v_max3_f32 v0, v0, v82, v83
	v_max3_f32 v0, v0, v80, v81
	v_max3_f32 v0, v0, v86, v87
	v_max3_f32 v0, v0, v84, v85
	s_waitcnt lgkmcnt(0)
	v_fma_f32 v88, v132, v88, v92
	v_fma_f32 v89, v133, v89, v93
	v_fma_f32 v90, v132, v90, v94
	v_fma_f32 v91, v133, v91, v95
	v_max3_f32 v0, v0, v88, v89
	v_max3_f32 v0, v0, v90, v91
	v_mov_b32_e32 v92, v0
	s_nop 1
	v_permlane32_swap_b32_e32 v0, v92
	v_max_f32_e32 v92, v92, v92
	v_max_f32_e32 v0, v0, v0
	v_max_f32_e32 v0, v0, v92
	v_sub_f32_e32 v92, v0, v134
	v_cmp_lt_f32_e32 vcc, s9, v92
	s_cbranch_vccz .LBB0_492
	v_max_f32_e32 v0, v0, v0
	v_max_f32_e32 v92, v134, v134
	v_max_f32_e32 v0, v92, v0
	v_sub_f32_e32 v92, v134, v0
	v_exp_f32_e32 v92, v92
	v_mov_b32_e32 v134, v0
	v_mul_f32_e32 v154, v154, v92
	v_mul_f32_e32 v46, v46, v92
	v_mul_f32_e32 v47, v47, v92
	v_mul_f32_e32 v44, v44, v92
	v_mul_f32_e32 v45, v45, v92
	v_mul_f32_e32 v42, v42, v92
	v_mul_f32_e32 v43, v43, v92
	v_mul_f32_e32 v40, v40, v92
	v_mul_f32_e32 v41, v41, v92
	v_mul_f32_e32 v38, v38, v92
	v_mul_f32_e32 v39, v39, v92
	v_mul_f32_e32 v36, v36, v92
	v_mul_f32_e32 v37, v37, v92
	v_mul_f32_e32 v34, v34, v92
	v_mul_f32_e32 v35, v35, v92
	v_mul_f32_e32 v32, v32, v92
	v_mul_f32_e32 v33, v33, v92
	v_mul_f32_e32 v30, v30, v92
	v_mul_f32_e32 v31, v31, v92
	v_mul_f32_e32 v28, v28, v92
	v_mul_f32_e32 v29, v29, v92
	v_mul_f32_e32 v26, v26, v92
	v_mul_f32_e32 v27, v27, v92
	v_mul_f32_e32 v24, v24, v92
	v_mul_f32_e32 v25, v25, v92
	v_mul_f32_e32 v22, v22, v92
	v_mul_f32_e32 v23, v23, v92
	v_mul_f32_e32 v20, v20, v92
	v_mul_f32_e32 v21, v21, v92
	v_mul_f32_e32 v18, v18, v92
	v_mul_f32_e32 v19, v19, v92
	v_mul_f32_e32 v16, v16, v92
	v_mul_f32_e32 v17, v17, v92
	s_branch .LBB0_493

; __device__ __forceinline__ unsigned cvt_pk_bf16(float lo, float hi) { f32x2_t v = {lo, hi}; bf16x2_t b = __builtin_convertvector(v, bf16x2_t); return __builtin_bit_cast(unsigned, b); }
; __device__ __forceinline__ float fast_exp2(float x) { return __builtin_amdgcn_exp2f(x); }
; template <bool MASK> ...
;     ...
;     { const f32x2_t m2 = {m, m}; f32x2_t ps2 = {0.f, 0.f};
; #pragma unroll
;       for (int i = 0; i < 8; ++i) { f32x2_t t = sp[i] - m2; t[0] = fast_exp2(t[0]); t[1] = fast_exp2(t[1]); sp[i] = t; ps2 = ps2 + t; }
;       l += ps2[0] + ps2[1]; }
;     u32x4 pw0, pw1;
;     pw0.x = cvt_pk_bf16(sp[0][0], sp[0][1]); pw0.y = cvt_pk_bf16(sp[1][0], sp[1][1]); pw0.z = cvt_pk_bf16(sp[2][0], sp[2][1]); pw0.w = cvt_pk_bf16(sp[3][0], sp[3][1]);
;     pw1.x = cvt_pk_bf16(sp[4][0], sp[4][1]); pw1.y = cvt_pk_bf16(sp[5][0], sp[5][1]); pw1.z = cvt_pk_bf16(sp[6][0], sp[6][1]); pw1.w = cvt_pk_bf16(sp[7][0], sp[7][1]);
;     asm volatile("s_waitcnt lgkmcnt(0)" : "+v"(l00), "+v"(h00), "+v"(l01), "+v"(h01), "+v"(l10), "+v"(h10), "+v"(l11), "+v"(h11) :: "memory");
;     { const bf16x8 pb0 = __builtin_bit_cast(bf16x8, pw0), pb1 = __builtin_bit_cast(bf16x8, pw1);
;       const bf16x8 v00 = {l00[0], l00[1], l00[2], l00[3], h00[0], h00[1], h00[2], h00[3]}, v01 = {l01[0], l01[1], l01[2], l01[3], h01[0], h01[1], h01[2], h01[3]};
;       const bf16x8 v10 = {l10[0], l10[1], l10[2], l10[3], h10[0], h10[1], h10[2], h10[3]}, v11 = {l11[0], l11[1], l11[2], l11[3], h11[0], h11[1], h11[2], h11[3]};
;       o0 = __builtin_amdgcn_mfma_f32_32x32x16_bf16(v00, pb0, o0, 0, 0, 0); o1 = __builtin_amdgcn_mfma_f32_32x32x16_bf16(v01, pb0, o1, 0, 0, 0);
;       o0 = __builtin_amdgcn_mfma_f32_32x32x16_bf16(v10, pb1, o0, 0, 0, 0); o1 = __builtin_amdgcn_mfma_f32_32x32x16_bf16(v11, pb1, o1, 0, 0, 0); }
.LBB0_490:
	v_sub_f32_e32 v92, v142, v0
	v_sub_f32_e32 v93, v143, v0
	v_sub_f32_e32 v140, v140, v0
	v_sub_f32_e32 v141, v141, v0
	v_exp_f32_e32 v92, v92
	v_exp_f32_e32 v93, v93
	v_exp_f32_e32 v140, v140
	v_exp_f32_e32 v141, v141
	v_sub_f32_e32 v82, v82, v0
	v_sub_f32_e32 v83, v83, v0
	v_sub_f32_e32 v80, v80, v0
	v_sub_f32_e32 v81, v81, v0
	v_exp_f32_e32 v82, v82
	v_exp_f32_e32 v83, v83
	v_exp_f32_e32 v142, v80
	v_exp_f32_e32 v143, v81
	v_add_f32_e32 v94, 0, v92
	v_add_f32_e32 v95, 0, v93
	v_sub_f32_e32 v86, v86, v0
	v_sub_f32_e32 v87, v87, v0
	v_add_f32_e32 v94, v140, v94
	v_add_f32_e32 v95, v141, v95
	v_exp_f32_e32 v86, v86
	v_add_f32_e32 v94, v82, v94
	v_add_f32_e32 v95, v83, v95
	v_exp_f32_e32 v87, v87
	v_sub_f32_e32 v84, v84, v0
	v_sub_f32_e32 v85, v85, v0
	v_add_f32_e32 v80, v142, v94
	v_add_f32_e32 v81, v143, v95
	v_exp_f32_e32 v94, v84
	v_exp_f32_e32 v95, v85
	v_sub_f32_e32 v84, v88, v0
	v_sub_f32_e32 v85, v89, v0
	v_add_f32_e32 v80, v86, v80
	v_add_f32_e32 v81, v87, v81
	v_exp_f32_e32 v88, v84
	v_exp_f32_e32 v89, v85
	v_sub_f32_e32 v84, v90, v0
	v_sub_f32_e32 v85, v91, v0
	v_add_f32_e32 v80, v94, v80
	v_add_f32_e32 v81, v95, v81
	v_exp_f32_e32 v90, v84
	v_exp_f32_e32 v91, v85
	v_add_f32_e32 v80, v88, v80
	v_add_f32_e32 v81, v89, v81
	v_cvt_pk_bf16_f32 v82, v82, v83
	v_cvt_pk_bf16_f32 v83, v142, v143
	v_add_f32_e32 v80, v90, v80
	v_add_f32_e32 v81, v91, v81
	s_waitcnt lgkmcnt(0)
	v_cvt_pk_bf16_f32 v84, v86, v87
	v_add_f32_e32 v0, v80, v81
	v_cvt_pk_bf16_f32 v80, v92, v93
	v_cvt_pk_bf16_f32 v81, v140, v141
	v_cvt_pk_bf16_f32 v85, v94, v95
	v_cvt_pk_bf16_f32 v86, v88, v89
	v_mfma_f32_32x32x16_bf16 v[64:79], v[128:131], v[80:83], v[64:79]
	v_cvt_pk_bf16_f32 v87, v90, v91
	v_add_f32_e32 v155, v155, v0
	v_mfma_f32_32x32x16_bf16 v[48:63], v[10:13], v[80:83], v[48:63]
	v_mfma_f32_32x32x16_bf16 v[64:79], v[6:9], v[84:87], v[64:79]
	v_mfma_f32_32x32x16_bf16 v[48:63], v[2:5], v[84:87], v[48:63]
	s_and_b64 vcc, exec, s[50:51]
	v_add_u32_e32 v161, 0x1000, v159
	v_add_u32_e32 v159, 0x1000, v160
	s_cbranch_vccz .LBB0_487

; template <bool MASK> ...
;     s16x4 l00, h00, l01, h01, l10, h10, l11, h11; { const unsigned a0 = va0 + sub * 4096, a1 = va1 + sub * 4096;
;       asm volatile("ds_read_b64_tr_b16 %0, %1" : "=&v"(l00) : "v"(a0) : "memory"); asm volatile("ds_read_b64_tr_b16 %0, %1 offset:1024" : "=&v"(h00) : "v"(a0) : "memory");
;       asm volatile("ds_read_b64_tr_b16 %0, %1" : "=&v"(l01) : "v"(a1) : "memory"); asm volatile("ds_read_b64_tr_b16 %0, %1 offset:1024" : "=&v"(h01) : "v"(a1) : "memory");
;       asm volatile("ds_read_b64_tr_b16 %0, %1 offset:2048" : "=&v"(l10) : "v"(a0) : "memory"); asm volatile("ds_read_b64_tr_b16 %0, %1 offset:3072" : "=&v"(h10) : "v"(a0) : "memory");
;       asm volatile("ds_read_b64_tr_b16 %0, %1 offset:2048" : "=&v"(l11) : "v"(a1) : "memory"); asm volatile("ds_read_b64_tr_b16 %0, %1 offset:3072" : "=&v"(h11) : "v"(a1) : "memory"); }
;     const int r = lane & 31, hh = lane >> 5;
;     f32x16 st = {0.f, 0.f, 0.f, 0.f, 0.f, 0.f, 0.f, 0.f, 0.f, 0.f, 0.f, 0.f, 0.f, 0.f, 0.f, 0.f};
;     { const int key = sub * 32 + r; const LAS char* kp = Kt + key * 128; const int ksw = (key >> 1) & 7;
; #pragma unroll
;       for (int d0 = 0; d0 < 4; ++d0) { const bf16x8 kf = *(const LAS bf16x8*)(kp + (((2 * d0 + hh) ^ ksw) << 4)); st = __builtin_amdgcn_mfma_f32_32x32x16_bf16(kf, qr[d0], st, 0, 0, 0); } }
;     f32x2_t sp[8]; const f32x2_t cs2 = {cscale, cscale};
; #pragma unroll
;     for (int g = 0; g < 4; ++g) { const f32x4 c4 = *(const LAS f32x4*)(cb + sub * 32 + 8 * g + 4 * hh);
;         sp[2 * g] = (f32x2_t){st[4 * g], st[4 * g + 1]} + cs2 * (f32x2_t){c4[0], c4[1]};
;         sp[2 * g + 1] = (f32x2_t){st[4 * g + 2], st[4 * g + 3]} + cs2 * (f32x2_t){c4[2], c4[3]};
;         if (MASK) {
; #pragma unroll
;             for (int e = 0; e < 4; ++e) { const int kpos = kpos_sub + 8 * g + 4 * hh + e; const bool ok = (kpos <= qpos && kpos >= qpos - win);
;                 sp[2 * g + (e >> 1)][e & 1] = ok ? sp[2 * g + (e >> 1)][e & 1] : -INFINITY; } } }
;     float rm = fmaxf(sp[0][0], sp[0][1]);
; #pragma unroll
;     for (int i = 1; i < 8; ++i) rm = fmaxf(fmaxf(rm, sp[i][0]), sp[i][1]);
;     rm = swap_max(rm);
;     if (__any(rm - m > 8.0f)) { const float mnew = fmaxf(m, rm); const float f = fast_exp2(m - mnew); l *= f; o0 = o0 * f; o1 = o1 * f; m = mnew; }
;     { const f32x2_t m2 = {m, m}; f32x2_t ps2 = {0.f, 0.f};
; #pragma unroll
.LBB0_493:
	v_sub_f32_e32 v92, v142, v0
	v_sub_f32_e32 v93, v143, v0
	v_sub_f32_e32 v140, v140, v0
	v_sub_f32_e32 v141, v141, v0
	v_exp_f32_e32 v92, v92
	v_exp_f32_e32 v93, v93
	v_exp_f32_e32 v140, v140
	v_exp_f32_e32 v141, v141
	v_sub_f32_e32 v82, v82, v0
	v_sub_f32_e32 v83, v83, v0
	v_sub_f32_e32 v80, v80, v0
	v_sub_f32_e32 v81, v81, v0
	v_exp_f32_e32 v82, v82
	v_exp_f32_e32 v83, v83
	v_exp_f32_e32 v142, v80
	v_exp_f32_e32 v143, v81
	v_add_f32_e32 v94, 0, v92
	v_add_f32_e32 v95, 0, v93
	v_sub_f32_e32 v86, v86, v0
	v_sub_f32_e32 v87, v87, v0
	v_add_f32_e32 v94, v140, v94
	v_add_f32_e32 v95, v141, v95
	v_exp_f32_e32 v86, v86
	v_add_f32_e32 v94, v82, v94
	v_add_f32_e32 v95, v83, v95
	v_exp_f32_e32 v87, v87
	v_sub_f32_e32 v84, v84, v0
	v_sub_f32_e32 v85, v85, v0
	v_add_f32_e32 v80, v142, v94
	v_add_f32_e32 v81, v143, v95
	v_exp_f32_e32 v94, v84
	v_exp_f32_e32 v95, v85
	v_sub_f32_e32 v84, v88, v0
	v_sub_f32_e32 v85, v89, v0
	v_add_f32_e32 v80, v86, v80
	v_add_f32_e32 v81, v87, v81
	v_exp_f32_e32 v88, v84
	v_exp_f32_e32 v89, v85
	v_sub_f32_e32 v84, v90, v0
	v_sub_f32_e32 v85, v91, v0
	v_add_f32_e32 v80, v94, v80
	v_add_f32_e32 v81, v95, v81
	v_exp_f32_e32 v90, v84
	v_exp_f32_e32 v91, v85
	v_add_f32_e32 v80, v88, v80
	v_add_f32_e32 v81, v89, v81
	v_cvt_pk_bf16_f32 v82, v82, v83
	v_cvt_pk_bf16_f32 v83, v142, v143
	v_add_f32_e32 v80, v90, v80
	v_add_f32_e32 v81, v91, v81
	s_waitcnt lgkmcnt(0)
	v_cvt_pk_bf16_f32 v84, v86, v87
	v_add_f32_e32 v0, v80, v81
	v_cvt_pk_bf16_f32 v80, v92, v93
	v_cvt_pk_bf16_f32 v81, v140, v141
	v_cvt_pk_bf16_f32 v85, v94, v95
	v_cvt_pk_bf16_f32 v86, v88, v89
	v_mfma_f32_32x32x16_bf16 v[32:47], v[128:131], v[80:83], v[32:47]
	v_cvt_pk_bf16_f32 v87, v90, v91
	v_add_f32_e32 v154, v154, v0
	v_mfma_f32_32x32x16_bf16 v[16:31], v[10:13], v[80:83], v[16:31]
	v_mfma_f32_32x32x16_bf16 v[32:47], v[6:9], v[84:87], v[32:47]
	v_mfma_f32_32x32x16_bf16 v[16:31], v[2:5], v[84:87], v[16:31]
	s_and_b64 vcc, exec, s[52:53]
	s_cbranch_vccnz .LBB0_470
.LBB0_494:
	ds_read_b64_tr_b16 v[128:129], v161
	ds_read_b64_tr_b16 v[130:131], v161 offset:1024
	ds_read_b64_tr_b16 v[10:11], v159
	ds_read_b64_tr_b16 v[12:13], v159 offset:1024
	ds_read_b64_tr_b16 v[6:7], v161 offset:2048
	ds_read_b64_tr_b16 v[8:9], v161 offset:3072
	ds_read_b64_tr_b16 v[2:3], v159 offset:2048
	ds_read_b64_tr_b16 v[4:5], v159 offset:3072
	ds_read_b128 v[80:83], v158 offset:4096
	ds_read_b128 v[140:143], v157 offset:4096
	s_waitcnt lgkmcnt(0)
	v_mfma_f32_32x32x16_bf16 v[80:95], v[80:83], v[112:115], 0
	v_mfma_f32_32x32x16_bf16 v[80:95], v[140:143], v[116:119], v[80:95]
	ds_read_b128 v[140:143], v156 offset:4096
	s_waitcnt lgkmcnt(0)
	v_mfma_f32_32x32x16_bf16 v[80:95], v[140:143], v[120:123], v[80:95]
	ds_read_b128 v[140:143], v145 offset:4096
	ds_read_b128 v[156:159], v144 offset:49280
	ds_read_b128 v[160:163], v144 offset:49312
	s_waitcnt lgkmcnt(0)
	v_mfma_f32_32x32x16_bf16 v[80:95], v[140:143], v[124:127], v[80:95]
	s_nop 11
	v_fma_f32 v142, v132, v156, v80
	v_fma_f32 v143, v133, v157, v81
	v_fma_f32 v140, v132, v158, v82
	v_fma_f32 v141, v133, v159, v83
	ds_read_b128 v[156:159], v144 offset:49344
	v_fma_f32 v82, v132, v160, v84
	v_fma_f32 v83, v133, v161, v85
	v_fma_f32 v80, v132, v162, v86
	v_fma_f32 v81, v133, v163, v87
	v_max_f32_e32 v0, v142, v143
	v_max3_f32 v0, v0, v140, v141
	s_waitcnt lgkmcnt(0)
	v_fma_f32 v86, v132, v156, v88
	v_fma_f32 v87, v133, v157, v89
	v_fma_f32 v84, v132, v158, v90
	v_fma_f32 v85, v133, v159, v91
	ds_read_b128 v[88:91], v144 offset:49376
	v_max3_f32 v0, v0, v82, v83
	v_max3_f32 v0, v0, v80, v81
	v_max3_f32 v0, v0, v86, v87
	v_max3_f32 v0, v0, v84, v85
	s_waitcnt lgkmcnt(0)
	v_fma_f32 v88, v132, v88, v92
	v_fma_f32 v89, v133, v89, v93
	v_fma_f32 v90, v132, v90, v94
	v_fma_f32 v91, v133, v91, v95
	v_max3_f32 v0, v0, v88, v89
	v_max3_f32 v0, v0, v90, v91
	v_mov_b32_e32 v92, v0
	s_nop 1
	v_permlane32_swap_b32_e32 v0, v92
	v_max_f32_e32 v92, v92, v92
	v_max_f32_e32 v0, v0, v0
	v_max_f32_e32 v0, v0, v92
	v_sub_f32_e32 v92, v0, v136
	v_cmp_lt_f32_e32 vcc, s9, v92
	s_cbranch_vccnz .LBB0_468
	v_mov_b32_e32 v0, v136
	s_branch .LBB0_469
; __device__ __forceinline__ unsigned cvt_pk_bf16(float lo, float hi) { f32x2_t v = {lo, hi}; bf16x2_t b = __builtin_convertvector(v, bf16x2_t); return __builtin_bit_cast(unsigned, b); }
; __device__ __forceinline__ float fast_rcp(float x) { return __builtin_amdgcn_rcpf(x); }
; __device__ __forceinline__ float swap_sum(float v) { auto rr = __builtin_amdgcn_permlane32_swap(__float_as_uint(v), __float_as_uint(v), false, false); return __uint_as_float(rr[0]) + __uint_as_float(rr[1]); }
; __device__ __forceinline__ void moba_partial_store(const f32x16& o0, const f32x16& o1, float m, float l, float slope2, int t, int j, int rs, int b, int h, int hh, bf16_t* PO, float* PML) {
;     const float lt = swap_sum(l), inv = fast_rcp(lt);
;     const size_t pidx = (((size_t)b * SEQ + t) * 8 + h) * 3 + rs;
;     bf16_t* po = PO + pidx * 64;
; #pragma unroll
;     for (int d0 = 0; d0 < 2; ++d0)
; #pragma unroll
;         for (int g = 0; g < 4; ++g) { const int d = 32 * d0 + 8 * g + 4 * hh; const f32x16& o = d0 ? o1 : o0;
;             u32x2 w; w.x = cvt_pk_bf16(o[4 * g] * inv, o[4 * g + 1] * inv); w.y = cvt_pk_bf16(o[4 * g + 2] * inv, o[4 * g + 3] * inv); *(u32x2*)(po + d) = w; }
;     if (hh == 0) { PML[pidx * 2] = m - slope2 * (float)(t - j * 256); PML[pidx * 2 + 1] = lt; }
.LBB0_496:
	s_waitcnt lgkmcnt(0)
	s_barrier
	s_lshl_b32 s1, s1, 8
	s_and_saveexec_b64 s[18:19], s[46:47]
	s_cbranch_execz .LBB0_499
	v_mov_b32_e32 v0, v154
	s_nop 1
	v_permlane32_swap_b32_e32 v154, v0
	v_add_f32_e32 v3, v154, v0
	s_lshl_b64 s[4:5], s[28:29], 17
	v_lshlrev_b32_sdwa v0, v241, v137 dst_sel:DWORD dst_unused:UNUSED_PAD src0_sel:DWORD src1_sel:WORD_0
	v_rcp_f32_e32 v2, v3
	v_lshl_add_u64 v[6:7], s[4:5], 0, v[0:1]
	v_lshrrev_b32_e32 v4, 16, v137
	v_or_b32_e32 v0, s0, v6
	v_mov_b32_e32 v5, v1
	v_mad_u64_u32 v[4:5], s[4:5], v0, 3, v[4:5]
	v_mad_i32_i24 v5, v7, 3, v5
	v_lshlrev_b64 v[6:7], 7, v[4:5]
	v_mul_f32_e32 v8, v32, v2
	v_mul_f32_e32 v9, v33, v2
	v_mul_f32_e32 v10, v34, v2
	v_mul_f32_e32 v11, v35, v2
	v_cvt_pk_bf16_f32 v8, v8, v9
	v_cvt_pk_bf16_f32 v9, v10, v11
	v_lshl_add_u64 v[6:7], v[152:153], 0, v[6:7]
	global_store_dwordx2 v[6:7], v[8:9], off
	v_mul_f32_e32 v8, v36, v2
	v_mul_f32_e32 v9, v37, v2
	v_mul_f32_e32 v10, v38, v2
	v_mul_f32_e32 v11, v39, v2
	v_cvt_pk_bf16_f32 v8, v8, v9
	v_cvt_pk_bf16_f32 v9, v10, v11
	global_store_dwordx2 v[6:7], v[8:9], off offset:16
	v_mul_f32_e32 v8, v40, v2
	v_mul_f32_e32 v9, v41, v2
	v_mul_f32_e32 v10, v42, v2
	v_mul_f32_e32 v11, v43, v2
	v_cvt_pk_bf16_f32 v8, v8, v9
	v_cvt_pk_bf16_f32 v9, v10, v11
	global_store_dwordx2 v[6:7], v[8:9], off offset:32
	v_mul_f32_e32 v8, v44, v2
	v_mul_f32_e32 v9, v45, v2
	v_mul_f32_e32 v10, v46, v2
	v_mul_f32_e32 v11, v47, v2
	v_cvt_pk_bf16_f32 v8, v8, v9
	v_cvt_pk_bf16_f32 v9, v10, v11
	global_store_dwordx2 v[6:7], v[8:9], off offset:48
	v_mul_f32_e32 v8, v16, v2
	v_mul_f32_e32 v9, v17, v2
	v_mul_f32_e32 v10, v18, v2
	v_mul_f32_e32 v11, v19, v2
	v_cvt_pk_bf16_f32 v8, v8, v9
	v_cvt_pk_bf16_f32 v9, v10, v11
	global_store_dwordx2 v[6:7], v[8:9], off offset:64
	v_mul_f32_e32 v8, v20, v2
	v_mul_f32_e32 v9, v21, v2
	v_mul_f32_e32 v10, v22, v2
	v_mul_f32_e32 v11, v23, v2
	v_cvt_pk_bf16_f32 v8, v8, v9
	v_cvt_pk_bf16_f32 v9, v10, v11
	global_store_dwordx2 v[6:7], v[8:9], off offset:80
	v_mul_f32_e32 v8, v24, v2
	v_mul_f32_e32 v9, v25, v2
	v_mul_f32_e32 v10, v26, v2
	v_mul_f32_e32 v11, v27, v2
	v_cvt_pk_bf16_f32 v8, v8, v9
	v_cvt_pk_bf16_f32 v9, v10, v11
	global_store_dwordx2 v[6:7], v[8:9], off offset:96
	v_mul_f32_e32 v8, v28, v2
	v_mul_f32_e32 v9, v29, v2
	v_mul_f32_e32 v10, v30, v2
	v_mul_f32_e32 v11, v31, v2
	v_cvt_pk_bf16_f32 v8, v8, v9
	v_cvt_pk_bf16_f32 v9, v10, v11
	global_store_dwordx2 v[6:7], v[8:9], off offset:112
	s_and_b64 exec, exec, s[78:79]
	s_cbranch_execz .LBB0_499
	v_sub_u32_sdwa v0, v137, s1 dst_sel:DWORD dst_unused:UNUSED_PAD src0_sel:WORD_0 src1_sel:DWORD
	v_cvt_f32_i32_e32 v0, v0
	v_readlane_b32 s4, v252, 9
	v_readlane_b32 s5, v252, 10
	v_fma_f32 v2, -v132, v0, v134
	s_nop 0
	v_lshl_add_u64 v[4:5], v[4:5], 3, s[4:5]
	global_store_dwordx2 v[4:5], v[2:3], off
.LBB0_499:
	s_or_b64 exec, exec, s[18:19]
	s_and_saveexec_b64 s[18:19], s[44:45]
	v_readlane_b32 s52, v254, 59
	v_readlane_b32 s53, v254, 60
	s_cbranch_execz .LBB0_502
	v_mov_b32_e32 v0, v155
	s_nop 1
	v_permlane32_swap_b32_e32 v155, v0
	v_add_f32_e32 v3, v155, v0
	s_lshl_b64 s[4:5], s[28:29], 17
	v_lshlrev_b32_sdwa v0, v241, v135 dst_sel:DWORD dst_unused:UNUSED_PAD src0_sel:DWORD src1_sel:WORD_0
	v_rcp_f32_e32 v2, v3
	v_lshl_add_u64 v[6:7], s[4:5], 0, v[0:1]
	v_lshrrev_b32_e32 v4, 16, v135
	v_or_b32_e32 v0, s0, v6
	v_mov_b32_e32 v5, v1
	v_mad_u64_u32 v[4:5], s[4:5], v0, 3, v[4:5]
	v_mad_i32_i24 v5, v7, 3, v5
	v_lshlrev_b64 v[6:7], 7, v[4:5]
	v_mul_f32_e32 v8, v64, v2
	v_mul_f32_e32 v9, v65, v2
	v_mul_f32_e32 v10, v66, v2
	v_mul_f32_e32 v11, v67, v2
	v_cvt_pk_bf16_f32 v8, v8, v9
	v_cvt_pk_bf16_f32 v9, v10, v11
	v_lshl_add_u64 v[6:7], v[152:153], 0, v[6:7]
	global_store_dwordx2 v[6:7], v[8:9], off
	v_mul_f32_e32 v8, v68, v2
	v_mul_f32_e32 v9, v69, v2
	v_mul_f32_e32 v10, v70, v2
	v_mul_f32_e32 v11, v71, v2
	v_cvt_pk_bf16_f32 v8, v8, v9
	v_cvt_pk_bf16_f32 v9, v10, v11
	global_store_dwordx2 v[6:7], v[8:9], off offset:16
	v_mul_f32_e32 v8, v72, v2
	v_mul_f32_e32 v9, v73, v2
	v_mul_f32_e32 v10, v74, v2
	v_mul_f32_e32 v11, v75, v2
	v_cvt_pk_bf16_f32 v8, v8, v9
	v_cvt_pk_bf16_f32 v9, v10, v11
	global_store_dwordx2 v[6:7], v[8:9], off offset:32
	v_mul_f32_e32 v8, v76, v2
	v_mul_f32_e32 v9, v77, v2
	v_mul_f32_e32 v10, v78, v2
	v_mul_f32_e32 v11, v79, v2
	v_cvt_pk_bf16_f32 v8, v8, v9
	v_cvt_pk_bf16_f32 v9, v10, v11
	global_store_dwordx2 v[6:7], v[8:9], off offset:48
	v_mul_f32_e32 v8, v48, v2
	v_mul_f32_e32 v9, v49, v2
	v_mul_f32_e32 v10, v50, v2
	v_mul_f32_e32 v11, v51, v2
	v_cvt_pk_bf16_f32 v8, v8, v9
	v_cvt_pk_bf16_f32 v9, v10, v11
	global_store_dwordx2 v[6:7], v[8:9], off offset:64
	v_mul_f32_e32 v8, v52, v2
	v_mul_f32_e32 v9, v53, v2
	v_mul_f32_e32 v10, v54, v2
	v_mul_f32_e32 v11, v55, v2
	v_cvt_pk_bf16_f32 v8, v8, v9
	v_cvt_pk_bf16_f32 v9, v10, v11
	global_store_dwordx2 v[6:7], v[8:9], off offset:80
	v_mul_f32_e32 v8, v56, v2
	v_mul_f32_e32 v9, v57, v2
	v_mul_f32_e32 v10, v58, v2
	v_mul_f32_e32 v11, v59, v2
	v_cvt_pk_bf16_f32 v8, v8, v9
	v_cvt_pk_bf16_f32 v9, v10, v11
	global_store_dwordx2 v[6:7], v[8:9], off offset:96
	v_mul_f32_e32 v8, v60, v2
	v_mul_f32_e32 v9, v61, v2
	v_mul_f32_e32 v10, v62, v2
	v_mul_f32_e32 v11, v63, v2
	v_cvt_pk_bf16_f32 v8, v8, v9
	v_cvt_pk_bf16_f32 v9, v10, v11
	global_store_dwordx2 v[6:7], v[8:9], off offset:112
	s_and_b64 exec, exec, s[78:79]
	s_cbranch_execz .LBB0_502
	v_sub_u32_sdwa v0, v135, s1 dst_sel:DWORD dst_unused:UNUSED_PAD src0_sel:WORD_0 src1_sel:DWORD
	v_cvt_f32_i32_e32 v0, v0
	v_readlane_b32 s0, v252, 9
	v_readlane_b32 s1, v252, 10
	v_fma_f32 v2, -v132, v0, v136
	s_nop 0
	v_lshl_add_u64 v[4:5], v[4:5], 3, s[0:1]
	global_store_dwordx2 v[4:5], v[2:3], off

; __device__ __forceinline__ void fox_unit(LAS char* lds, int bh, int qb2, const bf16_t* H, const float* c, const unsigned* ctl, bf16_t* U, int tid) {
;     ...
;     for (int kt = lane; kt < nprev; kt += 64) npass += ((cref - cbh[64 * kt + 63]) * LOG2E >= thr) ? 1 : 0;
.LBB0_507:
	v_lshlrev_b32_e32 v0, 6, v4
	v_lshlrev_b32_e32 v14, 6, v5
	v_mov_b32_e32 v15, v1
	v_lshl_add_u64 v[16:17], v[0:1], 2, s[18:19]
	v_lshl_add_u64 v[14:15], v[14:15], 2, s[18:19]
	global_load_dword v16, v[16:17], off offset:252
	s_nop 0
	global_load_dword v17, v[14:15], off offset:252
	v_add_u32_e32 v12, -2, v12
	v_cmp_eq_u32_e32 vcc, 0, v12
	s_or_b64 s[50:51], vcc, s[50:51]
	v_add_u32_e32 v5, 0x80, v5
	v_add_u32_e32 v4, 0x80, v4
	s_waitcnt vmcnt(0)
	v_sub_f32_e32 v14, v2, v16
	v_sub_f32_e32 v15, v3, v17
	s_nop 0
	v_mul_f32_e64 v14, v14, s34
	v_mul_f32_e64 v15, v15, s34
	s_nop 0
	v_cmp_ge_f32_e32 vcc, v15, v10
	s_nop 1
	v_addc_co_u32_e32 v11, vcc, 0, v11, vcc
	v_cmp_ge_f32_e32 vcc, v14, v10
	s_nop 1
	v_addc_co_u32_e32 v9, vcc, 0, v9, vcc
	s_andn2_b64 exec, exec, s[50:51]
	s_cbranch_execnz .LBB0_507
	s_or_b64 exec, exec, s[50:51]
	v_cmp_ne_u32_e32 vcc, v7, v8
	v_lshl_or_b32 v4, v8, 6, v146
	v_add_u32_e32 v3, v9, v11
	s_orn2_b64 s[50:51], vcc, exec

; __device__ __forceinline__ unsigned cvt_pk_bf16(float lo, float hi) { f32x2_t v = {lo, hi}; bf16x2_t b = __builtin_convertvector(v, bf16x2_t); return __builtin_bit_cast(unsigned, b); }
; __device__ __forceinline__ float fast_exp2(float x) { return __builtin_amdgcn_exp2f(x); }
; template <bool MASK> ...
;     ...
;     { const f32x2_t m2 = {m, m}; f32x2_t ps2 = {0.f, 0.f};
; #pragma unroll
;       for (int i = 0; i < 8; ++i) { f32x2_t t = sp[i] - m2; t[0] = fast_exp2(t[0]); t[1] = fast_exp2(t[1]); sp[i] = t; ps2 = ps2 + t; }
;       l += ps2[0] + ps2[1]; }
;     u32x4 pw0, pw1;
;     pw0.x = cvt_pk_bf16(sp[0][0], sp[0][1]); pw0.y = cvt_pk_bf16(sp[1][0], sp[1][1]); pw0.z = cvt_pk_bf16(sp[2][0], sp[2][1]); pw0.w = cvt_pk_bf16(sp[3][0], sp[3][1]);
;     pw1.x = cvt_pk_bf16(sp[4][0], sp[4][1]); pw1.y = cvt_pk_bf16(sp[5][0], sp[5][1]); pw1.z = cvt_pk_bf16(sp[6][0], sp[6][1]); pw1.w = cvt_pk_bf16(sp[7][0], sp[7][1]);
;     asm volatile("s_waitcnt lgkmcnt(0)" : "+v"(l00), "+v"(h00), "+v"(l01), "+v"(h01), "+v"(l10), "+v"(h10), "+v"(l11), "+v"(h11) :: "memory");
;     { const bf16x8 pb0 = __builtin_bit_cast(bf16x8, pw0), pb1 = __builtin_bit_cast(bf16x8, pw1);
;       const bf16x8 v00 = {l00[0], l00[1], l00[2], l00[3], h00[0], h00[1], h00[2], h00[3]}, v01 = {l01[0], l01[1], l01[2], l01[3], h01[0], h01[1], h01[2], h01[3]};
;       const bf16x8 v10 = {l10[0], l10[1], l10[2], l10[3], h10[0], h10[1], h10[2], h10[3]}, v11 = {l11[0], l11[1], l11[2], l11[3], h11[0], h11[1], h11[2], h11[3]};
;       o0 = __builtin_amdgcn_mfma_f32_32x32x16_bf16(v00, pb0, o0, 0, 0, 0); o1 = __builtin_amdgcn_mfma_f32_32x32x16_bf16(v01, pb0, o1, 0, 0, 0);
;       o0 = __builtin_amdgcn_mfma_f32_32x32x16_bf16(v10, pb1, o0, 0, 0, 0); o1 = __builtin_amdgcn_mfma_f32_32x32x16_bf16(v11, pb1, o1, 0, 0, 0); }
.LBB0_521:
	v_sub_f32_e32 v66, v66, v0
	v_sub_f32_e32 v67, v67, v0
	v_sub_f32_e32 v68, v68, v0
	v_sub_f32_e32 v69, v69, v0
	v_exp_f32_e32 v66, v66
	v_exp_f32_e32 v67, v67
	v_sub_f32_e32 v70, v70, v0
	v_sub_f32_e32 v71, v71, v0
	v_sub_f32_e32 v72, v72, v0
	v_sub_f32_e32 v73, v73, v0
	v_exp_f32_e32 v68, v68
	v_exp_f32_e32 v69, v69
	v_exp_f32_e32 v70, v70
	v_exp_f32_e32 v71, v71
	v_exp_f32_e32 v72, v72
	v_exp_f32_e32 v73, v73
	v_add_f32_e32 v130, 0, v66
	v_add_f32_e32 v131, 0, v67
	v_cvt_pk_bf16_f32 v66, v66, v67
	v_add_f32_e32 v130, v68, v130
	v_add_f32_e32 v131, v69, v131
	v_cvt_pk_bf16_f32 v67, v68, v69
	v_cvt_pk_bf16_f32 v68, v70, v71
	v_cvt_pk_bf16_f32 v69, v72, v73
	s_waitcnt lgkmcnt(0)
	v_sub_f32_e32 v74, v74, v0
	v_sub_f32_e32 v75, v75, v0
	v_sub_f32_e32 v76, v76, v0
	v_sub_f32_e32 v77, v77, v0
	v_mfma_f32_32x32x16_bf16 v[18:33], v[94:97], v[66:69], v[18:33]
	v_add_f32_e64 v78, v78, -v0
	v_add_f32_e64 v79, v79, -v0
	v_add_f32_e64 v80, v80, -v0
	v_add_f32_e64 v81, v81, -v0
	v_exp_f32_e32 v74, v74
	v_exp_f32_e32 v75, v75
	v_exp_f32_e32 v76, v76
	v_exp_f32_e32 v77, v77
	v_exp_f32_e32 v78, v78
	v_mfma_f32_32x32x16_bf16 v[2:17], v[90:93], v[66:69], v[2:17]
	v_exp_f32_e32 v79, v79
	v_exp_f32_e32 v80, v80
	v_exp_f32_e32 v81, v81
	v_add_f32_e32 v130, v70, v130
	v_add_f32_e32 v131, v71, v131
	v_cvt_pk_bf16_f32 v70, v74, v75
	v_add_f32_e32 v130, v72, v130
	v_add_f32_e32 v131, v73, v131
	v_cvt_pk_bf16_f32 v71, v76, v77
	v_cvt_pk_bf16_f32 v72, v78, v79
	v_cvt_pk_bf16_f32 v73, v80, v81
	v_add_f32_e32 v130, v74, v130
	v_add_f32_e32 v131, v75, v131
	v_mov_b32_e32 v245, v211
	v_mfma_f32_32x32x16_bf16 v[18:33], v[86:89], v[70:73], v[18:33]
	v_add_f32_e64 v130, v76, v130
	v_add_f32_e64 v131, v77, v131
	v_add_f32_e64 v130, v78, v130
	v_add_f32_e64 v131, v79, v131
	v_add_f32_e64 v130, v80, v130
	v_add_f32_e64 v131, v81, v131
	v_add_f32_e32 v0, v130, v131
	v_mfma_f32_32x32x16_bf16 v[2:17], v[82:85], v[70:73], v[2:17]
	s_nop 3
	v_add_f32_e32 v0, v194, v0
	s_nop 0

; #define LAS __attribute__((address_space(3)))
; template <bool MASK> ...
;     s16x4 l00, h00, l01, h01, l10, h10, l11, h11; { const unsigned a0 = va0 + sub * 4096, a1 = va1 + sub * 4096;
;       asm volatile("ds_read_b64_tr_b16 %0, %1" : "=&v"(l00) : "v"(a0) : "memory"); asm volatile("ds_read_b64_tr_b16 %0, %1 offset:1024" : "=&v"(h00) : "v"(a0) : "memory");
;       asm volatile("ds_read_b64_tr_b16 %0, %1" : "=&v"(l01) : "v"(a1) : "memory"); asm volatile("ds_read_b64_tr_b16 %0, %1 offset:1024" : "=&v"(h01) : "v"(a1) : "memory");
;       asm volatile("ds_read_b64_tr_b16 %0, %1 offset:2048" : "=&v"(l10) : "v"(a0) : "memory"); asm volatile("ds_read_b64_tr_b16 %0, %1 offset:3072" : "=&v"(h10) : "v"(a0) : "memory");
;       asm volatile("ds_read_b64_tr_b16 %0, %1 offset:2048" : "=&v"(l11) : "v"(a1) : "memory"); asm volatile("ds_read_b64_tr_b16 %0, %1 offset:3072" : "=&v"(h11) : "v"(a1) : "memory"); }
;     const int r = lane & 31, hh = lane >> 5;
;     f32x16 st = {0.f, 0.f, 0.f, 0.f, 0.f, 0.f, 0.f, 0.f, 0.f, 0.f, 0.f, 0.f, 0.f, 0.f, 0.f, 0.f};
;     { const int key = sub * 32 + r; const LAS char* kp = Kt + key * 128; const int ksw = (key >> 1) & 7;
; #pragma unroll
;       for (int d0 = 0; d0 < 4; ++d0) { const bf16x8 kf = *(const LAS bf16x8*)(kp + (((2 * d0 + hh) ^ ksw) << 4)); st = __builtin_amdgcn_mfma_f32_32x32x16_bf16(kf, qr[d0], st, 0, 0, 0); } }
;     f32x2_t sp[8]; const f32x2_t cs2 = {cscale, cscale};
; #pragma unroll
;     for (int g = 0; g < 4; ++g) { const f32x4 c4 = *(const LAS f32x4*)(cb + sub * 32 + 8 * g + 4 * hh);
;         sp[2 * g] = (f32x2_t){st[4 * g], st[4 * g + 1]} + cs2 * (f32x2_t){c4[0], c4[1]};
;         sp[2 * g + 1] = (f32x2_t){st[4 * g + 2], st[4 * g + 3]} + cs2 * (f32x2_t){c4[2], c4[3]};
;         if (MASK) {
; #pragma unroll
;             for (int e = 0; e < 4; ++e) { const int kpos = kpos_sub + 8 * g + 4 * hh + e; const bool ok = (kpos <= qpos && kpos >= qpos - win);
;                 sp[2 * g + (e >> 1)][e & 1] = ok ? sp[2 * g + (e >> 1)][e & 1] : -INFINITY; } } }
;     float rm = fmaxf(sp[0][0], sp[0][1]);
; #pragma unroll
;     for (int i = 1; i < 8; ++i) rm = fmaxf(fmaxf(rm, sp[i][0]), sp[i][1]);
;     rm = swap_max(rm);
;     if (__any(rm - m > 8.0f)) { const float mnew = fmaxf(m, rm); const float f = fast_exp2(m - mnew); l *= f; o0 = o0 * f; o1 = o1 * f; m = mnew; }
.LBB0_531:
	s_mul_hi_u32 s5, s1, 0xaaaaaaab
	s_lshr_b32 s5, s5, 1
	s_mul_i32 s5, s5, 3
	s_add_i32 s4, s1, s50
	s_sub_i32 s1, s1, s5
	s_lshl_b32 s5, s1, 13
	s_add_i32 s16, s5, 0
	s_mulk_i32 s1, 0xe100
	s_lshl_b32 s4, s4, 6
	s_add_i32 s1, s16, s1
	v_add_u32_e32 v0, s16, v198
	v_add_u32_e32 v217, s5, v189
	v_add_u32_e32 v243, s5, v190
	s_cmp_gt_i32 s4, s11
	v_add_u32_e32 v216, v0, v191
	v_add_u32_e32 v215, v0, v192
	v_add_u32_e32 v214, v0, v193
	v_add_u32_e32 v213, v0, v196
	s_cbranch_scc1 .LBB0_543
	s_or_b32 s5, s4, 31
	s_cmp_gt_i32 s5, s47
	s_mov_b64 s[18:19], -1
	s_cbranch_scc1 .LBB0_537
	ds_read_b64_tr_b16 v[142:143], v217
	ds_read_b64_tr_b16 v[144:145], v217 offset:1024
	ds_read_b64_tr_b16 v[138:139], v243
	ds_read_b64_tr_b16 v[140:141], v243 offset:1024
	ds_read_b64_tr_b16 v[134:135], v217 offset:2048
	ds_read_b64_tr_b16 v[136:137], v217 offset:3072
	ds_read_b64_tr_b16 v[130:131], v243 offset:2048
	ds_read_b64_tr_b16 v[132:133], v243 offset:3072
	ds_read_b128 v[66:69], v216
	ds_read_b128 v[82:85], v215
	ds_read_b128 v[86:89], v214
	ds_read_b128 v[90:93], v213
	v_add_u32_e32 v0, s1, v197
	s_waitcnt lgkmcnt(2)
	v_mfma_f32_32x32x16_bf16 v[66:81], v[66:69], v[98:101], 0
	v_mfma_f32_32x32x16_bf16 v[66:81], v[82:85], v[102:105], v[66:81]
	s_waitcnt lgkmcnt(1)
	v_mfma_f32_32x32x16_bf16 v[66:81], v[86:89], v[106:109], v[66:81]
	s_waitcnt lgkmcnt(0)
	v_mfma_f32_32x32x16_bf16 v[66:81], v[90:93], v[110:113], v[66:81]
	ds_read_b128 v[82:85], v0 offset:49152
	ds_read_b128 v[86:89], v0 offset:49184
	ds_read_b128 v[90:93], v0 offset:49216
	ds_read_b128 v[94:97], v0 offset:49248
	s_waitcnt lgkmcnt(0)
	s_nop 8
	v_fma_f32 v178, -v82, s34, v66
	v_fma_f32 v179, -v83, s34, v67
	v_fma_f32 v176, -v84, s34, v68
	v_fma_f32 v177, -v85, s34, v69
	v_fma_f32 v170, -v86, s34, v70
	v_fma_f32 v171, -v87, s34, v71
	v_fma_f32 v168, -v88, s34, v72
	v_fma_f32 v169, -v89, s34, v73
	v_fma_f32 v174, -v90, s34, v74
	v_fma_f32 v175, -v91, s34, v75
	v_fma_f32 v172, -v92, s34, v76
	v_fma_f32 v173, -v93, s34, v77
	v_max_f32_e32 v0, v178, v179
	v_max3_f32 v0, v0, v176, v177
	v_max3_f32 v0, v0, v170, v171
	v_max3_f32 v0, v0, v168, v169
	v_max3_f32 v0, v0, v174, v175
	v_fma_f32 v180, -v94, s34, v78
	v_fma_f32 v181, -v95, s34, v79
	v_max3_f32 v0, v0, v172, v173
	v_fma_f32 v182, -v96, s34, v80
	v_fma_f32 v183, -v97, s34, v81
	v_max3_f32 v0, v0, v180, v181
	v_max3_f32 v0, v0, v182, v183
	v_mov_b32_e32 v66, v0
	s_nop 1
	v_permlane32_swap_b32_e32 v0, v66
	v_max_f32_e32 v66, v66, v66
	v_max_f32_e32 v0, v0, v0
	v_max_f32_e32 v0, v0, v66
	v_sub_f32_e32 v66, v0, v210
	v_cmp_lt_f32_e32 vcc, s9, v66
	s_cbranch_vccz .LBB0_535
	v_max_f32_e32 v0, v0, v0
	v_max_f32_e32 v66, v210, v210
	v_max_f32_e32 v244, v66, v0
	v_sub_f32_e32 v0, v210, v244
	v_exp_f32_e32 v0, v0
	s_nop 0
	v_mul_f32_e32 v245, v212, v0
	v_mul_f32_e32 v64, v64, v0
	v_mul_f32_e32 v65, v65, v0
	v_mul_f32_e32 v62, v62, v0
	v_mul_f32_e32 v63, v63, v0
	v_mul_f32_e32 v60, v60, v0
	v_mul_f32_e32 v61, v61, v0
	v_mul_f32_e32 v58, v58, v0
	v_mul_f32_e32 v59, v59, v0
	v_mul_f32_e32 v56, v56, v0
	v_mul_f32_e32 v57, v57, v0
	v_mul_f32_e32 v54, v54, v0
	v_mul_f32_e32 v55, v55, v0
	v_mul_f32_e32 v52, v52, v0
	v_mul_f32_e32 v53, v53, v0
	v_mul_f32_e32 v50, v50, v0
	v_mul_f32_e32 v51, v51, v0
	v_mul_f32_e32 v48, v48, v0
	v_mul_f32_e32 v49, v49, v0
	v_mul_f32_e32 v46, v46, v0
	v_mul_f32_e32 v47, v47, v0
	v_mul_f32_e32 v44, v44, v0
	v_mul_f32_e32 v45, v45, v0
	v_mul_f32_e32 v42, v42, v0
	v_mul_f32_e32 v43, v43, v0
	v_mul_f32_e32 v40, v40, v0
	v_mul_f32_e32 v41, v41, v0
	v_mul_f32_e32 v38, v38, v0
	v_mul_f32_e32 v39, v39, v0
	v_mul_f32_e32 v36, v36, v0
	v_mul_f32_e32 v37, v37, v0
	v_mul_f32_e32 v34, v34, v0
	v_mul_f32_e32 v35, v35, v0
	v_mov_b32_e32 v0, v244
	s_branch .LBB0_536

; __device__ __forceinline__ unsigned cvt_pk_bf16(float lo, float hi) { f32x2_t v = {lo, hi}; bf16x2_t b = __builtin_convertvector(v, bf16x2_t); return __builtin_bit_cast(unsigned, b); }
; __device__ __forceinline__ float fast_exp2(float x) { return __builtin_amdgcn_exp2f(x); }
; template <bool MASK> ...
;     ...
;     { const f32x2_t m2 = {m, m}; f32x2_t ps2 = {0.f, 0.f};
; #pragma unroll
;       for (int i = 0; i < 8; ++i) { f32x2_t t = sp[i] - m2; t[0] = fast_exp2(t[0]); t[1] = fast_exp2(t[1]); sp[i] = t; ps2 = ps2 + t; }
;       l += ps2[0] + ps2[1]; }
;     u32x4 pw0, pw1;
;     pw0.x = cvt_pk_bf16(sp[0][0], sp[0][1]); pw0.y = cvt_pk_bf16(sp[1][0], sp[1][1]); pw0.z = cvt_pk_bf16(sp[2][0], sp[2][1]); pw0.w = cvt_pk_bf16(sp[3][0], sp[3][1]);
;     pw1.x = cvt_pk_bf16(sp[4][0], sp[4][1]); pw1.y = cvt_pk_bf16(sp[5][0], sp[5][1]); pw1.z = cvt_pk_bf16(sp[6][0], sp[6][1]); pw1.w = cvt_pk_bf16(sp[7][0], sp[7][1]);
;     asm volatile("s_waitcnt lgkmcnt(0)" : "+v"(l00), "+v"(h00), "+v"(l01), "+v"(h01), "+v"(l10), "+v"(h10), "+v"(l11), "+v"(h11) :: "memory");
;     { const bf16x8 pb0 = __builtin_bit_cast(bf16x8, pw0), pb1 = __builtin_bit_cast(bf16x8, pw1);
;       const bf16x8 v00 = {l00[0], l00[1], l00[2], l00[3], h00[0], h00[1], h00[2], h00[3]}, v01 = {l01[0], l01[1], l01[2], l01[3], h01[0], h01[1], h01[2], h01[3]};
;       const bf16x8 v10 = {l10[0], l10[1], l10[2], l10[3], h10[0], h10[1], h10[2], h10[3]}, v11 = {l11[0], l11[1], l11[2], l11[3], h11[0], h11[1], h11[2], h11[3]};
;       o0 = __builtin_amdgcn_mfma_f32_32x32x16_bf16(v00, pb0, o0, 0, 0, 0); o1 = __builtin_amdgcn_mfma_f32_32x32x16_bf16(v01, pb0, o1, 0, 0, 0);
;       o0 = __builtin_amdgcn_mfma_f32_32x32x16_bf16(v10, pb1, o0, 0, 0, 0); o1 = __builtin_amdgcn_mfma_f32_32x32x16_bf16(v11, pb1, o1, 0, 0, 0); }
.LBB0_536:
	v_sub_f32_e32 v178, v178, v0
	v_sub_f32_e32 v179, v179, v0
	v_sub_f32_e32 v176, v176, v0
	v_sub_f32_e32 v177, v177, v0
	v_exp_f32_e32 v178, v178
	v_exp_f32_e32 v179, v179
	v_exp_f32_e32 v176, v176
	v_exp_f32_e32 v177, v177
	v_sub_f32_e32 v170, v170, v0
	v_sub_f32_e32 v171, v171, v0
	v_sub_f32_e32 v168, v168, v0
	v_sub_f32_e32 v169, v169, v0
	v_exp_f32_e32 v170, v170
	v_exp_f32_e32 v171, v171
	v_exp_f32_e32 v248, v168
	v_exp_f32_e32 v249, v169
	v_add_f32_e32 v246, 0, v178
	v_add_f32_e32 v247, 0, v179
	v_sub_f32_e32 v174, v174, v0
	v_sub_f32_e32 v175, v175, v0
	v_add_f32_e32 v246, v176, v246
	v_add_f32_e32 v247, v177, v247
	v_exp_f32_e32 v174, v174
	v_add_f32_e32 v246, v170, v246
	v_add_f32_e32 v247, v171, v247
	v_exp_f32_e32 v175, v175
	v_sub_f32_e32 v172, v172, v0
	v_sub_f32_e32 v173, v173, v0
	v_add_f32_e32 v168, v248, v246
	v_add_f32_e32 v169, v249, v247
	v_exp_f32_e32 v246, v172
	v_exp_f32_e32 v247, v173
	v_sub_f32_e32 v172, v180, v0
	v_sub_f32_e32 v173, v181, v0
	v_add_f32_e32 v168, v174, v168
	v_add_f32_e32 v169, v175, v169
	v_exp_f32_e32 v180, v172
	v_exp_f32_e32 v181, v173
	v_sub_f32_e32 v172, v182, v0
	v_sub_f32_e32 v173, v183, v0
	v_add_f32_e32 v168, v246, v168
	v_add_f32_e32 v169, v247, v169
	v_exp_f32_e32 v182, v172
	v_exp_f32_e32 v183, v173
	v_add_f32_e32 v168, v180, v168
	v_add_f32_e32 v169, v181, v169
	v_cvt_pk_bf16_f32 v170, v170, v171
	v_cvt_pk_bf16_f32 v171, v248, v249
	v_add_f32_e32 v168, v182, v168
	v_add_f32_e32 v169, v183, v169
	s_waitcnt lgkmcnt(0)
	v_cvt_pk_bf16_f32 v172, v174, v175
	v_add_f32_e32 v0, v168, v169
	v_cvt_pk_bf16_f32 v168, v178, v179
	v_cvt_pk_bf16_f32 v169, v176, v177
	v_cvt_pk_bf16_f32 v173, v246, v247
	v_cvt_pk_bf16_f32 v174, v180, v181
	v_mfma_f32_32x32x16_bf16 v[50:65], v[142:145], v[168:171], v[50:65]
	v_cvt_pk_bf16_f32 v175, v182, v183
	v_add_f32_e32 v0, v245, v0
	s_mov_b64 s[18:19], 0
	v_mfma_f32_32x32x16_bf16 v[34:49], v[138:141], v[168:171], v[34:49]
	v_mfma_f32_32x32x16_bf16 v[50:65], v[134:137], v[172:175], v[50:65]
	v_mfma_f32_32x32x16_bf16 v[34:49], v[130:133], v[172:175], v[34:49]
; #define LAS __attribute__((address_space(3)))
; template <bool MASK> ...
;     s16x4 l00, h00, l01, h01, l10, h10, l11, h11; { const unsigned a0 = va0 + sub * 4096, a1 = va1 + sub * 4096;
;       asm volatile("ds_read_b64_tr_b16 %0, %1" : "=&v"(l00) : "v"(a0) : "memory"); asm volatile("ds_read_b64_tr_b16 %0, %1 offset:1024" : "=&v"(h00) : "v"(a0) : "memory");
;       asm volatile("ds_read_b64_tr_b16 %0, %1" : "=&v"(l01) : "v"(a1) : "memory"); asm volatile("ds_read_b64_tr_b16 %0, %1 offset:1024" : "=&v"(h01) : "v"(a1) : "memory");
;       asm volatile("ds_read_b64_tr_b16 %0, %1 offset:2048" : "=&v"(l10) : "v"(a0) : "memory"); asm volatile("ds_read_b64_tr_b16 %0, %1 offset:3072" : "=&v"(h10) : "v"(a0) : "memory");
;       asm volatile("ds_read_b64_tr_b16 %0, %1 offset:2048" : "=&v"(l11) : "v"(a1) : "memory"); asm volatile("ds_read_b64_tr_b16 %0, %1 offset:3072" : "=&v"(h11) : "v"(a1) : "memory"); }
;     const int r = lane & 31, hh = lane >> 5;
;     f32x16 st = {0.f, 0.f, 0.f, 0.f, 0.f, 0.f, 0.f, 0.f, 0.f, 0.f, 0.f, 0.f, 0.f, 0.f, 0.f, 0.f};
;     { const int key = sub * 32 + r; const LAS char* kp = Kt + key * 128; const int ksw = (key >> 1) & 7;
; #pragma unroll
;       for (int d0 = 0; d0 < 4; ++d0) { const bf16x8 kf = *(const LAS bf16x8*)(kp + (((2 * d0 + hh) ^ ksw) << 4)); st = __builtin_amdgcn_mfma_f32_32x32x16_bf16(kf, qr[d0], st, 0, 0, 0); } }
;     f32x2_t sp[8]; const f32x2_t cs2 = {cscale, cscale};
; #pragma unroll
;     for (int g = 0; g < 4; ++g) { const f32x4 c4 = *(const LAS f32x4*)(cb + sub * 32 + 8 * g + 4 * hh);
;         sp[2 * g] = (f32x2_t){st[4 * g], st[4 * g + 1]} + cs2 * (f32x2_t){c4[0], c4[1]};
;         sp[2 * g + 1] = (f32x2_t){st[4 * g + 2], st[4 * g + 3]} + cs2 * (f32x2_t){c4[2], c4[3]};
;         if (MASK) {
; #pragma unroll
;             for (int e = 0; e < 4; ++e) { const int kpos = kpos_sub + 8 * g + 4 * hh + e; const bool ok = (kpos <= qpos && kpos >= qpos - win);
;                 sp[2 * g + (e >> 1)][e & 1] = ok ? sp[2 * g + (e >> 1)][e & 1] : -INFINITY; } } }
;     float rm = fmaxf(sp[0][0], sp[0][1]);
; #pragma unroll
;     for (int i = 1; i < 8; ++i) rm = fmaxf(fmaxf(rm, sp[i][0]), sp[i][1]);
;     rm = swap_max(rm);
;     if (__any(rm - m > 8.0f)) { const float mnew = fmaxf(m, rm); const float f = fast_exp2(m - mnew); l *= f; o0 = o0 * f; o1 = o1 * f; m = mnew; }
.LBB0_537:
	s_and_b64 vcc, exec, s[18:19]
	s_cbranch_vccz .LBB0_542
	ds_read_b64_tr_b16 v[94:95], v217
	ds_read_b64_tr_b16 v[96:97], v217 offset:1024
	ds_read_b64_tr_b16 v[90:91], v243
	ds_read_b64_tr_b16 v[92:93], v243 offset:1024
	ds_read_b64_tr_b16 v[86:87], v217 offset:2048
	ds_read_b64_tr_b16 v[88:89], v217 offset:3072
	ds_read_b64_tr_b16 v[82:83], v243 offset:2048
	ds_read_b64_tr_b16 v[84:85], v243 offset:3072
	s_nop 8
	ds_read_b128 v[66:69], v216
	ds_read_b128 v[130:133], v215
	v_add_u32_e32 v138, s1, v197
	v_or_b32_e32 v0, s4, v150
	v_cmp_le_i32_e32 vcc, v0, v158
	v_cmp_ge_i32_e64 s[44:45], v0, v208
	s_and_b64 vcc, vcc, s[44:45]
	s_waitcnt lgkmcnt(0)
	v_mfma_f32_32x32x16_bf16 v[66:81], v[66:69], v[98:101], 0
	v_mfma_f32_32x32x16_bf16 v[66:81], v[130:133], v[102:105], v[66:81]
	ds_read_b128 v[130:133], v214
	s_waitcnt lgkmcnt(0)
	v_mfma_f32_32x32x16_bf16 v[66:81], v[130:133], v[106:109], v[66:81]
	ds_read_b128 v[130:133], v213
	s_waitcnt lgkmcnt(0)
	v_mfma_f32_32x32x16_bf16 v[66:81], v[130:133], v[110:113], v[66:81]
	ds_read_b128 v[130:133], v138 offset:49152
	ds_read_b128 v[134:137], v138 offset:49184
	s_waitcnt lgkmcnt(0)
	s_nop 8
	v_fma_f32 v66, -v130, s34, v66
	v_fma_f32 v67, -v131, s34, v67
	v_or_b32_e32 v130, 1, v0
	v_cndmask_b32_e32 v66, v240, v66, vcc
	v_cmp_lt_i32_e32 vcc, v0, v158
	v_cmp_ge_i32_e64 s[44:45], v130, v208
	s_and_b64 vcc, vcc, s[44:45]
	v_or_b32_e32 v130, 2, v0
	v_cndmask_b32_e32 v67, v240, v67, vcc
	v_cmp_le_i32_e32 vcc, v130, v158
	v_cmp_ge_i32_e64 s[44:45], v130, v208
	v_fma_f32 v68, -v132, s34, v68
	v_fma_f32 v69, -v133, s34, v69
	s_and_b64 vcc, vcc, s[44:45]
	v_or_b32_e32 v130, 3, v0
	v_cndmask_b32_e32 v68, v240, v68, vcc
	v_cmp_le_i32_e32 vcc, v130, v158
	v_cmp_ge_i32_e64 s[44:45], v130, v208
	s_and_b64 vcc, vcc, s[44:45]
	v_or_b32_e32 v130, 8, v0
	v_cndmask_b32_e32 v69, v240, v69, vcc
	v_cmp_le_i32_e32 vcc, v130, v158
	v_cmp_ge_i32_e64 s[44:45], v130, v208
	v_fma_f32 v70, -v134, s34, v70
	v_fma_f32 v71, -v135, s34, v71
	s_and_b64 vcc, vcc, s[44:45]
	v_or_b32_e32 v130, 9, v0
	v_cndmask_b32_e32 v70, v240, v70, vcc
	v_cmp_le_i32_e32 vcc, v130, v158
	v_cmp_ge_i32_e64 s[44:45], v130, v208
	s_and_b64 vcc, vcc, s[44:45]
	v_or_b32_e32 v130, 10, v0
	v_cndmask_b32_e32 v71, v240, v71, vcc
	v_cmp_le_i32_e32 vcc, v130, v158
	v_cmp_ge_i32_e64 s[44:45], v130, v208
	v_fma_f32 v72, -v136, s34, v72
	v_fma_f32 v73, -v137, s34, v73
	s_and_b64 vcc, vcc, s[44:45]
	v_or_b32_e32 v130, 11, v0
	v_cndmask_b32_e32 v72, v240, v72, vcc
	v_cmp_le_i32_e32 vcc, v130, v158
	v_cmp_ge_i32_e64 s[44:45], v130, v208
	ds_read_b128 v[130:133], v138 offset:49216
	s_and_b64 vcc, vcc, s[44:45]
	v_cndmask_b32_e32 v73, v240, v73, vcc
	s_waitcnt lgkmcnt(0)
	v_fma_f32 v74, -v130, s34, v74
	v_fma_f32 v75, -v131, s34, v75
	v_or_b32_e32 v130, 16, v0
	v_cmp_le_i32_e32 vcc, v130, v158
	v_cmp_ge_i32_e64 s[44:45], v130, v208
	s_and_b64 vcc, vcc, s[44:45]
	v_or_b32_e32 v130, 17, v0
	v_cndmask_b32_e32 v74, v240, v74, vcc
	v_cmp_le_i32_e32 vcc, v130, v158
	v_cmp_ge_i32_e64 s[44:45], v130, v208
	s_and_b64 vcc, vcc, s[44:45]
	v_or_b32_e32 v130, 18, v0
	v_cndmask_b32_e32 v75, v240, v75, vcc
	v_cmp_le_i32_e32 vcc, v130, v158
	v_cmp_ge_i32_e64 s[44:45], v130, v208
	v_fma_f32 v76, -v132, s34, v76
	v_fma_f32 v77, -v133, s34, v77
	s_and_b64 vcc, vcc, s[44:45]
	v_or_b32_e32 v130, 19, v0
	v_cndmask_b32_e32 v76, v240, v76, vcc
	v_cmp_le_i32_e32 vcc, v130, v158
	v_cmp_ge_i32_e64 s[44:45], v130, v208
	ds_read_b128 v[130:133], v138 offset:49248
	s_and_b64 vcc, vcc, s[44:45]
	v_cndmask_b32_e32 v77, v240, v77, vcc
	s_waitcnt lgkmcnt(0)
	v_fma_f32 v78, -v130, s34, v78
	v_fma_f32 v79, -v131, s34, v79
	v_or_b32_e32 v130, 24, v0
	v_cmp_le_i32_e32 vcc, v130, v158
	v_cmp_ge_i32_e64 s[44:45], v130, v208
	s_and_b64 vcc, vcc, s[44:45]
	v_or_b32_e32 v130, 25, v0
	v_cndmask_b32_e32 v78, v240, v78, vcc
	v_cmp_le_i32_e32 vcc, v130, v158
	v_cmp_ge_i32_e64 s[44:45], v130, v208
	s_and_b64 vcc, vcc, s[44:45]
	v_or_b32_e32 v130, 26, v0
	v_cndmask_b32_e32 v79, v240, v79, vcc
	v_cmp_le_i32_e32 vcc, v130, v158
	v_cmp_ge_i32_e64 s[44:45], v130, v208
	v_fma_f32 v80, -v132, s34, v80
	v_fma_f32 v81, -v133, s34, v81
	s_and_b64 vcc, vcc, s[44:45]
	v_or_b32_e32 v0, 27, v0
	v_cndmask_b32_e32 v80, v240, v80, vcc
	v_cmp_le_i32_e32 vcc, v0, v158
	v_cmp_ge_i32_e64 s[44:45], v0, v208
	v_max_f32_e32 v0, v66, v67
	v_max3_f32 v0, v0, v68, v69
	v_max3_f32 v0, v0, v70, v71
	v_max3_f32 v0, v0, v72, v73
	v_max3_f32 v0, v0, v74, v75
	s_and_b64 vcc, vcc, s[44:45]
	v_max3_f32 v0, v0, v76, v77
	v_cndmask_b32_e32 v81, v240, v81, vcc
	v_max3_f32 v0, v0, v78, v79
	v_max3_f32 v0, v0, v80, v81
	v_mov_b32_e32 v130, v0
	s_nop 1
	v_permlane32_swap_b32_e32 v0, v130
	v_max_f32_e32 v130, v130, v130
	v_max_f32_e32 v0, v0, v0
	v_max_f32_e32 v0, v0, v130
	v_sub_f32_e32 v130, v0, v210
	v_cmp_lt_f32_e32 vcc, s9, v130
	s_cbranch_vccz .LBB0_540
	v_max_f32_e32 v0, v0, v0
	v_max_f32_e32 v130, v210, v210
	v_max_f32_e32 v0, v130, v0
	v_sub_f32_e32 v130, v210, v0
	v_exp_f32_e32 v130, v130
	v_mov_b32_e32 v210, v0
	v_mul_f32_e32 v212, v212, v130
	v_mul_f32_e32 v64, v64, v130
	v_mul_f32_e32 v65, v65, v130
	v_mul_f32_e32 v62, v62, v130
	v_mul_f32_e32 v63, v63, v130
	v_mul_f32_e32 v60, v60, v130
	v_mul_f32_e32 v61, v61, v130
	v_mul_f32_e32 v58, v58, v130
	v_mul_f32_e32 v59, v59, v130
	v_mul_f32_e32 v56, v56, v130
	v_mul_f32_e32 v57, v57, v130
	v_mul_f32_e32 v54, v54, v130
	v_mul_f32_e32 v55, v55, v130
	v_mul_f32_e32 v52, v52, v130
	v_mul_f32_e32 v53, v53, v130
	v_mul_f32_e32 v50, v50, v130
	v_mul_f32_e32 v51, v51, v130
	v_mul_f32_e32 v48, v48, v130
	v_mul_f32_e32 v49, v49, v130
	v_mul_f32_e32 v46, v46, v130
	v_mul_f32_e32 v47, v47, v130
	v_mul_f32_e32 v44, v44, v130
	v_mul_f32_e32 v45, v45, v130
	v_mul_f32_e32 v42, v42, v130
	v_mul_f32_e32 v43, v43, v130
	v_mul_f32_e32 v40, v40, v130
	v_mul_f32_e32 v41, v41, v130
	v_mul_f32_e32 v38, v38, v130
	v_mul_f32_e32 v39, v39, v130
	v_mul_f32_e32 v36, v36, v130
	v_mul_f32_e32 v37, v37, v130
	v_mul_f32_e32 v34, v34, v130
	v_mul_f32_e32 v35, v35, v130
	s_branch .LBB0_541

; __device__ __forceinline__ unsigned cvt_pk_bf16(float lo, float hi) { f32x2_t v = {lo, hi}; bf16x2_t b = __builtin_convertvector(v, bf16x2_t); return __builtin_bit_cast(unsigned, b); }
; __device__ __forceinline__ float fast_exp2(float x) { return __builtin_amdgcn_exp2f(x); }
; template <bool MASK> ...
;     ...
;     { const f32x2_t m2 = {m, m}; f32x2_t ps2 = {0.f, 0.f};
; #pragma unroll
;       for (int i = 0; i < 8; ++i) { f32x2_t t = sp[i] - m2; t[0] = fast_exp2(t[0]); t[1] = fast_exp2(t[1]); sp[i] = t; ps2 = ps2 + t; }
;       l += ps2[0] + ps2[1]; }
;     u32x4 pw0, pw1;
;     pw0.x = cvt_pk_bf16(sp[0][0], sp[0][1]); pw0.y = cvt_pk_bf16(sp[1][0], sp[1][1]); pw0.z = cvt_pk_bf16(sp[2][0], sp[2][1]); pw0.w = cvt_pk_bf16(sp[3][0], sp[3][1]);
;     pw1.x = cvt_pk_bf16(sp[4][0], sp[4][1]); pw1.y = cvt_pk_bf16(sp[5][0], sp[5][1]); pw1.z = cvt_pk_bf16(sp[6][0], sp[6][1]); pw1.w = cvt_pk_bf16(sp[7][0], sp[7][1]);
;     asm volatile("s_waitcnt lgkmcnt(0)" : "+v"(l00), "+v"(h00), "+v"(l01), "+v"(h01), "+v"(l10), "+v"(h10), "+v"(l11), "+v"(h11) :: "memory");
;     { const bf16x8 pb0 = __builtin_bit_cast(bf16x8, pw0), pb1 = __builtin_bit_cast(bf16x8, pw1);
;       const bf16x8 v00 = {l00[0], l00[1], l00[2], l00[3], h00[0], h00[1], h00[2], h00[3]}, v01 = {l01[0], l01[1], l01[2], l01[3], h01[0], h01[1], h01[2], h01[3]};
;       const bf16x8 v10 = {l10[0], l10[1], l10[2], l10[3], h10[0], h10[1], h10[2], h10[3]}, v11 = {l11[0], l11[1], l11[2], l11[3], h11[0], h11[1], h11[2], h11[3]};
;       o0 = __builtin_amdgcn_mfma_f32_32x32x16_bf16(v00, pb0, o0, 0, 0, 0); o1 = __builtin_amdgcn_mfma_f32_32x32x16_bf16(v01, pb0, o1, 0, 0, 0);
;       o0 = __builtin_amdgcn_mfma_f32_32x32x16_bf16(v10, pb1, o0, 0, 0, 0); o1 = __builtin_amdgcn_mfma_f32_32x32x16_bf16(v11, pb1, o1, 0, 0, 0); }
.LBB0_541:
	v_sub_f32_e32 v66, v66, v0
	v_sub_f32_e32 v67, v67, v0
	v_sub_f32_e32 v68, v68, v0
	v_sub_f32_e32 v69, v69, v0
	v_exp_f32_e32 v66, v66
	v_exp_f32_e32 v67, v67
	v_sub_f32_e32 v70, v70, v0
	v_sub_f32_e32 v71, v71, v0
	v_sub_f32_e32 v72, v72, v0
	v_sub_f32_e32 v73, v73, v0
	v_exp_f32_e32 v68, v68
	v_exp_f32_e32 v69, v69
	v_exp_f32_e32 v70, v70
	v_exp_f32_e32 v71, v71
	v_exp_f32_e32 v72, v72
	v_exp_f32_e32 v73, v73
	v_add_f32_e32 v130, 0, v66
	v_add_f32_e32 v131, 0, v67
	v_cvt_pk_bf16_f32 v66, v66, v67
	v_add_f32_e32 v130, v68, v130
	v_add_f32_e32 v131, v69, v131
	v_cvt_pk_bf16_f32 v67, v68, v69
	v_cvt_pk_bf16_f32 v68, v70, v71
	v_cvt_pk_bf16_f32 v69, v72, v73
	s_waitcnt lgkmcnt(0)
	v_sub_f32_e32 v74, v74, v0
	v_sub_f32_e32 v75, v75, v0
	v_sub_f32_e32 v76, v76, v0
	v_sub_f32_e32 v77, v77, v0
	v_mfma_f32_32x32x16_bf16 v[50:65], v[94:97], v[66:69], v[50:65]
	v_add_f32_e64 v78, v78, -v0
	v_add_f32_e64 v79, v79, -v0
	v_add_f32_e64 v80, v80, -v0
	v_add_f32_e64 v81, v81, -v0
	v_exp_f32_e32 v74, v74
	v_exp_f32_e32 v75, v75
	v_exp_f32_e32 v76, v76
	v_exp_f32_e32 v77, v77
	v_exp_f32_e32 v78, v78
	v_mfma_f32_32x32x16_bf16 v[34:49], v[90:93], v[66:69], v[34:49]
	v_exp_f32_e32 v79, v79
	v_exp_f32_e32 v80, v80
	v_exp_f32_e32 v81, v81
	v_add_f32_e32 v130, v70, v130
	v_add_f32_e32 v131, v71, v131
	v_cvt_pk_bf16_f32 v70, v74, v75
	v_add_f32_e32 v130, v72, v130
	v_add_f32_e32 v131, v73, v131
	v_cvt_pk_bf16_f32 v71, v76, v77
	v_cvt_pk_bf16_f32 v72, v78, v79
	v_cvt_pk_bf16_f32 v73, v80, v81
	v_add_f32_e32 v130, v74, v130
	v_add_f32_e32 v131, v75, v131
	v_mov_b32_e32 v244, v210
	v_mfma_f32_32x32x16_bf16 v[50:65], v[86:89], v[70:73], v[50:65]
	v_add_f32_e64 v130, v76, v130
	v_add_f32_e64 v131, v77, v131
	v_add_f32_e64 v130, v78, v130
	v_add_f32_e64 v131, v79, v131
	v_add_f32_e64 v130, v80, v130
	v_add_f32_e64 v131, v81, v131
	v_add_f32_e32 v0, v130, v131
	v_mfma_f32_32x32x16_bf16 v[34:49], v[82:85], v[70:73], v[34:49]
	s_nop 3
	v_add_f32_e32 v0, v212, v0
	s_nop 0

; #define LAS __attribute__((address_space(3)))
; template <bool MASK> ...
;     s16x4 l00, h00, l01, h01, l10, h10, l11, h11; { const unsigned a0 = va0 + sub * 4096, a1 = va1 + sub * 4096;
;       asm volatile("ds_read_b64_tr_b16 %0, %1" : "=&v"(l00) : "v"(a0) : "memory"); asm volatile("ds_read_b64_tr_b16 %0, %1 offset:1024" : "=&v"(h00) : "v"(a0) : "memory");
;       asm volatile("ds_read_b64_tr_b16 %0, %1" : "=&v"(l01) : "v"(a1) : "memory"); asm volatile("ds_read_b64_tr_b16 %0, %1 offset:1024" : "=&v"(h01) : "v"(a1) : "memory");
;       asm volatile("ds_read_b64_tr_b16 %0, %1 offset:2048" : "=&v"(l10) : "v"(a0) : "memory"); asm volatile("ds_read_b64_tr_b16 %0, %1 offset:3072" : "=&v"(h10) : "v"(a0) : "memory");
;       asm volatile("ds_read_b64_tr_b16 %0, %1 offset:2048" : "=&v"(l11) : "v"(a1) : "memory"); asm volatile("ds_read_b64_tr_b16 %0, %1 offset:3072" : "=&v"(h11) : "v"(a1) : "memory"); }
;     const int r = lane & 31, hh = lane >> 5;
;     f32x16 st = {0.f, 0.f, 0.f, 0.f, 0.f, 0.f, 0.f, 0.f, 0.f, 0.f, 0.f, 0.f, 0.f, 0.f, 0.f, 0.f};
;     { const int key = sub * 32 + r; const LAS char* kp = Kt + key * 128; const int ksw = (key >> 1) & 7;
; #pragma unroll
;       for (int d0 = 0; d0 < 4; ++d0) { const bf16x8 kf = *(const LAS bf16x8*)(kp + (((2 * d0 + hh) ^ ksw) << 4)); st = __builtin_amdgcn_mfma_f32_32x32x16_bf16(kf, qr[d0], st, 0, 0, 0); } }
;     f32x2_t sp[8]; const f32x2_t cs2 = {cscale, cscale};
; #pragma unroll
;     for (int g = 0; g < 4; ++g) { const f32x4 c4 = *(const LAS f32x4*)(cb + sub * 32 + 8 * g + 4 * hh);
;         sp[2 * g] = (f32x2_t){st[4 * g], st[4 * g + 1]} + cs2 * (f32x2_t){c4[0], c4[1]};
;         sp[2 * g + 1] = (f32x2_t){st[4 * g + 2], st[4 * g + 3]} + cs2 * (f32x2_t){c4[2], c4[3]};
;         if (MASK) {
; #pragma unroll
;             for (int e = 0; e < 4; ++e) { const int kpos = kpos_sub + 8 * g + 4 * hh + e; const bool ok = (kpos <= qpos && kpos >= qpos - win);
;                 sp[2 * g + (e >> 1)][e & 1] = ok ? sp[2 * g + (e >> 1)][e & 1] : -INFINITY; } } }
;     float rm = fmaxf(sp[0][0], sp[0][1]);
; #pragma unroll
;     for (int i = 1; i < 8; ++i) rm = fmaxf(fmaxf(rm, sp[i][0]), sp[i][1]);
;     rm = swap_max(rm);
;     if (__any(rm - m > 8.0f)) { const float mnew = fmaxf(m, rm); const float f = fast_exp2(m - mnew); l *= f; o0 = o0 * f; o1 = o1 * f; m = mnew; }
.LBB0_543:
	s_cmp_gt_i32 s4, s12
	s_cbranch_scc1 .LBB0_555
	s_cmp_gt_i32 s4, s13
	s_mov_b64 s[18:19], -1
	s_cbranch_scc1 .LBB0_549
	ds_read_b64_tr_b16 v[142:143], v217
	ds_read_b64_tr_b16 v[144:145], v217 offset:1024
	ds_read_b64_tr_b16 v[138:139], v243
	ds_read_b64_tr_b16 v[140:141], v243 offset:1024
	ds_read_b64_tr_b16 v[134:135], v217 offset:2048
	ds_read_b64_tr_b16 v[136:137], v217 offset:3072
	ds_read_b64_tr_b16 v[130:131], v243 offset:2048
	ds_read_b64_tr_b16 v[132:133], v243 offset:3072
	ds_read_b128 v[66:69], v216
	ds_read_b128 v[82:85], v215
	ds_read_b128 v[86:89], v214
	ds_read_b128 v[90:93], v213
	v_add_u32_e32 v0, s1, v197
	s_waitcnt lgkmcnt(2)
	v_mfma_f32_32x32x16_bf16 v[66:81], v[66:69], v[114:117], 0
	v_mfma_f32_32x32x16_bf16 v[66:81], v[82:85], v[118:121], v[66:81]
	s_waitcnt lgkmcnt(1)
	v_mfma_f32_32x32x16_bf16 v[66:81], v[86:89], v[122:125], v[66:81]
	s_waitcnt lgkmcnt(0)
	v_mfma_f32_32x32x16_bf16 v[66:81], v[90:93], v[126:129], v[66:81]
	ds_read_b128 v[82:85], v0 offset:49152
	ds_read_b128 v[86:89], v0 offset:49184
	ds_read_b128 v[90:93], v0 offset:49216
	ds_read_b128 v[94:97], v0 offset:49248
	s_waitcnt lgkmcnt(0)
	s_nop 8
	v_fma_f32 v178, -v82, s34, v66
	v_fma_f32 v179, -v83, s34, v67
	v_fma_f32 v176, -v84, s34, v68
	v_fma_f32 v177, -v85, s34, v69
	v_fma_f32 v170, -v86, s34, v70
	v_fma_f32 v171, -v87, s34, v71
	v_fma_f32 v168, -v88, s34, v72
	v_fma_f32 v169, -v89, s34, v73
	v_fma_f32 v174, -v90, s34, v74
	v_fma_f32 v175, -v91, s34, v75
	v_fma_f32 v172, -v92, s34, v76
	v_fma_f32 v173, -v93, s34, v77
	v_max_f32_e32 v0, v178, v179
	v_max3_f32 v0, v0, v176, v177
	v_max3_f32 v0, v0, v170, v171
	v_max3_f32 v0, v0, v168, v169
	v_max3_f32 v0, v0, v174, v175
	v_fma_f32 v180, -v94, s34, v78
	v_fma_f32 v181, -v95, s34, v79
	v_max3_f32 v0, v0, v172, v173
	v_fma_f32 v182, -v96, s34, v80
	v_fma_f32 v183, -v97, s34, v81
	v_max3_f32 v0, v0, v180, v181
	v_max3_f32 v0, v0, v182, v183
	v_mov_b32_e32 v66, v0
	s_nop 1
	v_permlane32_swap_b32_e32 v0, v66
	v_max_f32_e32 v66, v66, v66
	v_max_f32_e32 v0, v0, v0
	v_max_f32_e32 v0, v0, v66
	v_sub_f32_e32 v66, v0, v211
	v_cmp_lt_f32_e32 vcc, s9, v66
	s_cbranch_vccz .LBB0_547
	v_max_f32_e32 v0, v0, v0
	v_max_f32_e32 v66, v211, v211
	v_max_f32_e32 v244, v66, v0
	v_sub_f32_e32 v0, v211, v244
	v_exp_f32_e32 v0, v0
	s_nop 0
	v_mul_f32_e32 v245, v194, v0
	v_mul_f32_e32 v32, v32, v0
	v_mul_f32_e32 v33, v33, v0
	v_mul_f32_e32 v30, v30, v0
	v_mul_f32_e32 v31, v31, v0
	v_mul_f32_e32 v28, v28, v0
	v_mul_f32_e32 v29, v29, v0
	v_mul_f32_e32 v26, v26, v0
	v_mul_f32_e32 v27, v27, v0
	v_mul_f32_e32 v24, v24, v0
	v_mul_f32_e32 v25, v25, v0
	v_mul_f32_e32 v22, v22, v0
	v_mul_f32_e32 v23, v23, v0
	v_mul_f32_e32 v20, v20, v0
	v_mul_f32_e32 v21, v21, v0
	v_mul_f32_e32 v18, v18, v0
	v_mul_f32_e32 v19, v19, v0
	v_mul_f32_e32 v16, v16, v0
	v_mul_f32_e32 v17, v17, v0
	v_mul_f32_e32 v14, v14, v0
	v_mul_f32_e32 v15, v15, v0
	v_mul_f32_e32 v12, v12, v0
	v_mul_f32_e32 v13, v13, v0
	v_mul_f32_e32 v10, v10, v0
	v_mul_f32_e32 v11, v11, v0
	v_mul_f32_e32 v8, v8, v0
	v_mul_f32_e32 v9, v9, v0
	v_mul_f32_e32 v6, v6, v0
	v_mul_f32_e32 v7, v7, v0
	v_mul_f32_e32 v4, v4, v0
	v_mul_f32_e32 v5, v5, v0
	v_mul_f32_e32 v2, v2, v0
	v_mul_f32_e32 v3, v3, v0
	v_mov_b32_e32 v0, v244
	s_branch .LBB0_548

; #define LAS __attribute__((address_space(3)))
; template <bool MASK> ...
;     s16x4 l00, h00, l01, h01, l10, h10, l11, h11; { const unsigned a0 = va0 + sub * 4096, a1 = va1 + sub * 4096;
;       asm volatile("ds_read_b64_tr_b16 %0, %1" : "=&v"(l00) : "v"(a0) : "memory"); asm volatile("ds_read_b64_tr_b16 %0, %1 offset:1024" : "=&v"(h00) : "v"(a0) : "memory");
;       asm volatile("ds_read_b64_tr_b16 %0, %1" : "=&v"(l01) : "v"(a1) : "memory"); asm volatile("ds_read_b64_tr_b16 %0, %1 offset:1024" : "=&v"(h01) : "v"(a1) : "memory");
;       asm volatile("ds_read_b64_tr_b16 %0, %1 offset:2048" : "=&v"(l10) : "v"(a0) : "memory"); asm volatile("ds_read_b64_tr_b16 %0, %1 offset:3072" : "=&v"(h10) : "v"(a0) : "memory");
;       asm volatile("ds_read_b64_tr_b16 %0, %1 offset:2048" : "=&v"(l11) : "v"(a1) : "memory"); asm volatile("ds_read_b64_tr_b16 %0, %1 offset:3072" : "=&v"(h11) : "v"(a1) : "memory"); }
;     const int r = lane & 31, hh = lane >> 5;
;     f32x16 st = {0.f, 0.f, 0.f, 0.f, 0.f, 0.f, 0.f, 0.f, 0.f, 0.f, 0.f, 0.f, 0.f, 0.f, 0.f, 0.f};
;     { const int key = sub * 32 + r; const LAS char* kp = Kt + key * 128; const int ksw = (key >> 1) & 7;
; #pragma unroll
;       for (int d0 = 0; d0 < 4; ++d0) { const bf16x8 kf = *(const LAS bf16x8*)(kp + (((2 * d0 + hh) ^ ksw) << 4)); st = __builtin_amdgcn_mfma_f32_32x32x16_bf16(kf, qr[d0], st, 0, 0, 0); } }
;     f32x2_t sp[8]; const f32x2_t cs2 = {cscale, cscale};
; #pragma unroll
;     for (int g = 0; g < 4; ++g) { const f32x4 c4 = *(const LAS f32x4*)(cb + sub * 32 + 8 * g + 4 * hh);
;         sp[2 * g] = (f32x2_t){st[4 * g], st[4 * g + 1]} + cs2 * (f32x2_t){c4[0], c4[1]};
;         sp[2 * g + 1] = (f32x2_t){st[4 * g + 2], st[4 * g + 3]} + cs2 * (f32x2_t){c4[2], c4[3]};
;         if (MASK) {
; #pragma unroll
;             for (int e = 0; e < 4; ++e) { const int kpos = kpos_sub + 8 * g + 4 * hh + e; const bool ok = (kpos <= qpos && kpos >= qpos - win);
;                 sp[2 * g + (e >> 1)][e & 1] = ok ? sp[2 * g + (e >> 1)][e & 1] : -INFINITY; } } }
;     float rm = fmaxf(sp[0][0], sp[0][1]);
; #pragma unroll
;     for (int i = 1; i < 8; ++i) rm = fmaxf(fmaxf(rm, sp[i][0]), sp[i][1]);
;     rm = swap_max(rm);
;     if (__any(rm - m > 8.0f)) { const float mnew = fmaxf(m, rm); const float f = fast_exp2(m - mnew); l *= f; o0 = o0 * f; o1 = o1 * f; m = mnew; }
.LBB0_549:
	s_and_b64 vcc, exec, s[18:19]
	s_cbranch_vccz .LBB0_554
	ds_read_b64_tr_b16 v[94:95], v217
	ds_read_b64_tr_b16 v[96:97], v217 offset:1024
	ds_read_b64_tr_b16 v[90:91], v243
	ds_read_b64_tr_b16 v[92:93], v243 offset:1024
	ds_read_b64_tr_b16 v[86:87], v217 offset:2048
	ds_read_b64_tr_b16 v[88:89], v217 offset:3072
	ds_read_b64_tr_b16 v[82:83], v243 offset:2048
	ds_read_b64_tr_b16 v[84:85], v243 offset:3072
	s_nop 8
	ds_read_b128 v[66:69], v216
	ds_read_b128 v[130:133], v215
	v_add_u32_e32 v138, s1, v197
	v_or_b32_e32 v0, s4, v150
	v_cmp_le_i32_e32 vcc, v0, v154
	v_cmp_ge_i32_e64 s[44:45], v0, v209
	s_and_b64 vcc, vcc, s[44:45]
	s_waitcnt lgkmcnt(0)
	v_mfma_f32_32x32x16_bf16 v[66:81], v[66:69], v[114:117], 0
	v_mfma_f32_32x32x16_bf16 v[66:81], v[130:133], v[118:121], v[66:81]
	ds_read_b128 v[130:133], v214
	s_waitcnt lgkmcnt(0)
	v_mfma_f32_32x32x16_bf16 v[66:81], v[130:133], v[122:125], v[66:81]
	ds_read_b128 v[130:133], v213
	s_waitcnt lgkmcnt(0)
	v_mfma_f32_32x32x16_bf16 v[66:81], v[130:133], v[126:129], v[66:81]
	ds_read_b128 v[130:133], v138 offset:49152
	ds_read_b128 v[134:137], v138 offset:49184
	s_waitcnt lgkmcnt(0)
	s_nop 8
	v_fma_f32 v66, -v130, s34, v66
	v_fma_f32 v67, -v131, s34, v67
	v_or_b32_e32 v130, 1, v0
	v_cndmask_b32_e32 v66, v240, v66, vcc
	v_cmp_lt_i32_e32 vcc, v0, v154
	v_cmp_ge_i32_e64 s[44:45], v130, v209
	s_and_b64 vcc, vcc, s[44:45]
	v_or_b32_e32 v130, 2, v0
	v_cndmask_b32_e32 v67, v240, v67, vcc
	v_cmp_le_i32_e32 vcc, v130, v154
	v_cmp_ge_i32_e64 s[44:45], v130, v209
	v_fma_f32 v68, -v132, s34, v68
	v_fma_f32 v69, -v133, s34, v69
	s_and_b64 vcc, vcc, s[44:45]
	v_or_b32_e32 v130, 3, v0
	v_cndmask_b32_e32 v68, v240, v68, vcc
	v_cmp_le_i32_e32 vcc, v130, v154
	v_cmp_ge_i32_e64 s[44:45], v130, v209
	s_and_b64 vcc, vcc, s[44:45]
	v_or_b32_e32 v130, 8, v0
	v_cndmask_b32_e32 v69, v240, v69, vcc
	v_cmp_le_i32_e32 vcc, v130, v154
	v_cmp_ge_i32_e64 s[44:45], v130, v209
	v_fma_f32 v70, -v134, s34, v70
	v_fma_f32 v71, -v135, s34, v71
	s_and_b64 vcc, vcc, s[44:45]
	v_or_b32_e32 v130, 9, v0
	v_cndmask_b32_e32 v70, v240, v70, vcc
	v_cmp_le_i32_e32 vcc, v130, v154
	v_cmp_ge_i32_e64 s[44:45], v130, v209
	s_and_b64 vcc, vcc, s[44:45]
	v_or_b32_e32 v130, 10, v0
	v_cndmask_b32_e32 v71, v240, v71, vcc
	v_cmp_le_i32_e32 vcc, v130, v154
	v_cmp_ge_i32_e64 s[44:45], v130, v209
	v_fma_f32 v72, -v136, s34, v72
	v_fma_f32 v73, -v137, s34, v73
	s_and_b64 vcc, vcc, s[44:45]
	v_or_b32_e32 v130, 11, v0
	v_cndmask_b32_e32 v72, v240, v72, vcc
	v_cmp_le_i32_e32 vcc, v130, v154
	v_cmp_ge_i32_e64 s[44:45], v130, v209
	ds_read_b128 v[130:133], v138 offset:49216
	s_and_b64 vcc, vcc, s[44:45]
	v_cndmask_b32_e32 v73, v240, v73, vcc
	s_waitcnt lgkmcnt(0)
	v_fma_f32 v74, -v130, s34, v74
	v_fma_f32 v75, -v131, s34, v75
	v_or_b32_e32 v130, 16, v0
	v_cmp_le_i32_e32 vcc, v130, v154
	v_cmp_ge_i32_e64 s[44:45], v130, v209
	s_and_b64 vcc, vcc, s[44:45]
	v_or_b32_e32 v130, 17, v0
	v_cndmask_b32_e32 v74, v240, v74, vcc
	v_cmp_le_i32_e32 vcc, v130, v154
	v_cmp_ge_i32_e64 s[44:45], v130, v209
	s_and_b64 vcc, vcc, s[44:45]
	v_or_b32_e32 v130, 18, v0
	v_cndmask_b32_e32 v75, v240, v75, vcc
	v_cmp_le_i32_e32 vcc, v130, v154
	v_cmp_ge_i32_e64 s[44:45], v130, v209
	v_fma_f32 v76, -v132, s34, v76
	v_fma_f32 v77, -v133, s34, v77
	s_and_b64 vcc, vcc, s[44:45]
	v_or_b32_e32 v130, 19, v0
	v_cndmask_b32_e32 v76, v240, v76, vcc
	v_cmp_le_i32_e32 vcc, v130, v154
	v_cmp_ge_i32_e64 s[44:45], v130, v209
	ds_read_b128 v[130:133], v138 offset:49248
	s_and_b64 vcc, vcc, s[44:45]
	v_cndmask_b32_e32 v77, v240, v77, vcc
	s_waitcnt lgkmcnt(0)
	v_fma_f32 v78, -v130, s34, v78
	v_fma_f32 v79, -v131, s34, v79
	v_or_b32_e32 v130, 24, v0
	v_cmp_le_i32_e32 vcc, v130, v154
	v_cmp_ge_i32_e64 s[44:45], v130, v209
	s_and_b64 vcc, vcc, s[44:45]
	v_or_b32_e32 v130, 25, v0
	v_cndmask_b32_e32 v78, v240, v78, vcc
	v_cmp_le_i32_e32 vcc, v130, v154
	v_cmp_ge_i32_e64 s[44:45], v130, v209
	s_and_b64 vcc, vcc, s[44:45]
	v_or_b32_e32 v130, 26, v0
	v_cndmask_b32_e32 v79, v240, v79, vcc
	v_cmp_le_i32_e32 vcc, v130, v154
	v_cmp_ge_i32_e64 s[44:45], v130, v209
	v_fma_f32 v80, -v132, s34, v80
	v_fma_f32 v81, -v133, s34, v81
	s_and_b64 vcc, vcc, s[44:45]
	v_or_b32_e32 v0, 27, v0
	v_cndmask_b32_e32 v80, v240, v80, vcc
	v_cmp_le_i32_e32 vcc, v0, v154
	v_cmp_ge_i32_e64 s[44:45], v0, v209
	v_max_f32_e32 v0, v66, v67
	v_max3_f32 v0, v0, v68, v69
	v_max3_f32 v0, v0, v70, v71
	v_max3_f32 v0, v0, v72, v73
	v_max3_f32 v0, v0, v74, v75
	s_and_b64 vcc, vcc, s[44:45]
	v_max3_f32 v0, v0, v76, v77
	v_cndmask_b32_e32 v81, v240, v81, vcc
	v_max3_f32 v0, v0, v78, v79
	v_max3_f32 v0, v0, v80, v81
	v_mov_b32_e32 v130, v0
	s_nop 1
	v_permlane32_swap_b32_e32 v0, v130
	v_max_f32_e32 v130, v130, v130
	v_max_f32_e32 v0, v0, v0
	v_max_f32_e32 v0, v0, v130
	v_sub_f32_e32 v130, v0, v211
	v_cmp_lt_f32_e32 vcc, s9, v130
	s_cbranch_vccz .LBB0_552
	v_max_f32_e32 v0, v0, v0
	v_max_f32_e32 v130, v211, v211
	v_max_f32_e32 v0, v130, v0
	v_sub_f32_e32 v130, v211, v0
	v_exp_f32_e32 v130, v130
	v_mov_b32_e32 v211, v0
	v_mul_f32_e32 v194, v194, v130
	v_mul_f32_e32 v32, v32, v130
	v_mul_f32_e32 v33, v33, v130
	v_mul_f32_e32 v30, v30, v130
	v_mul_f32_e32 v31, v31, v130
	v_mul_f32_e32 v28, v28, v130
	v_mul_f32_e32 v29, v29, v130
	v_mul_f32_e32 v26, v26, v130
	v_mul_f32_e32 v27, v27, v130
	v_mul_f32_e32 v24, v24, v130
	v_mul_f32_e32 v25, v25, v130
	v_mul_f32_e32 v22, v22, v130
	v_mul_f32_e32 v23, v23, v130
	v_mul_f32_e32 v20, v20, v130
	v_mul_f32_e32 v21, v21, v130
	v_mul_f32_e32 v18, v18, v130
	v_mul_f32_e32 v19, v19, v130
	v_mul_f32_e32 v16, v16, v130
	v_mul_f32_e32 v17, v17, v130
	v_mul_f32_e32 v14, v14, v130
	v_mul_f32_e32 v15, v15, v130
	v_mul_f32_e32 v12, v12, v130
	v_mul_f32_e32 v13, v13, v130
	v_mul_f32_e32 v10, v10, v130
	v_mul_f32_e32 v11, v11, v130
	v_mul_f32_e32 v8, v8, v130
	v_mul_f32_e32 v9, v9, v130
	v_mul_f32_e32 v6, v6, v130
	v_mul_f32_e32 v7, v7, v130
	v_mul_f32_e32 v4, v4, v130
	v_mul_f32_e32 v5, v5, v130
	v_mul_f32_e32 v2, v2, v130
	v_mul_f32_e32 v3, v3, v130
	s_branch .LBB0_553

; __device__ __forceinline__ unsigned cvt_pk_bf16(float lo, float hi) { f32x2_t v = {lo, hi}; bf16x2_t b = __builtin_convertvector(v, bf16x2_t); return __builtin_bit_cast(unsigned, b); }
; __device__ __forceinline__ float fast_exp2(float x) { return __builtin_amdgcn_exp2f(x); }
; template <bool MASK> ...
;     ...
;     { const f32x2_t m2 = {m, m}; f32x2_t ps2 = {0.f, 0.f};
; #pragma unroll
;       for (int i = 0; i < 8; ++i) { f32x2_t t = sp[i] - m2; t[0] = fast_exp2(t[0]); t[1] = fast_exp2(t[1]); sp[i] = t; ps2 = ps2 + t; }
;       l += ps2[0] + ps2[1]; }
;     u32x4 pw0, pw1;
;     pw0.x = cvt_pk_bf16(sp[0][0], sp[0][1]); pw0.y = cvt_pk_bf16(sp[1][0], sp[1][1]); pw0.z = cvt_pk_bf16(sp[2][0], sp[2][1]); pw0.w = cvt_pk_bf16(sp[3][0], sp[3][1]);
;     pw1.x = cvt_pk_bf16(sp[4][0], sp[4][1]); pw1.y = cvt_pk_bf16(sp[5][0], sp[5][1]); pw1.z = cvt_pk_bf16(sp[6][0], sp[6][1]); pw1.w = cvt_pk_bf16(sp[7][0], sp[7][1]);
;     asm volatile("s_waitcnt lgkmcnt(0)" : "+v"(l00), "+v"(h00), "+v"(l01), "+v"(h01), "+v"(l10), "+v"(h10), "+v"(l11), "+v"(h11) :: "memory");
;     { const bf16x8 pb0 = __builtin_bit_cast(bf16x8, pw0), pb1 = __builtin_bit_cast(bf16x8, pw1);
;       const bf16x8 v00 = {l00[0], l00[1], l00[2], l00[3], h00[0], h00[1], h00[2], h00[3]}, v01 = {l01[0], l01[1], l01[2], l01[3], h01[0], h01[1], h01[2], h01[3]};
;       const bf16x8 v10 = {l10[0], l10[1], l10[2], l10[3], h10[0], h10[1], h10[2], h10[3]}, v11 = {l11[0], l11[1], l11[2], l11[3], h11[0], h11[1], h11[2], h11[3]};
;       o0 = __builtin_amdgcn_mfma_f32_32x32x16_bf16(v00, pb0, o0, 0, 0, 0); o1 = __builtin_amdgcn_mfma_f32_32x32x16_bf16(v01, pb0, o1, 0, 0, 0);
;       o0 = __builtin_amdgcn_mfma_f32_32x32x16_bf16(v10, pb1, o0, 0, 0, 0); o1 = __builtin_amdgcn_mfma_f32_32x32x16_bf16(v11, pb1, o1, 0, 0, 0); }
.LBB0_553:
	v_sub_f32_e32 v66, v66, v0
	v_sub_f32_e32 v67, v67, v0
	v_sub_f32_e32 v68, v68, v0
	v_sub_f32_e32 v69, v69, v0
	v_exp_f32_e32 v66, v66
	v_exp_f32_e32 v67, v67
	v_sub_f32_e32 v70, v70, v0
	v_sub_f32_e32 v71, v71, v0
	v_sub_f32_e32 v72, v72, v0
	v_sub_f32_e32 v73, v73, v0
	v_exp_f32_e32 v68, v68
	v_exp_f32_e32 v69, v69
	v_exp_f32_e32 v70, v70
	v_exp_f32_e32 v71, v71
	v_exp_f32_e32 v72, v72
	v_exp_f32_e32 v73, v73
	v_add_f32_e32 v130, 0, v66
	v_add_f32_e32 v131, 0, v67
	v_cvt_pk_bf16_f32 v66, v66, v67
	v_add_f32_e32 v130, v68, v130
	v_add_f32_e32 v131, v69, v131
	v_cvt_pk_bf16_f32 v67, v68, v69
	v_cvt_pk_bf16_f32 v68, v70, v71
	v_cvt_pk_bf16_f32 v69, v72, v73
	s_waitcnt lgkmcnt(0)
	v_sub_f32_e32 v74, v74, v0
	v_sub_f32_e32 v75, v75, v0
	v_sub_f32_e32 v76, v76, v0
	v_sub_f32_e32 v77, v77, v0
	v_mfma_f32_32x32x16_bf16 v[18:33], v[94:97], v[66:69], v[18:33]
	v_add_f32_e64 v78, v78, -v0
	v_add_f32_e64 v79, v79, -v0
	v_add_f32_e64 v80, v80, -v0
	v_add_f32_e64 v81, v81, -v0
	v_exp_f32_e32 v74, v74
	v_exp_f32_e32 v75, v75
	v_exp_f32_e32 v76, v76
	v_exp_f32_e32 v77, v77
	v_exp_f32_e32 v78, v78
	v_mfma_f32_32x32x16_bf16 v[2:17], v[90:93], v[66:69], v[2:17]
	v_exp_f32_e32 v79, v79
	v_exp_f32_e32 v80, v80
	v_exp_f32_e32 v81, v81
	v_add_f32_e32 v130, v70, v130
	v_add_f32_e32 v131, v71, v131
	v_cvt_pk_bf16_f32 v70, v74, v75
	v_add_f32_e32 v130, v72, v130
	v_add_f32_e32 v131, v73, v131
	v_cvt_pk_bf16_f32 v71, v76, v77
	v_cvt_pk_bf16_f32 v72, v78, v79
	v_cvt_pk_bf16_f32 v73, v80, v81
	v_add_f32_e32 v130, v74, v130
	v_add_f32_e32 v131, v75, v131
	v_mov_b32_e32 v244, v211
	v_mfma_f32_32x32x16_bf16 v[18:33], v[86:89], v[70:73], v[18:33]
	v_add_f32_e64 v130, v76, v130
	v_add_f32_e64 v131, v77, v131
	v_add_f32_e64 v130, v78, v130
	v_add_f32_e64 v131, v79, v131
	v_add_f32_e64 v130, v80, v130
	v_add_f32_e64 v131, v81, v131
	v_add_f32_e32 v0, v130, v131
	v_mfma_f32_32x32x16_bf16 v[2:17], v[82:85], v[70:73], v[2:17]
	s_nop 3
	v_add_f32_e32 v0, v194, v0
	s_nop 0

; #define LAS __attribute__((address_space(3)))
; template <bool MASK> ...
;     s16x4 l00, h00, l01, h01, l10, h10, l11, h11; { const unsigned a0 = va0 + sub * 4096, a1 = va1 + sub * 4096;
;       asm volatile("ds_read_b64_tr_b16 %0, %1" : "=&v"(l00) : "v"(a0) : "memory"); asm volatile("ds_read_b64_tr_b16 %0, %1 offset:1024" : "=&v"(h00) : "v"(a0) : "memory");
;       asm volatile("ds_read_b64_tr_b16 %0, %1" : "=&v"(l01) : "v"(a1) : "memory"); asm volatile("ds_read_b64_tr_b16 %0, %1 offset:1024" : "=&v"(h01) : "v"(a1) : "memory");
;       asm volatile("ds_read_b64_tr_b16 %0, %1 offset:2048" : "=&v"(l10) : "v"(a0) : "memory"); asm volatile("ds_read_b64_tr_b16 %0, %1 offset:3072" : "=&v"(h10) : "v"(a0) : "memory");
;       asm volatile("ds_read_b64_tr_b16 %0, %1 offset:2048" : "=&v"(l11) : "v"(a1) : "memory"); asm volatile("ds_read_b64_tr_b16 %0, %1 offset:3072" : "=&v"(h11) : "v"(a1) : "memory"); }
;     const int r = lane & 31, hh = lane >> 5;
;     f32x16 st = {0.f, 0.f, 0.f, 0.f, 0.f, 0.f, 0.f, 0.f, 0.f, 0.f, 0.f, 0.f, 0.f, 0.f, 0.f, 0.f};
;     { const int key = sub * 32 + r; const LAS char* kp = Kt + key * 128; const int ksw = (key >> 1) & 7;
; #pragma unroll
;       for (int d0 = 0; d0 < 4; ++d0) { const bf16x8 kf = *(const LAS bf16x8*)(kp + (((2 * d0 + hh) ^ ksw) << 4)); st = __builtin_amdgcn_mfma_f32_32x32x16_bf16(kf, qr[d0], st, 0, 0, 0); } }
;     f32x2_t sp[8]; const f32x2_t cs2 = {cscale, cscale};
; #pragma unroll
;     for (int g = 0; g < 4; ++g) { const f32x4 c4 = *(const LAS f32x4*)(cb + sub * 32 + 8 * g + 4 * hh);
;         sp[2 * g] = (f32x2_t){st[4 * g], st[4 * g + 1]} + cs2 * (f32x2_t){c4[0], c4[1]};
;         sp[2 * g + 1] = (f32x2_t){st[4 * g + 2], st[4 * g + 3]} + cs2 * (f32x2_t){c4[2], c4[3]};
;         if (MASK) {
; #pragma unroll
;             for (int e = 0; e < 4; ++e) { const int kpos = kpos_sub + 8 * g + 4 * hh + e; const bool ok = (kpos <= qpos && kpos >= qpos - win);
;                 sp[2 * g + (e >> 1)][e & 1] = ok ? sp[2 * g + (e >> 1)][e & 1] : -INFINITY; } } }
;     float rm = fmaxf(sp[0][0], sp[0][1]);
; #pragma unroll
;     for (int i = 1; i < 8; ++i) rm = fmaxf(fmaxf(rm, sp[i][0]), sp[i][1]);
;     rm = swap_max(rm);
;     if (__any(rm - m > 8.0f)) { const float mnew = fmaxf(m, rm); const float f = fast_exp2(m - mnew); l *= f; o0 = o0 * f; o1 = o1 * f; m = mnew; }
.LBB0_555:
	s_or_b32 s5, s4, 32
	s_cmp_gt_i32 s5, s11
	v_add_u32_e32 v244, 0x1000, v217
	v_add_u32_e32 v217, 0x1000, v243
	s_cbranch_scc1 .LBB0_559
	s_or_b32 s4, s4, 63
	s_cmp_gt_i32 s4, s47
	s_mov_b64 s[18:19], -1
	s_cbranch_scc1 .LBB0_565
	ds_read_b64_tr_b16 v[142:143], v244
	ds_read_b64_tr_b16 v[144:145], v244 offset:1024
	ds_read_b64_tr_b16 v[138:139], v217
	ds_read_b64_tr_b16 v[140:141], v217 offset:1024
	ds_read_b64_tr_b16 v[134:135], v244 offset:2048
	ds_read_b64_tr_b16 v[136:137], v244 offset:3072
	ds_read_b64_tr_b16 v[130:131], v217 offset:2048
	ds_read_b64_tr_b16 v[132:133], v217 offset:3072
	ds_read_b128 v[66:69], v216 offset:4096
	ds_read_b128 v[82:85], v215 offset:4096
	ds_read_b128 v[86:89], v214 offset:4096
	ds_read_b128 v[90:93], v213 offset:4096
	v_add_u32_e32 v0, s1, v197
	s_waitcnt lgkmcnt(2)
	v_mfma_f32_32x32x16_bf16 v[66:81], v[66:69], v[98:101], 0
	v_mfma_f32_32x32x16_bf16 v[66:81], v[82:85], v[102:105], v[66:81]
	s_waitcnt lgkmcnt(1)
	v_mfma_f32_32x32x16_bf16 v[66:81], v[86:89], v[106:109], v[66:81]
	s_waitcnt lgkmcnt(0)
	v_mfma_f32_32x32x16_bf16 v[66:81], v[90:93], v[110:113], v[66:81]
	ds_read_b128 v[82:85], v0 offset:49280
	ds_read_b128 v[86:89], v0 offset:49312
	ds_read_b128 v[90:93], v0 offset:49344
	ds_read_b128 v[94:97], v0 offset:49376
	s_waitcnt lgkmcnt(0)
	s_nop 8
	v_fma_f32 v178, -v82, s34, v66
	v_fma_f32 v179, -v83, s34, v67
	v_fma_f32 v176, -v84, s34, v68
	v_fma_f32 v177, -v85, s34, v69
	v_fma_f32 v170, -v86, s34, v70
	v_fma_f32 v171, -v87, s34, v71
	v_fma_f32 v168, -v88, s34, v72
	v_fma_f32 v169, -v89, s34, v73
	v_fma_f32 v174, -v90, s34, v74
	v_fma_f32 v175, -v91, s34, v75
	v_fma_f32 v172, -v92, s34, v76
	v_fma_f32 v173, -v93, s34, v77
	v_max_f32_e32 v0, v178, v179
	v_max3_f32 v0, v0, v176, v177
	v_max3_f32 v0, v0, v170, v171
	v_max3_f32 v0, v0, v168, v169
	v_max3_f32 v0, v0, v174, v175
	v_fma_f32 v180, -v94, s34, v78
	v_fma_f32 v181, -v95, s34, v79
	v_max3_f32 v0, v0, v172, v173
	v_fma_f32 v182, -v96, s34, v80
	v_fma_f32 v183, -v97, s34, v81
	v_max3_f32 v0, v0, v180, v181
	v_max3_f32 v0, v0, v182, v183
	v_mov_b32_e32 v66, v0
	s_nop 1
	v_permlane32_swap_b32_e32 v0, v66
	v_max_f32_e32 v66, v66, v66
	v_max_f32_e32 v0, v0, v0
	v_max_f32_e32 v0, v0, v66
	v_sub_f32_e32 v66, v0, v210
	v_cmp_lt_f32_e32 vcc, s9, v66
	s_cbranch_vccz .LBB0_563
	v_max_f32_e32 v0, v0, v0
	v_max_f32_e32 v66, v210, v210
	v_max_f32_e32 v243, v66, v0
	v_sub_f32_e32 v0, v210, v243
	v_exp_f32_e32 v0, v0
	s_nop 0
	v_mul_f32_e32 v245, v212, v0
	v_mul_f32_e32 v64, v64, v0
	v_mul_f32_e32 v65, v65, v0
	v_mul_f32_e32 v62, v62, v0
	v_mul_f32_e32 v63, v63, v0
	v_mul_f32_e32 v60, v60, v0
	v_mul_f32_e32 v61, v61, v0
	v_mul_f32_e32 v58, v58, v0
	v_mul_f32_e32 v59, v59, v0
	v_mul_f32_e32 v56, v56, v0
	v_mul_f32_e32 v57, v57, v0
	v_mul_f32_e32 v54, v54, v0
	v_mul_f32_e32 v55, v55, v0
	v_mul_f32_e32 v52, v52, v0
	v_mul_f32_e32 v53, v53, v0
	v_mul_f32_e32 v50, v50, v0
	v_mul_f32_e32 v51, v51, v0
	v_mul_f32_e32 v48, v48, v0
	v_mul_f32_e32 v49, v49, v0
	v_mul_f32_e32 v46, v46, v0
	v_mul_f32_e32 v47, v47, v0
	v_mul_f32_e32 v44, v44, v0
	v_mul_f32_e32 v45, v45, v0
	v_mul_f32_e32 v42, v42, v0
	v_mul_f32_e32 v43, v43, v0
	v_mul_f32_e32 v40, v40, v0
	v_mul_f32_e32 v41, v41, v0
	v_mul_f32_e32 v38, v38, v0
	v_mul_f32_e32 v39, v39, v0
	v_mul_f32_e32 v36, v36, v0
	v_mul_f32_e32 v37, v37, v0
	v_mul_f32_e32 v34, v34, v0
	v_mul_f32_e32 v35, v35, v0
	v_mov_b32_e32 v0, v243
	s_branch .LBB0_564

; #define LAS __attribute__((address_space(3)))
; template <bool MASK> ...
;     s16x4 l00, h00, l01, h01, l10, h10, l11, h11; { const unsigned a0 = va0 + sub * 4096, a1 = va1 + sub * 4096;
;       asm volatile("ds_read_b64_tr_b16 %0, %1" : "=&v"(l00) : "v"(a0) : "memory"); asm volatile("ds_read_b64_tr_b16 %0, %1 offset:1024" : "=&v"(h00) : "v"(a0) : "memory");
;       asm volatile("ds_read_b64_tr_b16 %0, %1" : "=&v"(l01) : "v"(a1) : "memory"); asm volatile("ds_read_b64_tr_b16 %0, %1 offset:1024" : "=&v"(h01) : "v"(a1) : "memory");
;       asm volatile("ds_read_b64_tr_b16 %0, %1 offset:2048" : "=&v"(l10) : "v"(a0) : "memory"); asm volatile("ds_read_b64_tr_b16 %0, %1 offset:3072" : "=&v"(h10) : "v"(a0) : "memory");
;       asm volatile("ds_read_b64_tr_b16 %0, %1 offset:2048" : "=&v"(l11) : "v"(a1) : "memory"); asm volatile("ds_read_b64_tr_b16 %0, %1 offset:3072" : "=&v"(h11) : "v"(a1) : "memory"); }
;     const int r = lane & 31, hh = lane >> 5;
;     f32x16 st = {0.f, 0.f, 0.f, 0.f, 0.f, 0.f, 0.f, 0.f, 0.f, 0.f, 0.f, 0.f, 0.f, 0.f, 0.f, 0.f};
;     { const int key = sub * 32 + r; const LAS char* kp = Kt + key * 128; const int ksw = (key >> 1) & 7;
; #pragma unroll
;       for (int d0 = 0; d0 < 4; ++d0) { const bf16x8 kf = *(const LAS bf16x8*)(kp + (((2 * d0 + hh) ^ ksw) << 4)); st = __builtin_amdgcn_mfma_f32_32x32x16_bf16(kf, qr[d0], st, 0, 0, 0); } }
;     f32x2_t sp[8]; const f32x2_t cs2 = {cscale, cscale};
; #pragma unroll
;     for (int g = 0; g < 4; ++g) { const f32x4 c4 = *(const LAS f32x4*)(cb + sub * 32 + 8 * g + 4 * hh);
;         sp[2 * g] = (f32x2_t){st[4 * g], st[4 * g + 1]} + cs2 * (f32x2_t){c4[0], c4[1]};
;         sp[2 * g + 1] = (f32x2_t){st[4 * g + 2], st[4 * g + 3]} + cs2 * (f32x2_t){c4[2], c4[3]};
;         if (MASK) {
; #pragma unroll
;             for (int e = 0; e < 4; ++e) { const int kpos = kpos_sub + 8 * g + 4 * hh + e; const bool ok = (kpos <= qpos && kpos >= qpos - win);
;                 sp[2 * g + (e >> 1)][e & 1] = ok ? sp[2 * g + (e >> 1)][e & 1] : -INFINITY; } } }
;     float rm = fmaxf(sp[0][0], sp[0][1]);
; #pragma unroll
;     for (int i = 1; i < 8; ++i) rm = fmaxf(fmaxf(rm, sp[i][0]), sp[i][1]);
;     rm = swap_max(rm);
;     if (__any(rm - m > 8.0f)) { const float mnew = fmaxf(m, rm); const float f = fast_exp2(m - mnew); l *= f; o0 = o0 * f; o1 = o1 * f; m = mnew; }
.LBB0_560:
	s_cmp_gt_i32 s5, s13
	s_mov_b64 s[18:19], -1
	v_add_u32_e32 v243, s1, v197
	s_cbranch_scc1 .LBB0_570
	ds_read_b64_tr_b16 v[142:143], v244
	ds_read_b64_tr_b16 v[144:145], v244 offset:1024
	ds_read_b64_tr_b16 v[138:139], v217
	ds_read_b64_tr_b16 v[140:141], v217 offset:1024
	ds_read_b64_tr_b16 v[134:135], v244 offset:2048
	ds_read_b64_tr_b16 v[136:137], v244 offset:3072
	ds_read_b64_tr_b16 v[130:131], v217 offset:2048
	ds_read_b64_tr_b16 v[132:133], v217 offset:3072
	ds_read_b128 v[66:69], v216 offset:4096
	ds_read_b128 v[82:85], v215 offset:4096
	ds_read_b128 v[86:89], v214 offset:4096
	ds_read_b128 v[90:93], v213 offset:4096
	s_waitcnt lgkmcnt(2)
	v_mfma_f32_32x32x16_bf16 v[66:81], v[66:69], v[114:117], 0
	v_mfma_f32_32x32x16_bf16 v[66:81], v[82:85], v[118:121], v[66:81]
	s_waitcnt lgkmcnt(1)
	v_mfma_f32_32x32x16_bf16 v[66:81], v[86:89], v[122:125], v[66:81]
	s_waitcnt lgkmcnt(0)
	v_mfma_f32_32x32x16_bf16 v[66:81], v[90:93], v[126:129], v[66:81]
	ds_read_b128 v[82:85], v243 offset:49280
	ds_read_b128 v[86:89], v243 offset:49312
	ds_read_b128 v[90:93], v243 offset:49344
	ds_read_b128 v[94:97], v243 offset:49376
	s_waitcnt lgkmcnt(0)
	s_nop 8
	v_fma_f32 v178, -v82, s34, v66
	v_fma_f32 v179, -v83, s34, v67
	v_fma_f32 v176, -v84, s34, v68
	v_fma_f32 v177, -v85, s34, v69
	v_max_f32_e32 v0, v178, v179
	v_fma_f32 v170, -v86, s34, v70
	v_fma_f32 v171, -v87, s34, v71
	v_max3_f32 v0, v0, v176, v177
	v_fma_f32 v168, -v88, s34, v72
	v_fma_f32 v169, -v89, s34, v73
	v_fma_f32 v174, -v90, s34, v74
	v_fma_f32 v175, -v91, s34, v75
	v_fma_f32 v172, -v92, s34, v76
	v_fma_f32 v173, -v93, s34, v77
	v_max3_f32 v0, v0, v170, v171
	v_max3_f32 v0, v0, v168, v169
	v_max3_f32 v0, v0, v174, v175
	v_max3_f32 v0, v0, v172, v173
	v_fma_f32 v180, -v94, s34, v78
	v_fma_f32 v181, -v95, s34, v79
	v_fma_f32 v182, -v96, s34, v80
	v_fma_f32 v183, -v97, s34, v81
	v_max3_f32 v0, v0, v180, v181
	v_max3_f32 v0, v0, v182, v183
	v_mov_b32_e32 v66, v0
	s_nop 1
	v_permlane32_swap_b32_e32 v0, v66
	v_max_f32_e32 v66, v66, v66
	v_max_f32_e32 v0, v0, v0
	v_max_f32_e32 v0, v0, v66
	v_sub_f32_e32 v66, v0, v211
	v_cmp_lt_f32_e32 vcc, s9, v66
	s_cbranch_vccz .LBB0_568
	v_max_f32_e32 v0, v0, v0
	v_max_f32_e32 v66, v211, v211
	v_max_f32_e32 v245, v66, v0
	v_sub_f32_e32 v0, v211, v245
	v_exp_f32_e32 v0, v0
	s_nop 0
	v_mul_f32_e32 v246, v194, v0
	v_mul_f32_e32 v32, v32, v0
	v_mul_f32_e32 v33, v33, v0
	v_mul_f32_e32 v30, v30, v0
	v_mul_f32_e32 v31, v31, v0
	v_mul_f32_e32 v28, v28, v0
	v_mul_f32_e32 v29, v29, v0
	v_mul_f32_e32 v26, v26, v0
	v_mul_f32_e32 v27, v27, v0
	v_mul_f32_e32 v24, v24, v0
	v_mul_f32_e32 v25, v25, v0
	v_mul_f32_e32 v22, v22, v0
	v_mul_f32_e32 v23, v23, v0
	v_mul_f32_e32 v20, v20, v0
	v_mul_f32_e32 v21, v21, v0
	v_mul_f32_e32 v18, v18, v0
	v_mul_f32_e32 v19, v19, v0
	v_mul_f32_e32 v16, v16, v0
	v_mul_f32_e32 v17, v17, v0
	v_mul_f32_e32 v14, v14, v0
	v_mul_f32_e32 v15, v15, v0
	v_mul_f32_e32 v12, v12, v0
	v_mul_f32_e32 v13, v13, v0
	v_mul_f32_e32 v10, v10, v0
	v_mul_f32_e32 v11, v11, v0
	v_mul_f32_e32 v8, v8, v0
	v_mul_f32_e32 v9, v9, v0
	v_mul_f32_e32 v6, v6, v0
	v_mul_f32_e32 v7, v7, v0
	v_mul_f32_e32 v4, v4, v0
	v_mul_f32_e32 v5, v5, v0
	v_mul_f32_e32 v2, v2, v0
	v_mul_f32_e32 v3, v3, v0
	v_mov_b32_e32 v0, v245
	s_branch .LBB0_569

; #define LAS __attribute__((address_space(3)))
; template <bool MASK> ...
;     s16x4 l00, h00, l01, h01, l10, h10, l11, h11; { const unsigned a0 = va0 + sub * 4096, a1 = va1 + sub * 4096;
;       asm volatile("ds_read_b64_tr_b16 %0, %1" : "=&v"(l00) : "v"(a0) : "memory"); asm volatile("ds_read_b64_tr_b16 %0, %1 offset:1024" : "=&v"(h00) : "v"(a0) : "memory");
;       asm volatile("ds_read_b64_tr_b16 %0, %1" : "=&v"(l01) : "v"(a1) : "memory"); asm volatile("ds_read_b64_tr_b16 %0, %1 offset:1024" : "=&v"(h01) : "v"(a1) : "memory");
;       asm volatile("ds_read_b64_tr_b16 %0, %1 offset:2048" : "=&v"(l10) : "v"(a0) : "memory"); asm volatile("ds_read_b64_tr_b16 %0, %1 offset:3072" : "=&v"(h10) : "v"(a0) : "memory");
;       asm volatile("ds_read_b64_tr_b16 %0, %1 offset:2048" : "=&v"(l11) : "v"(a1) : "memory"); asm volatile("ds_read_b64_tr_b16 %0, %1 offset:3072" : "=&v"(h11) : "v"(a1) : "memory"); }
;     const int r = lane & 31, hh = lane >> 5;
;     f32x16 st = {0.f, 0.f, 0.f, 0.f, 0.f, 0.f, 0.f, 0.f, 0.f, 0.f, 0.f, 0.f, 0.f, 0.f, 0.f, 0.f};
;     { const int key = sub * 32 + r; const LAS char* kp = Kt + key * 128; const int ksw = (key >> 1) & 7;
; #pragma unroll
;       for (int d0 = 0; d0 < 4; ++d0) { const bf16x8 kf = *(const LAS bf16x8*)(kp + (((2 * d0 + hh) ^ ksw) << 4)); st = __builtin_amdgcn_mfma_f32_32x32x16_bf16(kf, qr[d0], st, 0, 0, 0); } }
;     f32x2_t sp[8]; const f32x2_t cs2 = {cscale, cscale};
; #pragma unroll
;     for (int g = 0; g < 4; ++g) { const f32x4 c4 = *(const LAS f32x4*)(cb + sub * 32 + 8 * g + 4 * hh);
;         sp[2 * g] = (f32x2_t){st[4 * g], st[4 * g + 1]} + cs2 * (f32x2_t){c4[0], c4[1]};
;         sp[2 * g + 1] = (f32x2_t){st[4 * g + 2], st[4 * g + 3]} + cs2 * (f32x2_t){c4[2], c4[3]};
;         if (MASK) {
; #pragma unroll
;             for (int e = 0; e < 4; ++e) { const int kpos = kpos_sub + 8 * g + 4 * hh + e; const bool ok = (kpos <= qpos && kpos >= qpos - win);
;                 sp[2 * g + (e >> 1)][e & 1] = ok ? sp[2 * g + (e >> 1)][e & 1] : -INFINITY; } } }
;     float rm = fmaxf(sp[0][0], sp[0][1]);
; #pragma unroll
;     for (int i = 1; i < 8; ++i) rm = fmaxf(fmaxf(rm, sp[i][0]), sp[i][1]);
;     rm = swap_max(rm);
;     if (__any(rm - m > 8.0f)) { const float mnew = fmaxf(m, rm); const float f = fast_exp2(m - mnew); l *= f; o0 = o0 * f; o1 = o1 * f; m = mnew; }
.LBB0_565:
	s_and_b64 vcc, exec, s[18:19]
	s_cbranch_vccz .LBB0_575
	ds_read_b64_tr_b16 v[94:95], v244
	ds_read_b64_tr_b16 v[96:97], v244 offset:1024
	ds_read_b64_tr_b16 v[90:91], v217
	ds_read_b64_tr_b16 v[92:93], v217 offset:1024
	ds_read_b64_tr_b16 v[86:87], v244 offset:2048
	ds_read_b64_tr_b16 v[88:89], v244 offset:3072
	ds_read_b64_tr_b16 v[82:83], v217 offset:2048
	ds_read_b64_tr_b16 v[84:85], v217 offset:3072
	s_nop 8
	ds_read_b128 v[66:69], v216 offset:4096
	ds_read_b128 v[130:133], v215 offset:4096
	v_add_u32_e32 v138, s1, v197
	v_or_b32_e32 v0, s5, v150
	v_cmp_le_i32_e32 vcc, v0, v158
	v_cmp_ge_i32_e64 s[44:45], v0, v208
	s_and_b64 vcc, vcc, s[44:45]
	s_waitcnt lgkmcnt(0)
	v_mfma_f32_32x32x16_bf16 v[66:81], v[66:69], v[98:101], 0
	v_mfma_f32_32x32x16_bf16 v[66:81], v[130:133], v[102:105], v[66:81]
	ds_read_b128 v[130:133], v214 offset:4096
	s_waitcnt lgkmcnt(0)
	v_mfma_f32_32x32x16_bf16 v[66:81], v[130:133], v[106:109], v[66:81]
	ds_read_b128 v[130:133], v213 offset:4096
	s_waitcnt lgkmcnt(0)
	v_mfma_f32_32x32x16_bf16 v[66:81], v[130:133], v[110:113], v[66:81]
	ds_read_b128 v[130:133], v138 offset:49280
	ds_read_b128 v[134:137], v138 offset:49312
	s_waitcnt lgkmcnt(0)
	s_nop 8
	v_fma_f32 v66, -v130, s34, v66
	v_fma_f32 v67, -v131, s34, v67
	v_or_b32_e32 v130, 1, v0
	v_cndmask_b32_e32 v66, v240, v66, vcc
	v_cmp_lt_i32_e32 vcc, v0, v158
	v_cmp_ge_i32_e64 s[44:45], v130, v208
	s_and_b64 vcc, vcc, s[44:45]
	v_or_b32_e32 v130, 2, v0
	v_cndmask_b32_e32 v67, v240, v67, vcc
	v_cmp_le_i32_e32 vcc, v130, v158
	v_cmp_ge_i32_e64 s[44:45], v130, v208
	v_fma_f32 v68, -v132, s34, v68
	v_fma_f32 v69, -v133, s34, v69
	s_and_b64 vcc, vcc, s[44:45]
	v_or_b32_e32 v130, 3, v0
	v_cndmask_b32_e32 v68, v240, v68, vcc
	v_cmp_le_i32_e32 vcc, v130, v158
	v_cmp_ge_i32_e64 s[44:45], v130, v208
	s_and_b64 vcc, vcc, s[44:45]
	v_or_b32_e32 v130, 8, v0
	v_cndmask_b32_e32 v69, v240, v69, vcc
	v_cmp_le_i32_e32 vcc, v130, v158
	v_cmp_ge_i32_e64 s[44:45], v130, v208
	v_fma_f32 v70, -v134, s34, v70
	v_fma_f32 v71, -v135, s34, v71
	s_and_b64 vcc, vcc, s[44:45]
	v_or_b32_e32 v130, 9, v0
	v_cndmask_b32_e32 v70, v240, v70, vcc
	v_cmp_le_i32_e32 vcc, v130, v158
	v_cmp_ge_i32_e64 s[44:45], v130, v208
	s_and_b64 vcc, vcc, s[44:45]
	v_or_b32_e32 v130, 10, v0
	v_cndmask_b32_e32 v71, v240, v71, vcc
	v_cmp_le_i32_e32 vcc, v130, v158
	v_cmp_ge_i32_e64 s[44:45], v130, v208
	v_fma_f32 v72, -v136, s34, v72
	v_fma_f32 v73, -v137, s34, v73
	s_and_b64 vcc, vcc, s[44:45]
	v_or_b32_e32 v130, 11, v0
	v_cndmask_b32_e32 v72, v240, v72, vcc
	v_cmp_le_i32_e32 vcc, v130, v158
	v_cmp_ge_i32_e64 s[44:45], v130, v208
	ds_read_b128 v[130:133], v138 offset:49344
	s_and_b64 vcc, vcc, s[44:45]
	v_cndmask_b32_e32 v73, v240, v73, vcc
	s_waitcnt lgkmcnt(0)
	v_fma_f32 v74, -v130, s34, v74
	v_fma_f32 v75, -v131, s34, v75
	v_or_b32_e32 v130, 16, v0
	v_cmp_le_i32_e32 vcc, v130, v158
	v_cmp_ge_i32_e64 s[44:45], v130, v208
	s_and_b64 vcc, vcc, s[44:45]
	v_or_b32_e32 v130, 17, v0
	v_cndmask_b32_e32 v74, v240, v74, vcc
	v_cmp_le_i32_e32 vcc, v130, v158
	v_cmp_ge_i32_e64 s[44:45], v130, v208
	s_and_b64 vcc, vcc, s[44:45]
	v_or_b32_e32 v130, 18, v0
	v_cndmask_b32_e32 v75, v240, v75, vcc
	v_cmp_le_i32_e32 vcc, v130, v158
	v_cmp_ge_i32_e64 s[44:45], v130, v208
	v_fma_f32 v76, -v132, s34, v76
	v_fma_f32 v77, -v133, s34, v77
	s_and_b64 vcc, vcc, s[44:45]
	v_or_b32_e32 v130, 19, v0
	v_cndmask_b32_e32 v76, v240, v76, vcc
	v_cmp_le_i32_e32 vcc, v130, v158
	v_cmp_ge_i32_e64 s[44:45], v130, v208
	ds_read_b128 v[130:133], v138 offset:49376
	s_and_b64 vcc, vcc, s[44:45]
	v_cndmask_b32_e32 v77, v240, v77, vcc
	s_waitcnt lgkmcnt(0)
	v_fma_f32 v78, -v130, s34, v78
	v_fma_f32 v79, -v131, s34, v79
	v_or_b32_e32 v130, 24, v0
	v_cmp_le_i32_e32 vcc, v130, v158
	v_cmp_ge_i32_e64 s[44:45], v130, v208
	s_and_b64 vcc, vcc, s[44:45]
	v_or_b32_e32 v130, 25, v0
	v_cndmask_b32_e32 v78, v240, v78, vcc
	v_cmp_le_i32_e32 vcc, v130, v158
	v_cmp_ge_i32_e64 s[44:45], v130, v208
	s_and_b64 vcc, vcc, s[44:45]
	v_or_b32_e32 v130, 26, v0
	v_cndmask_b32_e32 v79, v240, v79, vcc
	v_cmp_le_i32_e32 vcc, v130, v158
	v_cmp_ge_i32_e64 s[44:45], v130, v208
	v_fma_f32 v80, -v132, s34, v80
	v_fma_f32 v81, -v133, s34, v81
	s_and_b64 vcc, vcc, s[44:45]
	v_or_b32_e32 v0, 27, v0
	v_cndmask_b32_e32 v80, v240, v80, vcc
	v_cmp_le_i32_e32 vcc, v0, v158
	v_cmp_ge_i32_e64 s[44:45], v0, v208
	v_max_f32_e32 v0, v66, v67
	v_max3_f32 v0, v0, v68, v69
	v_max3_f32 v0, v0, v70, v71
	v_max3_f32 v0, v0, v72, v73
	v_max3_f32 v0, v0, v74, v75
	s_and_b64 vcc, vcc, s[44:45]
	v_max3_f32 v0, v0, v76, v77
	v_cndmask_b32_e32 v81, v240, v81, vcc
	v_max3_f32 v0, v0, v78, v79
	v_max3_f32 v0, v0, v80, v81
	v_mov_b32_e32 v130, v0
	s_nop 1
	v_permlane32_swap_b32_e32 v0, v130
	v_max_f32_e32 v130, v130, v130
	v_max_f32_e32 v0, v0, v0
	v_max_f32_e32 v0, v0, v130
	v_sub_f32_e32 v130, v0, v210
	v_cmp_lt_f32_e32 vcc, s9, v130
	s_cbranch_vccz .LBB0_573
	v_max_f32_e32 v0, v0, v0
	v_max_f32_e32 v130, v210, v210
	v_max_f32_e32 v0, v130, v0
	v_sub_f32_e32 v130, v210, v0
	v_exp_f32_e32 v130, v130
	v_mov_b32_e32 v210, v0
	v_mul_f32_e32 v212, v212, v130
	v_mul_f32_e32 v64, v64, v130
	v_mul_f32_e32 v65, v65, v130
	v_mul_f32_e32 v62, v62, v130
	v_mul_f32_e32 v63, v63, v130
	v_mul_f32_e32 v60, v60, v130
	v_mul_f32_e32 v61, v61, v130
	v_mul_f32_e32 v58, v58, v130
	v_mul_f32_e32 v59, v59, v130
	v_mul_f32_e32 v56, v56, v130
	v_mul_f32_e32 v57, v57, v130
	v_mul_f32_e32 v54, v54, v130
	v_mul_f32_e32 v55, v55, v130
	v_mul_f32_e32 v52, v52, v130
	v_mul_f32_e32 v53, v53, v130
	v_mul_f32_e32 v50, v50, v130
	v_mul_f32_e32 v51, v51, v130
	v_mul_f32_e32 v48, v48, v130
	v_mul_f32_e32 v49, v49, v130
	v_mul_f32_e32 v46, v46, v130
	v_mul_f32_e32 v47, v47, v130
	v_mul_f32_e32 v44, v44, v130
	v_mul_f32_e32 v45, v45, v130
	v_mul_f32_e32 v42, v42, v130
	v_mul_f32_e32 v43, v43, v130
	v_mul_f32_e32 v40, v40, v130
	v_mul_f32_e32 v41, v41, v130
	v_mul_f32_e32 v38, v38, v130
	v_mul_f32_e32 v39, v39, v130
	v_mul_f32_e32 v36, v36, v130
	v_mul_f32_e32 v37, v37, v130
	v_mul_f32_e32 v34, v34, v130
	v_mul_f32_e32 v35, v35, v130
	s_branch .LBB0_574

; __device__ __forceinline__ unsigned cvt_pk_bf16(float lo, float hi) { f32x2_t v = {lo, hi}; bf16x2_t b = __builtin_convertvector(v, bf16x2_t); return __builtin_bit_cast(unsigned, b); }
; __device__ __forceinline__ float fast_exp2(float x) { return __builtin_amdgcn_exp2f(x); }
; template <bool MASK> ...
;     ...
;     { const f32x2_t m2 = {m, m}; f32x2_t ps2 = {0.f, 0.f};
; #pragma unroll
;       for (int i = 0; i < 8; ++i) { f32x2_t t = sp[i] - m2; t[0] = fast_exp2(t[0]); t[1] = fast_exp2(t[1]); sp[i] = t; ps2 = ps2 + t; }
;       l += ps2[0] + ps2[1]; }
;     u32x4 pw0, pw1;
;     pw0.x = cvt_pk_bf16(sp[0][0], sp[0][1]); pw0.y = cvt_pk_bf16(sp[1][0], sp[1][1]); pw0.z = cvt_pk_bf16(sp[2][0], sp[2][1]); pw0.w = cvt_pk_bf16(sp[3][0], sp[3][1]);
;     pw1.x = cvt_pk_bf16(sp[4][0], sp[4][1]); pw1.y = cvt_pk_bf16(sp[5][0], sp[5][1]); pw1.z = cvt_pk_bf16(sp[6][0], sp[6][1]); pw1.w = cvt_pk_bf16(sp[7][0], sp[7][1]);
;     asm volatile("s_waitcnt lgkmcnt(0)" : "+v"(l00), "+v"(h00), "+v"(l01), "+v"(h01), "+v"(l10), "+v"(h10), "+v"(l11), "+v"(h11) :: "memory");
;     { const bf16x8 pb0 = __builtin_bit_cast(bf16x8, pw0), pb1 = __builtin_bit_cast(bf16x8, pw1);
;       const bf16x8 v00 = {l00[0], l00[1], l00[2], l00[3], h00[0], h00[1], h00[2], h00[3]}, v01 = {l01[0], l01[1], l01[2], l01[3], h01[0], h01[1], h01[2], h01[3]};
;       const bf16x8 v10 = {l10[0], l10[1], l10[2], l10[3], h10[0], h10[1], h10[2], h10[3]}, v11 = {l11[0], l11[1], l11[2], l11[3], h11[0], h11[1], h11[2], h11[3]};
;       o0 = __builtin_amdgcn_mfma_f32_32x32x16_bf16(v00, pb0, o0, 0, 0, 0); o1 = __builtin_amdgcn_mfma_f32_32x32x16_bf16(v01, pb0, o1, 0, 0, 0);
;       o0 = __builtin_amdgcn_mfma_f32_32x32x16_bf16(v10, pb1, o0, 0, 0, 0); o1 = __builtin_amdgcn_mfma_f32_32x32x16_bf16(v11, pb1, o1, 0, 0, 0); }
.LBB0_569:
	v_sub_f32_e32 v178, v178, v0
	v_sub_f32_e32 v179, v179, v0
	v_sub_f32_e32 v176, v176, v0
	v_sub_f32_e32 v177, v177, v0
	v_exp_f32_e32 v178, v178
	v_exp_f32_e32 v179, v179
	v_exp_f32_e32 v176, v176
	v_exp_f32_e32 v177, v177
	v_sub_f32_e32 v170, v170, v0
	v_sub_f32_e32 v171, v171, v0
	v_sub_f32_e32 v168, v168, v0
	v_sub_f32_e32 v169, v169, v0
	v_exp_f32_e32 v170, v170
	v_exp_f32_e32 v171, v171
	v_exp_f32_e32 v250, v168
	v_exp_f32_e32 v251, v169
	v_add_f32_e32 v248, 0, v178
	v_add_f32_e32 v249, 0, v179
	v_sub_f32_e32 v174, v174, v0
	v_sub_f32_e32 v175, v175, v0
	v_add_f32_e32 v248, v176, v248
	v_add_f32_e32 v249, v177, v249
	v_exp_f32_e32 v174, v174
	v_add_f32_e32 v248, v170, v248
	v_add_f32_e32 v249, v171, v249
	v_exp_f32_e32 v175, v175
	v_sub_f32_e32 v172, v172, v0
	v_sub_f32_e32 v173, v173, v0
	v_add_f32_e32 v168, v250, v248
	v_add_f32_e32 v169, v251, v249
	v_exp_f32_e32 v248, v172
	v_exp_f32_e32 v249, v173
	v_sub_f32_e32 v172, v180, v0
	v_sub_f32_e32 v173, v181, v0
	v_add_f32_e32 v168, v174, v168
	v_add_f32_e32 v169, v175, v169
	v_exp_f32_e32 v180, v172
	v_exp_f32_e32 v181, v173
	v_sub_f32_e32 v172, v182, v0
	v_sub_f32_e32 v173, v183, v0
	v_add_f32_e32 v168, v248, v168
	v_add_f32_e32 v169, v249, v169
	v_exp_f32_e32 v182, v172
	v_exp_f32_e32 v183, v173
	v_add_f32_e32 v168, v180, v168
	v_add_f32_e32 v169, v181, v169
	v_cvt_pk_bf16_f32 v170, v170, v171
	v_cvt_pk_bf16_f32 v171, v250, v251
	v_add_f32_e32 v168, v182, v168
	v_add_f32_e32 v169, v183, v169
	s_waitcnt lgkmcnt(0)
	v_cvt_pk_bf16_f32 v172, v174, v175
	v_add_f32_e32 v0, v168, v169
	v_cvt_pk_bf16_f32 v168, v178, v179
	v_cvt_pk_bf16_f32 v169, v176, v177
	v_cvt_pk_bf16_f32 v173, v248, v249
	v_cvt_pk_bf16_f32 v174, v180, v181
	v_mfma_f32_32x32x16_bf16 v[18:33], v[142:145], v[168:171], v[18:33]
	v_cvt_pk_bf16_f32 v175, v182, v183
	v_add_f32_e32 v0, v246, v0
	s_mov_b64 s[18:19], 0
	v_mfma_f32_32x32x16_bf16 v[2:17], v[138:141], v[168:171], v[2:17]
	v_mfma_f32_32x32x16_bf16 v[18:33], v[134:137], v[172:175], v[18:33]
	v_mfma_f32_32x32x16_bf16 v[2:17], v[130:133], v[172:175], v[2:17]
; #define LAS __attribute__((address_space(3)))
; template <bool MASK> ...
;     s16x4 l00, h00, l01, h01, l10, h10, l11, h11; { const unsigned a0 = va0 + sub * 4096, a1 = va1 + sub * 4096;
;       asm volatile("ds_read_b64_tr_b16 %0, %1" : "=&v"(l00) : "v"(a0) : "memory"); asm volatile("ds_read_b64_tr_b16 %0, %1 offset:1024" : "=&v"(h00) : "v"(a0) : "memory");
;       asm volatile("ds_read_b64_tr_b16 %0, %1" : "=&v"(l01) : "v"(a1) : "memory"); asm volatile("ds_read_b64_tr_b16 %0, %1 offset:1024" : "=&v"(h01) : "v"(a1) : "memory");
;       asm volatile("ds_read_b64_tr_b16 %0, %1 offset:2048" : "=&v"(l10) : "v"(a0) : "memory"); asm volatile("ds_read_b64_tr_b16 %0, %1 offset:3072" : "=&v"(h10) : "v"(a0) : "memory");
;       asm volatile("ds_read_b64_tr_b16 %0, %1 offset:2048" : "=&v"(l11) : "v"(a1) : "memory"); asm volatile("ds_read_b64_tr_b16 %0, %1 offset:3072" : "=&v"(h11) : "v"(a1) : "memory"); }
;     const int r = lane & 31, hh = lane >> 5;
;     f32x16 st = {0.f, 0.f, 0.f, 0.f, 0.f, 0.f, 0.f, 0.f, 0.f, 0.f, 0.f, 0.f, 0.f, 0.f, 0.f, 0.f};
;     { const int key = sub * 32 + r; const LAS char* kp = Kt + key * 128; const int ksw = (key >> 1) & 7;
; #pragma unroll
;       for (int d0 = 0; d0 < 4; ++d0) { const bf16x8 kf = *(const LAS bf16x8*)(kp + (((2 * d0 + hh) ^ ksw) << 4)); st = __builtin_amdgcn_mfma_f32_32x32x16_bf16(kf, qr[d0], st, 0, 0, 0); } }
;     f32x2_t sp[8]; const f32x2_t cs2 = {cscale, cscale};
; #pragma unroll
;     for (int g = 0; g < 4; ++g) { const f32x4 c4 = *(const LAS f32x4*)(cb + sub * 32 + 8 * g + 4 * hh);
;         sp[2 * g] = (f32x2_t){st[4 * g], st[4 * g + 1]} + cs2 * (f32x2_t){c4[0], c4[1]};
;         sp[2 * g + 1] = (f32x2_t){st[4 * g + 2], st[4 * g + 3]} + cs2 * (f32x2_t){c4[2], c4[3]};
;         if (MASK) {
; #pragma unroll
;             for (int e = 0; e < 4; ++e) { const int kpos = kpos_sub + 8 * g + 4 * hh + e; const bool ok = (kpos <= qpos && kpos >= qpos - win);
;                 sp[2 * g + (e >> 1)][e & 1] = ok ? sp[2 * g + (e >> 1)][e & 1] : -INFINITY; } } }
;     float rm = fmaxf(sp[0][0], sp[0][1]);
; #pragma unroll
;     for (int i = 1; i < 8; ++i) rm = fmaxf(fmaxf(rm, sp[i][0]), sp[i][1]);
;     rm = swap_max(rm);
;     if (__any(rm - m > 8.0f)) { const float mnew = fmaxf(m, rm); const float f = fast_exp2(m - mnew); l *= f; o0 = o0 * f; o1 = o1 * f; m = mnew; }
.LBB0_570:
	s_and_b64 vcc, exec, s[18:19]
	s_cbranch_vccz .LBB0_522
	ds_read_b64_tr_b16 v[94:95], v244
	ds_read_b64_tr_b16 v[96:97], v244 offset:1024
	ds_read_b64_tr_b16 v[90:91], v217
	ds_read_b64_tr_b16 v[92:93], v217 offset:1024
	ds_read_b64_tr_b16 v[86:87], v244 offset:2048
	ds_read_b64_tr_b16 v[88:89], v244 offset:3072
	ds_read_b64_tr_b16 v[82:83], v217 offset:2048
	ds_read_b64_tr_b16 v[84:85], v217 offset:3072
	s_nop 8
	ds_read_b128 v[66:69], v216 offset:4096
	ds_read_b128 v[130:133], v215 offset:4096
	v_or_b32_e32 v0, s5, v150
	v_cmp_le_i32_e32 vcc, v0, v154
	v_cmp_ge_i32_e64 s[44:45], v0, v209
	s_and_b64 vcc, vcc, s[44:45]
	s_waitcnt lgkmcnt(0)
	v_mfma_f32_32x32x16_bf16 v[66:81], v[66:69], v[114:117], 0
	v_mfma_f32_32x32x16_bf16 v[66:81], v[130:133], v[118:121], v[66:81]
	ds_read_b128 v[130:133], v214 offset:4096
	s_waitcnt lgkmcnt(0)
	v_mfma_f32_32x32x16_bf16 v[66:81], v[130:133], v[122:125], v[66:81]
	ds_read_b128 v[130:133], v213 offset:4096
	s_waitcnt lgkmcnt(0)
	v_mfma_f32_32x32x16_bf16 v[66:81], v[130:133], v[126:129], v[66:81]
	ds_read_b128 v[130:133], v243 offset:49280
	ds_read_b128 v[134:137], v243 offset:49312
	s_waitcnt lgkmcnt(0)
	s_nop 8
	v_fma_f32 v66, -v130, s34, v66
	v_fma_f32 v67, -v131, s34, v67
	v_or_b32_e32 v130, 1, v0
	v_cndmask_b32_e32 v66, v240, v66, vcc
	v_cmp_lt_i32_e32 vcc, v0, v154
	v_cmp_ge_i32_e64 s[44:45], v130, v209
	s_and_b64 vcc, vcc, s[44:45]
	v_or_b32_e32 v130, 2, v0
	v_cndmask_b32_e32 v67, v240, v67, vcc
	v_cmp_le_i32_e32 vcc, v130, v154
	v_cmp_ge_i32_e64 s[44:45], v130, v209
	v_fma_f32 v68, -v132, s34, v68
	v_fma_f32 v69, -v133, s34, v69
	s_and_b64 vcc, vcc, s[44:45]
	v_or_b32_e32 v130, 3, v0
	v_cndmask_b32_e32 v68, v240, v68, vcc
	v_cmp_le_i32_e32 vcc, v130, v154
	v_cmp_ge_i32_e64 s[44:45], v130, v209
	s_and_b64 vcc, vcc, s[44:45]
	v_or_b32_e32 v130, 8, v0
	v_cndmask_b32_e32 v69, v240, v69, vcc
	v_cmp_le_i32_e32 vcc, v130, v154
	v_cmp_ge_i32_e64 s[44:45], v130, v209
	v_fma_f32 v70, -v134, s34, v70
	v_fma_f32 v71, -v135, s34, v71
	s_and_b64 vcc, vcc, s[44:45]
	v_or_b32_e32 v130, 9, v0
	v_cndmask_b32_e32 v70, v240, v70, vcc
	v_cmp_le_i32_e32 vcc, v130, v154
	v_cmp_ge_i32_e64 s[44:45], v130, v209
	s_and_b64 vcc, vcc, s[44:45]
	v_or_b32_e32 v130, 10, v0
	v_cndmask_b32_e32 v71, v240, v71, vcc
	v_cmp_le_i32_e32 vcc, v130, v154
	v_cmp_ge_i32_e64 s[44:45], v130, v209
	v_fma_f32 v72, -v136, s34, v72
	v_fma_f32 v73, -v137, s34, v73
	s_and_b64 vcc, vcc, s[44:45]
	v_or_b32_e32 v130, 11, v0
	v_cndmask_b32_e32 v72, v240, v72, vcc
	v_cmp_le_i32_e32 vcc, v130, v154
	v_cmp_ge_i32_e64 s[44:45], v130, v209
	ds_read_b128 v[130:133], v243 offset:49344
	s_and_b64 vcc, vcc, s[44:45]
	v_cndmask_b32_e32 v73, v240, v73, vcc
	s_waitcnt lgkmcnt(0)
	v_fma_f32 v74, -v130, s34, v74
	v_fma_f32 v75, -v131, s34, v75
	v_or_b32_e32 v130, 16, v0
	v_cmp_le_i32_e32 vcc, v130, v154
	v_cmp_ge_i32_e64 s[44:45], v130, v209
	s_and_b64 vcc, vcc, s[44:45]
	v_or_b32_e32 v130, 17, v0
	v_cndmask_b32_e32 v74, v240, v74, vcc
	v_cmp_le_i32_e32 vcc, v130, v154
	v_cmp_ge_i32_e64 s[44:45], v130, v209
	s_and_b64 vcc, vcc, s[44:45]
	v_or_b32_e32 v130, 18, v0
	v_cndmask_b32_e32 v75, v240, v75, vcc
	v_cmp_le_i32_e32 vcc, v130, v154
	v_cmp_ge_i32_e64 s[44:45], v130, v209
	v_fma_f32 v76, -v132, s34, v76
	v_fma_f32 v77, -v133, s34, v77
	s_and_b64 vcc, vcc, s[44:45]
	v_or_b32_e32 v130, 19, v0
	v_cndmask_b32_e32 v76, v240, v76, vcc
	v_cmp_le_i32_e32 vcc, v130, v154
	v_cmp_ge_i32_e64 s[44:45], v130, v209
	ds_read_b128 v[130:133], v243 offset:49376
	s_and_b64 vcc, vcc, s[44:45]
	v_cndmask_b32_e32 v77, v240, v77, vcc
	s_waitcnt lgkmcnt(0)
	v_fma_f32 v78, -v130, s34, v78
	v_fma_f32 v79, -v131, s34, v79
	v_or_b32_e32 v130, 24, v0
	v_cmp_le_i32_e32 vcc, v130, v154
	v_cmp_ge_i32_e64 s[44:45], v130, v209
	s_and_b64 vcc, vcc, s[44:45]
	v_or_b32_e32 v130, 25, v0
	v_cndmask_b32_e32 v78, v240, v78, vcc
	v_cmp_le_i32_e32 vcc, v130, v154
	v_cmp_ge_i32_e64 s[44:45], v130, v209
	s_and_b64 vcc, vcc, s[44:45]
	v_or_b32_e32 v130, 26, v0
	v_cndmask_b32_e32 v79, v240, v79, vcc
	v_cmp_le_i32_e32 vcc, v130, v154
	v_cmp_ge_i32_e64 s[44:45], v130, v209
	v_fma_f32 v80, -v132, s34, v80
	v_fma_f32 v81, -v133, s34, v81
	s_and_b64 vcc, vcc, s[44:45]
	v_or_b32_e32 v0, 27, v0
	v_cndmask_b32_e32 v80, v240, v80, vcc
	v_cmp_le_i32_e32 vcc, v0, v154
	v_cmp_ge_i32_e64 s[44:45], v0, v209
	v_max_f32_e32 v0, v66, v67
	v_max3_f32 v0, v0, v68, v69
	v_max3_f32 v0, v0, v70, v71
	v_max3_f32 v0, v0, v72, v73
	v_max3_f32 v0, v0, v74, v75
	s_and_b64 vcc, vcc, s[44:45]
	v_max3_f32 v0, v0, v76, v77
	v_cndmask_b32_e32 v81, v240, v81, vcc
	v_max3_f32 v0, v0, v78, v79
	v_max3_f32 v0, v0, v80, v81
	v_mov_b32_e32 v130, v0
	s_nop 1
	v_permlane32_swap_b32_e32 v0, v130
	v_max_f32_e32 v130, v130, v130
	v_max_f32_e32 v0, v0, v0
	v_max_f32_e32 v0, v0, v130
	v_sub_f32_e32 v130, v0, v211
	v_cmp_lt_f32_e32 vcc, s9, v130
	s_cbranch_vccz .LBB0_520
	v_max_f32_e32 v0, v0, v0
	v_max_f32_e32 v130, v211, v211
	v_max_f32_e32 v0, v130, v0
	v_sub_f32_e32 v130, v211, v0
	v_exp_f32_e32 v130, v130
	v_mov_b32_e32 v211, v0
	v_mul_f32_e32 v194, v194, v130
	v_mul_f32_e32 v32, v32, v130
	v_mul_f32_e32 v33, v33, v130
	v_mul_f32_e32 v30, v30, v130
	v_mul_f32_e32 v31, v31, v130
	v_mul_f32_e32 v28, v28, v130
	v_mul_f32_e32 v29, v29, v130
	v_mul_f32_e32 v26, v26, v130
	v_mul_f32_e32 v27, v27, v130
	v_mul_f32_e32 v24, v24, v130
	v_mul_f32_e32 v25, v25, v130
	v_mul_f32_e32 v22, v22, v130
	v_mul_f32_e32 v23, v23, v130
	v_mul_f32_e32 v20, v20, v130
	v_mul_f32_e32 v21, v21, v130
	v_mul_f32_e32 v18, v18, v130
	v_mul_f32_e32 v19, v19, v130
	v_mul_f32_e32 v16, v16, v130
	v_mul_f32_e32 v17, v17, v130
	v_mul_f32_e32 v14, v14, v130
	v_mul_f32_e32 v15, v15, v130
	v_mul_f32_e32 v12, v12, v130
	v_mul_f32_e32 v13, v13, v130
	v_mul_f32_e32 v10, v10, v130
	v_mul_f32_e32 v11, v11, v130
	v_mul_f32_e32 v8, v8, v130
	v_mul_f32_e32 v9, v9, v130
	v_mul_f32_e32 v6, v6, v130
	v_mul_f32_e32 v7, v7, v130
	v_mul_f32_e32 v4, v4, v130
	v_mul_f32_e32 v5, v5, v130
	v_mul_f32_e32 v2, v2, v130
	v_mul_f32_e32 v3, v3, v130
	s_branch .LBB0_521

; __device__ __forceinline__ unsigned cvt_pk_bf16(float lo, float hi) { f32x2_t v = {lo, hi}; bf16x2_t b = __builtin_convertvector(v, bf16x2_t); return __builtin_bit_cast(unsigned, b); }
; __device__ __forceinline__ float fast_exp2(float x) { return __builtin_amdgcn_exp2f(x); }
; template <bool MASK> ...
;     ...
;     { const f32x2_t m2 = {m, m}; f32x2_t ps2 = {0.f, 0.f};
; #pragma unroll
;       for (int i = 0; i < 8; ++i) { f32x2_t t = sp[i] - m2; t[0] = fast_exp2(t[0]); t[1] = fast_exp2(t[1]); sp[i] = t; ps2 = ps2 + t; }
;       l += ps2[0] + ps2[1]; }
;     u32x4 pw0, pw1;
;     pw0.x = cvt_pk_bf16(sp[0][0], sp[0][1]); pw0.y = cvt_pk_bf16(sp[1][0], sp[1][1]); pw0.z = cvt_pk_bf16(sp[2][0], sp[2][1]); pw0.w = cvt_pk_bf16(sp[3][0], sp[3][1]);
;     pw1.x = cvt_pk_bf16(sp[4][0], sp[4][1]); pw1.y = cvt_pk_bf16(sp[5][0], sp[5][1]); pw1.z = cvt_pk_bf16(sp[6][0], sp[6][1]); pw1.w = cvt_pk_bf16(sp[7][0], sp[7][1]);
;     asm volatile("s_waitcnt lgkmcnt(0)" : "+v"(l00), "+v"(h00), "+v"(l01), "+v"(h01), "+v"(l10), "+v"(h10), "+v"(l11), "+v"(h11) :: "memory");
;     { const bf16x8 pb0 = __builtin_bit_cast(bf16x8, pw0), pb1 = __builtin_bit_cast(bf16x8, pw1);
;       const bf16x8 v00 = {l00[0], l00[1], l00[2], l00[3], h00[0], h00[1], h00[2], h00[3]}, v01 = {l01[0], l01[1], l01[2], l01[3], h01[0], h01[1], h01[2], h01[3]};
;       const bf16x8 v10 = {l10[0], l10[1], l10[2], l10[3], h10[0], h10[1], h10[2], h10[3]}, v11 = {l11[0], l11[1], l11[2], l11[3], h11[0], h11[1], h11[2], h11[3]};
;       o0 = __builtin_amdgcn_mfma_f32_32x32x16_bf16(v00, pb0, o0, 0, 0, 0); o1 = __builtin_amdgcn_mfma_f32_32x32x16_bf16(v01, pb0, o1, 0, 0, 0);
;       o0 = __builtin_amdgcn_mfma_f32_32x32x16_bf16(v10, pb1, o0, 0, 0, 0); o1 = __builtin_amdgcn_mfma_f32_32x32x16_bf16(v11, pb1, o1, 0, 0, 0); }
.LBB0_574:
	v_sub_f32_e32 v66, v66, v0
	v_sub_f32_e32 v67, v67, v0
	v_sub_f32_e32 v68, v68, v0
	v_sub_f32_e32 v69, v69, v0
	v_exp_f32_e32 v66, v66
	v_exp_f32_e32 v67, v67
	v_sub_f32_e32 v70, v70, v0
	v_sub_f32_e32 v71, v71, v0
	v_sub_f32_e32 v72, v72, v0
	v_sub_f32_e32 v73, v73, v0
	v_exp_f32_e32 v68, v68
	v_exp_f32_e32 v69, v69
	v_exp_f32_e32 v70, v70
	v_exp_f32_e32 v71, v71
	v_exp_f32_e32 v72, v72
	v_exp_f32_e32 v73, v73
	v_add_f32_e32 v130, 0, v66
	v_add_f32_e32 v131, 0, v67
	v_cvt_pk_bf16_f32 v66, v66, v67
	v_add_f32_e32 v130, v68, v130
	v_add_f32_e32 v131, v69, v131
	v_cvt_pk_bf16_f32 v67, v68, v69
	v_cvt_pk_bf16_f32 v68, v70, v71
	v_cvt_pk_bf16_f32 v69, v72, v73
	s_waitcnt lgkmcnt(0)
	v_sub_f32_e32 v74, v74, v0
	v_sub_f32_e32 v75, v75, v0
	v_sub_f32_e32 v76, v76, v0
	v_sub_f32_e32 v77, v77, v0
	v_mfma_f32_32x32x16_bf16 v[50:65], v[94:97], v[66:69], v[50:65]
	v_add_f32_e64 v78, v78, -v0
	v_add_f32_e64 v79, v79, -v0
	v_add_f32_e64 v80, v80, -v0
	v_add_f32_e64 v81, v81, -v0
	v_exp_f32_e32 v74, v74
	v_exp_f32_e32 v75, v75
	v_exp_f32_e32 v76, v76
	v_exp_f32_e32 v77, v77
	v_exp_f32_e32 v78, v78
	v_mfma_f32_32x32x16_bf16 v[34:49], v[90:93], v[66:69], v[34:49]
	v_exp_f32_e32 v79, v79
	v_exp_f32_e32 v80, v80
	v_exp_f32_e32 v81, v81
	v_add_f32_e32 v130, v70, v130
	v_add_f32_e32 v131, v71, v131
	v_cvt_pk_bf16_f32 v70, v74, v75
	v_add_f32_e32 v130, v72, v130
	v_add_f32_e32 v131, v73, v131
	v_cvt_pk_bf16_f32 v71, v76, v77
	v_cvt_pk_bf16_f32 v72, v78, v79
	v_cvt_pk_bf16_f32 v73, v80, v81
	v_add_f32_e32 v130, v74, v130
	v_add_f32_e32 v131, v75, v131
	v_mov_b32_e32 v243, v210
	v_mfma_f32_32x32x16_bf16 v[50:65], v[86:89], v[70:73], v[50:65]
	v_add_f32_e64 v130, v76, v130
	v_add_f32_e64 v131, v77, v131
	v_add_f32_e64 v130, v78, v130
	v_add_f32_e64 v131, v79, v131
	v_add_f32_e64 v130, v80, v130
	v_add_f32_e64 v131, v81, v131
	v_add_f32_e32 v0, v130, v131
	v_mfma_f32_32x32x16_bf16 v[34:49], v[82:85], v[70:73], v[34:49]
	s_nop 3
	v_add_f32_e32 v0, v212, v0
	s_nop 0

; __device__ __forceinline__ unsigned cvt_pk_bf16(float lo, float hi) { f32x2_t v = {lo, hi}; bf16x2_t b = __builtin_convertvector(v, bf16x2_t); return __builtin_bit_cast(unsigned, b); }
; __device__ __forceinline__ float bf_lo(unsigned w) { return __uint_as_float(w << 16); }
; __device__ __forceinline__ float bf_hi(unsigned w) { return __uint_as_float(w & 0xffff0000u); }
; __device__ __forceinline__ void moba_own_unit(LAS char* lds, int bh, int jblk, const bf16_t* H, const bf16_t* PO, const float* PML, bf16_t* U, int tid) {
;     ...
;         for (int g = 0; g < 4; ++g) { const int d = 32 * d0 + 8 * g + 4 * hh; const f32x16& o = d0 ? o1 : o0;
;             float a0 = o[4 * g] * wown, a1 = o[4 * g + 1] * wown, a2 = o[4 * g + 2] * wown, a3 = o[4 * g + 3] * wown;
; #pragma unroll
;             for (int s = 0; s < 3; ++s) if (s < nsel) { const u32x2 pv = *(const u32x2*)(PO + (pidx + s) * 64 + d); a0 += wi[s] * bf_lo(pv.x); a1 += wi[s] * bf_hi(pv.x); a2 += wi[s] * bf_lo(pv.y); a3 += wi[s] * bf_hi(pv.y); }
;             const u32x2 z = zr.z[d0][g];
;             u32x2 w; w.x = cvt_pk_bf16(a0 * inv * bf_lo(z.x), a1 * inv * bf_hi(z.x)); w.y = cvt_pk_bf16(a2 * inv * bf_lo(z.y), a3 * inv * bf_hi(z.y));
;             *(u32x2*)(urow + d) = w; }
.LBB0_631:
	v_mul_f32_e32 v4, v34, v4
	v_mul_f32_e32 v5, v35, v5
	v_lshlrev_b32_e32 v6, 16, v120
	v_and_b32_e32 v7, 0xffff0000, v120
	v_mul_f32_e32 v4, v4, v6
	v_mul_f32_e32 v5, v5, v7
	v_mul_f32_e32 v2, v34, v2
	v_mul_f32_e32 v3, v35, v3
	v_lshlrev_b32_e32 v6, 16, v121
	v_and_b32_e32 v7, 0xffff0000, v121
	v_mul_f32_e32 v2, v2, v6
	v_mul_f32_e32 v3, v3, v7
	s_add_i32 s23, s23, s56
	v_cvt_pk_bf16_f32 v4, v4, v5
	v_cvt_pk_bf16_f32 v5, v2, v3
	s_cmpk_gt_i32 s23, 0x3ff
	global_store_dwordx2 v[22:23], v[4:5], off offset:112
	s_cbranch_scc1 .LBB0_773

; #define LAS __attribute__((address_space(3)))
; template <bool MASK> ...
;     s16x4 l00, h00, l01, h01, l10, h10, l11, h11; { const unsigned a0 = va0 + sub * 4096, a1 = va1 + sub * 4096;
;       asm volatile("ds_read_b64_tr_b16 %0, %1" : "=&v"(l00) : "v"(a0) : "memory"); asm volatile("ds_read_b64_tr_b16 %0, %1 offset:1024" : "=&v"(h00) : "v"(a0) : "memory");
;       asm volatile("ds_read_b64_tr_b16 %0, %1" : "=&v"(l01) : "v"(a1) : "memory"); asm volatile("ds_read_b64_tr_b16 %0, %1 offset:1024" : "=&v"(h01) : "v"(a1) : "memory");
;       asm volatile("ds_read_b64_tr_b16 %0, %1 offset:2048" : "=&v"(l10) : "v"(a0) : "memory"); asm volatile("ds_read_b64_tr_b16 %0, %1 offset:3072" : "=&v"(h10) : "v"(a0) : "memory");
;       asm volatile("ds_read_b64_tr_b16 %0, %1 offset:2048" : "=&v"(l11) : "v"(a1) : "memory"); asm volatile("ds_read_b64_tr_b16 %0, %1 offset:3072" : "=&v"(h11) : "v"(a1) : "memory"); }
;     const int r = lane & 31, hh = lane >> 5;
;     f32x16 st = {0.f, 0.f, 0.f, 0.f, 0.f, 0.f, 0.f, 0.f, 0.f, 0.f, 0.f, 0.f, 0.f, 0.f, 0.f, 0.f};
;     { const int key = sub * 32 + r; const LAS char* kp = Kt + key * 128; const int ksw = (key >> 1) & 7;
; #pragma unroll
;       for (int d0 = 0; d0 < 4; ++d0) { const bf16x8 kf = *(const LAS bf16x8*)(kp + (((2 * d0 + hh) ^ ksw) << 4)); st = __builtin_amdgcn_mfma_f32_32x32x16_bf16(kf, qr[d0], st, 0, 0, 0); } }
;     f32x2_t sp[8]; const f32x2_t cs2 = {cscale, cscale};
; #pragma unroll
;     for (int g = 0; g < 4; ++g) { const f32x4 c4 = *(const LAS f32x4*)(cb + sub * 32 + 8 * g + 4 * hh);
;         sp[2 * g] = (f32x2_t){st[4 * g], st[4 * g + 1]} + cs2 * (f32x2_t){c4[0], c4[1]};
;         sp[2 * g + 1] = (f32x2_t){st[4 * g + 2], st[4 * g + 3]} + cs2 * (f32x2_t){c4[2], c4[3]};
;         if (MASK) {
; #pragma unroll
;             for (int e = 0; e < 4; ++e) { const int kpos = kpos_sub + 8 * g + 4 * hh + e; const bool ok = (kpos <= qpos && kpos >= qpos - win);
;                 sp[2 * g + (e >> 1)][e & 1] = ok ? sp[2 * g + (e >> 1)][e & 1] : -INFINITY; } } }
;     float rm = fmaxf(sp[0][0], sp[0][1]);
; #pragma unroll
;     for (int i = 1; i < 8; ++i) rm = fmaxf(fmaxf(rm, sp[i][0]), sp[i][1]);
;     rm = swap_max(rm);
;     if (__any(rm - m > 8.0f)) { const float mnew = fmaxf(m, rm); const float f = fast_exp2(m - mnew); l *= f; o0 = o0 * f; o1 = o1 * f; m = mnew; }
.LBB0_645:
	s_add_i32 s11, s11, 1
	v_cvt_f32_ubyte0_e32 v2, s11
	v_cmp_lt_f32_e32 vcc, s33, v2
	s_and_b64 s[16:17], vcc, exec
	s_cselect_b32 s11, 0xffffffc0, 0
	v_cndmask_b32_e32 v3, 0, v238, vcc
	v_sub_f32_e32 v2, v3, v2
	v_exp_f32_e32 v2, v2
	s_or_b32 s36, s25, 31
	s_cmp_gt_i32 s24, s36
	v_add_u32_e32 v119, -2.0, v144
	v_ldexp_f32 v2, v2, s11
	v_mul_f32_e32 v148, 0x3fb8aa3b, v2
	v_mov_b32_e32 v149, v148
	s_cbranch_scc1 .LBB0_649
	s_cmp_lt_i32 s3, 1
	s_mov_b64 s[18:19], -1
	s_cbranch_scc1 .LBB0_650
	ds_read_b64_tr_b16 v[48:49], v178
	ds_read_b64_tr_b16 v[50:51], v178 offset:1024
	ds_read_b64_tr_b16 v[44:45], v179
	ds_read_b64_tr_b16 v[46:47], v179 offset:1024
	ds_read_b64_tr_b16 v[40:41], v178 offset:2048
	ds_read_b64_tr_b16 v[42:43], v178 offset:3072
	ds_read_b64_tr_b16 v[36:37], v179 offset:2048
	ds_read_b64_tr_b16 v[38:39], v179 offset:3072
	v_add_u32_e32 v2, v188, v180
	ds_read_b128 v[2:5], v2
	v_add_u32_e32 v18, v188, v181
	ds_read_b128 v[18:21], v18
	s_waitcnt lgkmcnt(0)
	v_mfma_f32_32x32x16_bf16 v[2:17], v[2:5], v[76:79], 0
	v_mfma_f32_32x32x16_bf16 v[2:17], v[18:21], v[68:71], v[2:17]
	v_add_u32_e32 v18, v188, v182
	ds_read_b128 v[18:21], v18
	s_waitcnt lgkmcnt(0)
	v_mfma_f32_32x32x16_bf16 v[2:17], v[18:21], v[72:75], v[2:17]
	v_add_u32_e32 v18, v188, v183
	ds_read_b128 v[18:21], v18
	s_waitcnt lgkmcnt(0)
	v_mfma_f32_32x32x16_bf16 v[2:17], v[18:21], v[80:83], v[2:17]
	ds_read_b128 v[18:21], v186 offset:49152
	ds_read_b128 v[22:25], v186 offset:49184
	s_waitcnt lgkmcnt(0)
	s_nop 8
	v_fma_f32 v28, v148, v18, v2
	v_fma_f32 v29, v149, v19, v3
	v_fma_f32 v26, v148, v20, v4
	v_fma_f32 v27, v149, v21, v5
	ds_read_b128 v[2:5], v186 offset:49216
	v_fma_f32 v18, v148, v24, v8
	v_fma_f32 v19, v149, v25, v9
	v_fma_f32 v22, v148, v22, v6
	v_fma_f32 v23, v149, v23, v7
	s_waitcnt lgkmcnt(0)
	v_fma_f32 v24, v148, v2, v10
	v_fma_f32 v25, v149, v3, v11
	v_fma_f32 v20, v148, v4, v12
	v_fma_f32 v21, v149, v5, v13
	ds_read_b128 v[2:5], v186 offset:49248
	s_waitcnt lgkmcnt(0)
	v_fma_f32 v32, v148, v2, v14
	v_fma_f32 v33, v149, v3, v15
	v_max_f32_e32 v2, v28, v29
	v_max3_f32 v2, v2, v26, v27
	v_max3_f32 v2, v2, v22, v23
	v_max3_f32 v2, v2, v18, v19
	v_max3_f32 v2, v2, v24, v25
	v_max3_f32 v2, v2, v20, v21
	v_fma_f32 v30, v148, v4, v16
	v_fma_f32 v31, v149, v5, v17
	v_max3_f32 v2, v2, v32, v33
	v_max3_f32 v2, v2, v30, v31
	v_mov_b32_e32 v3, v2
	s_nop 1
	v_permlane32_swap_b32_e32 v2, v3
	v_max_f32_e32 v3, v3, v3
	v_max_f32_e32 v2, v2, v2
	v_max_f32_e32 v2, v2, v3
	v_add_f32_e32 v3, 0x7149f2ca, v2
	v_cmp_lt_f32_e32 vcc, s9, v3
	s_cbranch_vccz .LBB0_653
	v_max_f32_e32 v2, v2, v2
	v_max_f32_e32 v122, 0xf149f2ca, v2
	v_sub_f32_e32 v2, 0xf149f2ca, v122
	v_exp_f32_e32 v2, v2
	s_nop 0
	v_mul_f32_e32 v2, 0, v2
	s_branch .LBB0_654

; #define LAS __attribute__((address_space(3)))
; template <bool MASK> ...
;     s16x4 l00, h00, l01, h01, l10, h10, l11, h11; { const unsigned a0 = va0 + sub * 4096, a1 = va1 + sub * 4096;
;       asm volatile("ds_read_b64_tr_b16 %0, %1" : "=&v"(l00) : "v"(a0) : "memory"); asm volatile("ds_read_b64_tr_b16 %0, %1 offset:1024" : "=&v"(h00) : "v"(a0) : "memory");
;       asm volatile("ds_read_b64_tr_b16 %0, %1" : "=&v"(l01) : "v"(a1) : "memory"); asm volatile("ds_read_b64_tr_b16 %0, %1 offset:1024" : "=&v"(h01) : "v"(a1) : "memory");
;       asm volatile("ds_read_b64_tr_b16 %0, %1 offset:2048" : "=&v"(l10) : "v"(a0) : "memory"); asm volatile("ds_read_b64_tr_b16 %0, %1 offset:3072" : "=&v"(h10) : "v"(a0) : "memory");
;       asm volatile("ds_read_b64_tr_b16 %0, %1 offset:2048" : "=&v"(l11) : "v"(a1) : "memory"); asm volatile("ds_read_b64_tr_b16 %0, %1 offset:3072" : "=&v"(h11) : "v"(a1) : "memory"); }
;     const int r = lane & 31, hh = lane >> 5;
;     f32x16 st = {0.f, 0.f, 0.f, 0.f, 0.f, 0.f, 0.f, 0.f, 0.f, 0.f, 0.f, 0.f, 0.f, 0.f, 0.f, 0.f};
;     { const int key = sub * 32 + r; const LAS char* kp = Kt + key * 128; const int ksw = (key >> 1) & 7;
; #pragma unroll
;       for (int d0 = 0; d0 < 4; ++d0) { const bf16x8 kf = *(const LAS bf16x8*)(kp + (((2 * d0 + hh) ^ ksw) << 4)); st = __builtin_amdgcn_mfma_f32_32x32x16_bf16(kf, qr[d0], st, 0, 0, 0); } }
;     f32x2_t sp[8]; const f32x2_t cs2 = {cscale, cscale};
; #pragma unroll
;     for (int g = 0; g < 4; ++g) { const f32x4 c4 = *(const LAS f32x4*)(cb + sub * 32 + 8 * g + 4 * hh);
;         sp[2 * g] = (f32x2_t){st[4 * g], st[4 * g + 1]} + cs2 * (f32x2_t){c4[0], c4[1]};
;         sp[2 * g + 1] = (f32x2_t){st[4 * g + 2], st[4 * g + 3]} + cs2 * (f32x2_t){c4[2], c4[3]};
;         if (MASK) {
; #pragma unroll
;             for (int e = 0; e < 4; ++e) { const int kpos = kpos_sub + 8 * g + 4 * hh + e; const bool ok = (kpos <= qpos && kpos >= qpos - win);
;                 sp[2 * g + (e >> 1)][e & 1] = ok ? sp[2 * g + (e >> 1)][e & 1] : -INFINITY; } } }
;     float rm = fmaxf(sp[0][0], sp[0][1]);
; #pragma unroll
;     for (int i = 1; i < 8; ++i) rm = fmaxf(fmaxf(rm, sp[i][0]), sp[i][1]);
;     rm = swap_max(rm);
;     if (__any(rm - m > 8.0f)) { const float mnew = fmaxf(m, rm); const float f = fast_exp2(m - mnew); l *= f; o0 = o0 * f; o1 = o1 * f; m = mnew; }
.LBB0_650:
	s_and_b64 vcc, exec, s[18:19]
	s_cbranch_vccz .LBB0_655
	ds_read_b64_tr_b16 v[48:49], v178
	ds_read_b64_tr_b16 v[50:51], v178 offset:1024
	ds_read_b64_tr_b16 v[44:45], v179
	ds_read_b64_tr_b16 v[46:47], v179 offset:1024
	ds_read_b64_tr_b16 v[40:41], v178 offset:2048
	ds_read_b64_tr_b16 v[42:43], v178 offset:3072
	ds_read_b64_tr_b16 v[36:37], v179 offset:2048
	ds_read_b64_tr_b16 v[38:39], v179 offset:3072
	v_add_u32_e32 v2, v188, v180
	ds_read_b128 v[2:5], v2
	v_add_u32_e32 v18, v188, v181
	ds_read_b128 v[18:21], v18
	v_or_b32_e32 v31, s24, v100
	v_cmp_le_i32_e32 vcc, v31, v144
	v_cmp_ge_i32_e64 s[48:49], v31, v119
	s_and_b64 vcc, vcc, s[48:49]
	s_waitcnt lgkmcnt(0)
	v_mfma_f32_32x32x16_bf16 v[2:17], v[2:5], v[76:79], 0
	v_mfma_f32_32x32x16_bf16 v[2:17], v[18:21], v[68:71], v[2:17]
	v_add_u32_e32 v18, v188, v182
	ds_read_b128 v[18:21], v18
	s_waitcnt lgkmcnt(0)
	v_mfma_f32_32x32x16_bf16 v[2:17], v[18:21], v[72:75], v[2:17]
	v_add_u32_e32 v18, v188, v183
	ds_read_b128 v[18:21], v18
	s_waitcnt lgkmcnt(0)
	v_mfma_f32_32x32x16_bf16 v[2:17], v[18:21], v[80:83], v[2:17]
	ds_read_b128 v[18:21], v186 offset:49152
	ds_read_b128 v[22:25], v186 offset:49184
	s_waitcnt lgkmcnt(0)
	s_nop 8
	v_fma_f32 v2, v148, v18, v2
	v_fma_f32 v3, v149, v19, v3
	s_nop 0
	v_cndmask_b32_e32 v18, v240, v2, vcc
	v_or_b32_e32 v2, 1, v31
	v_cmp_lt_i32_e32 vcc, v31, v144
	v_cmp_ge_i32_e64 s[48:49], v2, v119
	s_and_b64 vcc, vcc, s[48:49]
	v_or_b32_e32 v2, 2, v31
	v_cndmask_b32_e32 v19, v240, v3, vcc
	v_cmp_le_i32_e32 vcc, v2, v144
	v_cmp_ge_i32_e64 s[48:49], v2, v119
	v_fma_f32 v4, v148, v20, v4
	v_fma_f32 v5, v149, v21, v5
	s_and_b64 vcc, vcc, s[48:49]
	v_or_b32_e32 v2, 3, v31
	v_cndmask_b32_e32 v20, v240, v4, vcc
	v_cmp_le_i32_e32 vcc, v2, v144
	v_cmp_ge_i32_e64 s[48:49], v2, v119
	s_and_b64 vcc, vcc, s[48:49]
	v_fma_f32 v2, v148, v22, v6
	v_fma_f32 v3, v149, v23, v7
	v_or_b32_e32 v6, 8, v31
	v_cndmask_b32_e32 v21, v240, v5, vcc
	v_cmp_le_i32_e32 vcc, v6, v144
	v_cmp_ge_i32_e64 s[48:49], v6, v119
	s_and_b64 vcc, vcc, s[48:49]
	v_fma_f32 v4, v148, v24, v8
	v_fma_f32 v5, v149, v25, v9
	v_cndmask_b32_e32 v24, v240, v2, vcc
	v_or_b32_e32 v2, 9, v31
	v_cmp_le_i32_e32 vcc, v2, v144
	v_cmp_ge_i32_e64 s[48:49], v2, v119
	s_and_b64 vcc, vcc, s[48:49]
	v_or_b32_e32 v2, 10, v31
	v_cndmask_b32_e32 v25, v240, v3, vcc
	v_cmp_le_i32_e32 vcc, v2, v144
	v_cmp_ge_i32_e64 s[48:49], v2, v119
	s_and_b64 vcc, vcc, s[48:49]
	v_or_b32_e32 v2, 11, v31
	v_cndmask_b32_e32 v22, v240, v4, vcc
	v_cmp_le_i32_e32 vcc, v2, v144
	v_cmp_ge_i32_e64 s[48:49], v2, v119
	s_and_b64 vcc, vcc, s[48:49]
	v_cndmask_b32_e32 v23, v240, v5, vcc
	ds_read_b128 v[2:5], v186 offset:49216
	v_or_b32_e32 v6, 16, v31
	v_cmp_le_i32_e32 vcc, v6, v144
	v_cmp_ge_i32_e64 s[48:49], v6, v119
	s_and_b64 vcc, vcc, s[48:49]
	s_waitcnt lgkmcnt(0)
	v_fma_f32 v2, v148, v2, v10
	v_fma_f32 v3, v149, v3, v11
	v_fma_f32 v4, v148, v4, v12
	v_fma_f32 v5, v149, v5, v13
	v_cndmask_b32_e32 v28, v240, v2, vcc
	v_or_b32_e32 v2, 17, v31
	v_cmp_le_i32_e32 vcc, v2, v144
	v_cmp_ge_i32_e64 s[48:49], v2, v119
	s_and_b64 vcc, vcc, s[48:49]
	v_or_b32_e32 v2, 18, v31
	v_cndmask_b32_e32 v29, v240, v3, vcc
	v_cmp_le_i32_e32 vcc, v2, v144
	v_cmp_ge_i32_e64 s[48:49], v2, v119
	s_and_b64 vcc, vcc, s[48:49]
	v_or_b32_e32 v2, 19, v31
	v_cndmask_b32_e32 v26, v240, v4, vcc
	v_cmp_le_i32_e32 vcc, v2, v144
	v_cmp_ge_i32_e64 s[48:49], v2, v119
	s_and_b64 vcc, vcc, s[48:49]
	v_cndmask_b32_e32 v27, v240, v5, vcc
	ds_read_b128 v[2:5], v186 offset:49248
	v_or_b32_e32 v6, 24, v31
	v_cmp_le_i32_e32 vcc, v6, v144
	v_cmp_ge_i32_e64 s[48:49], v6, v119
	s_and_b64 vcc, vcc, s[48:49]
	s_waitcnt lgkmcnt(0)
	v_fma_f32 v2, v148, v2, v14
	v_fma_f32 v3, v149, v3, v15
	v_fma_f32 v4, v148, v4, v16
	v_fma_f32 v5, v149, v5, v17
	v_cndmask_b32_e32 v32, v240, v2, vcc
	v_or_b32_e32 v2, 25, v31
	v_cmp_le_i32_e32 vcc, v2, v144
	v_cmp_ge_i32_e64 s[48:49], v2, v119
	s_and_b64 vcc, vcc, s[48:49]
	v_or_b32_e32 v2, 26, v31
	v_cndmask_b32_e32 v33, v240, v3, vcc
	v_cmp_le_i32_e32 vcc, v2, v144
	v_cmp_ge_i32_e64 s[48:49], v2, v119
	s_and_b64 vcc, vcc, s[48:49]
	v_or_b32_e32 v2, 27, v31
	v_cndmask_b32_e32 v30, v240, v4, vcc
	v_cmp_le_i32_e32 vcc, v2, v144
	v_cmp_ge_i32_e64 s[48:49], v2, v119
	v_max_f32_e32 v2, v18, v19
	v_max3_f32 v2, v2, v20, v21
	v_max3_f32 v2, v2, v24, v25
	v_max3_f32 v2, v2, v22, v23
	v_max3_f32 v2, v2, v28, v29
	s_and_b64 vcc, vcc, s[48:49]
	v_max3_f32 v2, v2, v26, v27
	v_cndmask_b32_e32 v31, v240, v5, vcc
	v_max3_f32 v2, v2, v32, v33
	v_max3_f32 v2, v2, v30, v31
	v_mov_b32_e32 v3, v2
	s_nop 1
	v_permlane32_swap_b32_e32 v2, v3
	v_max_f32_e32 v3, v3, v3
	v_max_f32_e32 v2, v2, v2
	v_max_f32_e32 v2, v2, v3
	v_add_f32_e32 v3, 0x7149f2ca, v2
	v_cmp_lt_f32_e32 vcc, s9, v3
	s_cbranch_vccz .LBB0_659
	v_max_f32_e32 v2, v2, v2
	v_max_f32_e32 v122, 0xf149f2ca, v2
	v_sub_f32_e32 v2, 0xf149f2ca, v122
	v_exp_f32_e32 v2, v2
	s_nop 0
	v_mul_f32_e32 v2, 0, v2
	s_branch .LBB0_660

; __device__ __forceinline__ unsigned cvt_pk_bf16(float lo, float hi) { f32x2_t v = {lo, hi}; bf16x2_t b = __builtin_convertvector(v, bf16x2_t); return __builtin_bit_cast(unsigned, b); }
; __device__ __forceinline__ float fast_exp2(float x) { return __builtin_amdgcn_exp2f(x); }
; template <bool MASK> ...
;     ...
;     { const f32x2_t m2 = {m, m}; f32x2_t ps2 = {0.f, 0.f};
; #pragma unroll
;       for (int i = 0; i < 8; ++i) { f32x2_t t = sp[i] - m2; t[0] = fast_exp2(t[0]); t[1] = fast_exp2(t[1]); sp[i] = t; ps2 = ps2 + t; }
;       l += ps2[0] + ps2[1]; }
;     u32x4 pw0, pw1;
;     pw0.x = cvt_pk_bf16(sp[0][0], sp[0][1]); pw0.y = cvt_pk_bf16(sp[1][0], sp[1][1]); pw0.z = cvt_pk_bf16(sp[2][0], sp[2][1]); pw0.w = cvt_pk_bf16(sp[3][0], sp[3][1]);
;     pw1.x = cvt_pk_bf16(sp[4][0], sp[4][1]); pw1.y = cvt_pk_bf16(sp[5][0], sp[5][1]); pw1.z = cvt_pk_bf16(sp[6][0], sp[6][1]); pw1.w = cvt_pk_bf16(sp[7][0], sp[7][1]);
;     asm volatile("s_waitcnt lgkmcnt(0)" : "+v"(l00), "+v"(h00), "+v"(l01), "+v"(h01), "+v"(l10), "+v"(h10), "+v"(l11), "+v"(h11) :: "memory");
;     { const bf16x8 pb0 = __builtin_bit_cast(bf16x8, pw0), pb1 = __builtin_bit_cast(bf16x8, pw1);
;       const bf16x8 v00 = {l00[0], l00[1], l00[2], l00[3], h00[0], h00[1], h00[2], h00[3]}, v01 = {l01[0], l01[1], l01[2], l01[3], h01[0], h01[1], h01[2], h01[3]};
;       const bf16x8 v10 = {l10[0], l10[1], l10[2], l10[3], h10[0], h10[1], h10[2], h10[3]}, v11 = {l11[0], l11[1], l11[2], l11[3], h11[0], h11[1], h11[2], h11[3]};
;       o0 = __builtin_amdgcn_mfma_f32_32x32x16_bf16(v00, pb0, o0, 0, 0, 0); o1 = __builtin_amdgcn_mfma_f32_32x32x16_bf16(v01, pb0, o1, 0, 0, 0);
;       o0 = __builtin_amdgcn_mfma_f32_32x32x16_bf16(v10, pb1, o0, 0, 0, 0); o1 = __builtin_amdgcn_mfma_f32_32x32x16_bf16(v11, pb1, o1, 0, 0, 0); }
.LBB0_654:
	v_sub_f32_e32 v28, v28, v122
	v_sub_f32_e32 v29, v29, v122
	v_sub_f32_e32 v26, v26, v122
	v_sub_f32_e32 v27, v27, v122
	v_exp_f32_e32 v28, v28
	v_exp_f32_e32 v29, v29
	v_exp_f32_e32 v26, v26
	v_exp_f32_e32 v27, v27
	v_sub_f32_e32 v22, v22, v122
	v_sub_f32_e32 v23, v23, v122
	v_sub_f32_e32 v18, v18, v122
	v_sub_f32_e32 v19, v19, v122
	v_exp_f32_e32 v22, v22
	v_exp_f32_e32 v23, v23
	v_exp_f32_e32 v18, v18
	v_exp_f32_e32 v19, v19
	v_sub_f32_e32 v24, v24, v122
	v_sub_f32_e32 v25, v25, v122
	v_add_f32_e32 v34, 0, v28
	v_add_f32_e32 v35, 0, v29
	v_exp_f32_e32 v24, v24
	v_exp_f32_e32 v25, v25
	v_sub_f32_e32 v20, v20, v122
	v_sub_f32_e32 v21, v21, v122
	v_add_f32_e32 v34, v26, v34
	v_add_f32_e32 v35, v27, v35
	v_exp_f32_e32 v20, v20
	v_exp_f32_e32 v21, v21
	v_sub_f32_e32 v32, v32, v122
	v_sub_f32_e32 v33, v33, v122
	v_add_f32_e32 v34, v22, v34
	v_add_f32_e32 v35, v23, v35
	v_exp_f32_e32 v32, v32
	v_exp_f32_e32 v33, v33
	v_sub_f32_e32 v30, v30, v122
	v_sub_f32_e32 v31, v31, v122
	v_add_f32_e32 v34, v18, v34
	v_add_f32_e32 v35, v19, v35
	v_exp_f32_e32 v30, v30
	v_exp_f32_e32 v31, v31
	v_add_f32_e32 v34, v24, v34
	v_add_f32_e32 v35, v25, v35
	v_mov_b32_e32 v3, v2
	v_add_f32_e32 v34, v20, v34
	v_add_f32_e32 v35, v21, v35
	v_mov_b32_e32 v4, v2
	v_add_f32_e32 v34, v32, v34
	v_add_f32_e32 v35, v33, v35
	v_mov_b32_e32 v5, v2
	v_add_f32_e32 v34, v30, v34
	v_add_f32_e32 v35, v31, v35
	v_mov_b32_e32 v6, v2
	v_mov_b32_e32 v7, v2
	v_mov_b32_e32 v8, v2
	v_mov_b32_e32 v9, v2
	v_mov_b32_e32 v10, v2
	v_mov_b32_e32 v11, v2
	v_mov_b32_e32 v12, v2
	v_mov_b32_e32 v13, v2
	v_mov_b32_e32 v14, v2
	v_mov_b32_e32 v15, v2
	v_mov_b32_e32 v16, v2
	v_mov_b32_e32 v17, v2
	v_add_f32_e32 v34, v34, v35
	v_cvt_pk_bf16_f32 v52, v28, v29
	v_cvt_pk_bf16_f32 v53, v26, v27
	v_cvt_pk_bf16_f32 v54, v22, v23
	v_cvt_pk_bf16_f32 v55, v18, v19
	v_add_f32_e32 v34, v2, v34
	v_cvt_pk_bf16_f32 v56, v24, v25
	v_cvt_pk_bf16_f32 v57, v20, v21
	v_cvt_pk_bf16_f32 v58, v32, v33
	v_cvt_pk_bf16_f32 v59, v30, v31
	s_waitcnt lgkmcnt(0)
	s_nop 0
	v_mfma_f32_32x32x16_bf16 v[18:33], v[48:51], v[52:55], v[2:17]
	v_mfma_f32_32x32x16_bf16 v[2:17], v[44:47], v[52:55], v[2:17]
	v_mfma_f32_32x32x16_bf16 v[18:33], v[40:43], v[56:59], v[18:33]
	v_mfma_f32_32x32x16_bf16 v[2:17], v[36:39], v[56:59], v[2:17]

; #define LAS __attribute__((address_space(3)))
; template <bool MASK> ...
;     s16x4 l00, h00, l01, h01, l10, h10, l11, h11; { const unsigned a0 = va0 + sub * 4096, a1 = va1 + sub * 4096;
;       asm volatile("ds_read_b64_tr_b16 %0, %1" : "=&v"(l00) : "v"(a0) : "memory"); asm volatile("ds_read_b64_tr_b16 %0, %1 offset:1024" : "=&v"(h00) : "v"(a0) : "memory");
;       asm volatile("ds_read_b64_tr_b16 %0, %1" : "=&v"(l01) : "v"(a1) : "memory"); asm volatile("ds_read_b64_tr_b16 %0, %1 offset:1024" : "=&v"(h01) : "v"(a1) : "memory");
;       asm volatile("ds_read_b64_tr_b16 %0, %1 offset:2048" : "=&v"(l10) : "v"(a0) : "memory"); asm volatile("ds_read_b64_tr_b16 %0, %1 offset:3072" : "=&v"(h10) : "v"(a0) : "memory");
;       asm volatile("ds_read_b64_tr_b16 %0, %1 offset:2048" : "=&v"(l11) : "v"(a1) : "memory"); asm volatile("ds_read_b64_tr_b16 %0, %1 offset:3072" : "=&v"(h11) : "v"(a1) : "memory"); }
;     const int r = lane & 31, hh = lane >> 5;
;     f32x16 st = {0.f, 0.f, 0.f, 0.f, 0.f, 0.f, 0.f, 0.f, 0.f, 0.f, 0.f, 0.f, 0.f, 0.f, 0.f, 0.f};
;     { const int key = sub * 32 + r; const LAS char* kp = Kt + key * 128; const int ksw = (key >> 1) & 7;
; #pragma unroll
;       for (int d0 = 0; d0 < 4; ++d0) { const bf16x8 kf = *(const LAS bf16x8*)(kp + (((2 * d0 + hh) ^ ksw) << 4)); st = __builtin_amdgcn_mfma_f32_32x32x16_bf16(kf, qr[d0], st, 0, 0, 0); } }
;     f32x2_t sp[8]; const f32x2_t cs2 = {cscale, cscale};
; #pragma unroll
;     for (int g = 0; g < 4; ++g) { const f32x4 c4 = *(const LAS f32x4*)(cb + sub * 32 + 8 * g + 4 * hh);
;         sp[2 * g] = (f32x2_t){st[4 * g], st[4 * g + 1]} + cs2 * (f32x2_t){c4[0], c4[1]};
;         sp[2 * g + 1] = (f32x2_t){st[4 * g + 2], st[4 * g + 3]} + cs2 * (f32x2_t){c4[2], c4[3]};
;         if (MASK) {
; #pragma unroll
;             for (int e = 0; e < 4; ++e) { const int kpos = kpos_sub + 8 * g + 4 * hh + e; const bool ok = (kpos <= qpos && kpos >= qpos - win);
;                 sp[2 * g + (e >> 1)][e & 1] = ok ? sp[2 * g + (e >> 1)][e & 1] : -INFINITY; } } }
;     float rm = fmaxf(sp[0][0], sp[0][1]);
; #pragma unroll
;     for (int i = 1; i < 8; ++i) rm = fmaxf(fmaxf(rm, sp[i][0]), sp[i][1]);
;     rm = swap_max(rm);
;     if (__any(rm - m > 8.0f)) { const float mnew = fmaxf(m, rm); const float f = fast_exp2(m - mnew); l *= f; o0 = o0 * f; o1 = o1 * f; m = mnew; }
.LBB0_656:
	s_cmp_lt_i32 s3, 2
	s_mov_b64 s[18:19], -1
	s_cbranch_scc1 .LBB0_663
	ds_read_b64_tr_b16 v[96:97], v189
	ds_read_b64_tr_b16 v[98:99], v189 offset:1024
	ds_read_b64_tr_b16 v[92:93], v190
	ds_read_b64_tr_b16 v[94:95], v190 offset:1024
	ds_read_b64_tr_b16 v[88:89], v189 offset:2048
	ds_read_b64_tr_b16 v[90:91], v189 offset:3072
	ds_read_b64_tr_b16 v[84:85], v190 offset:2048
	ds_read_b64_tr_b16 v[86:87], v190 offset:3072
	v_add_u32_e32 v35, v188, v180
	ds_read_b128 v[36:39], v35 offset:4096
	v_add_u32_e32 v35, v188, v181
	ds_read_b128 v[52:55], v35 offset:4096
	v_add_u32_e32 v35, v188, v182
	s_waitcnt lgkmcnt(0)
	v_mfma_f32_32x32x16_bf16 v[36:51], v[36:39], v[76:79], 0
	v_mfma_f32_32x32x16_bf16 v[36:51], v[52:55], v[68:71], v[36:51]
	ds_read_b128 v[52:55], v35 offset:4096
	v_add_u32_e32 v35, v188, v183
	s_waitcnt lgkmcnt(0)
	v_mfma_f32_32x32x16_bf16 v[36:51], v[52:55], v[72:75], v[36:51]
	ds_read_b128 v[52:55], v35 offset:4096
	s_waitcnt lgkmcnt(0)
	v_mfma_f32_32x32x16_bf16 v[36:51], v[52:55], v[80:83], v[36:51]
	ds_read_b128 v[52:55], v186 offset:49280
	ds_read_b128 v[56:59], v186 offset:49312
	s_waitcnt lgkmcnt(0)
	s_nop 8
	v_fma_f32 v164, v148, v52, v36
	v_fma_f32 v165, v149, v53, v37
	v_fma_f32 v162, v148, v54, v38
	v_fma_f32 v163, v149, v55, v39
	ds_read_b128 v[36:39], v186 offset:49344
	v_max_f32_e32 v35, v164, v165
	v_fma_f32 v156, v148, v56, v40
	v_fma_f32 v157, v149, v57, v41
	v_max3_f32 v35, v35, v162, v163
	v_fma_f32 v154, v148, v58, v42
	v_fma_f32 v155, v149, v59, v43
	s_waitcnt lgkmcnt(0)
	v_fma_f32 v160, v148, v36, v44
	v_fma_f32 v161, v149, v37, v45
	v_fma_f32 v158, v148, v38, v46
	v_fma_f32 v159, v149, v39, v47
	ds_read_b128 v[36:39], v186 offset:49376
	v_max3_f32 v35, v35, v156, v157
	v_max3_f32 v35, v35, v154, v155
	v_max3_f32 v35, v35, v160, v161
	v_max3_f32 v35, v35, v158, v159
	s_waitcnt lgkmcnt(0)
	v_fma_f32 v166, v148, v36, v48
	v_fma_f32 v167, v149, v37, v49
	v_fma_f32 v168, v148, v38, v50
	v_fma_f32 v169, v149, v39, v51
	v_max3_f32 v35, v35, v166, v167
	v_max3_f32 v35, v35, v168, v169
	v_mov_b32_e32 v36, v35
	s_nop 1
	v_permlane32_swap_b32_e32 v35, v36
	v_max_f32_e32 v36, v36, v36
	v_max_f32_e32 v35, v35, v35
	v_max_f32_e32 v35, v35, v36
	v_sub_f32_e32 v36, v35, v122
	v_cmp_lt_f32_e32 vcc, s9, v36
	s_cbranch_vccz .LBB0_661
	v_max_f32_e32 v35, v35, v35
	v_max_f32_e32 v36, v122, v122
	v_max_f32_e32 v197, v36, v35
	v_sub_f32_e32 v35, v122, v197
	v_exp_f32_e32 v52, v35
	v_mov_b32_e32 v170, v197
	v_mul_f32_e32 v35, v34, v52
	v_mul_f32_e32 v50, v32, v52
	v_mul_f32_e32 v51, v33, v52
	v_mul_f32_e32 v48, v30, v52
	v_mul_f32_e32 v49, v31, v52
	v_mul_f32_e32 v46, v28, v52
	v_mul_f32_e32 v47, v29, v52
	v_mul_f32_e32 v44, v26, v52
	v_mul_f32_e32 v45, v27, v52
	v_mul_f32_e32 v42, v24, v52
	v_mul_f32_e32 v43, v25, v52
	v_mul_f32_e32 v40, v22, v52
	v_mul_f32_e32 v41, v23, v52
	v_mul_f32_e32 v38, v20, v52
	v_mul_f32_e32 v39, v21, v52
	v_mul_f32_e32 v36, v18, v52
	v_mul_f32_e32 v37, v19, v52
	v_mul_f32_e32 v66, v16, v52
	v_mul_f32_e32 v67, v17, v52
	v_mul_f32_e32 v64, v14, v52
	v_mul_f32_e32 v65, v15, v52
	v_mul_f32_e32 v62, v12, v52
	v_mul_f32_e32 v63, v13, v52
	v_mul_f32_e32 v60, v10, v52
	v_mul_f32_e32 v61, v11, v52
	v_mul_f32_e32 v58, v8, v52
	v_mul_f32_e32 v59, v9, v52
	v_mul_f32_e32 v56, v6, v52
	v_mul_f32_e32 v57, v7, v52
	v_mul_f32_e32 v54, v4, v52
	v_mul_f32_e32 v55, v5, v52
	v_mul_f32_e32 v53, v3, v52
	v_mul_f32_e32 v52, v2, v52
	s_branch .LBB0_662

; __device__ __forceinline__ unsigned cvt_pk_bf16(float lo, float hi) { f32x2_t v = {lo, hi}; bf16x2_t b = __builtin_convertvector(v, bf16x2_t); return __builtin_bit_cast(unsigned, b); }
; __device__ __forceinline__ float fast_exp2(float x) { return __builtin_amdgcn_exp2f(x); }
; template <bool MASK> ...
;     ...
;     { const f32x2_t m2 = {m, m}; f32x2_t ps2 = {0.f, 0.f};
; #pragma unroll
;       for (int i = 0; i < 8; ++i) { f32x2_t t = sp[i] - m2; t[0] = fast_exp2(t[0]); t[1] = fast_exp2(t[1]); sp[i] = t; ps2 = ps2 + t; }
;       l += ps2[0] + ps2[1]; }
;     u32x4 pw0, pw1;
;     pw0.x = cvt_pk_bf16(sp[0][0], sp[0][1]); pw0.y = cvt_pk_bf16(sp[1][0], sp[1][1]); pw0.z = cvt_pk_bf16(sp[2][0], sp[2][1]); pw0.w = cvt_pk_bf16(sp[3][0], sp[3][1]);
;     pw1.x = cvt_pk_bf16(sp[4][0], sp[4][1]); pw1.y = cvt_pk_bf16(sp[5][0], sp[5][1]); pw1.z = cvt_pk_bf16(sp[6][0], sp[6][1]); pw1.w = cvt_pk_bf16(sp[7][0], sp[7][1]);
;     asm volatile("s_waitcnt lgkmcnt(0)" : "+v"(l00), "+v"(h00), "+v"(l01), "+v"(h01), "+v"(l10), "+v"(h10), "+v"(l11), "+v"(h11) :: "memory");
;     { const bf16x8 pb0 = __builtin_bit_cast(bf16x8, pw0), pb1 = __builtin_bit_cast(bf16x8, pw1);
;       const bf16x8 v00 = {l00[0], l00[1], l00[2], l00[3], h00[0], h00[1], h00[2], h00[3]}, v01 = {l01[0], l01[1], l01[2], l01[3], h01[0], h01[1], h01[2], h01[3]};
;       const bf16x8 v10 = {l10[0], l10[1], l10[2], l10[3], h10[0], h10[1], h10[2], h10[3]}, v11 = {l11[0], l11[1], l11[2], l11[3], h11[0], h11[1], h11[2], h11[3]};
;       o0 = __builtin_amdgcn_mfma_f32_32x32x16_bf16(v00, pb0, o0, 0, 0, 0); o1 = __builtin_amdgcn_mfma_f32_32x32x16_bf16(v01, pb0, o1, 0, 0, 0);
;       o0 = __builtin_amdgcn_mfma_f32_32x32x16_bf16(v10, pb1, o0, 0, 0, 0); o1 = __builtin_amdgcn_mfma_f32_32x32x16_bf16(v11, pb1, o1, 0, 0, 0); }
.LBB0_660:
	v_sub_f32_e32 v18, v18, v122
	v_sub_f32_e32 v19, v19, v122
	v_sub_f32_e32 v20, v20, v122
	v_sub_f32_e32 v21, v21, v122
	v_exp_f32_e32 v18, v18
	v_exp_f32_e32 v19, v19
	v_exp_f32_e32 v20, v20
	v_exp_f32_e32 v21, v21
	v_sub_f32_e32 v24, v24, v122
	v_sub_f32_e32 v25, v25, v122
	v_sub_f32_e32 v22, v22, v122
	v_sub_f32_e32 v23, v23, v122
	v_exp_f32_e32 v24, v24
	v_exp_f32_e32 v25, v25
	v_exp_f32_e32 v22, v22
	v_exp_f32_e32 v23, v23
	v_sub_f32_e32 v28, v28, v122
	v_sub_f32_e32 v29, v29, v122
	v_add_f32_e32 v34, 0, v18
	v_add_f32_e32 v35, 0, v19
	v_exp_f32_e32 v28, v28
	v_exp_f32_e32 v29, v29
	v_sub_f32_e32 v26, v26, v122
	v_sub_f32_e32 v27, v27, v122
	v_add_f32_e32 v34, v20, v34
	v_add_f32_e32 v35, v21, v35
	v_exp_f32_e32 v26, v26
	v_exp_f32_e32 v27, v27
	v_sub_f32_e32 v32, v32, v122
	v_sub_f32_e32 v33, v33, v122
	v_add_f32_e32 v34, v24, v34
	v_add_f32_e32 v35, v25, v35
	v_exp_f32_e32 v32, v32
	v_exp_f32_e32 v33, v33
	v_sub_f32_e32 v30, v30, v122
	v_sub_f32_e32 v31, v31, v122
	v_add_f32_e32 v34, v22, v34
	v_add_f32_e32 v35, v23, v35
	v_exp_f32_e32 v30, v30
	v_exp_f32_e32 v31, v31
	v_add_f32_e32 v34, v28, v34
	v_add_f32_e32 v35, v29, v35
	v_mov_b32_e32 v3, v2
	v_add_f32_e32 v34, v26, v34
	v_add_f32_e32 v35, v27, v35
	v_mov_b32_e32 v4, v2
	v_add_f32_e32 v34, v32, v34
	v_add_f32_e32 v35, v33, v35
	v_mov_b32_e32 v5, v2
	v_add_f32_e32 v34, v30, v34
	v_add_f32_e32 v35, v31, v35
	v_mov_b32_e32 v6, v2
	v_mov_b32_e32 v7, v2
	v_mov_b32_e32 v8, v2
	v_mov_b32_e32 v9, v2
	v_mov_b32_e32 v10, v2
	v_mov_b32_e32 v11, v2
	v_mov_b32_e32 v12, v2
	v_mov_b32_e32 v13, v2
	v_mov_b32_e32 v14, v2
	v_mov_b32_e32 v15, v2
	v_mov_b32_e32 v16, v2
	v_mov_b32_e32 v17, v2
	v_add_f32_e32 v34, v34, v35
	v_cvt_pk_bf16_f32 v52, v18, v19
	v_cvt_pk_bf16_f32 v53, v20, v21
	v_cvt_pk_bf16_f32 v54, v24, v25
	v_cvt_pk_bf16_f32 v55, v22, v23
	v_add_f32_e32 v34, v2, v34
	v_cvt_pk_bf16_f32 v56, v28, v29
	v_cvt_pk_bf16_f32 v57, v26, v27
	v_cvt_pk_bf16_f32 v58, v32, v33
	v_cvt_pk_bf16_f32 v59, v30, v31
	s_waitcnt lgkmcnt(0)
	s_nop 0
	v_mfma_f32_32x32x16_bf16 v[18:33], v[48:51], v[52:55], v[2:17]
	v_mfma_f32_32x32x16_bf16 v[2:17], v[44:47], v[52:55], v[2:17]
	v_mfma_f32_32x32x16_bf16 v[18:33], v[40:43], v[56:59], v[18:33]
	v_mfma_f32_32x32x16_bf16 v[2:17], v[36:39], v[56:59], v[2:17]
	s_or_b32 s11, s24, 32
	s_cmp_gt_i32 s11, s36
	s_cbranch_scc1 .LBB0_669
	s_branch .LBB0_656

; __device__ __forceinline__ unsigned cvt_pk_bf16(float lo, float hi) { f32x2_t v = {lo, hi}; bf16x2_t b = __builtin_convertvector(v, bf16x2_t); return __builtin_bit_cast(unsigned, b); }
; __device__ __forceinline__ float fast_exp2(float x) { return __builtin_amdgcn_exp2f(x); }
; template <bool MASK> ...
;     ...
;     { const f32x2_t m2 = {m, m}; f32x2_t ps2 = {0.f, 0.f};
; #pragma unroll
;       for (int i = 0; i < 8; ++i) { f32x2_t t = sp[i] - m2; t[0] = fast_exp2(t[0]); t[1] = fast_exp2(t[1]); sp[i] = t; ps2 = ps2 + t; }
;       l += ps2[0] + ps2[1]; }
;     u32x4 pw0, pw1;
;     pw0.x = cvt_pk_bf16(sp[0][0], sp[0][1]); pw0.y = cvt_pk_bf16(sp[1][0], sp[1][1]); pw0.z = cvt_pk_bf16(sp[2][0], sp[2][1]); pw0.w = cvt_pk_bf16(sp[3][0], sp[3][1]);
;     pw1.x = cvt_pk_bf16(sp[4][0], sp[4][1]); pw1.y = cvt_pk_bf16(sp[5][0], sp[5][1]); pw1.z = cvt_pk_bf16(sp[6][0], sp[6][1]); pw1.w = cvt_pk_bf16(sp[7][0], sp[7][1]);
;     asm volatile("s_waitcnt lgkmcnt(0)" : "+v"(l00), "+v"(h00), "+v"(l01), "+v"(h01), "+v"(l10), "+v"(h10), "+v"(l11), "+v"(h11) :: "memory");
;     { const bf16x8 pb0 = __builtin_bit_cast(bf16x8, pw0), pb1 = __builtin_bit_cast(bf16x8, pw1);
;       const bf16x8 v00 = {l00[0], l00[1], l00[2], l00[3], h00[0], h00[1], h00[2], h00[3]}, v01 = {l01[0], l01[1], l01[2], l01[3], h01[0], h01[1], h01[2], h01[3]};
;       const bf16x8 v10 = {l10[0], l10[1], l10[2], l10[3], h10[0], h10[1], h10[2], h10[3]}, v11 = {l11[0], l11[1], l11[2], l11[3], h11[0], h11[1], h11[2], h11[3]};
;       o0 = __builtin_amdgcn_mfma_f32_32x32x16_bf16(v00, pb0, o0, 0, 0, 0); o1 = __builtin_amdgcn_mfma_f32_32x32x16_bf16(v01, pb0, o1, 0, 0, 0);
;       o0 = __builtin_amdgcn_mfma_f32_32x32x16_bf16(v10, pb1, o0, 0, 0, 0); o1 = __builtin_amdgcn_mfma_f32_32x32x16_bf16(v11, pb1, o1, 0, 0, 0); }
.LBB0_662:
	v_sub_f32_e32 v164, v164, v170
	v_sub_f32_e32 v165, v165, v170
	v_sub_f32_e32 v162, v162, v170
	v_sub_f32_e32 v163, v163, v170
	v_exp_f32_e32 v164, v164
	v_exp_f32_e32 v165, v165
	v_exp_f32_e32 v162, v162
	v_exp_f32_e32 v163, v163
	v_sub_f32_e32 v156, v156, v170
	v_sub_f32_e32 v157, v157, v170
	v_sub_f32_e32 v154, v154, v170
	v_sub_f32_e32 v155, v155, v170
	v_exp_f32_e32 v156, v156
	v_exp_f32_e32 v157, v157
	v_exp_f32_e32 v200, v154
	v_exp_f32_e32 v201, v155
	v_add_f32_e32 v198, 0, v164
	v_add_f32_e32 v199, 0, v165
	v_sub_f32_e32 v160, v160, v170
	v_sub_f32_e32 v161, v161, v170
	v_add_f32_e32 v198, v162, v198
	v_add_f32_e32 v199, v163, v199
	v_exp_f32_e32 v160, v160
	v_add_f32_e32 v198, v156, v198
	v_add_f32_e32 v199, v157, v199
	v_exp_f32_e32 v161, v161
	v_sub_f32_e32 v158, v158, v170
	v_sub_f32_e32 v159, v159, v170
	v_add_f32_e32 v154, v200, v198
	v_add_f32_e32 v155, v201, v199
	v_exp_f32_e32 v198, v158
	v_exp_f32_e32 v199, v159
	v_sub_f32_e32 v158, v166, v170
	v_sub_f32_e32 v159, v167, v170
	v_add_f32_e32 v154, v160, v154
	v_add_f32_e32 v155, v161, v155
	v_exp_f32_e32 v166, v158
	v_exp_f32_e32 v167, v159
	v_sub_f32_e32 v158, v168, v170
	v_sub_f32_e32 v159, v169, v170
	v_add_f32_e32 v154, v198, v154
	v_add_f32_e32 v155, v199, v155
	v_exp_f32_e32 v168, v158
	v_exp_f32_e32 v169, v159
	v_add_f32_e32 v154, v166, v154
	v_add_f32_e32 v155, v167, v155
	v_cvt_pk_bf16_f32 v156, v156, v157
	v_cvt_pk_bf16_f32 v157, v200, v201
	v_add_f32_e32 v154, v168, v154
	v_add_f32_e32 v155, v169, v155
	s_waitcnt lgkmcnt(0)
	v_cvt_pk_bf16_f32 v158, v160, v161
	v_add_f32_e32 v154, v154, v155
	v_add_f32_e32 v35, v35, v154
	v_cvt_pk_bf16_f32 v154, v164, v165
	v_cvt_pk_bf16_f32 v155, v162, v163
	v_cvt_pk_bf16_f32 v159, v198, v199
	v_cvt_pk_bf16_f32 v160, v166, v167
	v_mfma_f32_32x32x16_bf16 v[36:51], v[96:99], v[154:157], v[36:51]
	v_cvt_pk_bf16_f32 v161, v168, v169
	s_mov_b64 s[18:19], 0
	v_mfma_f32_32x32x16_bf16 v[52:67], v[92:95], v[154:157], v[52:67]
	v_mfma_f32_32x32x16_bf16 v[36:51], v[88:91], v[158:161], v[36:51]
	v_mfma_f32_32x32x16_bf16 v[52:67], v[84:87], v[158:161], v[52:67]
; #define LAS __attribute__((address_space(3)))
; template <bool MASK> ...
;     s16x4 l00, h00, l01, h01, l10, h10, l11, h11; { const unsigned a0 = va0 + sub * 4096, a1 = va1 + sub * 4096;
;       asm volatile("ds_read_b64_tr_b16 %0, %1" : "=&v"(l00) : "v"(a0) : "memory"); asm volatile("ds_read_b64_tr_b16 %0, %1 offset:1024" : "=&v"(h00) : "v"(a0) : "memory");
;       asm volatile("ds_read_b64_tr_b16 %0, %1" : "=&v"(l01) : "v"(a1) : "memory"); asm volatile("ds_read_b64_tr_b16 %0, %1 offset:1024" : "=&v"(h01) : "v"(a1) : "memory");
;       asm volatile("ds_read_b64_tr_b16 %0, %1 offset:2048" : "=&v"(l10) : "v"(a0) : "memory"); asm volatile("ds_read_b64_tr_b16 %0, %1 offset:3072" : "=&v"(h10) : "v"(a0) : "memory");
;       asm volatile("ds_read_b64_tr_b16 %0, %1 offset:2048" : "=&v"(l11) : "v"(a1) : "memory"); asm volatile("ds_read_b64_tr_b16 %0, %1 offset:3072" : "=&v"(h11) : "v"(a1) : "memory"); }
;     const int r = lane & 31, hh = lane >> 5;
;     f32x16 st = {0.f, 0.f, 0.f, 0.f, 0.f, 0.f, 0.f, 0.f, 0.f, 0.f, 0.f, 0.f, 0.f, 0.f, 0.f, 0.f};
;     { const int key = sub * 32 + r; const LAS char* kp = Kt + key * 128; const int ksw = (key >> 1) & 7;
; #pragma unroll
;       for (int d0 = 0; d0 < 4; ++d0) { const bf16x8 kf = *(const LAS bf16x8*)(kp + (((2 * d0 + hh) ^ ksw) << 4)); st = __builtin_amdgcn_mfma_f32_32x32x16_bf16(kf, qr[d0], st, 0, 0, 0); } }
;     f32x2_t sp[8]; const f32x2_t cs2 = {cscale, cscale};
; #pragma unroll
;     for (int g = 0; g < 4; ++g) { const f32x4 c4 = *(const LAS f32x4*)(cb + sub * 32 + 8 * g + 4 * hh);
;         sp[2 * g] = (f32x2_t){st[4 * g], st[4 * g + 1]} + cs2 * (f32x2_t){c4[0], c4[1]};
;         sp[2 * g + 1] = (f32x2_t){st[4 * g + 2], st[4 * g + 3]} + cs2 * (f32x2_t){c4[2], c4[3]};
;         if (MASK) {
; #pragma unroll
;             for (int e = 0; e < 4; ++e) { const int kpos = kpos_sub + 8 * g + 4 * hh + e; const bool ok = (kpos <= qpos && kpos >= qpos - win);
;                 sp[2 * g + (e >> 1)][e & 1] = ok ? sp[2 * g + (e >> 1)][e & 1] : -INFINITY; } } }
;     float rm = fmaxf(sp[0][0], sp[0][1]);
; #pragma unroll
;     for (int i = 1; i < 8; ++i) rm = fmaxf(fmaxf(rm, sp[i][0]), sp[i][1]);
;     rm = swap_max(rm);
;     if (__any(rm - m > 8.0f)) { const float mnew = fmaxf(m, rm); const float f = fast_exp2(m - mnew); l *= f; o0 = o0 * f; o1 = o1 * f; m = mnew; }
.LBB0_663:
	s_and_b64 vcc, exec, s[18:19]
	s_cbranch_vccz .LBB0_668
	ds_read_b64_tr_b16 v[64:65], v189
	ds_read_b64_tr_b16 v[66:67], v189 offset:1024
	ds_read_b64_tr_b16 v[60:61], v190
	ds_read_b64_tr_b16 v[62:63], v190 offset:1024
	ds_read_b64_tr_b16 v[56:57], v189 offset:2048
	ds_read_b64_tr_b16 v[58:59], v189 offset:3072
	ds_read_b64_tr_b16 v[52:53], v190 offset:2048
	ds_read_b64_tr_b16 v[54:55], v190 offset:3072
	v_add_u32_e32 v35, v188, v180
	s_nop 7
	ds_read_b128 v[36:39], v35 offset:4096
	v_add_u32_e32 v35, v188, v181
	ds_read_b128 v[84:87], v35 offset:4096
	v_add_u32_e32 v35, v188, v182
	s_waitcnt lgkmcnt(0)
	v_mfma_f32_32x32x16_bf16 v[36:51], v[36:39], v[76:79], 0
	v_mfma_f32_32x32x16_bf16 v[36:51], v[84:87], v[68:71], v[36:51]
	ds_read_b128 v[84:87], v35 offset:4096
	v_add_u32_e32 v35, v188, v183
	s_waitcnt lgkmcnt(0)
	v_mfma_f32_32x32x16_bf16 v[36:51], v[84:87], v[72:75], v[36:51]
	ds_read_b128 v[84:87], v35 offset:4096
	v_or_b32_e32 v35, s11, v100
	v_cmp_le_i32_e32 vcc, v35, v144
	v_cmp_ge_i32_e64 s[48:49], v35, v119
	s_and_b64 vcc, vcc, s[48:49]
	s_waitcnt lgkmcnt(0)
	v_mfma_f32_32x32x16_bf16 v[36:51], v[84:87], v[80:83], v[36:51]
	ds_read_b128 v[84:87], v186 offset:49280
	ds_read_b128 v[88:91], v186 offset:49312
	s_waitcnt lgkmcnt(0)
	s_nop 8
	v_fma_f32 v36, v148, v84, v36
	v_fma_f32 v37, v149, v85, v37
	v_or_b32_e32 v84, 1, v35
	v_cndmask_b32_e32 v36, v240, v36, vcc
	v_cmp_lt_i32_e32 vcc, v35, v144
	v_cmp_ge_i32_e64 s[48:49], v84, v119
	s_and_b64 vcc, vcc, s[48:49]
	v_or_b32_e32 v84, 2, v35
	v_cndmask_b32_e32 v37, v240, v37, vcc
	v_cmp_le_i32_e32 vcc, v84, v144
	v_cmp_ge_i32_e64 s[48:49], v84, v119
	v_fma_f32 v38, v148, v86, v38
	v_fma_f32 v39, v149, v87, v39
	s_and_b64 vcc, vcc, s[48:49]
	v_or_b32_e32 v84, 3, v35
	v_cndmask_b32_e32 v38, v240, v38, vcc
	v_cmp_le_i32_e32 vcc, v84, v144
	v_cmp_ge_i32_e64 s[48:49], v84, v119
	s_and_b64 vcc, vcc, s[48:49]
	v_fma_f32 v84, v148, v90, v42
	v_fma_f32 v85, v149, v91, v43
	v_or_b32_e32 v42, 8, v35
	v_cndmask_b32_e32 v39, v240, v39, vcc
	v_cmp_le_i32_e32 vcc, v42, v144
	v_cmp_ge_i32_e64 s[48:49], v42, v119
	v_fma_f32 v40, v148, v88, v40
	v_fma_f32 v41, v149, v89, v41
	s_and_b64 vcc, vcc, s[48:49]
	v_cndmask_b32_e32 v42, v240, v40, vcc
	v_or_b32_e32 v40, 9, v35
	v_cmp_le_i32_e32 vcc, v40, v144
	v_cmp_ge_i32_e64 s[48:49], v40, v119
	s_and_b64 vcc, vcc, s[48:49]
	v_or_b32_e32 v40, 10, v35
	v_cndmask_b32_e32 v43, v240, v41, vcc
	v_cmp_le_i32_e32 vcc, v40, v144
	v_cmp_ge_i32_e64 s[48:49], v40, v119
	s_and_b64 vcc, vcc, s[48:49]
	v_or_b32_e32 v41, 11, v35
	v_cndmask_b32_e32 v40, v240, v84, vcc
	v_cmp_le_i32_e32 vcc, v41, v144
	v_cmp_ge_i32_e64 s[48:49], v41, v119
	s_and_b64 vcc, vcc, s[48:49]
	v_cndmask_b32_e32 v41, v240, v85, vcc
	ds_read_b128 v[84:87], v186 offset:49344
	s_waitcnt lgkmcnt(0)
	v_fma_f32 v44, v148, v84, v44
	v_fma_f32 v45, v149, v85, v45
	v_or_b32_e32 v84, 16, v35
	v_cmp_le_i32_e32 vcc, v84, v144
	v_cmp_ge_i32_e64 s[48:49], v84, v119
	s_and_b64 vcc, vcc, s[48:49]
	v_or_b32_e32 v84, 17, v35
	v_cndmask_b32_e32 v44, v240, v44, vcc
	v_cmp_le_i32_e32 vcc, v84, v144
	v_cmp_ge_i32_e64 s[48:49], v84, v119
	s_and_b64 vcc, vcc, s[48:49]
	v_or_b32_e32 v84, 18, v35
	v_cndmask_b32_e32 v45, v240, v45, vcc
	v_cmp_le_i32_e32 vcc, v84, v144
	v_cmp_ge_i32_e64 s[48:49], v84, v119
	v_fma_f32 v46, v148, v86, v46
	v_fma_f32 v47, v149, v87, v47
	s_and_b64 vcc, vcc, s[48:49]
	v_or_b32_e32 v84, 19, v35
	v_cndmask_b32_e32 v46, v240, v46, vcc
	v_cmp_le_i32_e32 vcc, v84, v144
	v_cmp_ge_i32_e64 s[48:49], v84, v119
	ds_read_b128 v[84:87], v186 offset:49376
	s_and_b64 vcc, vcc, s[48:49]
	v_cndmask_b32_e32 v47, v240, v47, vcc
	s_waitcnt lgkmcnt(0)
	v_fma_f32 v48, v148, v84, v48
	v_fma_f32 v49, v149, v85, v49
	v_or_b32_e32 v84, 24, v35
	v_cmp_le_i32_e32 vcc, v84, v144
	v_cmp_ge_i32_e64 s[48:49], v84, v119
	s_and_b64 vcc, vcc, s[48:49]
	v_or_b32_e32 v84, 25, v35
	v_cndmask_b32_e32 v48, v240, v48, vcc
	v_cmp_le_i32_e32 vcc, v84, v144
	v_cmp_ge_i32_e64 s[48:49], v84, v119
	s_and_b64 vcc, vcc, s[48:49]
	v_or_b32_e32 v84, 26, v35
	v_cndmask_b32_e32 v49, v240, v49, vcc
	v_cmp_le_i32_e32 vcc, v84, v144
	v_cmp_ge_i32_e64 s[48:49], v84, v119
	v_fma_f32 v50, v148, v86, v50
	v_fma_f32 v51, v149, v87, v51
	s_and_b64 vcc, vcc, s[48:49]
	v_or_b32_e32 v35, 27, v35
	v_cndmask_b32_e32 v50, v240, v50, vcc
	v_cmp_le_i32_e32 vcc, v35, v144
	v_cmp_ge_i32_e64 s[48:49], v35, v119
	v_max_f32_e32 v35, v36, v37
	v_max3_f32 v35, v35, v38, v39
	v_max3_f32 v35, v35, v42, v43
	v_max3_f32 v35, v35, v40, v41
	v_max3_f32 v35, v35, v44, v45
	s_and_b64 vcc, vcc, s[48:49]
	v_max3_f32 v35, v35, v46, v47
	v_cndmask_b32_e32 v51, v240, v51, vcc
	v_max3_f32 v35, v35, v48, v49
	v_max3_f32 v35, v35, v50, v51
	v_mov_b32_e32 v84, v35
	s_nop 1
	v_permlane32_swap_b32_e32 v35, v84
	v_max_f32_e32 v84, v84, v84
	v_max_f32_e32 v35, v35, v35
	v_max_f32_e32 v35, v35, v84
	v_sub_f32_e32 v84, v35, v122
	v_cmp_lt_f32_e32 vcc, s9, v84
	s_cbranch_vccz .LBB0_666
	v_max_f32_e32 v35, v35, v35
	v_max_f32_e32 v84, v122, v122
	v_max_f32_e32 v84, v84, v35
	v_sub_f32_e32 v35, v122, v84
	v_exp_f32_e32 v86, v35
	v_mov_b32_e32 v122, v84
	v_mul_f32_e32 v34, v34, v86
	v_mul_f32_e32 v32, v32, v86
	v_mul_f32_e32 v33, v33, v86
	v_mul_f32_e32 v30, v30, v86
	v_mul_f32_e32 v31, v31, v86
	v_mul_f32_e32 v28, v28, v86
	v_mul_f32_e32 v29, v29, v86
	v_mul_f32_e32 v26, v26, v86
	v_mul_f32_e32 v27, v27, v86
	v_mul_f32_e32 v24, v24, v86
	v_mul_f32_e32 v25, v25, v86
	v_mul_f32_e32 v22, v22, v86
	v_mul_f32_e32 v23, v23, v86
	v_mul_f32_e32 v20, v20, v86
	v_mul_f32_e32 v21, v21, v86
	v_mul_f32_e32 v18, v18, v86
	v_mul_f32_e32 v19, v19, v86
	v_mul_f32_e32 v16, v16, v86
	v_mul_f32_e32 v17, v17, v86
	v_mul_f32_e32 v14, v14, v86
	v_mul_f32_e32 v15, v15, v86
	v_mul_f32_e32 v12, v12, v86
	v_mul_f32_e32 v13, v13, v86
	v_mul_f32_e32 v10, v10, v86
	v_mul_f32_e32 v11, v11, v86
	v_mul_f32_e32 v8, v8, v86
	v_mul_f32_e32 v9, v9, v86
	v_mul_f32_e32 v6, v6, v86
	v_mul_f32_e32 v7, v7, v86
	v_mul_f32_e32 v4, v4, v86
	v_mul_f32_e32 v5, v5, v86
	v_mul_f32_e32 v2, v2, v86
	v_mul_f32_e32 v3, v3, v86
	s_branch .LBB0_667

; __device__ __forceinline__ unsigned cvt_pk_bf16(float lo, float hi) { f32x2_t v = {lo, hi}; bf16x2_t b = __builtin_convertvector(v, bf16x2_t); return __builtin_bit_cast(unsigned, b); }
; __device__ __forceinline__ float fast_exp2(float x) { return __builtin_amdgcn_exp2f(x); }
; template <bool MASK> ...
;     ...
;     { const f32x2_t m2 = {m, m}; f32x2_t ps2 = {0.f, 0.f};
; #pragma unroll
;       for (int i = 0; i < 8; ++i) { f32x2_t t = sp[i] - m2; t[0] = fast_exp2(t[0]); t[1] = fast_exp2(t[1]); sp[i] = t; ps2 = ps2 + t; }
;       l += ps2[0] + ps2[1]; }
;     u32x4 pw0, pw1;
;     pw0.x = cvt_pk_bf16(sp[0][0], sp[0][1]); pw0.y = cvt_pk_bf16(sp[1][0], sp[1][1]); pw0.z = cvt_pk_bf16(sp[2][0], sp[2][1]); pw0.w = cvt_pk_bf16(sp[3][0], sp[3][1]);
;     pw1.x = cvt_pk_bf16(sp[4][0], sp[4][1]); pw1.y = cvt_pk_bf16(sp[5][0], sp[5][1]); pw1.z = cvt_pk_bf16(sp[6][0], sp[6][1]); pw1.w = cvt_pk_bf16(sp[7][0], sp[7][1]);
;     asm volatile("s_waitcnt lgkmcnt(0)" : "+v"(l00), "+v"(h00), "+v"(l01), "+v"(h01), "+v"(l10), "+v"(h10), "+v"(l11), "+v"(h11) :: "memory");
;     { const bf16x8 pb0 = __builtin_bit_cast(bf16x8, pw0), pb1 = __builtin_bit_cast(bf16x8, pw1);
;       const bf16x8 v00 = {l00[0], l00[1], l00[2], l00[3], h00[0], h00[1], h00[2], h00[3]}, v01 = {l01[0], l01[1], l01[2], l01[3], h01[0], h01[1], h01[2], h01[3]};
;       const bf16x8 v10 = {l10[0], l10[1], l10[2], l10[3], h10[0], h10[1], h10[2], h10[3]}, v11 = {l11[0], l11[1], l11[2], l11[3], h11[0], h11[1], h11[2], h11[3]};
;       o0 = __builtin_amdgcn_mfma_f32_32x32x16_bf16(v00, pb0, o0, 0, 0, 0); o1 = __builtin_amdgcn_mfma_f32_32x32x16_bf16(v01, pb0, o1, 0, 0, 0);
;       o0 = __builtin_amdgcn_mfma_f32_32x32x16_bf16(v10, pb1, o0, 0, 0, 0); o1 = __builtin_amdgcn_mfma_f32_32x32x16_bf16(v11, pb1, o1, 0, 0, 0); }
.LBB0_667:
	v_sub_f32_e32 v36, v36, v84
	v_sub_f32_e32 v37, v37, v84
	v_sub_f32_e32 v38, v38, v84
	v_sub_f32_e32 v39, v39, v84
	v_exp_f32_e32 v36, v36
	v_exp_f32_e32 v37, v37
	v_sub_f32_e32 v42, v42, v84
	v_sub_f32_e32 v43, v43, v84
	v_sub_f32_e32 v40, v40, v84
	v_sub_f32_e32 v41, v41, v84
	v_exp_f32_e32 v38, v38
	v_exp_f32_e32 v39, v39
	v_exp_f32_e32 v42, v42
	v_exp_f32_e32 v43, v43
	v_exp_f32_e32 v40, v40
	v_exp_f32_e32 v41, v41
	v_add_f32_e32 v86, 0, v36
	v_add_f32_e32 v87, 0, v37
	v_cvt_pk_bf16_f32 v36, v36, v37
	v_add_f32_e32 v86, v38, v86
	v_add_f32_e32 v87, v39, v87
	v_cvt_pk_bf16_f32 v37, v38, v39
	v_cvt_pk_bf16_f32 v38, v42, v43
	v_cvt_pk_bf16_f32 v39, v40, v41
	s_waitcnt lgkmcnt(0)
	v_sub_f32_e32 v44, v44, v84
	v_sub_f32_e32 v45, v45, v84
	v_sub_f32_e32 v46, v46, v84
	v_sub_f32_e32 v47, v47, v84
	v_mfma_f32_32x32x16_bf16 v[18:33], v[64:67], v[36:39], v[18:33]
	v_add_f32_e64 v48, v48, -v84
	v_add_f32_e64 v49, v49, -v84
	v_add_f32_e64 v50, v50, -v84
	v_add_f32_e64 v51, v51, -v84
	v_exp_f32_e32 v44, v44
	v_exp_f32_e32 v45, v45
	v_exp_f32_e32 v46, v46
	v_exp_f32_e32 v47, v47
	v_exp_f32_e32 v48, v48
	v_mfma_f32_32x32x16_bf16 v[2:17], v[60:63], v[36:39], v[2:17]
	v_exp_f32_e32 v49, v49
	v_exp_f32_e32 v50, v50
	v_exp_f32_e32 v51, v51
	v_add_f32_e32 v86, v42, v86
	v_add_f32_e32 v87, v43, v87
	v_cvt_pk_bf16_f32 v42, v48, v49
	v_add_f32_e32 v86, v40, v86
	v_add_f32_e32 v87, v41, v87
	v_cvt_pk_bf16_f32 v40, v44, v45
	v_cvt_pk_bf16_f32 v41, v46, v47
	v_cvt_pk_bf16_f32 v43, v50, v51
	v_add_f32_e32 v86, v44, v86
	v_add_f32_e32 v87, v45, v87
	v_mov_b32_e32 v197, v122
	v_mfma_f32_32x32x16_bf16 v[18:33], v[56:59], v[40:43], v[18:33]
	v_add_f32_e64 v86, v46, v86
	v_add_f32_e64 v87, v47, v87
	v_add_f32_e64 v86, v48, v86
	v_add_f32_e64 v87, v49, v87
	v_add_f32_e64 v84, v50, v86
	v_add_f32_e64 v85, v51, v87
	v_add_f32_e32 v35, v84, v85
	v_mfma_f32_32x32x16_bf16 v[2:17], v[52:55], v[40:43], v[2:17]
	s_nop 3
	v_mov_b64_e32 v[50:51], v[32:33]
	v_add_f32_e32 v35, v34, v35
	v_mov_b64_e32 v[48:49], v[30:31]
	v_mov_b64_e32 v[46:47], v[28:29]
	v_mov_b64_e32 v[44:45], v[26:27]
	v_mov_b64_e32 v[42:43], v[24:25]
	v_mov_b64_e32 v[40:41], v[22:23]
	s_nop 0
	v_mov_b64_e32 v[66:67], v[16:17]
	v_mov_b64_e32 v[38:39], v[20:21]
	v_mov_b64_e32 v[36:37], v[18:19]
	v_mov_b64_e32 v[64:65], v[14:15]
	v_mov_b64_e32 v[62:63], v[12:13]
	v_mov_b64_e32 v[60:61], v[10:11]
	v_mov_b64_e32 v[58:59], v[8:9]
	v_mov_b64_e32 v[56:57], v[6:7]
	v_mov_b64_e32 v[54:55], v[4:5]
	v_mov_b64_e32 v[52:53], v[2:3]

; #define LAS __attribute__((address_space(3)))
; template <bool MASK> ...
;     s16x4 l00, h00, l01, h01, l10, h10, l11, h11; { const unsigned a0 = va0 + sub * 4096, a1 = va1 + sub * 4096;
;       asm volatile("ds_read_b64_tr_b16 %0, %1" : "=&v"(l00) : "v"(a0) : "memory"); asm volatile("ds_read_b64_tr_b16 %0, %1 offset:1024" : "=&v"(h00) : "v"(a0) : "memory");
;       asm volatile("ds_read_b64_tr_b16 %0, %1" : "=&v"(l01) : "v"(a1) : "memory"); asm volatile("ds_read_b64_tr_b16 %0, %1 offset:1024" : "=&v"(h01) : "v"(a1) : "memory");
;       asm volatile("ds_read_b64_tr_b16 %0, %1 offset:2048" : "=&v"(l10) : "v"(a0) : "memory"); asm volatile("ds_read_b64_tr_b16 %0, %1 offset:3072" : "=&v"(h10) : "v"(a0) : "memory");
;       asm volatile("ds_read_b64_tr_b16 %0, %1 offset:2048" : "=&v"(l11) : "v"(a1) : "memory"); asm volatile("ds_read_b64_tr_b16 %0, %1 offset:3072" : "=&v"(h11) : "v"(a1) : "memory"); }
;     const int r = lane & 31, hh = lane >> 5;
;     f32x16 st = {0.f, 0.f, 0.f, 0.f, 0.f, 0.f, 0.f, 0.f, 0.f, 0.f, 0.f, 0.f, 0.f, 0.f, 0.f, 0.f};
;     { const int key = sub * 32 + r; const LAS char* kp = Kt + key * 128; const int ksw = (key >> 1) & 7;
; #pragma unroll
;       for (int d0 = 0; d0 < 4; ++d0) { const bf16x8 kf = *(const LAS bf16x8*)(kp + (((2 * d0 + hh) ^ ksw) << 4)); st = __builtin_amdgcn_mfma_f32_32x32x16_bf16(kf, qr[d0], st, 0, 0, 0); } }
;     f32x2_t sp[8]; const f32x2_t cs2 = {cscale, cscale};
; #pragma unroll
;     for (int g = 0; g < 4; ++g) { const f32x4 c4 = *(const LAS f32x4*)(cb + sub * 32 + 8 * g + 4 * hh);
;         sp[2 * g] = (f32x2_t){st[4 * g], st[4 * g + 1]} + cs2 * (f32x2_t){c4[0], c4[1]};
;         sp[2 * g + 1] = (f32x2_t){st[4 * g + 2], st[4 * g + 3]} + cs2 * (f32x2_t){c4[2], c4[3]};
;         if (MASK) {
; #pragma unroll
;             for (int e = 0; e < 4; ++e) { const int kpos = kpos_sub + 8 * g + 4 * hh + e; const bool ok = (kpos <= qpos && kpos >= qpos - win);
;                 sp[2 * g + (e >> 1)][e & 1] = ok ? sp[2 * g + (e >> 1)][e & 1] : -INFINITY; } } }
;     float rm = fmaxf(sp[0][0], sp[0][1]);
; #pragma unroll
;     for (int i = 1; i < 8; ++i) rm = fmaxf(fmaxf(rm, sp[i][0]), sp[i][1]);
;     rm = swap_max(rm);
;     if (__any(rm - m > 8.0f)) { const float mnew = fmaxf(m, rm); const float f = fast_exp2(m - mnew); l *= f; o0 = o0 * f; o1 = o1 * f; m = mnew; }
.LBB0_673:
	s_cmp_lt_i32 s3, 3
	s_mov_b64 s[18:19], -1
	s_cbranch_scc1 .LBB0_678
	ds_read_b64_tr_b16 v[96:97], v192
	ds_read_b64_tr_b16 v[98:99], v192 offset:1024
	ds_read_b64_tr_b16 v[92:93], v193
	ds_read_b64_tr_b16 v[94:95], v193 offset:1024
	ds_read_b64_tr_b16 v[88:89], v192 offset:2048
	ds_read_b64_tr_b16 v[90:91], v192 offset:3072
	ds_read_b64_tr_b16 v[84:85], v193 offset:2048
	ds_read_b64_tr_b16 v[86:87], v193 offset:3072
	v_add_u32_e32 v35, v188, v180
	ds_read_b128 v[36:39], v35 offset:8192
	v_add_u32_e32 v35, v188, v181
	ds_read_b128 v[52:55], v35 offset:8192
	v_add_u32_e32 v35, v188, v182
	s_waitcnt lgkmcnt(0)
	v_mfma_f32_32x32x16_bf16 v[36:51], v[36:39], v[76:79], 0
	v_mfma_f32_32x32x16_bf16 v[36:51], v[52:55], v[68:71], v[36:51]
	ds_read_b128 v[52:55], v35 offset:8192
	v_add_u32_e32 v35, v188, v183
	s_waitcnt lgkmcnt(0)
	v_mfma_f32_32x32x16_bf16 v[36:51], v[52:55], v[72:75], v[36:51]
	ds_read_b128 v[52:55], v35 offset:8192
	s_waitcnt lgkmcnt(0)
	v_mfma_f32_32x32x16_bf16 v[36:51], v[52:55], v[80:83], v[36:51]
	ds_read_b128 v[52:55], v186 offset:49408
	ds_read_b128 v[56:59], v186 offset:49440
	s_waitcnt lgkmcnt(0)
	s_nop 8
	v_fma_f32 v160, v148, v52, v36
	v_fma_f32 v161, v149, v53, v37
	v_fma_f32 v158, v148, v54, v38
	v_fma_f32 v159, v149, v55, v39
	ds_read_b128 v[36:39], v186 offset:49472
	v_max_f32_e32 v35, v160, v161
	v_fma_f32 v152, v148, v56, v40
	v_fma_f32 v153, v149, v57, v41
	v_max3_f32 v35, v35, v158, v159
	v_fma_f32 v150, v148, v58, v42
	v_fma_f32 v151, v149, v59, v43
	s_waitcnt lgkmcnt(0)
	v_fma_f32 v156, v148, v36, v44
	v_fma_f32 v157, v149, v37, v45
	v_fma_f32 v154, v148, v38, v46
	v_fma_f32 v155, v149, v39, v47
	ds_read_b128 v[36:39], v186 offset:49504
	v_max3_f32 v35, v35, v152, v153
	v_max3_f32 v35, v35, v150, v151
	v_max3_f32 v35, v35, v156, v157
	v_max3_f32 v35, v35, v154, v155
	s_waitcnt lgkmcnt(0)
	v_fma_f32 v162, v148, v36, v48
	v_fma_f32 v163, v149, v37, v49
	v_fma_f32 v164, v148, v38, v50
	v_fma_f32 v165, v149, v39, v51
	v_max3_f32 v35, v35, v162, v163
	v_max3_f32 v35, v35, v164, v165
	v_mov_b32_e32 v36, v35
	s_nop 1
	v_permlane32_swap_b32_e32 v35, v36
	v_max_f32_e32 v36, v36, v36
	v_max_f32_e32 v35, v35, v35
	v_max_f32_e32 v35, v35, v36
	v_sub_f32_e32 v36, v35, v122
	v_cmp_lt_f32_e32 vcc, s9, v36
	s_cbranch_vccz .LBB0_676
	v_max_f32_e32 v35, v35, v35
	v_max_f32_e32 v36, v122, v122
	v_max_f32_e32 v167, v36, v35
	v_sub_f32_e32 v35, v122, v167
	v_exp_f32_e32 v52, v35
	v_mov_b32_e32 v166, v167
	v_mul_f32_e32 v35, v34, v52
	v_mul_f32_e32 v50, v32, v52
	v_mul_f32_e32 v51, v33, v52
	v_mul_f32_e32 v48, v30, v52
	v_mul_f32_e32 v49, v31, v52
	v_mul_f32_e32 v46, v28, v52
	v_mul_f32_e32 v47, v29, v52
	v_mul_f32_e32 v44, v26, v52
	v_mul_f32_e32 v45, v27, v52
	v_mul_f32_e32 v42, v24, v52
	v_mul_f32_e32 v43, v25, v52
	v_mul_f32_e32 v40, v22, v52
	v_mul_f32_e32 v41, v23, v52
	v_mul_f32_e32 v38, v20, v52
	v_mul_f32_e32 v39, v21, v52
	v_mul_f32_e32 v36, v18, v52
	v_mul_f32_e32 v37, v19, v52
	v_mul_f32_e32 v66, v16, v52
	v_mul_f32_e32 v67, v17, v52
	v_mul_f32_e32 v64, v14, v52
	v_mul_f32_e32 v65, v15, v52
	v_mul_f32_e32 v62, v12, v52
	v_mul_f32_e32 v63, v13, v52
	v_mul_f32_e32 v60, v10, v52
	v_mul_f32_e32 v61, v11, v52
	v_mul_f32_e32 v58, v8, v52
	v_mul_f32_e32 v59, v9, v52
	v_mul_f32_e32 v56, v6, v52
	v_mul_f32_e32 v57, v7, v52
	v_mul_f32_e32 v54, v4, v52
	v_mul_f32_e32 v55, v5, v52
	v_mul_f32_e32 v53, v3, v52
	v_mul_f32_e32 v52, v2, v52
	s_branch .LBB0_677

; __device__ __forceinline__ unsigned cvt_pk_bf16(float lo, float hi) { f32x2_t v = {lo, hi}; bf16x2_t b = __builtin_convertvector(v, bf16x2_t); return __builtin_bit_cast(unsigned, b); }
; __device__ __forceinline__ float fast_exp2(float x) { return __builtin_amdgcn_exp2f(x); }
; template <bool MASK> ...
;     ...
;     { const f32x2_t m2 = {m, m}; f32x2_t ps2 = {0.f, 0.f};
; #pragma unroll
;       for (int i = 0; i < 8; ++i) { f32x2_t t = sp[i] - m2; t[0] = fast_exp2(t[0]); t[1] = fast_exp2(t[1]); sp[i] = t; ps2 = ps2 + t; }
;       l += ps2[0] + ps2[1]; }
;     u32x4 pw0, pw1;
;     pw0.x = cvt_pk_bf16(sp[0][0], sp[0][1]); pw0.y = cvt_pk_bf16(sp[1][0], sp[1][1]); pw0.z = cvt_pk_bf16(sp[2][0], sp[2][1]); pw0.w = cvt_pk_bf16(sp[3][0], sp[3][1]);
;     pw1.x = cvt_pk_bf16(sp[4][0], sp[4][1]); pw1.y = cvt_pk_bf16(sp[5][0], sp[5][1]); pw1.z = cvt_pk_bf16(sp[6][0], sp[6][1]); pw1.w = cvt_pk_bf16(sp[7][0], sp[7][1]);
;     asm volatile("s_waitcnt lgkmcnt(0)" : "+v"(l00), "+v"(h00), "+v"(l01), "+v"(h01), "+v"(l10), "+v"(h10), "+v"(l11), "+v"(h11) :: "memory");
;     { const bf16x8 pb0 = __builtin_bit_cast(bf16x8, pw0), pb1 = __builtin_bit_cast(bf16x8, pw1);
;       const bf16x8 v00 = {l00[0], l00[1], l00[2], l00[3], h00[0], h00[1], h00[2], h00[3]}, v01 = {l01[0], l01[1], l01[2], l01[3], h01[0], h01[1], h01[2], h01[3]};
;       const bf16x8 v10 = {l10[0], l10[1], l10[2], l10[3], h10[0], h10[1], h10[2], h10[3]}, v11 = {l11[0], l11[1], l11[2], l11[3], h11[0], h11[1], h11[2], h11[3]};
;       o0 = __builtin_amdgcn_mfma_f32_32x32x16_bf16(v00, pb0, o0, 0, 0, 0); o1 = __builtin_amdgcn_mfma_f32_32x32x16_bf16(v01, pb0, o1, 0, 0, 0);
;       o0 = __builtin_amdgcn_mfma_f32_32x32x16_bf16(v10, pb1, o0, 0, 0, 0); o1 = __builtin_amdgcn_mfma_f32_32x32x16_bf16(v11, pb1, o1, 0, 0, 0); }
.LBB0_677:
	v_sub_f32_e32 v160, v160, v166
	v_sub_f32_e32 v161, v161, v166
	v_sub_f32_e32 v158, v158, v166
	v_sub_f32_e32 v159, v159, v166
	v_exp_f32_e32 v160, v160
	v_exp_f32_e32 v161, v161
	v_exp_f32_e32 v158, v158
	v_exp_f32_e32 v159, v159
	v_sub_f32_e32 v152, v152, v166
	v_sub_f32_e32 v153, v153, v166
	v_sub_f32_e32 v150, v150, v166
	v_sub_f32_e32 v151, v151, v166
	v_exp_f32_e32 v152, v152
	v_exp_f32_e32 v153, v153
	v_exp_f32_e32 v198, v150
	v_exp_f32_e32 v199, v151
	v_add_f32_e32 v168, 0, v160
	v_add_f32_e32 v169, 0, v161
	v_sub_f32_e32 v156, v156, v166
	v_sub_f32_e32 v157, v157, v166
	v_add_f32_e32 v168, v158, v168
	v_add_f32_e32 v169, v159, v169
	v_exp_f32_e32 v156, v156
	v_add_f32_e32 v168, v152, v168
	v_add_f32_e32 v169, v153, v169
	v_exp_f32_e32 v157, v157
	v_sub_f32_e32 v154, v154, v166
	v_sub_f32_e32 v155, v155, v166
	v_add_f32_e32 v150, v198, v168
	v_add_f32_e32 v151, v199, v169
	v_exp_f32_e32 v168, v154
	v_exp_f32_e32 v169, v155
	v_sub_f32_e32 v154, v162, v166
	v_sub_f32_e32 v155, v163, v166
	v_add_f32_e32 v150, v156, v150
	v_add_f32_e32 v151, v157, v151
	v_exp_f32_e32 v162, v154
	v_exp_f32_e32 v163, v155
	v_sub_f32_e32 v154, v164, v166
	v_sub_f32_e32 v155, v165, v166
	v_add_f32_e32 v150, v168, v150
	v_add_f32_e32 v151, v169, v151
	v_exp_f32_e32 v164, v154
	v_exp_f32_e32 v165, v155
	v_add_f32_e32 v150, v162, v150
	v_add_f32_e32 v151, v163, v151
	v_cvt_pk_bf16_f32 v152, v152, v153
	v_cvt_pk_bf16_f32 v153, v198, v199
	v_add_f32_e32 v150, v164, v150
	v_add_f32_e32 v151, v165, v151
	s_waitcnt lgkmcnt(0)
	v_cvt_pk_bf16_f32 v154, v156, v157
	v_add_f32_e32 v150, v150, v151
	v_add_f32_e32 v35, v35, v150
	v_cvt_pk_bf16_f32 v150, v160, v161
	v_cvt_pk_bf16_f32 v151, v158, v159
	v_cvt_pk_bf16_f32 v155, v168, v169
	v_cvt_pk_bf16_f32 v156, v162, v163
	v_mfma_f32_32x32x16_bf16 v[36:51], v[96:99], v[150:153], v[36:51]
	v_cvt_pk_bf16_f32 v157, v164, v165
	s_mov_b64 s[18:19], 0
	v_mfma_f32_32x32x16_bf16 v[52:67], v[92:95], v[150:153], v[52:67]
	v_mfma_f32_32x32x16_bf16 v[36:51], v[88:91], v[154:157], v[36:51]
	v_mfma_f32_32x32x16_bf16 v[52:67], v[84:87], v[154:157], v[52:67]
; #define LAS __attribute__((address_space(3)))
; template <bool MASK> ...
;     s16x4 l00, h00, l01, h01, l10, h10, l11, h11; { const unsigned a0 = va0 + sub * 4096, a1 = va1 + sub * 4096;
;       asm volatile("ds_read_b64_tr_b16 %0, %1" : "=&v"(l00) : "v"(a0) : "memory"); asm volatile("ds_read_b64_tr_b16 %0, %1 offset:1024" : "=&v"(h00) : "v"(a0) : "memory");
;       asm volatile("ds_read_b64_tr_b16 %0, %1" : "=&v"(l01) : "v"(a1) : "memory"); asm volatile("ds_read_b64_tr_b16 %0, %1 offset:1024" : "=&v"(h01) : "v"(a1) : "memory");
;       asm volatile("ds_read_b64_tr_b16 %0, %1 offset:2048" : "=&v"(l10) : "v"(a0) : "memory"); asm volatile("ds_read_b64_tr_b16 %0, %1 offset:3072" : "=&v"(h10) : "v"(a0) : "memory");
;       asm volatile("ds_read_b64_tr_b16 %0, %1 offset:2048" : "=&v"(l11) : "v"(a1) : "memory"); asm volatile("ds_read_b64_tr_b16 %0, %1 offset:3072" : "=&v"(h11) : "v"(a1) : "memory"); }
;     const int r = lane & 31, hh = lane >> 5;
;     f32x16 st = {0.f, 0.f, 0.f, 0.f, 0.f, 0.f, 0.f, 0.f, 0.f, 0.f, 0.f, 0.f, 0.f, 0.f, 0.f, 0.f};
;     { const int key = sub * 32 + r; const LAS char* kp = Kt + key * 128; const int ksw = (key >> 1) & 7;
; #pragma unroll
;       for (int d0 = 0; d0 < 4; ++d0) { const bf16x8 kf = *(const LAS bf16x8*)(kp + (((2 * d0 + hh) ^ ksw) << 4)); st = __builtin_amdgcn_mfma_f32_32x32x16_bf16(kf, qr[d0], st, 0, 0, 0); } }
;     f32x2_t sp[8]; const f32x2_t cs2 = {cscale, cscale};
; #pragma unroll
;     for (int g = 0; g < 4; ++g) { const f32x4 c4 = *(const LAS f32x4*)(cb + sub * 32 + 8 * g + 4 * hh);
;         sp[2 * g] = (f32x2_t){st[4 * g], st[4 * g + 1]} + cs2 * (f32x2_t){c4[0], c4[1]};
;         sp[2 * g + 1] = (f32x2_t){st[4 * g + 2], st[4 * g + 3]} + cs2 * (f32x2_t){c4[2], c4[3]};
;         if (MASK) {
; #pragma unroll
;             for (int e = 0; e < 4; ++e) { const int kpos = kpos_sub + 8 * g + 4 * hh + e; const bool ok = (kpos <= qpos && kpos >= qpos - win);
;                 sp[2 * g + (e >> 1)][e & 1] = ok ? sp[2 * g + (e >> 1)][e & 1] : -INFINITY; } } }
;     float rm = fmaxf(sp[0][0], sp[0][1]);
; #pragma unroll
;     for (int i = 1; i < 8; ++i) rm = fmaxf(fmaxf(rm, sp[i][0]), sp[i][1]);
;     rm = swap_max(rm);
;     if (__any(rm - m > 8.0f)) { const float mnew = fmaxf(m, rm); const float f = fast_exp2(m - mnew); l *= f; o0 = o0 * f; o1 = o1 * f; m = mnew; }
.LBB0_678:
	s_and_b64 vcc, exec, s[18:19]
	s_cbranch_vccz .LBB0_683
	ds_read_b64_tr_b16 v[64:65], v192
	ds_read_b64_tr_b16 v[66:67], v192 offset:1024
	ds_read_b64_tr_b16 v[60:61], v193
	ds_read_b64_tr_b16 v[62:63], v193 offset:1024
	ds_read_b64_tr_b16 v[56:57], v192 offset:2048
	ds_read_b64_tr_b16 v[58:59], v192 offset:3072
	ds_read_b64_tr_b16 v[52:53], v193 offset:2048
	ds_read_b64_tr_b16 v[54:55], v193 offset:3072
	v_add_u32_e32 v35, v188, v180
	s_nop 7
	ds_read_b128 v[36:39], v35 offset:8192
	v_add_u32_e32 v35, v188, v181
	ds_read_b128 v[84:87], v35 offset:8192
	v_add_u32_e32 v35, v188, v182
	s_waitcnt lgkmcnt(0)
	v_mfma_f32_32x32x16_bf16 v[36:51], v[36:39], v[76:79], 0
	v_mfma_f32_32x32x16_bf16 v[36:51], v[84:87], v[68:71], v[36:51]
	ds_read_b128 v[84:87], v35 offset:8192
	v_add_u32_e32 v35, v188, v183
	s_waitcnt lgkmcnt(0)
	v_mfma_f32_32x32x16_bf16 v[36:51], v[84:87], v[72:75], v[36:51]
	ds_read_b128 v[84:87], v35 offset:8192
	v_or_b32_e32 v35, s4, v100
	v_cmp_le_i32_e32 vcc, v35, v144
	v_cmp_ge_i32_e64 s[46:47], v35, v119
	s_and_b64 vcc, vcc, s[46:47]
	s_waitcnt lgkmcnt(0)
	v_mfma_f32_32x32x16_bf16 v[36:51], v[84:87], v[80:83], v[36:51]
	ds_read_b128 v[84:87], v186 offset:49408
	ds_read_b128 v[88:91], v186 offset:49440
	s_waitcnt lgkmcnt(0)
	s_nop 8
	v_fma_f32 v36, v148, v84, v36
	v_fma_f32 v37, v149, v85, v37
	v_or_b32_e32 v84, 1, v35
	v_cndmask_b32_e32 v36, v240, v36, vcc
	v_cmp_lt_i32_e32 vcc, v35, v144
	v_cmp_ge_i32_e64 s[46:47], v84, v119
	s_and_b64 vcc, vcc, s[46:47]
	v_or_b32_e32 v84, 2, v35
	v_cndmask_b32_e32 v37, v240, v37, vcc
	v_cmp_le_i32_e32 vcc, v84, v144
	v_cmp_ge_i32_e64 s[46:47], v84, v119
	v_fma_f32 v38, v148, v86, v38
	v_fma_f32 v39, v149, v87, v39
	s_and_b64 vcc, vcc, s[46:47]
	v_or_b32_e32 v84, 3, v35
	v_cndmask_b32_e32 v38, v240, v38, vcc
	v_cmp_le_i32_e32 vcc, v84, v144
	v_cmp_ge_i32_e64 s[46:47], v84, v119
	s_and_b64 vcc, vcc, s[46:47]
	v_fma_f32 v84, v148, v90, v42
	v_fma_f32 v85, v149, v91, v43
	v_or_b32_e32 v42, 8, v35
	v_cndmask_b32_e32 v39, v240, v39, vcc
	v_cmp_le_i32_e32 vcc, v42, v144
	v_cmp_ge_i32_e64 s[46:47], v42, v119
	v_fma_f32 v40, v148, v88, v40
	v_fma_f32 v41, v149, v89, v41
	s_and_b64 vcc, vcc, s[46:47]
	v_cndmask_b32_e32 v42, v240, v40, vcc
	v_or_b32_e32 v40, 9, v35
	v_cmp_le_i32_e32 vcc, v40, v144
	v_cmp_ge_i32_e64 s[46:47], v40, v119
	s_and_b64 vcc, vcc, s[46:47]
	v_or_b32_e32 v40, 10, v35
	v_cndmask_b32_e32 v43, v240, v41, vcc
	v_cmp_le_i32_e32 vcc, v40, v144
	v_cmp_ge_i32_e64 s[46:47], v40, v119
	s_and_b64 vcc, vcc, s[46:47]
	v_or_b32_e32 v41, 11, v35
	v_cndmask_b32_e32 v40, v240, v84, vcc
	v_cmp_le_i32_e32 vcc, v41, v144
	v_cmp_ge_i32_e64 s[46:47], v41, v119
	s_and_b64 vcc, vcc, s[46:47]
	v_cndmask_b32_e32 v41, v240, v85, vcc
	ds_read_b128 v[84:87], v186 offset:49472
	s_waitcnt lgkmcnt(0)
	v_fma_f32 v44, v148, v84, v44
	v_fma_f32 v45, v149, v85, v45
	v_or_b32_e32 v84, 16, v35
	v_cmp_le_i32_e32 vcc, v84, v144
	v_cmp_ge_i32_e64 s[46:47], v84, v119
	s_and_b64 vcc, vcc, s[46:47]
	v_or_b32_e32 v84, 17, v35
	v_cndmask_b32_e32 v44, v240, v44, vcc
	v_cmp_le_i32_e32 vcc, v84, v144
	v_cmp_ge_i32_e64 s[46:47], v84, v119
	s_and_b64 vcc, vcc, s[46:47]
	v_or_b32_e32 v84, 18, v35
	v_cndmask_b32_e32 v45, v240, v45, vcc
	v_cmp_le_i32_e32 vcc, v84, v144
	v_cmp_ge_i32_e64 s[46:47], v84, v119
	v_fma_f32 v46, v148, v86, v46
	v_fma_f32 v47, v149, v87, v47
	s_and_b64 vcc, vcc, s[46:47]
	v_or_b32_e32 v84, 19, v35
	v_cndmask_b32_e32 v46, v240, v46, vcc
	v_cmp_le_i32_e32 vcc, v84, v144
	v_cmp_ge_i32_e64 s[46:47], v84, v119
	ds_read_b128 v[84:87], v186 offset:49504
	s_and_b64 vcc, vcc, s[46:47]
	v_cndmask_b32_e32 v47, v240, v47, vcc
	s_waitcnt lgkmcnt(0)
	v_fma_f32 v48, v148, v84, v48
	v_fma_f32 v49, v149, v85, v49
	v_or_b32_e32 v84, 24, v35
	v_cmp_le_i32_e32 vcc, v84, v144
	v_cmp_ge_i32_e64 s[46:47], v84, v119
	s_and_b64 vcc, vcc, s[46:47]
	v_or_b32_e32 v84, 25, v35
	v_cndmask_b32_e32 v48, v240, v48, vcc
	v_cmp_le_i32_e32 vcc, v84, v144
	v_cmp_ge_i32_e64 s[46:47], v84, v119
	s_and_b64 vcc, vcc, s[46:47]
	v_or_b32_e32 v84, 26, v35
	v_cndmask_b32_e32 v49, v240, v49, vcc
	v_cmp_le_i32_e32 vcc, v84, v144
	v_cmp_ge_i32_e64 s[46:47], v84, v119
	v_fma_f32 v50, v148, v86, v50
	v_fma_f32 v51, v149, v87, v51
	s_and_b64 vcc, vcc, s[46:47]
	v_or_b32_e32 v35, 27, v35
	v_cndmask_b32_e32 v50, v240, v50, vcc
	v_cmp_le_i32_e32 vcc, v35, v144
	v_cmp_ge_i32_e64 s[46:47], v35, v119
	v_max_f32_e32 v35, v36, v37
	v_max3_f32 v35, v35, v38, v39
	v_max3_f32 v35, v35, v42, v43
	v_max3_f32 v35, v35, v40, v41
	v_max3_f32 v35, v35, v44, v45
	s_and_b64 vcc, vcc, s[46:47]
	v_max3_f32 v35, v35, v46, v47
	v_cndmask_b32_e32 v51, v240, v51, vcc
	v_max3_f32 v35, v35, v48, v49
	v_max3_f32 v35, v35, v50, v51
	v_mov_b32_e32 v84, v35
	s_nop 1
	v_permlane32_swap_b32_e32 v35, v84
	v_max_f32_e32 v84, v84, v84
	v_max_f32_e32 v35, v35, v35
	v_max_f32_e32 v35, v35, v84
	v_sub_f32_e32 v84, v35, v122
	v_cmp_lt_f32_e32 vcc, s9, v84
	s_cbranch_vccz .LBB0_681
	v_max_f32_e32 v35, v35, v35
	v_max_f32_e32 v84, v122, v122
	v_max_f32_e32 v84, v84, v35
	v_sub_f32_e32 v35, v122, v84
	v_exp_f32_e32 v86, v35
	v_mov_b32_e32 v122, v84
	v_mul_f32_e32 v34, v34, v86
	v_mul_f32_e32 v32, v32, v86
	v_mul_f32_e32 v33, v33, v86
	v_mul_f32_e32 v30, v30, v86
	v_mul_f32_e32 v31, v31, v86
	v_mul_f32_e32 v28, v28, v86
	v_mul_f32_e32 v29, v29, v86
	v_mul_f32_e32 v26, v26, v86
	v_mul_f32_e32 v27, v27, v86
	v_mul_f32_e32 v24, v24, v86
	v_mul_f32_e32 v25, v25, v86
	v_mul_f32_e32 v22, v22, v86
	v_mul_f32_e32 v23, v23, v86
	v_mul_f32_e32 v20, v20, v86
	v_mul_f32_e32 v21, v21, v86
	v_mul_f32_e32 v18, v18, v86
	v_mul_f32_e32 v19, v19, v86
	v_mul_f32_e32 v16, v16, v86
	v_mul_f32_e32 v17, v17, v86
	v_mul_f32_e32 v14, v14, v86
	v_mul_f32_e32 v15, v15, v86
	v_mul_f32_e32 v12, v12, v86
	v_mul_f32_e32 v13, v13, v86
	v_mul_f32_e32 v10, v10, v86
	v_mul_f32_e32 v11, v11, v86
	v_mul_f32_e32 v8, v8, v86
	v_mul_f32_e32 v9, v9, v86
	v_mul_f32_e32 v6, v6, v86
	v_mul_f32_e32 v7, v7, v86
	v_mul_f32_e32 v4, v4, v86
	v_mul_f32_e32 v5, v5, v86
	v_mul_f32_e32 v2, v2, v86
	v_mul_f32_e32 v3, v3, v86
	s_branch .LBB0_682

; __device__ __forceinline__ unsigned cvt_pk_bf16(float lo, float hi) { f32x2_t v = {lo, hi}; bf16x2_t b = __builtin_convertvector(v, bf16x2_t); return __builtin_bit_cast(unsigned, b); }
; __device__ __forceinline__ float fast_exp2(float x) { return __builtin_amdgcn_exp2f(x); }
; template <bool MASK> ...
;     ...
;     { const f32x2_t m2 = {m, m}; f32x2_t ps2 = {0.f, 0.f};
; #pragma unroll
;       for (int i = 0; i < 8; ++i) { f32x2_t t = sp[i] - m2; t[0] = fast_exp2(t[0]); t[1] = fast_exp2(t[1]); sp[i] = t; ps2 = ps2 + t; }
;       l += ps2[0] + ps2[1]; }
;     u32x4 pw0, pw1;
;     pw0.x = cvt_pk_bf16(sp[0][0], sp[0][1]); pw0.y = cvt_pk_bf16(sp[1][0], sp[1][1]); pw0.z = cvt_pk_bf16(sp[2][0], sp[2][1]); pw0.w = cvt_pk_bf16(sp[3][0], sp[3][1]);
;     pw1.x = cvt_pk_bf16(sp[4][0], sp[4][1]); pw1.y = cvt_pk_bf16(sp[5][0], sp[5][1]); pw1.z = cvt_pk_bf16(sp[6][0], sp[6][1]); pw1.w = cvt_pk_bf16(sp[7][0], sp[7][1]);
;     asm volatile("s_waitcnt lgkmcnt(0)" : "+v"(l00), "+v"(h00), "+v"(l01), "+v"(h01), "+v"(l10), "+v"(h10), "+v"(l11), "+v"(h11) :: "memory");
;     { const bf16x8 pb0 = __builtin_bit_cast(bf16x8, pw0), pb1 = __builtin_bit_cast(bf16x8, pw1);
;       const bf16x8 v00 = {l00[0], l00[1], l00[2], l00[3], h00[0], h00[1], h00[2], h00[3]}, v01 = {l01[0], l01[1], l01[2], l01[3], h01[0], h01[1], h01[2], h01[3]};
;       const bf16x8 v10 = {l10[0], l10[1], l10[2], l10[3], h10[0], h10[1], h10[2], h10[3]}, v11 = {l11[0], l11[1], l11[2], l11[3], h11[0], h11[1], h11[2], h11[3]};
;       o0 = __builtin_amdgcn_mfma_f32_32x32x16_bf16(v00, pb0, o0, 0, 0, 0); o1 = __builtin_amdgcn_mfma_f32_32x32x16_bf16(v01, pb0, o1, 0, 0, 0);
;       o0 = __builtin_amdgcn_mfma_f32_32x32x16_bf16(v10, pb1, o0, 0, 0, 0); o1 = __builtin_amdgcn_mfma_f32_32x32x16_bf16(v11, pb1, o1, 0, 0, 0); }
.LBB0_682:
	v_sub_f32_e32 v36, v36, v84
	v_sub_f32_e32 v37, v37, v84
	v_sub_f32_e32 v38, v38, v84
	v_sub_f32_e32 v39, v39, v84
	v_exp_f32_e32 v36, v36
	v_exp_f32_e32 v37, v37
	v_sub_f32_e32 v42, v42, v84
	v_sub_f32_e32 v43, v43, v84
	v_sub_f32_e32 v40, v40, v84
	v_sub_f32_e32 v41, v41, v84
	v_exp_f32_e32 v38, v38
	v_exp_f32_e32 v39, v39
	v_exp_f32_e32 v42, v42
	v_exp_f32_e32 v43, v43
	v_exp_f32_e32 v40, v40
	v_exp_f32_e32 v41, v41
	v_add_f32_e32 v86, 0, v36
	v_add_f32_e32 v87, 0, v37
	v_cvt_pk_bf16_f32 v36, v36, v37
	v_add_f32_e32 v86, v38, v86
	v_add_f32_e32 v87, v39, v87
	v_cvt_pk_bf16_f32 v37, v38, v39
	v_cvt_pk_bf16_f32 v38, v42, v43
	v_cvt_pk_bf16_f32 v39, v40, v41
	s_waitcnt lgkmcnt(0)
	v_sub_f32_e32 v44, v44, v84
	v_sub_f32_e32 v45, v45, v84
	v_sub_f32_e32 v46, v46, v84
	v_sub_f32_e32 v47, v47, v84
	v_mfma_f32_32x32x16_bf16 v[18:33], v[64:67], v[36:39], v[18:33]
	v_add_f32_e64 v48, v48, -v84
	v_add_f32_e64 v49, v49, -v84
	v_add_f32_e64 v50, v50, -v84
	v_add_f32_e64 v51, v51, -v84
	v_exp_f32_e32 v44, v44
	v_exp_f32_e32 v45, v45
	v_exp_f32_e32 v46, v46
	v_exp_f32_e32 v47, v47
	v_exp_f32_e32 v48, v48
	v_mfma_f32_32x32x16_bf16 v[2:17], v[60:63], v[36:39], v[2:17]
	v_exp_f32_e32 v49, v49
	v_exp_f32_e32 v50, v50
	v_exp_f32_e32 v51, v51
	v_add_f32_e32 v86, v42, v86
	v_add_f32_e32 v87, v43, v87
	v_cvt_pk_bf16_f32 v42, v48, v49
	v_add_f32_e32 v86, v40, v86
	v_add_f32_e32 v87, v41, v87
	v_cvt_pk_bf16_f32 v40, v44, v45
	v_cvt_pk_bf16_f32 v41, v46, v47
	v_cvt_pk_bf16_f32 v43, v50, v51
	v_add_f32_e32 v86, v44, v86
	v_add_f32_e32 v87, v45, v87
	v_mov_b32_e32 v167, v122
	v_mfma_f32_32x32x16_bf16 v[18:33], v[56:59], v[40:43], v[18:33]
	v_add_f32_e64 v86, v46, v86
	v_add_f32_e64 v87, v47, v87
	v_add_f32_e64 v86, v48, v86
	v_add_f32_e64 v87, v49, v87
	v_add_f32_e64 v84, v50, v86
	v_add_f32_e64 v85, v51, v87
	v_add_f32_e32 v35, v84, v85
	v_mfma_f32_32x32x16_bf16 v[2:17], v[52:55], v[40:43], v[2:17]
	s_nop 3
	v_mov_b64_e32 v[50:51], v[32:33]
	v_add_f32_e32 v35, v34, v35
	v_mov_b64_e32 v[48:49], v[30:31]
	v_mov_b64_e32 v[46:47], v[28:29]
	v_mov_b64_e32 v[44:45], v[26:27]
	v_mov_b64_e32 v[42:43], v[24:25]
	v_mov_b64_e32 v[40:41], v[22:23]
	s_nop 0
	v_mov_b64_e32 v[66:67], v[16:17]
	v_mov_b64_e32 v[38:39], v[20:21]
	v_mov_b64_e32 v[36:37], v[18:19]
	v_mov_b64_e32 v[64:65], v[14:15]
	v_mov_b64_e32 v[62:63], v[12:13]
	v_mov_b64_e32 v[60:61], v[10:11]
	v_mov_b64_e32 v[58:59], v[8:9]
	v_mov_b64_e32 v[56:57], v[6:7]
	v_mov_b64_e32 v[54:55], v[4:5]
	v_mov_b64_e32 v[52:53], v[2:3]

; #define LAS __attribute__((address_space(3)))
; template <bool MASK> ...
;     s16x4 l00, h00, l01, h01, l10, h10, l11, h11; { const unsigned a0 = va0 + sub * 4096, a1 = va1 + sub * 4096;
;       asm volatile("ds_read_b64_tr_b16 %0, %1" : "=&v"(l00) : "v"(a0) : "memory"); asm volatile("ds_read_b64_tr_b16 %0, %1 offset:1024" : "=&v"(h00) : "v"(a0) : "memory");
;       asm volatile("ds_read_b64_tr_b16 %0, %1" : "=&v"(l01) : "v"(a1) : "memory"); asm volatile("ds_read_b64_tr_b16 %0, %1 offset:1024" : "=&v"(h01) : "v"(a1) : "memory");
;       asm volatile("ds_read_b64_tr_b16 %0, %1 offset:2048" : "=&v"(l10) : "v"(a0) : "memory"); asm volatile("ds_read_b64_tr_b16 %0, %1 offset:3072" : "=&v"(h10) : "v"(a0) : "memory");
;       asm volatile("ds_read_b64_tr_b16 %0, %1 offset:2048" : "=&v"(l11) : "v"(a1) : "memory"); asm volatile("ds_read_b64_tr_b16 %0, %1 offset:3072" : "=&v"(h11) : "v"(a1) : "memory"); }
;     const int r = lane & 31, hh = lane >> 5;
;     f32x16 st = {0.f, 0.f, 0.f, 0.f, 0.f, 0.f, 0.f, 0.f, 0.f, 0.f, 0.f, 0.f, 0.f, 0.f, 0.f, 0.f};
;     { const int key = sub * 32 + r; const LAS char* kp = Kt + key * 128; const int ksw = (key >> 1) & 7;
; #pragma unroll
;       for (int d0 = 0; d0 < 4; ++d0) { const bf16x8 kf = *(const LAS bf16x8*)(kp + (((2 * d0 + hh) ^ ksw) << 4)); st = __builtin_amdgcn_mfma_f32_32x32x16_bf16(kf, qr[d0], st, 0, 0, 0); } }
;     f32x2_t sp[8]; const f32x2_t cs2 = {cscale, cscale};
; #pragma unroll
;     for (int g = 0; g < 4; ++g) { const f32x4 c4 = *(const LAS f32x4*)(cb + sub * 32 + 8 * g + 4 * hh);
;         sp[2 * g] = (f32x2_t){st[4 * g], st[4 * g + 1]} + cs2 * (f32x2_t){c4[0], c4[1]};
;         sp[2 * g + 1] = (f32x2_t){st[4 * g + 2], st[4 * g + 3]} + cs2 * (f32x2_t){c4[2], c4[3]};
;         if (MASK) {
; #pragma unroll
;             for (int e = 0; e < 4; ++e) { const int kpos = kpos_sub + 8 * g + 4 * hh + e; const bool ok = (kpos <= qpos && kpos >= qpos - win);
;                 sp[2 * g + (e >> 1)][e & 1] = ok ? sp[2 * g + (e >> 1)][e & 1] : -INFINITY; } } }
;     float rm = fmaxf(sp[0][0], sp[0][1]);
; #pragma unroll
;     for (int i = 1; i < 8; ++i) rm = fmaxf(fmaxf(rm, sp[i][0]), sp[i][1]);
;     rm = swap_max(rm);
;     if (__any(rm - m > 8.0f)) { const float mnew = fmaxf(m, rm); const float f = fast_exp2(m - mnew); l *= f; o0 = o0 * f; o1 = o1 * f; m = mnew; }
.LBB0_684:
	s_mov_b64 s[18:19], -1
	s_cmp_lt_i32 s3, 4
	v_add_u32_e32 v169, v188, v180
	v_add_u32_e32 v168, v188, v181
	v_add_u32_e32 v167, v188, v182
	v_add_u32_e32 v35, v188, v183
	s_cbranch_scc1 .LBB0_689
	ds_read_b64_tr_b16 v[96:97], v194
	ds_read_b64_tr_b16 v[98:99], v194 offset:1024
	ds_read_b64_tr_b16 v[92:93], v196
	ds_read_b64_tr_b16 v[94:95], v196 offset:1024
	ds_read_b64_tr_b16 v[88:89], v194 offset:2048
	ds_read_b64_tr_b16 v[90:91], v194 offset:3072
	ds_read_b64_tr_b16 v[84:85], v196 offset:2048
	ds_read_b64_tr_b16 v[86:87], v196 offset:3072
	ds_read_b128 v[36:39], v169 offset:12288
	ds_read_b128 v[52:55], v168 offset:12288
	s_waitcnt lgkmcnt(0)
	v_mfma_f32_32x32x16_bf16 v[36:51], v[36:39], v[76:79], 0
	v_mfma_f32_32x32x16_bf16 v[36:51], v[52:55], v[68:71], v[36:51]
	ds_read_b128 v[52:55], v167 offset:12288
	s_waitcnt lgkmcnt(0)
	v_mfma_f32_32x32x16_bf16 v[36:51], v[52:55], v[72:75], v[36:51]
	ds_read_b128 v[52:55], v35 offset:12288
	s_waitcnt lgkmcnt(0)
	v_mfma_f32_32x32x16_bf16 v[36:51], v[52:55], v[80:83], v[36:51]
	ds_read_b128 v[52:55], v186 offset:49536
	ds_read_b128 v[56:59], v186 offset:49568
	s_waitcnt lgkmcnt(0)
	s_nop 8
	v_fma_f32 v160, v148, v52, v36
	v_fma_f32 v161, v149, v53, v37
	v_fma_f32 v158, v148, v54, v38
	v_fma_f32 v159, v149, v55, v39
	ds_read_b128 v[36:39], v186 offset:49600
	v_fma_f32 v152, v148, v56, v40
	v_fma_f32 v153, v149, v57, v41
	v_fma_f32 v150, v148, v58, v42
	v_fma_f32 v151, v149, v59, v43
	s_waitcnt lgkmcnt(0)
	v_fma_f32 v156, v148, v36, v44
	v_fma_f32 v157, v149, v37, v45
	v_fma_f32 v154, v148, v38, v46
	v_fma_f32 v155, v149, v39, v47
	ds_read_b128 v[36:39], v186 offset:49632
	s_waitcnt lgkmcnt(0)
	v_fma_f32 v162, v148, v36, v48
	v_fma_f32 v163, v149, v37, v49
	v_max_f32_e32 v36, v160, v161
	v_max3_f32 v36, v36, v158, v159
	v_max3_f32 v36, v36, v152, v153
	v_max3_f32 v36, v36, v150, v151
	v_max3_f32 v36, v36, v156, v157
	v_max3_f32 v36, v36, v154, v155
	v_fma_f32 v164, v148, v38, v50
	v_fma_f32 v165, v149, v39, v51
	v_max3_f32 v36, v36, v162, v163
	v_max3_f32 v36, v36, v164, v165
	v_mov_b32_e32 v37, v36
	s_nop 1
	v_permlane32_swap_b32_e32 v36, v37
	v_max_f32_e32 v37, v37, v37
	v_max_f32_e32 v36, v36, v36
	v_max_f32_e32 v36, v36, v37
	v_sub_f32_e32 v37, v36, v122
	v_cmp_lt_f32_e32 vcc, s9, v37
	s_cbranch_vccz .LBB0_687
	v_max_f32_e32 v36, v36, v36
	v_max_f32_e32 v37, v122, v122
	v_max_f32_e32 v170, v37, v36
	v_sub_f32_e32 v36, v122, v170
	v_exp_f32_e32 v52, v36
	v_mov_b32_e32 v166, v170
	v_mul_f32_e32 v197, v34, v52
	v_mul_f32_e32 v50, v32, v52
	v_mul_f32_e32 v51, v33, v52
	v_mul_f32_e32 v48, v30, v52
	v_mul_f32_e32 v49, v31, v52
	v_mul_f32_e32 v46, v28, v52
	v_mul_f32_e32 v47, v29, v52
	v_mul_f32_e32 v44, v26, v52
	v_mul_f32_e32 v45, v27, v52
	v_mul_f32_e32 v42, v24, v52
	v_mul_f32_e32 v43, v25, v52
	v_mul_f32_e32 v40, v22, v52
	v_mul_f32_e32 v41, v23, v52
	v_mul_f32_e32 v38, v20, v52
	v_mul_f32_e32 v39, v21, v52
	v_mul_f32_e32 v36, v18, v52
	v_mul_f32_e32 v37, v19, v52
	v_mul_f32_e32 v66, v16, v52
	v_mul_f32_e32 v67, v17, v52
	v_mul_f32_e32 v64, v14, v52
	v_mul_f32_e32 v65, v15, v52
	v_mul_f32_e32 v62, v12, v52
	v_mul_f32_e32 v63, v13, v52
	v_mul_f32_e32 v60, v10, v52
	v_mul_f32_e32 v61, v11, v52
	v_mul_f32_e32 v58, v8, v52
	v_mul_f32_e32 v59, v9, v52
	v_mul_f32_e32 v56, v6, v52
	v_mul_f32_e32 v57, v7, v52
	v_mul_f32_e32 v54, v4, v52
	v_mul_f32_e32 v55, v5, v52
	v_mul_f32_e32 v53, v3, v52
	v_mul_f32_e32 v52, v2, v52
	s_branch .LBB0_688

; __device__ __forceinline__ unsigned cvt_pk_bf16(float lo, float hi) { f32x2_t v = {lo, hi}; bf16x2_t b = __builtin_convertvector(v, bf16x2_t); return __builtin_bit_cast(unsigned, b); }
; __device__ __forceinline__ float fast_exp2(float x) { return __builtin_amdgcn_exp2f(x); }
; template <bool MASK> ...
;     ...
;     { const f32x2_t m2 = {m, m}; f32x2_t ps2 = {0.f, 0.f};
; #pragma unroll
;       for (int i = 0; i < 8; ++i) { f32x2_t t = sp[i] - m2; t[0] = fast_exp2(t[0]); t[1] = fast_exp2(t[1]); sp[i] = t; ps2 = ps2 + t; }
;       l += ps2[0] + ps2[1]; }
;     u32x4 pw0, pw1;
;     pw0.x = cvt_pk_bf16(sp[0][0], sp[0][1]); pw0.y = cvt_pk_bf16(sp[1][0], sp[1][1]); pw0.z = cvt_pk_bf16(sp[2][0], sp[2][1]); pw0.w = cvt_pk_bf16(sp[3][0], sp[3][1]);
;     pw1.x = cvt_pk_bf16(sp[4][0], sp[4][1]); pw1.y = cvt_pk_bf16(sp[5][0], sp[5][1]); pw1.z = cvt_pk_bf16(sp[6][0], sp[6][1]); pw1.w = cvt_pk_bf16(sp[7][0], sp[7][1]);
;     asm volatile("s_waitcnt lgkmcnt(0)" : "+v"(l00), "+v"(h00), "+v"(l01), "+v"(h01), "+v"(l10), "+v"(h10), "+v"(l11), "+v"(h11) :: "memory");
;     { const bf16x8 pb0 = __builtin_bit_cast(bf16x8, pw0), pb1 = __builtin_bit_cast(bf16x8, pw1);
;       const bf16x8 v00 = {l00[0], l00[1], l00[2], l00[3], h00[0], h00[1], h00[2], h00[3]}, v01 = {l01[0], l01[1], l01[2], l01[3], h01[0], h01[1], h01[2], h01[3]};
;       const bf16x8 v10 = {l10[0], l10[1], l10[2], l10[3], h10[0], h10[1], h10[2], h10[3]}, v11 = {l11[0], l11[1], l11[2], l11[3], h11[0], h11[1], h11[2], h11[3]};
;       o0 = __builtin_amdgcn_mfma_f32_32x32x16_bf16(v00, pb0, o0, 0, 0, 0); o1 = __builtin_amdgcn_mfma_f32_32x32x16_bf16(v01, pb0, o1, 0, 0, 0);
;       o0 = __builtin_amdgcn_mfma_f32_32x32x16_bf16(v10, pb1, o0, 0, 0, 0); o1 = __builtin_amdgcn_mfma_f32_32x32x16_bf16(v11, pb1, o1, 0, 0, 0); }
.LBB0_688:
	v_sub_f32_e32 v160, v160, v166
	v_sub_f32_e32 v161, v161, v166
	v_sub_f32_e32 v158, v158, v166
	v_sub_f32_e32 v159, v159, v166
	v_exp_f32_e32 v160, v160
	v_exp_f32_e32 v161, v161
	v_exp_f32_e32 v158, v158
	v_exp_f32_e32 v159, v159
	v_sub_f32_e32 v152, v152, v166
	v_sub_f32_e32 v153, v153, v166
	v_add_f32_e32 v198, 0, v160
	v_add_f32_e32 v199, 0, v161
	v_exp_f32_e32 v200, v152
	v_exp_f32_e32 v201, v153
	v_add_f32_e32 v198, v158, v198
	v_add_f32_e32 v199, v159, v199
	v_sub_f32_e32 v150, v150, v166
	v_sub_f32_e32 v151, v151, v166
	s_waitcnt lgkmcnt(0)
	v_add_f32_e32 v152, v200, v198
	v_add_f32_e32 v153, v201, v199
	v_exp_f32_e32 v198, v150
	v_exp_f32_e32 v199, v151
	s_mov_b64 s[18:19], 0
	v_add_f32_e32 v150, v198, v152
	v_add_f32_e32 v151, v199, v153
	v_sub_f32_e32 v152, v156, v166
	v_sub_f32_e32 v153, v157, v166
	s_nop 0
	v_exp_f32_e32 v156, v152
	v_exp_f32_e32 v157, v153
	v_sub_f32_e32 v152, v154, v166
	v_sub_f32_e32 v153, v155, v166
	v_cvt_pk_bf16_f32 v154, v200, v201
	v_exp_f32_e32 v202, v152
	v_exp_f32_e32 v203, v153
	v_sub_f32_e32 v152, v162, v166
	v_sub_f32_e32 v153, v163, v166
	v_cvt_pk_bf16_f32 v155, v198, v199
	v_exp_f32_e32 v162, v152
	v_exp_f32_e32 v163, v153
	v_sub_f32_e32 v152, v164, v166
	v_sub_f32_e32 v153, v165, v166
	v_add_f32_e32 v150, v156, v150
	v_add_f32_e32 v151, v157, v151
	v_exp_f32_e32 v164, v152
	v_exp_f32_e32 v165, v153
	v_cvt_pk_bf16_f32 v152, v160, v161
	v_cvt_pk_bf16_f32 v153, v158, v159
	v_cvt_pk_bf16_f32 v156, v156, v157
	v_cvt_pk_bf16_f32 v157, v202, v203
	v_mfma_f32_32x32x16_bf16 v[36:51], v[96:99], v[152:155], v[36:51]
	v_cvt_pk_bf16_f32 v158, v162, v163
	v_cvt_pk_bf16_f32 v159, v164, v165
	v_add_f32_e64 v150, v202, v150
	v_add_f32_e64 v151, v203, v151
	v_add_f32_e64 v150, v162, v150
	v_add_f32_e64 v151, v163, v151
	v_add_f32_e32 v150, v164, v150
	v_add_f32_e32 v151, v165, v151
	v_mfma_f32_32x32x16_bf16 v[52:67], v[92:95], v[152:155], v[52:67]
	v_add_f32_e32 v150, v150, v151
	v_add_f32_e32 v150, v197, v150
	v_mfma_f32_32x32x16_bf16 v[36:51], v[88:91], v[156:159], v[36:51]
	v_mfma_f32_32x32x16_bf16 v[52:67], v[84:87], v[156:159], v[52:67]
; #define LAS __attribute__((address_space(3)))
; template <bool MASK> ...
;     s16x4 l00, h00, l01, h01, l10, h10, l11, h11; { const unsigned a0 = va0 + sub * 4096, a1 = va1 + sub * 4096;
;       asm volatile("ds_read_b64_tr_b16 %0, %1" : "=&v"(l00) : "v"(a0) : "memory"); asm volatile("ds_read_b64_tr_b16 %0, %1 offset:1024" : "=&v"(h00) : "v"(a0) : "memory");
;       asm volatile("ds_read_b64_tr_b16 %0, %1" : "=&v"(l01) : "v"(a1) : "memory"); asm volatile("ds_read_b64_tr_b16 %0, %1 offset:1024" : "=&v"(h01) : "v"(a1) : "memory");
;       asm volatile("ds_read_b64_tr_b16 %0, %1 offset:2048" : "=&v"(l10) : "v"(a0) : "memory"); asm volatile("ds_read_b64_tr_b16 %0, %1 offset:3072" : "=&v"(h10) : "v"(a0) : "memory");
;       asm volatile("ds_read_b64_tr_b16 %0, %1 offset:2048" : "=&v"(l11) : "v"(a1) : "memory"); asm volatile("ds_read_b64_tr_b16 %0, %1 offset:3072" : "=&v"(h11) : "v"(a1) : "memory"); }
;     const int r = lane & 31, hh = lane >> 5;
;     f32x16 st = {0.f, 0.f, 0.f, 0.f, 0.f, 0.f, 0.f, 0.f, 0.f, 0.f, 0.f, 0.f, 0.f, 0.f, 0.f, 0.f};
;     { const int key = sub * 32 + r; const LAS char* kp = Kt + key * 128; const int ksw = (key >> 1) & 7;
; #pragma unroll
;       for (int d0 = 0; d0 < 4; ++d0) { const bf16x8 kf = *(const LAS bf16x8*)(kp + (((2 * d0 + hh) ^ ksw) << 4)); st = __builtin_amdgcn_mfma_f32_32x32x16_bf16(kf, qr[d0], st, 0, 0, 0); } }
;     f32x2_t sp[8]; const f32x2_t cs2 = {cscale, cscale};
; #pragma unroll
;     for (int g = 0; g < 4; ++g) { const f32x4 c4 = *(const LAS f32x4*)(cb + sub * 32 + 8 * g + 4 * hh);
;         sp[2 * g] = (f32x2_t){st[4 * g], st[4 * g + 1]} + cs2 * (f32x2_t){c4[0], c4[1]};
;         sp[2 * g + 1] = (f32x2_t){st[4 * g + 2], st[4 * g + 3]} + cs2 * (f32x2_t){c4[2], c4[3]};
;         if (MASK) {
; #pragma unroll
;             for (int e = 0; e < 4; ++e) { const int kpos = kpos_sub + 8 * g + 4 * hh + e; const bool ok = (kpos <= qpos && kpos >= qpos - win);
;                 sp[2 * g + (e >> 1)][e & 1] = ok ? sp[2 * g + (e >> 1)][e & 1] : -INFINITY; } } }
;     float rm = fmaxf(sp[0][0], sp[0][1]);
; #pragma unroll
;     for (int i = 1; i < 8; ++i) rm = fmaxf(fmaxf(rm, sp[i][0]), sp[i][1]);
;     rm = swap_max(rm);
;     if (__any(rm - m > 8.0f)) { const float mnew = fmaxf(m, rm); const float f = fast_exp2(m - mnew); l *= f; o0 = o0 * f; o1 = o1 * f; m = mnew; }
.LBB0_689:
	s_and_b64 vcc, exec, s[18:19]
	s_cbranch_vccz .LBB0_694
	ds_read_b64_tr_b16 v[64:65], v194
	ds_read_b64_tr_b16 v[66:67], v194 offset:1024
	ds_read_b64_tr_b16 v[60:61], v196
	ds_read_b64_tr_b16 v[62:63], v196 offset:1024
	ds_read_b64_tr_b16 v[56:57], v194 offset:2048
	ds_read_b64_tr_b16 v[58:59], v194 offset:3072
	ds_read_b64_tr_b16 v[52:53], v196 offset:2048
	ds_read_b64_tr_b16 v[54:55], v196 offset:3072
	s_nop 8
	ds_read_b128 v[36:39], v169 offset:12288
	ds_read_b128 v[84:87], v168 offset:12288
	s_waitcnt lgkmcnt(0)
	v_mfma_f32_32x32x16_bf16 v[36:51], v[36:39], v[76:79], 0
	v_mfma_f32_32x32x16_bf16 v[36:51], v[84:87], v[68:71], v[36:51]
	ds_read_b128 v[84:87], v167 offset:12288
	s_waitcnt lgkmcnt(0)
	v_mfma_f32_32x32x16_bf16 v[36:51], v[84:87], v[72:75], v[36:51]
	ds_read_b128 v[84:87], v35 offset:12288
	v_or_b32_e32 v35, s4, v100
	v_cmp_le_i32_e32 vcc, v35, v144
	v_cmp_ge_i32_e64 s[46:47], v35, v119
	s_and_b64 vcc, vcc, s[46:47]
	s_waitcnt lgkmcnt(0)
	v_mfma_f32_32x32x16_bf16 v[36:51], v[84:87], v[80:83], v[36:51]
	ds_read_b128 v[84:87], v186 offset:49536
	ds_read_b128 v[88:91], v186 offset:49568
	s_waitcnt lgkmcnt(0)
	s_nop 8
	v_fma_f32 v36, v148, v84, v36
	v_fma_f32 v37, v149, v85, v37
	v_or_b32_e32 v84, 1, v35
	v_cndmask_b32_e32 v36, v240, v36, vcc
	v_cmp_lt_i32_e32 vcc, v35, v144
	v_cmp_ge_i32_e64 s[46:47], v84, v119
	s_and_b64 vcc, vcc, s[46:47]
	v_or_b32_e32 v84, 2, v35
	v_cndmask_b32_e32 v37, v240, v37, vcc
	v_cmp_le_i32_e32 vcc, v84, v144
	v_cmp_ge_i32_e64 s[46:47], v84, v119
	v_fma_f32 v38, v148, v86, v38
	v_fma_f32 v39, v149, v87, v39
	s_and_b64 vcc, vcc, s[46:47]
	v_or_b32_e32 v84, 3, v35
	v_cndmask_b32_e32 v38, v240, v38, vcc
	v_cmp_le_i32_e32 vcc, v84, v144
	v_cmp_ge_i32_e64 s[46:47], v84, v119
	s_and_b64 vcc, vcc, s[46:47]
	v_or_b32_e32 v84, 8, v35
	v_cndmask_b32_e32 v39, v240, v39, vcc
	v_cmp_le_i32_e32 vcc, v84, v144
	v_cmp_ge_i32_e64 s[46:47], v84, v119
	v_fma_f32 v40, v148, v88, v40
	v_fma_f32 v41, v149, v89, v41
	s_and_b64 vcc, vcc, s[46:47]
	v_or_b32_e32 v84, 9, v35
	v_cndmask_b32_e32 v40, v240, v40, vcc
	v_cmp_le_i32_e32 vcc, v84, v144
	v_cmp_ge_i32_e64 s[46:47], v84, v119
	s_and_b64 vcc, vcc, s[46:47]
	v_or_b32_e32 v84, 10, v35
	v_cndmask_b32_e32 v41, v240, v41, vcc
	v_cmp_le_i32_e32 vcc, v84, v144
	v_cmp_ge_i32_e64 s[46:47], v84, v119
	v_fma_f32 v42, v148, v90, v42
	v_fma_f32 v43, v149, v91, v43
	s_and_b64 vcc, vcc, s[46:47]
	v_or_b32_e32 v84, 11, v35
	v_cndmask_b32_e32 v42, v240, v42, vcc
	v_cmp_le_i32_e32 vcc, v84, v144
	v_cmp_ge_i32_e64 s[46:47], v84, v119
	ds_read_b128 v[84:87], v186 offset:49600
	s_and_b64 vcc, vcc, s[46:47]
	v_cndmask_b32_e32 v43, v240, v43, vcc
	s_waitcnt lgkmcnt(0)
	v_fma_f32 v44, v148, v84, v44
	v_fma_f32 v45, v149, v85, v45
	v_or_b32_e32 v84, 16, v35
	v_cmp_le_i32_e32 vcc, v84, v144
	v_cmp_ge_i32_e64 s[46:47], v84, v119
	s_and_b64 vcc, vcc, s[46:47]
	v_or_b32_e32 v84, 17, v35
	v_cndmask_b32_e32 v44, v240, v44, vcc
	v_cmp_le_i32_e32 vcc, v84, v144
	v_cmp_ge_i32_e64 s[46:47], v84, v119
	s_and_b64 vcc, vcc, s[46:47]
	v_or_b32_e32 v84, 18, v35
	v_cndmask_b32_e32 v45, v240, v45, vcc
	v_cmp_le_i32_e32 vcc, v84, v144
	v_cmp_ge_i32_e64 s[46:47], v84, v119
	v_fma_f32 v46, v148, v86, v46
	v_fma_f32 v47, v149, v87, v47
	s_and_b64 vcc, vcc, s[46:47]
	v_or_b32_e32 v84, 19, v35
	v_cndmask_b32_e32 v46, v240, v46, vcc
	v_cmp_le_i32_e32 vcc, v84, v144
	v_cmp_ge_i32_e64 s[46:47], v84, v119
	ds_read_b128 v[84:87], v186 offset:49632
	s_and_b64 vcc, vcc, s[46:47]
	v_cndmask_b32_e32 v47, v240, v47, vcc
	s_waitcnt lgkmcnt(0)
	v_fma_f32 v48, v148, v84, v48
	v_fma_f32 v49, v149, v85, v49
	v_or_b32_e32 v84, 24, v35
	v_cmp_le_i32_e32 vcc, v84, v144
	v_cmp_ge_i32_e64 s[46:47], v84, v119
	s_and_b64 vcc, vcc, s[46:47]
	v_or_b32_e32 v84, 25, v35
	v_cndmask_b32_e32 v48, v240, v48, vcc
	v_cmp_le_i32_e32 vcc, v84, v144
	v_cmp_ge_i32_e64 s[46:47], v84, v119
	s_and_b64 vcc, vcc, s[46:47]
	v_or_b32_e32 v84, 26, v35
	v_cndmask_b32_e32 v49, v240, v49, vcc
	v_cmp_le_i32_e32 vcc, v84, v144
	v_cmp_ge_i32_e64 s[46:47], v84, v119
	v_fma_f32 v50, v148, v86, v50
	v_fma_f32 v51, v149, v87, v51
	s_and_b64 vcc, vcc, s[46:47]
	v_or_b32_e32 v35, 27, v35
	v_cndmask_b32_e32 v50, v240, v50, vcc
	v_cmp_le_i32_e32 vcc, v35, v144
	v_cmp_ge_i32_e64 s[46:47], v35, v119
	v_max_f32_e32 v35, v36, v37
	v_max3_f32 v35, v35, v38, v39
	v_max3_f32 v35, v35, v40, v41
	v_max3_f32 v35, v35, v42, v43
	v_max3_f32 v35, v35, v44, v45
	s_and_b64 vcc, vcc, s[46:47]
	v_max3_f32 v35, v35, v46, v47
	v_cndmask_b32_e32 v51, v240, v51, vcc
	v_max3_f32 v35, v35, v48, v49
	v_max3_f32 v35, v35, v50, v51
	v_mov_b32_e32 v84, v35
	s_nop 1
	v_permlane32_swap_b32_e32 v35, v84
	v_max_f32_e32 v84, v84, v84
	v_max_f32_e32 v35, v35, v35
	v_max_f32_e32 v35, v35, v84
	v_sub_f32_e32 v84, v35, v122
	v_cmp_lt_f32_e32 vcc, s9, v84
	s_cbranch_vccz .LBB0_692
	v_max_f32_e32 v35, v35, v35
	v_max_f32_e32 v84, v122, v122
	v_max_f32_e32 v84, v84, v35
	v_sub_f32_e32 v35, v122, v84
	v_exp_f32_e32 v86, v35
	v_mov_b32_e32 v122, v84
	v_mul_f32_e32 v34, v34, v86
	v_mul_f32_e32 v32, v32, v86
	v_mul_f32_e32 v33, v33, v86
	v_mul_f32_e32 v30, v30, v86
	v_mul_f32_e32 v31, v31, v86
	v_mul_f32_e32 v28, v28, v86
	v_mul_f32_e32 v29, v29, v86
	v_mul_f32_e32 v26, v26, v86
	v_mul_f32_e32 v27, v27, v86
	v_mul_f32_e32 v24, v24, v86
	v_mul_f32_e32 v25, v25, v86
	v_mul_f32_e32 v22, v22, v86
	v_mul_f32_e32 v23, v23, v86
	v_mul_f32_e32 v20, v20, v86
	v_mul_f32_e32 v21, v21, v86
	v_mul_f32_e32 v18, v18, v86
	v_mul_f32_e32 v19, v19, v86
	v_mul_f32_e32 v16, v16, v86
	v_mul_f32_e32 v17, v17, v86
	v_mul_f32_e32 v14, v14, v86
	v_mul_f32_e32 v15, v15, v86
	v_mul_f32_e32 v12, v12, v86
	v_mul_f32_e32 v13, v13, v86
	v_mul_f32_e32 v10, v10, v86
	v_mul_f32_e32 v11, v11, v86
	v_mul_f32_e32 v8, v8, v86
	v_mul_f32_e32 v9, v9, v86
	v_mul_f32_e32 v6, v6, v86
	v_mul_f32_e32 v7, v7, v86
	v_mul_f32_e32 v4, v4, v86
	v_mul_f32_e32 v5, v5, v86
	v_mul_f32_e32 v2, v2, v86
	v_mul_f32_e32 v3, v3, v86
	s_branch .LBB0_693

; __device__ __forceinline__ unsigned cvt_pk_bf16(float lo, float hi) { f32x2_t v = {lo, hi}; bf16x2_t b = __builtin_convertvector(v, bf16x2_t); return __builtin_bit_cast(unsigned, b); }
; __device__ __forceinline__ float fast_exp2(float x) { return __builtin_amdgcn_exp2f(x); }
; template <bool MASK> ...
;     ...
;     { const f32x2_t m2 = {m, m}; f32x2_t ps2 = {0.f, 0.f};
; #pragma unroll
;       for (int i = 0; i < 8; ++i) { f32x2_t t = sp[i] - m2; t[0] = fast_exp2(t[0]); t[1] = fast_exp2(t[1]); sp[i] = t; ps2 = ps2 + t; }
;       l += ps2[0] + ps2[1]; }
;     u32x4 pw0, pw1;
;     pw0.x = cvt_pk_bf16(sp[0][0], sp[0][1]); pw0.y = cvt_pk_bf16(sp[1][0], sp[1][1]); pw0.z = cvt_pk_bf16(sp[2][0], sp[2][1]); pw0.w = cvt_pk_bf16(sp[3][0], sp[3][1]);
;     pw1.x = cvt_pk_bf16(sp[4][0], sp[4][1]); pw1.y = cvt_pk_bf16(sp[5][0], sp[5][1]); pw1.z = cvt_pk_bf16(sp[6][0], sp[6][1]); pw1.w = cvt_pk_bf16(sp[7][0], sp[7][1]);
;     asm volatile("s_waitcnt lgkmcnt(0)" : "+v"(l00), "+v"(h00), "+v"(l01), "+v"(h01), "+v"(l10), "+v"(h10), "+v"(l11), "+v"(h11) :: "memory");
;     { const bf16x8 pb0 = __builtin_bit_cast(bf16x8, pw0), pb1 = __builtin_bit_cast(bf16x8, pw1);
;       const bf16x8 v00 = {l00[0], l00[1], l00[2], l00[3], h00[0], h00[1], h00[2], h00[3]}, v01 = {l01[0], l01[1], l01[2], l01[3], h01[0], h01[1], h01[2], h01[3]};
;       const bf16x8 v10 = {l10[0], l10[1], l10[2], l10[3], h10[0], h10[1], h10[2], h10[3]}, v11 = {l11[0], l11[1], l11[2], l11[3], h11[0], h11[1], h11[2], h11[3]};
;       o0 = __builtin_amdgcn_mfma_f32_32x32x16_bf16(v00, pb0, o0, 0, 0, 0); o1 = __builtin_amdgcn_mfma_f32_32x32x16_bf16(v01, pb0, o1, 0, 0, 0);
;       o0 = __builtin_amdgcn_mfma_f32_32x32x16_bf16(v10, pb1, o0, 0, 0, 0); o1 = __builtin_amdgcn_mfma_f32_32x32x16_bf16(v11, pb1, o1, 0, 0, 0); }
.LBB0_693:
	v_sub_f32_e32 v36, v36, v84
	v_sub_f32_e32 v37, v37, v84
	v_sub_f32_e32 v38, v38, v84
	v_sub_f32_e32 v39, v39, v84
	v_exp_f32_e32 v36, v36
	v_exp_f32_e32 v37, v37
	v_exp_f32_e32 v38, v38
	v_exp_f32_e32 v39, v39
	v_sub_f32_e32 v40, v40, v84
	v_sub_f32_e32 v41, v41, v84
	v_sub_f32_e32 v42, v42, v84
	v_sub_f32_e32 v43, v43, v84
	v_exp_f32_e32 v40, v40
	v_exp_f32_e32 v41, v41
	v_exp_f32_e32 v42, v42
	v_exp_f32_e32 v43, v43
	v_sub_f32_e32 v44, v44, v84
	v_sub_f32_e32 v45, v45, v84
	v_add_f32_e32 v86, 0, v36
	v_add_f32_e32 v87, 0, v37
	v_exp_f32_e32 v44, v44
	v_exp_f32_e32 v45, v45
	v_sub_f32_e32 v46, v46, v84
	v_sub_f32_e32 v47, v47, v84
	v_add_f32_e32 v86, v38, v86
	v_add_f32_e32 v87, v39, v87
	v_exp_f32_e32 v46, v46
	v_exp_f32_e32 v47, v47
	v_sub_f32_e32 v48, v48, v84
	v_sub_f32_e32 v49, v49, v84
	v_add_f32_e32 v86, v40, v86
	v_add_f32_e32 v87, v41, v87
	v_exp_f32_e32 v48, v48
	v_exp_f32_e32 v49, v49
	v_sub_f32_e32 v50, v50, v84
	v_sub_f32_e32 v51, v51, v84
	v_add_f32_e32 v86, v42, v86
	v_add_f32_e32 v87, v43, v87
	v_exp_f32_e32 v50, v50
	v_exp_f32_e32 v51, v51
	v_add_f32_e32 v86, v44, v86
	v_add_f32_e32 v87, v45, v87
	s_waitcnt lgkmcnt(0)
	v_mov_b32_e32 v170, v122
	v_add_f32_e32 v86, v46, v86
	v_add_f32_e32 v87, v47, v87
	s_nop 0
	v_add_f32_e32 v86, v48, v86
	v_add_f32_e32 v87, v49, v87
	s_nop 0
	v_add_f32_e32 v84, v50, v86
	v_add_f32_e32 v85, v51, v87
	s_nop 0
	v_add_f32_e32 v35, v84, v85
	v_add_f32_e32 v150, v34, v35
	v_cvt_pk_bf16_f32 v34, v36, v37
	v_cvt_pk_bf16_f32 v35, v38, v39
	v_cvt_pk_bf16_f32 v36, v40, v41
	v_cvt_pk_bf16_f32 v37, v42, v43
	v_cvt_pk_bf16_f32 v38, v44, v45
	v_cvt_pk_bf16_f32 v39, v46, v47
	v_mfma_f32_32x32x16_bf16 v[18:33], v[64:67], v[34:37], v[18:33]
	v_cvt_pk_bf16_f32 v40, v48, v49
	v_cvt_pk_bf16_f32 v41, v50, v51
	v_mfma_f32_32x32x16_bf16 v[2:17], v[60:63], v[34:37], v[2:17]
	s_nop 0
	v_mfma_f32_32x32x16_bf16 v[18:33], v[56:59], v[38:41], v[18:33]
	v_mfma_f32_32x32x16_bf16 v[2:17], v[52:55], v[38:41], v[2:17]
	s_nop 10
	v_mov_b64_e32 v[50:51], v[32:33]
	v_mov_b64_e32 v[48:49], v[30:31]
	v_mov_b64_e32 v[46:47], v[28:29]
	v_mov_b64_e32 v[44:45], v[26:27]
	v_mov_b64_e32 v[42:43], v[24:25]
	v_mov_b64_e32 v[40:41], v[22:23]
	v_mov_b64_e32 v[38:39], v[20:21]
	v_mov_b64_e32 v[66:67], v[16:17]
	v_mov_b64_e32 v[64:65], v[14:15]
	v_mov_b64_e32 v[62:63], v[12:13]
	v_mov_b64_e32 v[60:61], v[10:11]
	v_mov_b64_e32 v[58:59], v[8:9]
	v_mov_b64_e32 v[56:57], v[6:7]
	v_mov_b64_e32 v[54:55], v[4:5]
	v_mov_b64_e32 v[52:53], v[2:3]
	v_mov_b64_e32 v[36:37], v[18:19]

; __device__ __forceinline__ unsigned cvt_pk_bf16(float lo, float hi) { f32x2_t v = {lo, hi}; bf16x2_t b = __builtin_convertvector(v, bf16x2_t); return __builtin_bit_cast(unsigned, b); }
; __device__ __forceinline__ float fast_exp2(float x) { return __builtin_amdgcn_exp2f(x); }
; template <bool MASK> ...
;     ...
;     { const f32x2_t m2 = {m, m}; f32x2_t ps2 = {0.f, 0.f};
; #pragma unroll
;       for (int i = 0; i < 8; ++i) { f32x2_t t = sp[i] - m2; t[0] = fast_exp2(t[0]); t[1] = fast_exp2(t[1]); sp[i] = t; ps2 = ps2 + t; }
;       l += ps2[0] + ps2[1]; }
;     u32x4 pw0, pw1;
;     pw0.x = cvt_pk_bf16(sp[0][0], sp[0][1]); pw0.y = cvt_pk_bf16(sp[1][0], sp[1][1]); pw0.z = cvt_pk_bf16(sp[2][0], sp[2][1]); pw0.w = cvt_pk_bf16(sp[3][0], sp[3][1]);
;     pw1.x = cvt_pk_bf16(sp[4][0], sp[4][1]); pw1.y = cvt_pk_bf16(sp[5][0], sp[5][1]); pw1.z = cvt_pk_bf16(sp[6][0], sp[6][1]); pw1.w = cvt_pk_bf16(sp[7][0], sp[7][1]);
;     asm volatile("s_waitcnt lgkmcnt(0)" : "+v"(l00), "+v"(h00), "+v"(l01), "+v"(h01), "+v"(l10), "+v"(h10), "+v"(l11), "+v"(h11) :: "memory");
;     { const bf16x8 pb0 = __builtin_bit_cast(bf16x8, pw0), pb1 = __builtin_bit_cast(bf16x8, pw1);
;       const bf16x8 v00 = {l00[0], l00[1], l00[2], l00[3], h00[0], h00[1], h00[2], h00[3]}, v01 = {l01[0], l01[1], l01[2], l01[3], h01[0], h01[1], h01[2], h01[3]};
;       const bf16x8 v10 = {l10[0], l10[1], l10[2], l10[3], h10[0], h10[1], h10[2], h10[3]}, v11 = {l11[0], l11[1], l11[2], l11[3], h11[0], h11[1], h11[2], h11[3]};
;       o0 = __builtin_amdgcn_mfma_f32_32x32x16_bf16(v00, pb0, o0, 0, 0, 0); o1 = __builtin_amdgcn_mfma_f32_32x32x16_bf16(v01, pb0, o1, 0, 0, 0);
;       o0 = __builtin_amdgcn_mfma_f32_32x32x16_bf16(v10, pb1, o0, 0, 0, 0); o1 = __builtin_amdgcn_mfma_f32_32x32x16_bf16(v11, pb1, o1, 0, 0, 0); }
.LBB0_697:
	v_sub_f32_e32 v36, v36, v84
	v_sub_f32_e32 v37, v37, v84
	v_sub_f32_e32 v38, v38, v84
	v_sub_f32_e32 v39, v39, v84
	v_exp_f32_e32 v36, v36
	v_exp_f32_e32 v37, v37
	v_exp_f32_e32 v38, v38
	v_exp_f32_e32 v39, v39
	v_sub_f32_e32 v40, v40, v84
	v_sub_f32_e32 v41, v41, v84
	v_sub_f32_e32 v42, v42, v84
	v_sub_f32_e32 v43, v43, v84
	v_exp_f32_e32 v40, v40
	v_exp_f32_e32 v41, v41
	v_exp_f32_e32 v42, v42
	v_exp_f32_e32 v43, v43
	v_sub_f32_e32 v44, v44, v84
	v_sub_f32_e32 v45, v45, v84
	v_add_f32_e32 v86, 0, v36
	v_add_f32_e32 v87, 0, v37
	v_exp_f32_e32 v44, v44
	v_exp_f32_e32 v45, v45
	v_sub_f32_e32 v46, v46, v84
	v_sub_f32_e32 v47, v47, v84
	v_add_f32_e32 v86, v38, v86
	v_add_f32_e32 v87, v39, v87
	v_exp_f32_e32 v46, v46
	v_exp_f32_e32 v47, v47
	v_sub_f32_e32 v48, v48, v84
	v_sub_f32_e32 v49, v49, v84
	v_add_f32_e32 v86, v40, v86
	v_add_f32_e32 v87, v41, v87
	v_exp_f32_e32 v48, v48
	v_exp_f32_e32 v49, v49
	v_sub_f32_e32 v50, v50, v84
	v_sub_f32_e32 v51, v51, v84
	v_add_f32_e32 v86, v42, v86
	v_add_f32_e32 v87, v43, v87
	v_exp_f32_e32 v50, v50
	v_exp_f32_e32 v51, v51
	v_add_f32_e32 v86, v44, v86
	v_add_f32_e32 v87, v45, v87
	s_waitcnt lgkmcnt(0)
	v_mov_b32_e32 v198, v122
	v_add_f32_e32 v86, v46, v86
	v_add_f32_e32 v87, v47, v87
	s_nop 0
	v_add_f32_e32 v86, v48, v86
	v_add_f32_e32 v87, v49, v87
	s_nop 0
	v_add_f32_e32 v84, v50, v86
	v_add_f32_e32 v85, v51, v87
	s_nop 0
	v_add_f32_e32 v35, v84, v85
	v_add_f32_e32 v150, v34, v35
	v_cvt_pk_bf16_f32 v34, v36, v37
	v_cvt_pk_bf16_f32 v35, v38, v39
	v_cvt_pk_bf16_f32 v36, v40, v41
	v_cvt_pk_bf16_f32 v37, v42, v43
	v_cvt_pk_bf16_f32 v38, v44, v45
	v_cvt_pk_bf16_f32 v39, v46, v47
	v_mfma_f32_32x32x16_bf16 v[18:33], v[64:67], v[34:37], v[18:33]
	v_cvt_pk_bf16_f32 v40, v48, v49
	v_cvt_pk_bf16_f32 v41, v50, v51
	v_mfma_f32_32x32x16_bf16 v[2:17], v[60:63], v[34:37], v[2:17]
	s_nop 0
	v_mfma_f32_32x32x16_bf16 v[18:33], v[56:59], v[38:41], v[18:33]
	v_mfma_f32_32x32x16_bf16 v[2:17], v[52:55], v[38:41], v[2:17]
	s_nop 10
	v_mov_b64_e32 v[50:51], v[32:33]
	v_mov_b64_e32 v[48:49], v[30:31]
	v_mov_b64_e32 v[46:47], v[28:29]
	v_mov_b64_e32 v[44:45], v[26:27]
	v_mov_b64_e32 v[42:43], v[24:25]
	v_mov_b64_e32 v[40:41], v[22:23]
	v_mov_b64_e32 v[38:39], v[20:21]
	v_mov_b64_e32 v[66:67], v[16:17]
	v_mov_b64_e32 v[36:37], v[18:19]
	v_mov_b64_e32 v[64:65], v[14:15]
	v_mov_b64_e32 v[62:63], v[12:13]
	v_mov_b64_e32 v[60:61], v[10:11]
	v_mov_b64_e32 v[58:59], v[8:9]
	v_mov_b64_e32 v[56:57], v[6:7]
	v_mov_b64_e32 v[54:55], v[4:5]
	v_mov_b64_e32 v[52:53], v[2:3]

; #define LAS __attribute__((address_space(3)))
; __device__ __forceinline__ float fast_exp2(float x) { return __builtin_amdgcn_exp2f(x); }
; __device__ __forceinline__ float swap_max(float v) { auto rr = __builtin_amdgcn_permlane32_swap(__float_as_uint(v), __float_as_uint(v), false, false); return fmaxf(__uint_as_float(rr[0]), __uint_as_float(rr[1])); }
; template <bool MASK> ...
;     ...
;     { const int key = sub * 32 + r; const LAS char* kp = Kt + key * 128; const int ksw = (key >> 1) & 7;
; #pragma unroll
;       for (int d0 = 0; d0 < 4; ++d0) { const bf16x8 kf = *(const LAS bf16x8*)(kp + (((2 * d0 + hh) ^ ksw) << 4)); st = __builtin_amdgcn_mfma_f32_32x32x16_bf16(kf, qr[d0], st, 0, 0, 0); } }
;     f32x2_t sp[8]; const f32x2_t cs2 = {cscale, cscale};
; #pragma unroll
;     for (int g = 0; g < 4; ++g) { const f32x4 c4 = *(const LAS f32x4*)(cb + sub * 32 + 8 * g + 4 * hh);
;         sp[2 * g] = (f32x2_t){st[4 * g], st[4 * g + 1]} + cs2 * (f32x2_t){c4[0], c4[1]};
;         sp[2 * g + 1] = (f32x2_t){st[4 * g + 2], st[4 * g + 3]} + cs2 * (f32x2_t){c4[2], c4[3]};
;         if (MASK) {
; #pragma unroll
;             for (int e = 0; e < 4; ++e) { const int kpos = kpos_sub + 8 * g + 4 * hh + e; const bool ok = (kpos <= qpos && kpos >= qpos - win);
;                 sp[2 * g + (e >> 1)][e & 1] = ok ? sp[2 * g + (e >> 1)][e & 1] : -INFINITY; } } }
;     float rm = fmaxf(sp[0][0], sp[0][1]);
; #pragma unroll
;     for (int i = 1; i < 8; ++i) rm = fmaxf(fmaxf(rm, sp[i][0]), sp[i][1]);
;     rm = swap_max(rm);
;     if (__any(rm - m > 8.0f)) { const float mnew = fmaxf(m, rm); const float f = fast_exp2(m - mnew); l *= f; o0 = o0 * f; o1 = o1 * f; m = mnew; }
; __device__ __forceinline__ void moba_own_unit(LAS char* lds, int bh, int jblk, const bf16_t* H, const bf16_t* PO, const float* PML, bf16_t* U, int tid) {
;     ...
;         for (int sub = 0; sub < 2; ++sub) { const int kss = ks + 32 * sub;
;             if (kss <= qmin + 31) { if (kss + 31 <= qmin) attn_sub<false>(Kt, vb0, vb1, cb, sub, qr, o0, o1, m, l, lane, slope2, qpos, 1 << 30, kss); else attn_sub<true>(Kt, vb0, vb1, cb, sub, qr, o0, o1, m, l, lane, slope2, qpos, 1 << 30, kss); } }
.LBB0_703:
	s_lshl_b32 s11, s3, 6
	s_and_b64 s[4:5], exec, s[18:19]
	s_cselect_b32 s3, 0, s3
	s_lshl_b32 s4, s3, 13
	s_add_i32 s5, s4, 0
	s_mulk_i32 s3, 0xe100
	v_add_u32_e32 v197, s4, v178
	v_add_u32_e32 v198, s4, v179
	s_add_i32 s3, s5, s3
	s_or_b32 s4, s11, s24
	v_add_u32_e32 v36, s5, v187
	v_lshl_add_u32 v35, v100, 2, s3
	s_cmp_gt_i32 s4, s36
	v_add_u32_e32 v170, v36, v180
	v_add_u32_e32 v169, v36, v181
	v_add_u32_e32 v168, v36, v182
	v_add_u32_e32 v167, v36, v183
	s_cbranch_scc1 .LBB0_707
	s_or_b32 s5, s4, 31
	s_cmp_gt_i32 s5, s25
	s_mov_b64 s[28:29], -1
	s_cbranch_scc1 .LBB0_713
	ds_read_b64_tr_b16 v[96:97], v197
	ds_read_b64_tr_b16 v[98:99], v197 offset:1024
	ds_read_b64_tr_b16 v[92:93], v198
	ds_read_b64_tr_b16 v[94:95], v198 offset:1024
	ds_read_b64_tr_b16 v[88:89], v197 offset:2048
	ds_read_b64_tr_b16 v[90:91], v197 offset:3072
	ds_read_b64_tr_b16 v[84:85], v198 offset:2048
	ds_read_b64_tr_b16 v[86:87], v198 offset:3072
	ds_read_b128 v[36:39], v170
	ds_read_b128 v[52:55], v169
	v_add_u32_e32 v60, s3, v184
	s_waitcnt lgkmcnt(0)
	v_mfma_f32_32x32x16_bf16 v[36:51], v[36:39], v[76:79], 0
	v_mfma_f32_32x32x16_bf16 v[36:51], v[52:55], v[68:71], v[36:51]
	ds_read_b128 v[52:55], v168
	s_waitcnt lgkmcnt(0)
	v_mfma_f32_32x32x16_bf16 v[36:51], v[52:55], v[72:75], v[36:51]
	ds_read_b128 v[52:55], v167
	s_waitcnt lgkmcnt(0)
	v_mfma_f32_32x32x16_bf16 v[36:51], v[52:55], v[80:83], v[36:51]
	ds_read_b128 v[52:55], v60 offset:49152
	ds_read_b128 v[56:59], v60 offset:49184
	s_waitcnt lgkmcnt(0)
	s_nop 8
	v_fma_f32 v160, v148, v52, v36
	v_fma_f32 v161, v149, v53, v37
	v_fma_f32 v158, v148, v54, v38
	v_fma_f32 v159, v149, v55, v39
	ds_read_b128 v[36:39], v60 offset:49216
	v_fma_f32 v152, v148, v56, v40
	v_fma_f32 v153, v149, v57, v41
	v_fma_f32 v150, v148, v58, v42
	v_fma_f32 v151, v149, v59, v43
	s_waitcnt lgkmcnt(0)
	v_fma_f32 v156, v148, v36, v44
	v_fma_f32 v157, v149, v37, v45
	v_fma_f32 v154, v148, v38, v46
	v_fma_f32 v155, v149, v39, v47
	ds_read_b128 v[36:39], v60 offset:49248
	s_waitcnt lgkmcnt(0)
	v_fma_f32 v162, v148, v36, v48
	v_fma_f32 v163, v149, v37, v49
	v_max_f32_e32 v36, v160, v161
	v_max3_f32 v36, v36, v158, v159
	v_max3_f32 v36, v36, v152, v153
	v_max3_f32 v36, v36, v150, v151
	v_max3_f32 v36, v36, v156, v157
	v_max3_f32 v36, v36, v154, v155
	v_fma_f32 v164, v148, v38, v50
	v_fma_f32 v165, v149, v39, v51
	v_max3_f32 v36, v36, v162, v163
	v_max3_f32 v36, v36, v164, v165
	v_mov_b32_e32 v37, v36
	s_nop 1
	v_permlane32_swap_b32_e32 v36, v37
	v_max_f32_e32 v37, v37, v37
	v_max_f32_e32 v36, v36, v36
	v_max_f32_e32 v36, v36, v37
	v_sub_f32_e32 v37, v36, v122
	v_cmp_lt_f32_e32 vcc, s9, v37
	s_cbranch_vccz .LBB0_711
	v_max_f32_e32 v36, v36, v36
	v_max_f32_e32 v37, v122, v122
	v_max_f32_e32 v199, v37, v36
	v_sub_f32_e32 v36, v122, v199
	v_exp_f32_e32 v52, v36
	v_mov_b32_e32 v166, v199
	v_mul_f32_e32 v200, v34, v52
	v_mul_f32_e32 v50, v32, v52
	v_mul_f32_e32 v51, v33, v52
	v_mul_f32_e32 v48, v30, v52
	v_mul_f32_e32 v49, v31, v52
	v_mul_f32_e32 v46, v28, v52
	v_mul_f32_e32 v47, v29, v52
	v_mul_f32_e32 v44, v26, v52
	v_mul_f32_e32 v45, v27, v52
	v_mul_f32_e32 v42, v24, v52
	v_mul_f32_e32 v43, v25, v52
	v_mul_f32_e32 v40, v22, v52
	v_mul_f32_e32 v41, v23, v52
	v_mul_f32_e32 v38, v20, v52
	v_mul_f32_e32 v39, v21, v52
	v_mul_f32_e32 v36, v18, v52
	v_mul_f32_e32 v37, v19, v52
	v_mul_f32_e32 v66, v16, v52
	v_mul_f32_e32 v67, v17, v52
	v_mul_f32_e32 v64, v14, v52
	v_mul_f32_e32 v65, v15, v52
	v_mul_f32_e32 v62, v12, v52
	v_mul_f32_e32 v63, v13, v52
	v_mul_f32_e32 v60, v10, v52
	v_mul_f32_e32 v61, v11, v52
	v_mul_f32_e32 v58, v8, v52
	v_mul_f32_e32 v59, v9, v52
	v_mul_f32_e32 v56, v6, v52
	v_mul_f32_e32 v57, v7, v52
	v_mul_f32_e32 v54, v4, v52
	v_mul_f32_e32 v55, v5, v52
	v_mul_f32_e32 v53, v3, v52
	v_mul_f32_e32 v52, v2, v52
	s_branch .LBB0_712

; #define LAS __attribute__((address_space(3)))
; __device__ __forceinline__ float fast_exp2(float x) { return __builtin_amdgcn_exp2f(x); }
; __device__ __forceinline__ float swap_max(float v) { auto rr = __builtin_amdgcn_permlane32_swap(__float_as_uint(v), __float_as_uint(v), false, false); return fmaxf(__uint_as_float(rr[0]), __uint_as_float(rr[1])); }
; template <bool MASK> ...
;     ...
;     { const int key = sub * 32 + r; const LAS char* kp = Kt + key * 128; const int ksw = (key >> 1) & 7;
; #pragma unroll
;       for (int d0 = 0; d0 < 4; ++d0) { const bf16x8 kf = *(const LAS bf16x8*)(kp + (((2 * d0 + hh) ^ ksw) << 4)); st = __builtin_amdgcn_mfma_f32_32x32x16_bf16(kf, qr[d0], st, 0, 0, 0); } }
;     f32x2_t sp[8]; const f32x2_t cs2 = {cscale, cscale};
; #pragma unroll
;     for (int g = 0; g < 4; ++g) { const f32x4 c4 = *(const LAS f32x4*)(cb + sub * 32 + 8 * g + 4 * hh);
;         sp[2 * g] = (f32x2_t){st[4 * g], st[4 * g + 1]} + cs2 * (f32x2_t){c4[0], c4[1]};
;         sp[2 * g + 1] = (f32x2_t){st[4 * g + 2], st[4 * g + 3]} + cs2 * (f32x2_t){c4[2], c4[3]};
;         if (MASK) {
; #pragma unroll
;             for (int e = 0; e < 4; ++e) { const int kpos = kpos_sub + 8 * g + 4 * hh + e; const bool ok = (kpos <= qpos && kpos >= qpos - win);
;                 sp[2 * g + (e >> 1)][e & 1] = ok ? sp[2 * g + (e >> 1)][e & 1] : -INFINITY; } } }
;     float rm = fmaxf(sp[0][0], sp[0][1]);
; #pragma unroll
;     for (int i = 1; i < 8; ++i) rm = fmaxf(fmaxf(rm, sp[i][0]), sp[i][1]);
;     rm = swap_max(rm);
;     if (__any(rm - m > 8.0f)) { const float mnew = fmaxf(m, rm); const float f = fast_exp2(m - mnew); l *= f; o0 = o0 * f; o1 = o1 * f; m = mnew; }
.LBB0_708:
	s_or_b32 s4, s4, 63
	s_cmp_gt_i32 s4, s25
	v_add_u32_e32 v199, 0x1000, v197
	v_add_u32_e32 v197, 0x1000, v198
	s_mov_b64 s[28:29], -1
	s_cbranch_scc1 .LBB0_718
	ds_read_b64_tr_b16 v[96:97], v199
	ds_read_b64_tr_b16 v[98:99], v199 offset:1024
	ds_read_b64_tr_b16 v[92:93], v197
	ds_read_b64_tr_b16 v[94:95], v197 offset:1024
	ds_read_b64_tr_b16 v[88:89], v199 offset:2048
	ds_read_b64_tr_b16 v[90:91], v199 offset:3072
	ds_read_b64_tr_b16 v[84:85], v197 offset:2048
	ds_read_b64_tr_b16 v[86:87], v197 offset:3072
	ds_read_b128 v[36:39], v170 offset:4096
	ds_read_b128 v[52:55], v169 offset:4096
	v_add_u32_e32 v60, s3, v184
	s_waitcnt lgkmcnt(0)
	v_mfma_f32_32x32x16_bf16 v[36:51], v[36:39], v[76:79], 0
	v_mfma_f32_32x32x16_bf16 v[36:51], v[52:55], v[68:71], v[36:51]
	ds_read_b128 v[52:55], v168 offset:4096
	s_waitcnt lgkmcnt(0)
	v_mfma_f32_32x32x16_bf16 v[36:51], v[52:55], v[72:75], v[36:51]
	ds_read_b128 v[52:55], v167 offset:4096
	s_waitcnt lgkmcnt(0)
	v_mfma_f32_32x32x16_bf16 v[36:51], v[52:55], v[80:83], v[36:51]
	ds_read_b128 v[52:55], v60 offset:49280
	ds_read_b128 v[56:59], v60 offset:49312
	s_waitcnt lgkmcnt(0)
	s_nop 8
	v_fma_f32 v160, v148, v52, v36
	v_fma_f32 v161, v149, v53, v37
	v_fma_f32 v158, v148, v54, v38
	v_fma_f32 v159, v149, v55, v39
	ds_read_b128 v[36:39], v60 offset:49344
	v_fma_f32 v152, v148, v56, v40
	v_fma_f32 v153, v149, v57, v41
	v_fma_f32 v150, v148, v58, v42
	v_fma_f32 v151, v149, v59, v43
	s_waitcnt lgkmcnt(0)
	v_fma_f32 v156, v148, v36, v44
	v_fma_f32 v157, v149, v37, v45
	v_fma_f32 v154, v148, v38, v46
	v_fma_f32 v155, v149, v39, v47
	ds_read_b128 v[36:39], v60 offset:49376
	s_waitcnt lgkmcnt(0)
	v_fma_f32 v162, v148, v36, v48
	v_fma_f32 v163, v149, v37, v49
	v_max_f32_e32 v36, v160, v161
	v_max3_f32 v36, v36, v158, v159
	v_max3_f32 v36, v36, v152, v153
	v_max3_f32 v36, v36, v150, v151
	v_max3_f32 v36, v36, v156, v157
	v_max3_f32 v36, v36, v154, v155
	v_fma_f32 v164, v148, v38, v50
	v_fma_f32 v165, v149, v39, v51
	v_max3_f32 v36, v36, v162, v163
	v_max3_f32 v36, v36, v164, v165
	v_mov_b32_e32 v37, v36
	s_nop 1
	v_permlane32_swap_b32_e32 v36, v37
	v_max_f32_e32 v37, v37, v37
	v_max_f32_e32 v36, v36, v36
	v_max_f32_e32 v36, v36, v37
	v_sub_f32_e32 v37, v36, v122
	v_cmp_lt_f32_e32 vcc, s9, v37
	s_cbranch_vccz .LBB0_716
	v_max_f32_e32 v36, v36, v36
	v_max_f32_e32 v37, v122, v122
	v_max_f32_e32 v198, v37, v36
	v_sub_f32_e32 v36, v122, v198
	v_exp_f32_e32 v52, v36
	v_mov_b32_e32 v166, v198
	v_mul_f32_e32 v200, v34, v52
	v_mul_f32_e32 v50, v32, v52
	v_mul_f32_e32 v51, v33, v52
	v_mul_f32_e32 v48, v30, v52
	v_mul_f32_e32 v49, v31, v52
	v_mul_f32_e32 v46, v28, v52
	v_mul_f32_e32 v47, v29, v52
	v_mul_f32_e32 v44, v26, v52
	v_mul_f32_e32 v45, v27, v52
	v_mul_f32_e32 v42, v24, v52
	v_mul_f32_e32 v43, v25, v52
	v_mul_f32_e32 v40, v22, v52
	v_mul_f32_e32 v41, v23, v52
	v_mul_f32_e32 v38, v20, v52
	v_mul_f32_e32 v39, v21, v52
	v_mul_f32_e32 v36, v18, v52
	v_mul_f32_e32 v37, v19, v52
	v_mul_f32_e32 v66, v16, v52
	v_mul_f32_e32 v67, v17, v52
	v_mul_f32_e32 v64, v14, v52
	v_mul_f32_e32 v65, v15, v52
	v_mul_f32_e32 v62, v12, v52
	v_mul_f32_e32 v63, v13, v52
	v_mul_f32_e32 v60, v10, v52
	v_mul_f32_e32 v61, v11, v52
	v_mul_f32_e32 v58, v8, v52
	v_mul_f32_e32 v59, v9, v52
	v_mul_f32_e32 v56, v6, v52
	v_mul_f32_e32 v57, v7, v52
	v_mul_f32_e32 v54, v4, v52
	v_mul_f32_e32 v55, v5, v52
	v_mul_f32_e32 v53, v3, v52
	v_mul_f32_e32 v52, v2, v52
	s_branch .LBB0_717

; __device__ __forceinline__ unsigned cvt_pk_bf16(float lo, float hi) { f32x2_t v = {lo, hi}; bf16x2_t b = __builtin_convertvector(v, bf16x2_t); return __builtin_bit_cast(unsigned, b); }
; __device__ __forceinline__ float fast_exp2(float x) { return __builtin_amdgcn_exp2f(x); }
; template <bool MASK> ...
;     ...
;     { const f32x2_t m2 = {m, m}; f32x2_t ps2 = {0.f, 0.f};
; #pragma unroll
;       for (int i = 0; i < 8; ++i) { f32x2_t t = sp[i] - m2; t[0] = fast_exp2(t[0]); t[1] = fast_exp2(t[1]); sp[i] = t; ps2 = ps2 + t; }
;       l += ps2[0] + ps2[1]; }
;     u32x4 pw0, pw1;
;     pw0.x = cvt_pk_bf16(sp[0][0], sp[0][1]); pw0.y = cvt_pk_bf16(sp[1][0], sp[1][1]); pw0.z = cvt_pk_bf16(sp[2][0], sp[2][1]); pw0.w = cvt_pk_bf16(sp[3][0], sp[3][1]);
;     pw1.x = cvt_pk_bf16(sp[4][0], sp[4][1]); pw1.y = cvt_pk_bf16(sp[5][0], sp[5][1]); pw1.z = cvt_pk_bf16(sp[6][0], sp[6][1]); pw1.w = cvt_pk_bf16(sp[7][0], sp[7][1]);
;     asm volatile("s_waitcnt lgkmcnt(0)" : "+v"(l00), "+v"(h00), "+v"(l01), "+v"(h01), "+v"(l10), "+v"(h10), "+v"(l11), "+v"(h11) :: "memory");
;     { const bf16x8 pb0 = __builtin_bit_cast(bf16x8, pw0), pb1 = __builtin_bit_cast(bf16x8, pw1);
;       const bf16x8 v00 = {l00[0], l00[1], l00[2], l00[3], h00[0], h00[1], h00[2], h00[3]}, v01 = {l01[0], l01[1], l01[2], l01[3], h01[0], h01[1], h01[2], h01[3]};
;       const bf16x8 v10 = {l10[0], l10[1], l10[2], l10[3], h10[0], h10[1], h10[2], h10[3]}, v11 = {l11[0], l11[1], l11[2], l11[3], h11[0], h11[1], h11[2], h11[3]};
;       o0 = __builtin_amdgcn_mfma_f32_32x32x16_bf16(v00, pb0, o0, 0, 0, 0); o1 = __builtin_amdgcn_mfma_f32_32x32x16_bf16(v01, pb0, o1, 0, 0, 0);
;       o0 = __builtin_amdgcn_mfma_f32_32x32x16_bf16(v10, pb1, o0, 0, 0, 0); o1 = __builtin_amdgcn_mfma_f32_32x32x16_bf16(v11, pb1, o1, 0, 0, 0); }
.LBB0_712:
	v_sub_f32_e32 v160, v160, v166
	v_sub_f32_e32 v161, v161, v166
	v_sub_f32_e32 v158, v158, v166
	v_sub_f32_e32 v159, v159, v166
	v_exp_f32_e32 v160, v160
	v_exp_f32_e32 v161, v161
	v_exp_f32_e32 v158, v158
	v_exp_f32_e32 v159, v159
	v_sub_f32_e32 v152, v152, v166
	v_sub_f32_e32 v153, v153, v166
	v_add_f32_e32 v202, 0, v160
	v_add_f32_e32 v203, 0, v161
	v_exp_f32_e32 v204, v152
	v_exp_f32_e32 v205, v153
	v_add_f32_e32 v202, v158, v202
	v_add_f32_e32 v203, v159, v203
	v_sub_f32_e32 v150, v150, v166
	v_sub_f32_e32 v151, v151, v166
	s_waitcnt lgkmcnt(0)
	v_add_f32_e32 v152, v204, v202
	v_add_f32_e32 v153, v205, v203
	v_exp_f32_e32 v202, v150
	v_exp_f32_e32 v203, v151
	s_mov_b64 s[28:29], 0
	v_add_f32_e32 v150, v202, v152
	v_add_f32_e32 v151, v203, v153
	v_sub_f32_e32 v152, v156, v166
	v_sub_f32_e32 v153, v157, v166
	s_nop 0
	v_exp_f32_e32 v156, v152
	v_exp_f32_e32 v157, v153
	v_sub_f32_e32 v152, v154, v166
	v_sub_f32_e32 v153, v155, v166
	v_cvt_pk_bf16_f32 v154, v204, v205
	v_exp_f32_e32 v206, v152
	v_exp_f32_e32 v207, v153
	v_sub_f32_e32 v152, v162, v166
	v_sub_f32_e32 v153, v163, v166
	v_cvt_pk_bf16_f32 v155, v202, v203
	v_exp_f32_e32 v162, v152
	v_exp_f32_e32 v163, v153
	v_sub_f32_e32 v152, v164, v166
	v_sub_f32_e32 v153, v165, v166
	v_add_f32_e32 v150, v156, v150
	v_add_f32_e32 v151, v157, v151
	v_exp_f32_e32 v164, v152
	v_exp_f32_e32 v165, v153
	v_cvt_pk_bf16_f32 v152, v160, v161
	v_cvt_pk_bf16_f32 v153, v158, v159
	v_cvt_pk_bf16_f32 v156, v156, v157
	v_cvt_pk_bf16_f32 v157, v206, v207
	v_mfma_f32_32x32x16_bf16 v[36:51], v[96:99], v[152:155], v[36:51]
	v_cvt_pk_bf16_f32 v158, v162, v163
	v_cvt_pk_bf16_f32 v159, v164, v165
	v_add_f32_e64 v150, v206, v150
	v_add_f32_e64 v151, v207, v151
	v_add_f32_e64 v150, v162, v150
	v_add_f32_e64 v151, v163, v151
	v_add_f32_e32 v150, v164, v150
	v_add_f32_e32 v151, v165, v151
	v_mfma_f32_32x32x16_bf16 v[52:67], v[92:95], v[152:155], v[52:67]
	v_add_f32_e32 v150, v150, v151
	v_add_f32_e32 v150, v200, v150
	v_mfma_f32_32x32x16_bf16 v[36:51], v[88:91], v[156:159], v[36:51]
	v_mfma_f32_32x32x16_bf16 v[52:67], v[84:87], v[156:159], v[52:67]
; #define LAS __attribute__((address_space(3)))
; __device__ __forceinline__ float fast_exp2(float x) { return __builtin_amdgcn_exp2f(x); }
; __device__ __forceinline__ float swap_max(float v) { auto rr = __builtin_amdgcn_permlane32_swap(__float_as_uint(v), __float_as_uint(v), false, false); return fmaxf(__uint_as_float(rr[0]), __uint_as_float(rr[1])); }
; template <bool MASK> ...
;     ...
;     { const int key = sub * 32 + r; const LAS char* kp = Kt + key * 128; const int ksw = (key >> 1) & 7;
; #pragma unroll
;       for (int d0 = 0; d0 < 4; ++d0) { const bf16x8 kf = *(const LAS bf16x8*)(kp + (((2 * d0 + hh) ^ ksw) << 4)); st = __builtin_amdgcn_mfma_f32_32x32x16_bf16(kf, qr[d0], st, 0, 0, 0); } }
;     f32x2_t sp[8]; const f32x2_t cs2 = {cscale, cscale};
; #pragma unroll
;     for (int g = 0; g < 4; ++g) { const f32x4 c4 = *(const LAS f32x4*)(cb + sub * 32 + 8 * g + 4 * hh);
;         sp[2 * g] = (f32x2_t){st[4 * g], st[4 * g + 1]} + cs2 * (f32x2_t){c4[0], c4[1]};
;         sp[2 * g + 1] = (f32x2_t){st[4 * g + 2], st[4 * g + 3]} + cs2 * (f32x2_t){c4[2], c4[3]};
;         if (MASK) {
; #pragma unroll
;             for (int e = 0; e < 4; ++e) { const int kpos = kpos_sub + 8 * g + 4 * hh + e; const bool ok = (kpos <= qpos && kpos >= qpos - win);
;                 sp[2 * g + (e >> 1)][e & 1] = ok ? sp[2 * g + (e >> 1)][e & 1] : -INFINITY; } } }
;     float rm = fmaxf(sp[0][0], sp[0][1]);
; #pragma unroll
;     for (int i = 1; i < 8; ++i) rm = fmaxf(fmaxf(rm, sp[i][0]), sp[i][1]);
;     rm = swap_max(rm);
;     if (__any(rm - m > 8.0f)) { const float mnew = fmaxf(m, rm); const float f = fast_exp2(m - mnew); l *= f; o0 = o0 * f; o1 = o1 * f; m = mnew; }
.LBB0_713:
	s_and_b64 vcc, exec, s[28:29]
	s_cbranch_vccz .LBB0_723
	ds_read_b64_tr_b16 v[64:65], v197
	ds_read_b64_tr_b16 v[66:67], v197 offset:1024
	ds_read_b64_tr_b16 v[60:61], v198
	ds_read_b64_tr_b16 v[62:63], v198 offset:1024
	ds_read_b64_tr_b16 v[56:57], v197 offset:2048
	ds_read_b64_tr_b16 v[58:59], v197 offset:3072
	ds_read_b64_tr_b16 v[52:53], v198 offset:2048
	ds_read_b64_tr_b16 v[54:55], v198 offset:3072
	s_nop 8
	ds_read_b128 v[36:39], v170
	ds_read_b128 v[84:87], v169
	v_or_b32_e32 v92, s4, v100
	v_cmp_le_i32_e32 vcc, v92, v144
	v_cmp_ge_i32_e64 s[46:47], v92, v119
	s_and_b64 vcc, vcc, s[46:47]
	s_waitcnt lgkmcnt(0)
	v_mfma_f32_32x32x16_bf16 v[36:51], v[36:39], v[76:79], 0
	v_mfma_f32_32x32x16_bf16 v[36:51], v[84:87], v[68:71], v[36:51]
	ds_read_b128 v[84:87], v168
	s_waitcnt lgkmcnt(0)
	v_mfma_f32_32x32x16_bf16 v[36:51], v[84:87], v[72:75], v[36:51]
	ds_read_b128 v[84:87], v167
	s_waitcnt lgkmcnt(0)
	v_mfma_f32_32x32x16_bf16 v[36:51], v[84:87], v[80:83], v[36:51]
	ds_read_b128 v[84:87], v35 offset:49152
	ds_read_b128 v[88:91], v35 offset:49184
	s_waitcnt lgkmcnt(0)
	s_nop 8
	v_fma_f32 v36, v148, v84, v36
	v_fma_f32 v37, v149, v85, v37
	v_or_b32_e32 v84, 1, v92
	v_cndmask_b32_e32 v36, v240, v36, vcc
	v_cmp_lt_i32_e32 vcc, v92, v144
	v_cmp_ge_i32_e64 s[46:47], v84, v119
	s_and_b64 vcc, vcc, s[46:47]
	v_or_b32_e32 v84, 2, v92
	v_cndmask_b32_e32 v37, v240, v37, vcc
	v_cmp_le_i32_e32 vcc, v84, v144
	v_cmp_ge_i32_e64 s[46:47], v84, v119
	v_fma_f32 v38, v148, v86, v38
	v_fma_f32 v39, v149, v87, v39
	s_and_b64 vcc, vcc, s[46:47]
	v_or_b32_e32 v84, 3, v92
	v_cndmask_b32_e32 v38, v240, v38, vcc
	v_cmp_le_i32_e32 vcc, v84, v144
	v_cmp_ge_i32_e64 s[46:47], v84, v119
	s_and_b64 vcc, vcc, s[46:47]
	v_or_b32_e32 v84, 8, v92
	v_cndmask_b32_e32 v39, v240, v39, vcc
	v_cmp_le_i32_e32 vcc, v84, v144
	v_cmp_ge_i32_e64 s[46:47], v84, v119
	v_fma_f32 v40, v148, v88, v40
	v_fma_f32 v41, v149, v89, v41
	s_and_b64 vcc, vcc, s[46:47]
	v_or_b32_e32 v84, 9, v92
	v_cndmask_b32_e32 v40, v240, v40, vcc
	v_cmp_le_i32_e32 vcc, v84, v144
	v_cmp_ge_i32_e64 s[46:47], v84, v119
	s_and_b64 vcc, vcc, s[46:47]
	v_or_b32_e32 v84, 10, v92
	v_cndmask_b32_e32 v41, v240, v41, vcc
	v_cmp_le_i32_e32 vcc, v84, v144
	v_cmp_ge_i32_e64 s[46:47], v84, v119
	v_fma_f32 v42, v148, v90, v42
	v_fma_f32 v43, v149, v91, v43
	s_and_b64 vcc, vcc, s[46:47]
	v_or_b32_e32 v84, 11, v92
	v_cndmask_b32_e32 v42, v240, v42, vcc
	v_cmp_le_i32_e32 vcc, v84, v144
	v_cmp_ge_i32_e64 s[46:47], v84, v119
	ds_read_b128 v[84:87], v35 offset:49216
	s_and_b64 vcc, vcc, s[46:47]
	v_cndmask_b32_e32 v43, v240, v43, vcc
	s_waitcnt lgkmcnt(0)
	v_fma_f32 v44, v148, v84, v44
	v_fma_f32 v45, v149, v85, v45
	v_or_b32_e32 v84, 16, v92
	v_cmp_le_i32_e32 vcc, v84, v144
	v_cmp_ge_i32_e64 s[46:47], v84, v119
	s_and_b64 vcc, vcc, s[46:47]
	v_or_b32_e32 v84, 17, v92
	v_cndmask_b32_e32 v44, v240, v44, vcc
	v_cmp_le_i32_e32 vcc, v84, v144
	v_cmp_ge_i32_e64 s[46:47], v84, v119
	s_and_b64 vcc, vcc, s[46:47]
	v_or_b32_e32 v84, 18, v92
	v_cndmask_b32_e32 v45, v240, v45, vcc
	v_cmp_le_i32_e32 vcc, v84, v144
	v_cmp_ge_i32_e64 s[46:47], v84, v119
	v_fma_f32 v46, v148, v86, v46
	v_fma_f32 v47, v149, v87, v47
	s_and_b64 vcc, vcc, s[46:47]
	v_or_b32_e32 v84, 19, v92
	v_cndmask_b32_e32 v46, v240, v46, vcc
	v_cmp_le_i32_e32 vcc, v84, v144
	v_cmp_ge_i32_e64 s[46:47], v84, v119
	ds_read_b128 v[84:87], v35 offset:49248
	s_and_b64 vcc, vcc, s[46:47]
	v_cndmask_b32_e32 v47, v240, v47, vcc
	s_waitcnt lgkmcnt(0)
	v_fma_f32 v48, v148, v84, v48
	v_fma_f32 v49, v149, v85, v49
	v_or_b32_e32 v84, 24, v92
	v_cmp_le_i32_e32 vcc, v84, v144
	v_cmp_ge_i32_e64 s[46:47], v84, v119
	s_and_b64 vcc, vcc, s[46:47]
	v_or_b32_e32 v84, 25, v92
	v_cndmask_b32_e32 v48, v240, v48, vcc
	v_cmp_le_i32_e32 vcc, v84, v144
	v_cmp_ge_i32_e64 s[46:47], v84, v119
	s_and_b64 vcc, vcc, s[46:47]
	v_or_b32_e32 v84, 26, v92
	v_cndmask_b32_e32 v49, v240, v49, vcc
	v_cmp_le_i32_e32 vcc, v84, v144
	v_cmp_ge_i32_e64 s[46:47], v84, v119
	v_fma_f32 v50, v148, v86, v50
	v_fma_f32 v51, v149, v87, v51
	s_and_b64 vcc, vcc, s[46:47]
	v_or_b32_e32 v84, 27, v92
	v_cndmask_b32_e32 v50, v240, v50, vcc
	v_cmp_le_i32_e32 vcc, v84, v144
	v_cmp_ge_i32_e64 s[46:47], v84, v119
	v_max_f32_e32 v84, v36, v37
	v_max3_f32 v84, v84, v38, v39
	v_max3_f32 v84, v84, v40, v41
	v_max3_f32 v84, v84, v42, v43
	v_max3_f32 v84, v84, v44, v45
	s_and_b64 vcc, vcc, s[46:47]
	v_max3_f32 v84, v84, v46, v47
	v_cndmask_b32_e32 v51, v240, v51, vcc
	v_max3_f32 v84, v84, v48, v49
	v_max3_f32 v84, v84, v50, v51
	v_mov_b32_e32 v85, v84
	s_nop 1
	v_permlane32_swap_b32_e32 v84, v85
	v_max_f32_e32 v85, v85, v85
	v_max_f32_e32 v84, v84, v84
	v_max_f32_e32 v84, v84, v85
	v_sub_f32_e32 v85, v84, v122
	v_cmp_lt_f32_e32 vcc, s9, v85
	s_cbranch_vccz .LBB0_721
	v_max_f32_e32 v84, v84, v84
	v_max_f32_e32 v85, v122, v122
	v_max_f32_e32 v84, v85, v84
	v_sub_f32_e32 v85, v122, v84
	v_exp_f32_e32 v86, v85
	v_mov_b32_e32 v122, v84
	v_mul_f32_e32 v34, v34, v86
	v_mul_f32_e32 v32, v32, v86
	v_mul_f32_e32 v33, v33, v86
	v_mul_f32_e32 v30, v30, v86
	v_mul_f32_e32 v31, v31, v86
	v_mul_f32_e32 v28, v28, v86
	v_mul_f32_e32 v29, v29, v86
	v_mul_f32_e32 v26, v26, v86
	v_mul_f32_e32 v27, v27, v86
	v_mul_f32_e32 v24, v24, v86
	v_mul_f32_e32 v25, v25, v86
	v_mul_f32_e32 v22, v22, v86
	v_mul_f32_e32 v23, v23, v86
	v_mul_f32_e32 v20, v20, v86
	v_mul_f32_e32 v21, v21, v86
	v_mul_f32_e32 v18, v18, v86
	v_mul_f32_e32 v19, v19, v86
	v_mul_f32_e32 v16, v16, v86
	v_mul_f32_e32 v17, v17, v86
	v_mul_f32_e32 v14, v14, v86
	v_mul_f32_e32 v15, v15, v86
	v_mul_f32_e32 v12, v12, v86
	v_mul_f32_e32 v13, v13, v86
	v_mul_f32_e32 v10, v10, v86
	v_mul_f32_e32 v11, v11, v86
	v_mul_f32_e32 v8, v8, v86
	v_mul_f32_e32 v9, v9, v86
	v_mul_f32_e32 v6, v6, v86
	v_mul_f32_e32 v7, v7, v86
	v_mul_f32_e32 v4, v4, v86
	v_mul_f32_e32 v5, v5, v86
	v_mul_f32_e32 v2, v2, v86
	v_mul_f32_e32 v3, v3, v86
	s_branch .LBB0_722

; #define LAS __attribute__((address_space(3)))
; __device__ __forceinline__ float fast_exp2(float x) { return __builtin_amdgcn_exp2f(x); }
; __device__ __forceinline__ float swap_max(float v) { auto rr = __builtin_amdgcn_permlane32_swap(__float_as_uint(v), __float_as_uint(v), false, false); return fmaxf(__uint_as_float(rr[0]), __uint_as_float(rr[1])); }
; template <bool MASK> ...
;     ...
;     { const int key = sub * 32 + r; const LAS char* kp = Kt + key * 128; const int ksw = (key >> 1) & 7;
; #pragma unroll
;       for (int d0 = 0; d0 < 4; ++d0) { const bf16x8 kf = *(const LAS bf16x8*)(kp + (((2 * d0 + hh) ^ ksw) << 4)); st = __builtin_amdgcn_mfma_f32_32x32x16_bf16(kf, qr[d0], st, 0, 0, 0); } }
;     f32x2_t sp[8]; const f32x2_t cs2 = {cscale, cscale};
; #pragma unroll
;     for (int g = 0; g < 4; ++g) { const f32x4 c4 = *(const LAS f32x4*)(cb + sub * 32 + 8 * g + 4 * hh);
;         sp[2 * g] = (f32x2_t){st[4 * g], st[4 * g + 1]} + cs2 * (f32x2_t){c4[0], c4[1]};
;         sp[2 * g + 1] = (f32x2_t){st[4 * g + 2], st[4 * g + 3]} + cs2 * (f32x2_t){c4[2], c4[3]};
;         if (MASK) {
; #pragma unroll
;             for (int e = 0; e < 4; ++e) { const int kpos = kpos_sub + 8 * g + 4 * hh + e; const bool ok = (kpos <= qpos && kpos >= qpos - win);
;                 sp[2 * g + (e >> 1)][e & 1] = ok ? sp[2 * g + (e >> 1)][e & 1] : -INFINITY; } } }
;     float rm = fmaxf(sp[0][0], sp[0][1]);
; #pragma unroll
;     for (int i = 1; i < 8; ++i) rm = fmaxf(fmaxf(rm, sp[i][0]), sp[i][1]);
;     rm = swap_max(rm);
;     if (__any(rm - m > 8.0f)) { const float mnew = fmaxf(m, rm); const float f = fast_exp2(m - mnew); l *= f; o0 = o0 * f; o1 = o1 * f; m = mnew; }
.LBB0_718:
	s_and_b64 vcc, exec, s[28:29]
	s_cbranch_vccz .LBB0_698
	ds_read_b64_tr_b16 v[64:65], v199
	ds_read_b64_tr_b16 v[66:67], v199 offset:1024
	ds_read_b64_tr_b16 v[60:61], v197
	ds_read_b64_tr_b16 v[62:63], v197 offset:1024
	ds_read_b64_tr_b16 v[56:57], v199 offset:2048
	ds_read_b64_tr_b16 v[58:59], v199 offset:3072
	ds_read_b64_tr_b16 v[52:53], v197 offset:2048
	ds_read_b64_tr_b16 v[54:55], v197 offset:3072
	s_nop 8
	ds_read_b128 v[36:39], v170 offset:4096
	ds_read_b128 v[84:87], v169 offset:4096
	v_or_b32_e32 v92, s5, v100
	v_cmp_le_i32_e32 vcc, v92, v144
	v_cmp_ge_i32_e64 s[46:47], v92, v119
	s_and_b64 vcc, vcc, s[46:47]
	s_waitcnt lgkmcnt(0)
	v_mfma_f32_32x32x16_bf16 v[36:51], v[36:39], v[76:79], 0
	v_mfma_f32_32x32x16_bf16 v[36:51], v[84:87], v[68:71], v[36:51]
	ds_read_b128 v[84:87], v168 offset:4096
	s_waitcnt lgkmcnt(0)
	v_mfma_f32_32x32x16_bf16 v[36:51], v[84:87], v[72:75], v[36:51]
	ds_read_b128 v[84:87], v167 offset:4096
	s_waitcnt lgkmcnt(0)
	v_mfma_f32_32x32x16_bf16 v[36:51], v[84:87], v[80:83], v[36:51]
	ds_read_b128 v[84:87], v35 offset:49280
	ds_read_b128 v[88:91], v35 offset:49312
	s_waitcnt lgkmcnt(0)
	s_nop 8
	v_fma_f32 v36, v148, v84, v36
	v_fma_f32 v37, v149, v85, v37
	v_or_b32_e32 v84, 1, v92
	v_cndmask_b32_e32 v36, v240, v36, vcc
	v_cmp_lt_i32_e32 vcc, v92, v144
	v_cmp_ge_i32_e64 s[46:47], v84, v119
	s_and_b64 vcc, vcc, s[46:47]
	v_or_b32_e32 v84, 2, v92
	v_cndmask_b32_e32 v37, v240, v37, vcc
	v_cmp_le_i32_e32 vcc, v84, v144
	v_cmp_ge_i32_e64 s[46:47], v84, v119
	v_fma_f32 v38, v148, v86, v38
	v_fma_f32 v39, v149, v87, v39
	s_and_b64 vcc, vcc, s[46:47]
	v_or_b32_e32 v84, 3, v92
	v_cndmask_b32_e32 v38, v240, v38, vcc
	v_cmp_le_i32_e32 vcc, v84, v144
	v_cmp_ge_i32_e64 s[46:47], v84, v119
	s_and_b64 vcc, vcc, s[46:47]
	v_or_b32_e32 v84, 8, v92
	v_cndmask_b32_e32 v39, v240, v39, vcc
	v_cmp_le_i32_e32 vcc, v84, v144
	v_cmp_ge_i32_e64 s[46:47], v84, v119
	v_fma_f32 v40, v148, v88, v40
	v_fma_f32 v41, v149, v89, v41
	s_and_b64 vcc, vcc, s[46:47]
	v_or_b32_e32 v84, 9, v92
	v_cndmask_b32_e32 v40, v240, v40, vcc
	v_cmp_le_i32_e32 vcc, v84, v144
	v_cmp_ge_i32_e64 s[46:47], v84, v119
	s_and_b64 vcc, vcc, s[46:47]
	v_or_b32_e32 v84, 10, v92
	v_cndmask_b32_e32 v41, v240, v41, vcc
	v_cmp_le_i32_e32 vcc, v84, v144
	v_cmp_ge_i32_e64 s[46:47], v84, v119
	v_fma_f32 v42, v148, v90, v42
	v_fma_f32 v43, v149, v91, v43
	s_and_b64 vcc, vcc, s[46:47]
	v_or_b32_e32 v84, 11, v92
	v_cndmask_b32_e32 v42, v240, v42, vcc
	v_cmp_le_i32_e32 vcc, v84, v144
	v_cmp_ge_i32_e64 s[46:47], v84, v119
	ds_read_b128 v[84:87], v35 offset:49344
	s_and_b64 vcc, vcc, s[46:47]
	v_cndmask_b32_e32 v43, v240, v43, vcc
	s_waitcnt lgkmcnt(0)
	v_fma_f32 v44, v148, v84, v44
	v_fma_f32 v45, v149, v85, v45
	v_or_b32_e32 v84, 16, v92
	v_cmp_le_i32_e32 vcc, v84, v144
	v_cmp_ge_i32_e64 s[46:47], v84, v119
	s_and_b64 vcc, vcc, s[46:47]
	v_or_b32_e32 v84, 17, v92
	v_cndmask_b32_e32 v44, v240, v44, vcc
	v_cmp_le_i32_e32 vcc, v84, v144
	v_cmp_ge_i32_e64 s[46:47], v84, v119
	s_and_b64 vcc, vcc, s[46:47]
	v_or_b32_e32 v84, 18, v92
	v_cndmask_b32_e32 v45, v240, v45, vcc
	v_cmp_le_i32_e32 vcc, v84, v144
	v_cmp_ge_i32_e64 s[46:47], v84, v119
	v_fma_f32 v46, v148, v86, v46
	v_fma_f32 v47, v149, v87, v47
	s_and_b64 vcc, vcc, s[46:47]
	v_or_b32_e32 v84, 19, v92
	v_cndmask_b32_e32 v46, v240, v46, vcc
	v_cmp_le_i32_e32 vcc, v84, v144
	v_cmp_ge_i32_e64 s[46:47], v84, v119
	ds_read_b128 v[84:87], v35 offset:49376
	s_and_b64 vcc, vcc, s[46:47]
	v_or_b32_e32 v35, 24, v92
	v_cndmask_b32_e32 v47, v240, v47, vcc
	v_cmp_le_i32_e32 vcc, v35, v144
	v_cmp_ge_i32_e64 s[46:47], v35, v119
	s_waitcnt lgkmcnt(0)
	v_fma_f32 v48, v148, v84, v48
	v_fma_f32 v49, v149, v85, v49
	s_and_b64 vcc, vcc, s[46:47]
	v_or_b32_e32 v35, 25, v92
	v_cndmask_b32_e32 v48, v240, v48, vcc
	v_cmp_le_i32_e32 vcc, v35, v144
	v_cmp_ge_i32_e64 s[46:47], v35, v119
	s_and_b64 vcc, vcc, s[46:47]
	v_or_b32_e32 v35, 26, v92
	v_cndmask_b32_e32 v49, v240, v49, vcc
	v_cmp_le_i32_e32 vcc, v35, v144
	v_cmp_ge_i32_e64 s[46:47], v35, v119
	v_fma_f32 v50, v148, v86, v50
	v_fma_f32 v51, v149, v87, v51
	s_and_b64 vcc, vcc, s[46:47]
	v_or_b32_e32 v35, 27, v92
	v_cndmask_b32_e32 v50, v240, v50, vcc
	v_cmp_le_i32_e32 vcc, v35, v144
	v_cmp_ge_i32_e64 s[46:47], v35, v119
	v_max_f32_e32 v35, v36, v37
	v_max3_f32 v35, v35, v38, v39
	v_max3_f32 v35, v35, v40, v41
	v_max3_f32 v35, v35, v42, v43
	v_max3_f32 v35, v35, v44, v45
	s_and_b64 vcc, vcc, s[46:47]
	v_max3_f32 v35, v35, v46, v47
	v_cndmask_b32_e32 v51, v240, v51, vcc
	v_max3_f32 v35, v35, v48, v49
	v_max3_f32 v35, v35, v50, v51
	v_mov_b32_e32 v84, v35
	s_nop 1
	v_permlane32_swap_b32_e32 v35, v84
	v_max_f32_e32 v84, v84, v84
	v_max_f32_e32 v35, v35, v35
	v_max_f32_e32 v35, v35, v84
	v_sub_f32_e32 v84, v35, v122
	v_cmp_lt_f32_e32 vcc, s9, v84
	s_cbranch_vccz .LBB0_696
	v_max_f32_e32 v35, v35, v35
	v_max_f32_e32 v84, v122, v122
	v_max_f32_e32 v84, v84, v35
	v_sub_f32_e32 v35, v122, v84
	v_exp_f32_e32 v86, v35
	v_mov_b32_e32 v122, v84
	v_mul_f32_e32 v34, v34, v86
	v_mul_f32_e32 v32, v32, v86
	v_mul_f32_e32 v33, v33, v86
	v_mul_f32_e32 v30, v30, v86
	v_mul_f32_e32 v31, v31, v86
	v_mul_f32_e32 v28, v28, v86
	v_mul_f32_e32 v29, v29, v86
	v_mul_f32_e32 v26, v26, v86
	v_mul_f32_e32 v27, v27, v86
	v_mul_f32_e32 v24, v24, v86
	v_mul_f32_e32 v25, v25, v86
	v_mul_f32_e32 v22, v22, v86
	v_mul_f32_e32 v23, v23, v86
	v_mul_f32_e32 v20, v20, v86
	v_mul_f32_e32 v21, v21, v86
	v_mul_f32_e32 v18, v18, v86
	v_mul_f32_e32 v19, v19, v86
	v_mul_f32_e32 v16, v16, v86
	v_mul_f32_e32 v17, v17, v86
	v_mul_f32_e32 v14, v14, v86
	v_mul_f32_e32 v15, v15, v86
	v_mul_f32_e32 v12, v12, v86
	v_mul_f32_e32 v13, v13, v86
	v_mul_f32_e32 v10, v10, v86
	v_mul_f32_e32 v11, v11, v86
	v_mul_f32_e32 v8, v8, v86
	v_mul_f32_e32 v9, v9, v86
	v_mul_f32_e32 v6, v6, v86
	v_mul_f32_e32 v7, v7, v86
	v_mul_f32_e32 v4, v4, v86
	v_mul_f32_e32 v5, v5, v86
	v_mul_f32_e32 v2, v2, v86
	v_mul_f32_e32 v3, v3, v86
	s_branch .LBB0_697

; __device__ __forceinline__ unsigned cvt_pk_bf16(float lo, float hi) { f32x2_t v = {lo, hi}; bf16x2_t b = __builtin_convertvector(v, bf16x2_t); return __builtin_bit_cast(unsigned, b); }
; __device__ __forceinline__ float fast_exp2(float x) { return __builtin_amdgcn_exp2f(x); }
; template <bool MASK> ...
;     ...
;     { const f32x2_t m2 = {m, m}; f32x2_t ps2 = {0.f, 0.f};
; #pragma unroll
;       for (int i = 0; i < 8; ++i) { f32x2_t t = sp[i] - m2; t[0] = fast_exp2(t[0]); t[1] = fast_exp2(t[1]); sp[i] = t; ps2 = ps2 + t; }
;       l += ps2[0] + ps2[1]; }
;     u32x4 pw0, pw1;
;     pw0.x = cvt_pk_bf16(sp[0][0], sp[0][1]); pw0.y = cvt_pk_bf16(sp[1][0], sp[1][1]); pw0.z = cvt_pk_bf16(sp[2][0], sp[2][1]); pw0.w = cvt_pk_bf16(sp[3][0], sp[3][1]);
;     pw1.x = cvt_pk_bf16(sp[4][0], sp[4][1]); pw1.y = cvt_pk_bf16(sp[5][0], sp[5][1]); pw1.z = cvt_pk_bf16(sp[6][0], sp[6][1]); pw1.w = cvt_pk_bf16(sp[7][0], sp[7][1]);
;     asm volatile("s_waitcnt lgkmcnt(0)" : "+v"(l00), "+v"(h00), "+v"(l01), "+v"(h01), "+v"(l10), "+v"(h10), "+v"(l11), "+v"(h11) :: "memory");
;     { const bf16x8 pb0 = __builtin_bit_cast(bf16x8, pw0), pb1 = __builtin_bit_cast(bf16x8, pw1);
;       const bf16x8 v00 = {l00[0], l00[1], l00[2], l00[3], h00[0], h00[1], h00[2], h00[3]}, v01 = {l01[0], l01[1], l01[2], l01[3], h01[0], h01[1], h01[2], h01[3]};
;       const bf16x8 v10 = {l10[0], l10[1], l10[2], l10[3], h10[0], h10[1], h10[2], h10[3]}, v11 = {l11[0], l11[1], l11[2], l11[3], h11[0], h11[1], h11[2], h11[3]};
;       o0 = __builtin_amdgcn_mfma_f32_32x32x16_bf16(v00, pb0, o0, 0, 0, 0); o1 = __builtin_amdgcn_mfma_f32_32x32x16_bf16(v01, pb0, o1, 0, 0, 0);
;       o0 = __builtin_amdgcn_mfma_f32_32x32x16_bf16(v10, pb1, o0, 0, 0, 0); o1 = __builtin_amdgcn_mfma_f32_32x32x16_bf16(v11, pb1, o1, 0, 0, 0); }
.LBB0_722:
	v_sub_f32_e32 v36, v36, v84
	v_sub_f32_e32 v37, v37, v84
	v_sub_f32_e32 v38, v38, v84
	v_sub_f32_e32 v39, v39, v84
	v_exp_f32_e32 v36, v36
	v_exp_f32_e32 v37, v37
	v_sub_f32_e32 v40, v40, v84
	v_sub_f32_e32 v41, v41, v84
	v_sub_f32_e32 v42, v42, v84
	v_sub_f32_e32 v43, v43, v84
	v_exp_f32_e32 v38, v38
	v_exp_f32_e32 v39, v39
	v_exp_f32_e32 v40, v40
	v_exp_f32_e32 v41, v41
	v_exp_f32_e32 v42, v42
	v_exp_f32_e32 v43, v43
	v_add_f32_e32 v86, 0, v36
	v_add_f32_e32 v87, 0, v37
	v_cvt_pk_bf16_f32 v36, v36, v37
	v_add_f32_e32 v86, v38, v86
	v_add_f32_e32 v87, v39, v87
	v_cvt_pk_bf16_f32 v37, v38, v39
	v_cvt_pk_bf16_f32 v38, v40, v41
	v_cvt_pk_bf16_f32 v39, v42, v43
	s_waitcnt lgkmcnt(0)
	v_sub_f32_e32 v44, v44, v84
	v_sub_f32_e32 v45, v45, v84
	v_sub_f32_e32 v46, v46, v84
	v_sub_f32_e32 v47, v47, v84
	v_mfma_f32_32x32x16_bf16 v[18:33], v[64:67], v[36:39], v[18:33]
	v_add_f32_e64 v48, v48, -v84
	v_add_f32_e64 v49, v49, -v84
	v_add_f32_e64 v50, v50, -v84
	v_add_f32_e64 v51, v51, -v84
	v_exp_f32_e32 v44, v44
	v_exp_f32_e32 v45, v45
	v_exp_f32_e32 v46, v46
	v_exp_f32_e32 v47, v47
	v_exp_f32_e32 v48, v48
	v_mfma_f32_32x32x16_bf16 v[2:17], v[60:63], v[36:39], v[2:17]
	v_exp_f32_e32 v49, v49
	v_exp_f32_e32 v50, v50
	v_exp_f32_e32 v51, v51
	v_add_f32_e32 v86, v40, v86
	v_add_f32_e32 v87, v41, v87
	v_cvt_pk_bf16_f32 v40, v44, v45
	v_add_f32_e32 v86, v42, v86
	v_add_f32_e32 v87, v43, v87
	v_cvt_pk_bf16_f32 v41, v46, v47
	v_cvt_pk_bf16_f32 v42, v48, v49
	v_cvt_pk_bf16_f32 v43, v50, v51
	v_add_f32_e32 v86, v44, v86
	v_add_f32_e32 v87, v45, v87
	v_mov_b32_e32 v199, v122
	v_mfma_f32_32x32x16_bf16 v[18:33], v[56:59], v[40:43], v[18:33]
	v_add_f32_e64 v86, v46, v86
	v_add_f32_e64 v87, v47, v87
	v_add_f32_e64 v86, v48, v86
	v_add_f32_e64 v87, v49, v87
	v_add_f32_e64 v84, v50, v86
	v_add_f32_e64 v85, v51, v87
	v_add_f32_e32 v84, v84, v85
	v_mfma_f32_32x32x16_bf16 v[2:17], v[52:55], v[40:43], v[2:17]
	s_nop 3
	v_mov_b64_e32 v[50:51], v[32:33]
	v_add_f32_e32 v150, v34, v84
	v_mov_b64_e32 v[48:49], v[30:31]
	v_mov_b64_e32 v[46:47], v[28:29]
	v_mov_b64_e32 v[44:45], v[26:27]
	v_mov_b64_e32 v[42:43], v[24:25]
	v_mov_b64_e32 v[40:41], v[22:23]
	s_nop 0
	v_mov_b64_e32 v[66:67], v[16:17]
	v_mov_b64_e32 v[38:39], v[20:21]
	v_mov_b64_e32 v[36:37], v[18:19]
	v_mov_b64_e32 v[64:65], v[14:15]
	v_mov_b64_e32 v[62:63], v[12:13]
	v_mov_b64_e32 v[60:61], v[10:11]
	v_mov_b64_e32 v[58:59], v[8:9]
	v_mov_b64_e32 v[56:57], v[6:7]
	v_mov_b64_e32 v[54:55], v[4:5]
	v_mov_b64_e32 v[52:53], v[2:3]

; __device__ __forceinline__ float bf_lo(unsigned w) { return __uint_as_float(w << 16); }
; __device__ __forceinline__ float bf_hi(unsigned w) { return __uint_as_float(w & 0xffff0000u); }
; __device__ __forceinline__ float fast_exp2(float x) { return __builtin_amdgcn_exp2f(x); }
; __device__ __forceinline__ float fast_rcp(float x) { return __builtin_amdgcn_rcpf(x); }
; __device__ __forceinline__ float swap_sum(float v) { auto rr = __builtin_amdgcn_permlane32_swap(__float_as_uint(v), __float_as_uint(v), false, false); return __uint_as_float(rr[0]) + __uint_as_float(rr[1]); }
; __device__ __forceinline__ void moba_own_unit(LAS char* lds, int bh, int jblk, const bf16_t* H, const bf16_t* PO, const float* PML, bf16_t* U, int tid) {
;     ...
;     const float lt = swap_sum(l);
;     const float mown = m - slope2 * (float)(qpos - s0);
;     float M = mown;
; #pragma unroll
;     for (int s = 0; s < 3; ++s) if (s < nsel) M = fmaxf(M, mi[s]);
;     const float wown = fast_exp2(mown - M); float den = wown * lt;
; #pragma unroll
;     for (int s = 0; s < 3; ++s) { wi[s] = (s < nsel) ? wi[s] * fast_exp2(mi[s] - M) : 0.f; den += wi[s]; }
;     const float inv = fast_rcp(den);
;     bf16_t* urow = U + ((size_t)b * SEQ + qpos) * 2048 + U_MOBA + h * 64;
; #pragma unroll
;     for (int d0 = 0; d0 < 2; ++d0)
; #pragma unroll
;         for (int g = 0; g < 4; ++g) { const int d = 32 * d0 + 8 * g + 4 * hh; const f32x16& o = d0 ? o1 : o0;
;             float a0 = o[4 * g] * wown, a1 = o[4 * g + 1] * wown, a2 = o[4 * g + 2] * wown, a3 = o[4 * g + 3] * wown;
; #pragma unroll
;             for (int s = 0; s < 3; ++s) if (s < nsel) { const u32x2 pv = *(const u32x2*)(PO + (pidx + s) * 64 + d); a0 += wi[s] * bf_lo(pv.x); a1 += wi[s] * bf_hi(pv.x); a2 += wi[s] * bf_lo(pv.y); a3 += wi[s] * bf_hi(pv.y); }
.LBB0_725:
	v_subrev_u32_e32 v36, s24, v144
	v_cvt_f32_i32_e32 v36, v36
	v_max_f32_e32 v37, v146, v146
	v_max_f32_e32 v38, v140, v140
	s_waitcnt lgkmcnt(0)
	s_barrier
	v_fma_f32 v36, -v148, v36, v122
	v_max_f32_e32 v37, v36, v37
	v_cndmask_b32_e64 v37, v36, v37, s[40:41]
	v_max_f32_e32 v38, v37, v38
	v_cndmask_b32_e64 v37, v37, v38, s[42:43]
	v_max_f32_e32 v38, v142, v142
	v_max_f32_e32 v38, v37, v38
	v_cndmask_b32_e64 v37, v37, v38, s[44:45]
	v_sub_f32_e32 v36, v36, v37
	v_exp_f32_e32 v38, v36
	v_sub_f32_e32 v36, v146, v37
	v_exp_f32_e32 v36, v36
	v_mov_b32_e32 v35, v34
	s_nop 1
	v_permlane32_swap_b32_e32 v34, v35
	v_mul_f32_e32 v36, v147, v36
	v_mul_f32_e32 v42, v18, v38
	v_mul_f32_e32 v43, v19, v38
	v_mul_f32_e32 v40, v20, v38
	v_mul_f32_e32 v41, v21, v38
	s_and_b64 vcc, exec, s[40:41]
	s_cbranch_vccz .LBB0_727
	v_mad_u64_u32 v[18:19], s[4:5], v145, s10, v[102:103]
	v_mov_b32_e32 v20, v19
	v_mad_u64_u32 v[20:21], s[4:5], v123, s10, v[20:21]
	v_mov_b32_e32 v19, v20
	global_load_dwordx2 v[18:19], v[18:19], off
	s_waitcnt vmcnt(0)
	v_lshlrev_b32_e32 v20, 16, v18
	v_and_b32_e32 v21, 0xffff0000, v18
	v_lshlrev_b32_e32 v18, 16, v19
	v_and_b32_e32 v19, 0xffff0000, v19
	v_fma_f32 v42, v36, v20, v42
	v_fma_f32 v43, v36, v21, v43
	v_fma_f32 v40, v36, v18, v40
	v_fma_f32 v41, v36, v19, v41
.LBB0_727:
	v_sub_f32_e32 v18, v140, v37
	v_exp_f32_e32 v18, v18
	v_cndmask_b32_e64 v19, 0, 1, s[42:43]
	v_cmp_ne_u32_e64 s[46:47], 1, v19
	s_andn2_b64 vcc, exec, s[42:43]
	v_mul_f32_e32 v18, v141, v18
	s_cbranch_vccnz .LBB0_729
	v_mad_u64_u32 v[20:21], s[4:5], v145, s10, v[102:103]
	v_mov_b32_e32 v44, v21
	v_mad_u64_u32 v[44:45], s[4:5], v123, s10, v[44:45]
	v_mov_b32_e32 v21, v44
	global_load_dwordx2 v[20:21], v[20:21], off offset:128
	s_waitcnt vmcnt(0)
	v_lshlrev_b32_e32 v44, 16, v20
	v_and_b32_e32 v45, 0xffff0000, v20
	v_lshlrev_b32_e32 v20, 16, v21
	v_and_b32_e32 v21, 0xffff0000, v21
	v_fma_f32 v42, v18, v44, v42
	v_fma_f32 v43, v18, v45, v43
	v_fma_f32 v40, v18, v20, v40
	v_fma_f32 v41, v18, v21, v41
.LBB0_729:
	v_sub_f32_e32 v19, v142, v37
	v_exp_f32_e32 v19, v19
	v_cndmask_b32_e64 v20, 0, 1, s[44:45]
	v_cmp_ne_u32_e64 s[48:49], 1, v20
	s_andn2_b64 vcc, exec, s[44:45]
	v_mul_f32_e32 v20, v143, v19
	s_cbranch_vccnz .LBB0_731
	v_mad_u64_u32 v[44:45], s[4:5], v145, s10, v[102:103]
	v_mov_b32_e32 v46, v45
	v_mad_u64_u32 v[46:47], s[4:5], v123, s10, v[46:47]
	v_mov_b32_e32 v45, v46
	global_load_dwordx2 v[44:45], v[44:45], off offset:256
	s_waitcnt vmcnt(0)
	v_lshlrev_b32_e32 v46, 16, v44
	v_and_b32_e32 v47, 0xffff0000, v44
	v_lshlrev_b32_e32 v44, 16, v45
	v_and_b32_e32 v45, 0xffff0000, v45
	v_fma_f32 v42, v20, v46, v42
	v_fma_f32 v43, v20, v47, v43
	v_fma_f32 v40, v20, v44, v40
	v_fma_f32 v41, v20, v45, v41
.LBB0_731:
	v_add_f32_e32 v19, v34, v35
	v_cndmask_b32_e64 v21, 0, v36, s[40:41]
	v_fmac_f32_e32 v21, v38, v19
	v_cndmask_b32_e64 v19, 0, v18, s[42:43]
	v_add_f32_e32 v19, v19, v21
	v_cndmask_b32_e64 v21, 0, v20, s[44:45]
	v_add_f32_e32 v19, v21, v19
	v_rcp_f32_e32 v34, v19
	v_lshlrev_b64 v[44:45], 12, v[138:139]
	v_lshlrev_b32_e32 v46, 16, v136
	v_and_b32_e32 v47, 0xffff0000, v136
	v_mul_f32_e32 v42, v34, v42
	v_mul_f32_e32 v43, v34, v43
	v_lshl_add_u64 v[44:45], s[0:1], 0, v[44:45]
	v_mul_f32_e32 v42, v42, v46
	v_mul_f32_e32 v43, v43, v47
	v_mul_f32_e32 v40, v34, v40
	v_mul_f32_e32 v41, v34, v41
	v_lshlrev_b32_e32 v46, 16, v137
	v_and_b32_e32 v47, 0xffff0000, v137
	v_lshl_add_u64 v[44:45], v[44:45], 0, s[30:31]
	v_mul_f32_e32 v40, v40, v46
	v_mul_f32_e32 v41, v41, v47
	v_mov_b32_e32 v119, v1
	v_cvt_pk_bf16_f32 v42, v42, v43
	v_cvt_pk_bf16_f32 v43, v40, v41
	v_lshl_add_u64 v[40:41], v[44:45], 0, v[118:119]
	v_add_co_u32_e32 v44, vcc, 0x10200000, v40
	v_mov_b32_e32 v39, v38
	s_nop 0
	v_addc_co_u32_e32 v45, vcc, 0, v41, vcc
	v_cndmask_b32_e64 v19, 0, 1, s[40:41]
	global_store_dwordx2 v[44:45], v[42:43], off offset:2048
	v_mul_f32_e32 v42, v22, v38
	v_mul_f32_e32 v43, v23, v39
	v_cmp_ne_u32_e64 s[42:43], 1, v19
	s_andn2_b64 vcc, exec, s[40:41]
	v_mul_f32_e32 v24, v24, v38
	v_mul_f32_e32 v25, v25, v39
	s_cbranch_vccnz .LBB0_733
	v_mad_u64_u32 v[22:23], s[4:5], v145, s10, v[104:105]
	v_mov_b32_e32 v44, v23
	v_mad_u64_u32 v[44:45], s[4:5], v123, s10, v[44:45]
	v_mov_b32_e32 v23, v44
	global_load_dwordx2 v[22:23], v[22:23], off
	s_waitcnt vmcnt(0)
	v_lshlrev_b32_e32 v44, 16, v22
	v_and_b32_e32 v45, 0xffff0000, v22
	v_lshlrev_b32_e32 v22, 16, v23
	v_and_b32_e32 v23, 0xffff0000, v23
	v_fma_f32 v42, v36, v44, v42
	v_fma_f32 v43, v36, v45, v43
	v_fma_f32 v24, v36, v22, v24
	v_fma_f32 v25, v36, v23, v25
.LBB0_733:
	s_and_b64 vcc, exec, s[46:47]
	s_cbranch_vccnz .LBB0_735
	v_mad_u64_u32 v[22:23], s[4:5], v145, s10, v[104:105]
	v_mov_b32_e32 v44, v23
	v_mad_u64_u32 v[44:45], s[4:5], v123, s10, v[44:45]
	v_mov_b32_e32 v23, v44
	global_load_dwordx2 v[22:23], v[22:23], off offset:128
	s_waitcnt vmcnt(0)
	v_lshlrev_b32_e32 v44, 16, v22
	v_and_b32_e32 v45, 0xffff0000, v22
	v_lshlrev_b32_e32 v22, 16, v23
	v_and_b32_e32 v23, 0xffff0000, v23
	v_fma_f32 v42, v18, v44, v42
	v_fma_f32 v43, v18, v45, v43
	v_fma_f32 v24, v18, v22, v24
	v_fma_f32 v25, v18, v23, v25
.LBB0_735:
	s_and_b64 vcc, exec, s[48:49]
	s_cbranch_vccnz .LBB0_737
	v_mad_u64_u32 v[22:23], s[4:5], v145, s10, v[104:105]
	v_mov_b32_e32 v44, v23
	v_mad_u64_u32 v[44:45], s[4:5], v123, s10, v[44:45]
	v_mov_b32_e32 v23, v44
	global_load_dwordx2 v[22:23], v[22:23], off offset:256
	s_waitcnt vmcnt(0)
	v_lshlrev_b32_e32 v44, 16, v22
	v_and_b32_e32 v45, 0xffff0000, v22
	v_lshlrev_b32_e32 v22, 16, v23
	v_and_b32_e32 v23, 0xffff0000, v23
	v_fma_f32 v42, v20, v44, v42
	v_fma_f32 v43, v20, v45, v43
	v_fma_f32 v24, v20, v22, v24
	v_fma_f32 v25, v20, v23, v25
; __device__ __forceinline__ unsigned cvt_pk_bf16(float lo, float hi) { f32x2_t v = {lo, hi}; bf16x2_t b = __builtin_convertvector(v, bf16x2_t); return __builtin_bit_cast(unsigned, b); }
; __device__ __forceinline__ float bf_lo(unsigned w) { return __uint_as_float(w << 16); }
; __device__ __forceinline__ float bf_hi(unsigned w) { return __uint_as_float(w & 0xffff0000u); }
; __device__ __forceinline__ void moba_own_unit(LAS char* lds, int bh, int jblk, const bf16_t* H, const bf16_t* PO, const float* PML, bf16_t* U, int tid) {
;     ...
; #pragma unroll
;     for (int d0 = 0; d0 < 2; ++d0)
; #pragma unroll
;         for (int g = 0; g < 4; ++g) { const int d = 32 * d0 + 8 * g + 4 * hh; const f32x16& o = d0 ? o1 : o0;
;             float a0 = o[4 * g] * wown, a1 = o[4 * g + 1] * wown, a2 = o[4 * g + 2] * wown, a3 = o[4 * g + 3] * wown;
; #pragma unroll
;             for (int s = 0; s < 3; ++s) if (s < nsel) { const u32x2 pv = *(const u32x2*)(PO + (pidx + s) * 64 + d); a0 += wi[s] * bf_lo(pv.x); a1 += wi[s] * bf_hi(pv.x); a2 += wi[s] * bf_lo(pv.y); a3 += wi[s] * bf_hi(pv.y); }
;             const u32x2 z = zr.z[d0][g];
;             u32x2 w; w.x = cvt_pk_bf16(a0 * inv * bf_lo(z.x), a1 * inv * bf_hi(z.x)); w.y = cvt_pk_bf16(a2 * inv * bf_lo(z.y), a3 * inv * bf_hi(z.y));
;             *(u32x2*)(urow + d) = w; }
.LBB0_737:
	v_mov_b32_e32 v35, v34
	s_mov_b64 s[4:5], 0x10200800
	v_lshl_add_u64 v[22:23], v[40:41], 0, s[4:5]
	v_mul_f32_e32 v40, v34, v42
	v_mul_f32_e32 v41, v35, v43
	v_lshlrev_b32_e32 v42, 16, v134
	v_and_b32_e32 v43, 0xffff0000, v134
	v_mul_f32_e32 v40, v40, v42
	v_mul_f32_e32 v41, v41, v43
	v_mul_f32_e32 v24, v34, v24
	v_mul_f32_e32 v25, v35, v25
	v_lshlrev_b32_e32 v42, 16, v135
	v_and_b32_e32 v43, 0xffff0000, v135
	v_mul_f32_e32 v24, v24, v42
	v_mul_f32_e32 v25, v25, v43
	v_cvt_pk_bf16_f32 v40, v40, v41
	v_cvt_pk_bf16_f32 v41, v24, v25
	v_mul_f32_e32 v26, v26, v38
	v_mul_f32_e32 v27, v27, v39
	s_and_b64 vcc, exec, s[42:43]
	v_mul_f32_e32 v24, v28, v38
	v_mul_f32_e32 v25, v29, v39
	global_store_dwordx2 v[22:23], v[40:41], off offset:16
	s_cbranch_vccnz .LBB0_739
	v_mad_u64_u32 v[28:29], s[4:5], v145, s10, v[106:107]
	v_mov_b32_e32 v40, v29
	v_mad_u64_u32 v[40:41], s[4:5], v123, s10, v[40:41]
	v_mov_b32_e32 v29, v40
	global_load_dwordx2 v[28:29], v[28:29], off
	s_waitcnt vmcnt(0)
	v_lshlrev_b32_e32 v40, 16, v28
	v_and_b32_e32 v41, 0xffff0000, v28
	v_lshlrev_b32_e32 v28, 16, v29
	v_and_b32_e32 v29, 0xffff0000, v29
	v_fma_f32 v26, v36, v40, v26
	v_fma_f32 v27, v36, v41, v27
	v_fma_f32 v24, v36, v28, v24
	v_fma_f32 v25, v36, v29, v25
.LBB0_739:
	s_and_b64 vcc, exec, s[46:47]
	s_cbranch_vccnz .LBB0_741
	v_mad_u64_u32 v[28:29], s[4:5], v145, s10, v[106:107]
	v_mov_b32_e32 v40, v29
	v_mad_u64_u32 v[40:41], s[4:5], v123, s10, v[40:41]
	v_mov_b32_e32 v29, v40
	global_load_dwordx2 v[28:29], v[28:29], off offset:128
	s_waitcnt vmcnt(0)
	v_lshlrev_b32_e32 v40, 16, v28
	v_and_b32_e32 v41, 0xffff0000, v28
	v_lshlrev_b32_e32 v28, 16, v29
	v_and_b32_e32 v29, 0xffff0000, v29
	v_fma_f32 v26, v18, v40, v26
	v_fma_f32 v27, v18, v41, v27
	v_fma_f32 v24, v18, v28, v24
	v_fma_f32 v25, v18, v29, v25
.LBB0_741:
	s_and_b64 vcc, exec, s[48:49]
	s_cbranch_vccnz .LBB0_743
	v_mad_u64_u32 v[28:29], s[4:5], v145, s10, v[106:107]
	v_mov_b32_e32 v40, v29
	v_mad_u64_u32 v[40:41], s[4:5], v123, s10, v[40:41]
	v_mov_b32_e32 v29, v40
	global_load_dwordx2 v[28:29], v[28:29], off offset:256
	s_waitcnt vmcnt(0)
	v_lshlrev_b32_e32 v40, 16, v28
	v_and_b32_e32 v41, 0xffff0000, v28
	v_lshlrev_b32_e32 v28, 16, v29
	v_and_b32_e32 v29, 0xffff0000, v29
	v_fma_f32 v26, v20, v40, v26
	v_fma_f32 v27, v20, v41, v27
	v_fma_f32 v24, v20, v28, v24
	v_fma_f32 v25, v20, v29, v25
.LBB0_743:
	v_mul_f32_e32 v26, v34, v26
	v_mul_f32_e32 v27, v35, v27
	v_lshlrev_b32_e32 v28, 16, v132
	v_and_b32_e32 v29, 0xffff0000, v132
	v_mul_f32_e32 v26, v26, v28
	v_mul_f32_e32 v27, v27, v29
	v_mul_f32_e32 v24, v34, v24
	v_mul_f32_e32 v25, v35, v25
	v_lshlrev_b32_e32 v28, 16, v133
	v_and_b32_e32 v29, 0xffff0000, v133
	v_mul_f32_e32 v24, v24, v28
	v_mul_f32_e32 v25, v25, v29
	v_cvt_pk_bf16_f32 v26, v26, v27
	v_cvt_pk_bf16_f32 v27, v24, v25
	global_store_dwordx2 v[22:23], v[26:27], off offset:32
	v_mul_f32_e32 v26, v30, v38
	v_mul_f32_e32 v27, v31, v39
	s_and_b64 vcc, exec, s[42:43]
	v_mul_f32_e32 v24, v32, v38
	v_mul_f32_e32 v25, v33, v39
	s_cbranch_vccnz .LBB0_745
	v_mad_u64_u32 v[28:29], s[4:5], v145, s10, v[108:109]
	v_mov_b32_e32 v30, v29
	v_mad_u64_u32 v[30:31], s[4:5], v123, s10, v[30:31]
	v_mov_b32_e32 v29, v30
	global_load_dwordx2 v[28:29], v[28:29], off
	s_waitcnt vmcnt(0)
	v_lshlrev_b32_e32 v30, 16, v28
	v_and_b32_e32 v31, 0xffff0000, v28
	v_lshlrev_b32_e32 v28, 16, v29
	v_and_b32_e32 v29, 0xffff0000, v29
	v_fma_f32 v26, v36, v30, v26
	v_fma_f32 v27, v36, v31, v27
	v_fma_f32 v24, v36, v28, v24
	v_fma_f32 v25, v36, v29, v25
.LBB0_745:
	s_and_b64 vcc, exec, s[46:47]
	s_cbranch_vccnz .LBB0_747
	v_mad_u64_u32 v[28:29], s[4:5], v145, s10, v[108:109]
	v_mov_b32_e32 v30, v29
	v_mad_u64_u32 v[30:31], s[4:5], v123, s10, v[30:31]
	v_mov_b32_e32 v29, v30
	global_load_dwordx2 v[28:29], v[28:29], off offset:128
	s_waitcnt vmcnt(0)
	v_lshlrev_b32_e32 v30, 16, v28
	v_and_b32_e32 v31, 0xffff0000, v28
	v_lshlrev_b32_e32 v28, 16, v29
	v_and_b32_e32 v29, 0xffff0000, v29
	v_fma_f32 v26, v18, v30, v26
	v_fma_f32 v27, v18, v31, v27
	v_fma_f32 v24, v18, v28, v24
	v_fma_f32 v25, v18, v29, v25
.LBB0_747:
	s_and_b64 vcc, exec, s[48:49]
	s_cbranch_vccnz .LBB0_749
	v_mad_u64_u32 v[28:29], s[4:5], v145, s10, v[108:109]
	v_mov_b32_e32 v30, v29
	v_mad_u64_u32 v[30:31], s[4:5], v123, s10, v[30:31]
	v_mov_b32_e32 v29, v30
	global_load_dwordx2 v[28:29], v[28:29], off offset:256
	s_waitcnt vmcnt(0)
	v_lshlrev_b32_e32 v30, 16, v28
	v_and_b32_e32 v31, 0xffff0000, v28
	v_lshlrev_b32_e32 v28, 16, v29
	v_and_b32_e32 v29, 0xffff0000, v29
	v_fma_f32 v26, v20, v30, v26
	v_fma_f32 v27, v20, v31, v27
	v_fma_f32 v24, v20, v28, v24
	v_fma_f32 v25, v20, v29, v25
.LBB0_749:
	v_mul_f32_e32 v26, v34, v26
	v_mul_f32_e32 v27, v35, v27
	v_lshlrev_b32_e32 v28, 16, v130
	v_and_b32_e32 v29, 0xffff0000, v130
	v_mul_f32_e32 v26, v26, v28
	v_mul_f32_e32 v27, v27, v29
	v_mul_f32_e32 v24, v34, v24
	v_mul_f32_e32 v25, v35, v25
	v_lshlrev_b32_e32 v28, 16, v131
	v_and_b32_e32 v29, 0xffff0000, v131
	v_mul_f32_e32 v24, v24, v28
	v_mul_f32_e32 v25, v25, v29
	v_cvt_pk_bf16_f32 v26, v26, v27
	v_cvt_pk_bf16_f32 v27, v24, v25
	v_mul_f32_e32 v24, v2, v38
	v_mul_f32_e32 v25, v3, v39
	s_and_b64 vcc, exec, s[42:43]
	v_mul_f32_e32 v2, v4, v38
	v_mul_f32_e32 v3, v5, v39
	global_store_dwordx2 v[22:23], v[26:27], off offset:48
	s_cbranch_vccnz .LBB0_751
	v_mad_u64_u32 v[4:5], s[4:5], v145, s10, v[110:111]
	v_mov_b32_e32 v26, v5
	v_mad_u64_u32 v[26:27], s[4:5], v123, s10, v[26:27]
	v_mov_b32_e32 v5, v26
	global_load_dwordx2 v[4:5], v[4:5], off
	s_waitcnt vmcnt(0)
	v_lshlrev_b32_e32 v26, 16, v4
	v_and_b32_e32 v27, 0xffff0000, v4
	v_lshlrev_b32_e32 v4, 16, v5
	v_and_b32_e32 v5, 0xffff0000, v5
	v_fma_f32 v24, v36, v26, v24
	v_fma_f32 v25, v36, v27, v25
	v_fma_f32 v2, v36, v4, v2
	v_fma_f32 v3, v36, v5, v3
; __device__ __forceinline__ unsigned cvt_pk_bf16(float lo, float hi) { f32x2_t v = {lo, hi}; bf16x2_t b = __builtin_convertvector(v, bf16x2_t); return __builtin_bit_cast(unsigned, b); }
; __device__ __forceinline__ float bf_lo(unsigned w) { return __uint_as_float(w << 16); }
; __device__ __forceinline__ float bf_hi(unsigned w) { return __uint_as_float(w & 0xffff0000u); }
; __device__ __forceinline__ void moba_own_unit(LAS char* lds, int bh, int jblk, const bf16_t* H, const bf16_t* PO, const float* PML, bf16_t* U, int tid) {
;     ...
; #pragma unroll
;     for (int d0 = 0; d0 < 2; ++d0)
; #pragma unroll
;         for (int g = 0; g < 4; ++g) { const int d = 32 * d0 + 8 * g + 4 * hh; const f32x16& o = d0 ? o1 : o0;
;             float a0 = o[4 * g] * wown, a1 = o[4 * g + 1] * wown, a2 = o[4 * g + 2] * wown, a3 = o[4 * g + 3] * wown;
; #pragma unroll
;             for (int s = 0; s < 3; ++s) if (s < nsel) { const u32x2 pv = *(const u32x2*)(PO + (pidx + s) * 64 + d); a0 += wi[s] * bf_lo(pv.x); a1 += wi[s] * bf_hi(pv.x); a2 += wi[s] * bf_lo(pv.y); a3 += wi[s] * bf_hi(pv.y); }
;             const u32x2 z = zr.z[d0][g];
;             u32x2 w; w.x = cvt_pk_bf16(a0 * inv * bf_lo(z.x), a1 * inv * bf_hi(z.x)); w.y = cvt_pk_bf16(a2 * inv * bf_lo(z.y), a3 * inv * bf_hi(z.y));
;             *(u32x2*)(urow + d) = w; }
.LBB0_751:
	s_and_b64 vcc, exec, s[46:47]
	s_cbranch_vccnz .LBB0_753
	v_mad_u64_u32 v[4:5], s[4:5], v145, s10, v[110:111]
	v_mov_b32_e32 v26, v5
	v_mad_u64_u32 v[26:27], s[4:5], v123, s10, v[26:27]
	v_mov_b32_e32 v5, v26
	global_load_dwordx2 v[4:5], v[4:5], off offset:128
	s_waitcnt vmcnt(0)
	v_lshlrev_b32_e32 v26, 16, v4
	v_and_b32_e32 v27, 0xffff0000, v4
	v_lshlrev_b32_e32 v4, 16, v5
	v_and_b32_e32 v5, 0xffff0000, v5
	v_fma_f32 v24, v18, v26, v24
	v_fma_f32 v25, v18, v27, v25
	v_fma_f32 v2, v18, v4, v2
	v_fma_f32 v3, v18, v5, v3
.LBB0_753:
	s_and_b64 vcc, exec, s[48:49]
	s_cbranch_vccnz .LBB0_755
	v_mad_u64_u32 v[4:5], s[4:5], v145, s10, v[110:111]
	v_mov_b32_e32 v26, v5
	v_mad_u64_u32 v[26:27], s[4:5], v123, s10, v[26:27]
	v_mov_b32_e32 v5, v26
	global_load_dwordx2 v[4:5], v[4:5], off offset:256
	s_waitcnt vmcnt(0)
	v_lshlrev_b32_e32 v26, 16, v4
	v_and_b32_e32 v27, 0xffff0000, v4
	v_lshlrev_b32_e32 v4, 16, v5
	v_and_b32_e32 v5, 0xffff0000, v5
	v_fma_f32 v24, v20, v26, v24
	v_fma_f32 v25, v20, v27, v25
	v_fma_f32 v2, v20, v4, v2
	v_fma_f32 v3, v20, v5, v3
.LBB0_755:
	v_mul_f32_e32 v4, v34, v24
	v_mul_f32_e32 v5, v35, v25
	v_lshlrev_b32_e32 v24, 16, v128
	v_and_b32_e32 v25, 0xffff0000, v128
	v_mul_f32_e32 v4, v4, v24
	v_mul_f32_e32 v5, v5, v25
	v_mul_f32_e32 v2, v34, v2
	v_mul_f32_e32 v3, v35, v3
	v_lshlrev_b32_e32 v24, 16, v129
	v_and_b32_e32 v25, 0xffff0000, v129
	v_mul_f32_e32 v2, v2, v24
	v_mul_f32_e32 v3, v3, v25
	v_cvt_pk_bf16_f32 v4, v4, v5
	v_cvt_pk_bf16_f32 v5, v2, v3
	global_store_dwordx2 v[22:23], v[4:5], off offset:64
	v_mul_f32_e32 v4, v6, v38
	v_mul_f32_e32 v5, v7, v39
	s_and_b64 vcc, exec, s[42:43]
	v_mul_f32_e32 v2, v8, v38
	v_mul_f32_e32 v3, v9, v39
	s_cbranch_vccnz .LBB0_757
	v_mad_u64_u32 v[6:7], s[4:5], v145, s10, v[112:113]
	v_mov_b32_e32 v8, v7
	v_mad_u64_u32 v[8:9], s[4:5], v123, s10, v[8:9]
	v_mov_b32_e32 v7, v8
	global_load_dwordx2 v[6:7], v[6:7], off
	s_waitcnt vmcnt(0)
	v_lshlrev_b32_e32 v8, 16, v6
	v_and_b32_e32 v9, 0xffff0000, v6
	v_lshlrev_b32_e32 v6, 16, v7
	v_and_b32_e32 v7, 0xffff0000, v7
	v_fma_f32 v4, v36, v8, v4
	v_fma_f32 v5, v36, v9, v5
	v_fma_f32 v2, v36, v6, v2
	v_fma_f32 v3, v36, v7, v3
.LBB0_757:
	s_and_b64 vcc, exec, s[46:47]
	s_cbranch_vccnz .LBB0_759
	v_mad_u64_u32 v[6:7], s[4:5], v145, s10, v[112:113]
	v_mov_b32_e32 v8, v7
	v_mad_u64_u32 v[8:9], s[4:5], v123, s10, v[8:9]
	v_mov_b32_e32 v7, v8
	global_load_dwordx2 v[6:7], v[6:7], off offset:128
	s_waitcnt vmcnt(0)
	v_lshlrev_b32_e32 v8, 16, v6
	v_and_b32_e32 v9, 0xffff0000, v6
	v_lshlrev_b32_e32 v6, 16, v7
	v_and_b32_e32 v7, 0xffff0000, v7
	v_fma_f32 v4, v18, v8, v4
	v_fma_f32 v5, v18, v9, v5
	v_fma_f32 v2, v18, v6, v2
	v_fma_f32 v3, v18, v7, v3
.LBB0_759:
	s_and_b64 vcc, exec, s[48:49]
	s_cbranch_vccnz .LBB0_761
	v_mad_u64_u32 v[6:7], s[4:5], v145, s10, v[112:113]
	v_mov_b32_e32 v8, v7
	v_mad_u64_u32 v[8:9], s[4:5], v123, s10, v[8:9]
	v_mov_b32_e32 v7, v8
	global_load_dwordx2 v[6:7], v[6:7], off offset:256
	s_waitcnt vmcnt(0)
	v_lshlrev_b32_e32 v8, 16, v6
	v_and_b32_e32 v9, 0xffff0000, v6
	v_lshlrev_b32_e32 v6, 16, v7
	v_and_b32_e32 v7, 0xffff0000, v7
	v_fma_f32 v4, v20, v8, v4
	v_fma_f32 v5, v20, v9, v5
	v_fma_f32 v2, v20, v6, v2
	v_fma_f32 v3, v20, v7, v3
; __device__ __forceinline__ unsigned cvt_pk_bf16(float lo, float hi) { f32x2_t v = {lo, hi}; bf16x2_t b = __builtin_convertvector(v, bf16x2_t); return __builtin_bit_cast(unsigned, b); }
; __device__ __forceinline__ float bf_lo(unsigned w) { return __uint_as_float(w << 16); }
; __device__ __forceinline__ float bf_hi(unsigned w) { return __uint_as_float(w & 0xffff0000u); }
; __device__ __forceinline__ void moba_own_unit(LAS char* lds, int bh, int jblk, const bf16_t* H, const bf16_t* PO, const float* PML, bf16_t* U, int tid) {
;     ...
; #pragma unroll
;     for (int d0 = 0; d0 < 2; ++d0)
; #pragma unroll
;         for (int g = 0; g < 4; ++g) { const int d = 32 * d0 + 8 * g + 4 * hh; const f32x16& o = d0 ? o1 : o0;
;             float a0 = o[4 * g] * wown, a1 = o[4 * g + 1] * wown, a2 = o[4 * g + 2] * wown, a3 = o[4 * g + 3] * wown;
; #pragma unroll
;             for (int s = 0; s < 3; ++s) if (s < nsel) { const u32x2 pv = *(const u32x2*)(PO + (pidx + s) * 64 + d); a0 += wi[s] * bf_lo(pv.x); a1 += wi[s] * bf_hi(pv.x); a2 += wi[s] * bf_lo(pv.y); a3 += wi[s] * bf_hi(pv.y); }
;             const u32x2 z = zr.z[d0][g];
;             u32x2 w; w.x = cvt_pk_bf16(a0 * inv * bf_lo(z.x), a1 * inv * bf_hi(z.x)); w.y = cvt_pk_bf16(a2 * inv * bf_lo(z.y), a3 * inv * bf_hi(z.y));
;             *(u32x2*)(urow + d) = w; }
.LBB0_761:
	v_mul_f32_e32 v4, v34, v4
	v_mul_f32_e32 v5, v35, v5
	v_lshlrev_b32_e32 v6, 16, v126
	v_and_b32_e32 v7, 0xffff0000, v126
	v_mul_f32_e32 v4, v4, v6
	v_mul_f32_e32 v5, v5, v7
	v_mul_f32_e32 v2, v34, v2
	v_mul_f32_e32 v3, v35, v3
	v_lshlrev_b32_e32 v6, 16, v127
	v_and_b32_e32 v7, 0xffff0000, v127
	v_mul_f32_e32 v2, v2, v6
	v_mul_f32_e32 v3, v3, v7
	v_cvt_pk_bf16_f32 v4, v4, v5
	v_cvt_pk_bf16_f32 v5, v2, v3
	global_store_dwordx2 v[22:23], v[4:5], off offset:80
	v_mul_f32_e32 v4, v10, v38
	v_mul_f32_e32 v5, v11, v39
	s_and_b64 vcc, exec, s[42:43]
	v_mul_f32_e32 v2, v12, v38
	v_mul_f32_e32 v3, v13, v39
	s_cbranch_vccnz .LBB0_763
	v_mad_u64_u32 v[6:7], s[4:5], v145, s10, v[114:115]
	v_mov_b32_e32 v8, v7
	v_mad_u64_u32 v[8:9], s[4:5], v123, s10, v[8:9]
	v_mov_b32_e32 v7, v8
	global_load_dwordx2 v[6:7], v[6:7], off
	s_waitcnt vmcnt(0)
	v_lshlrev_b32_e32 v8, 16, v6
	v_and_b32_e32 v9, 0xffff0000, v6
	v_lshlrev_b32_e32 v6, 16, v7
	v_and_b32_e32 v7, 0xffff0000, v7
	v_fma_f32 v4, v36, v8, v4
	v_fma_f32 v5, v36, v9, v5
	v_fma_f32 v2, v36, v6, v2
	v_fma_f32 v3, v36, v7, v3
.LBB0_763:
	s_and_b64 vcc, exec, s[46:47]
	s_cbranch_vccnz .LBB0_765
	v_mad_u64_u32 v[6:7], s[4:5], v145, s10, v[114:115]
	v_mov_b32_e32 v8, v7
	v_mad_u64_u32 v[8:9], s[4:5], v123, s10, v[8:9]
	v_mov_b32_e32 v7, v8
	global_load_dwordx2 v[6:7], v[6:7], off offset:128
	s_waitcnt vmcnt(0)
	v_lshlrev_b32_e32 v8, 16, v6
	v_and_b32_e32 v9, 0xffff0000, v6
	v_lshlrev_b32_e32 v6, 16, v7
	v_and_b32_e32 v7, 0xffff0000, v7
	v_fma_f32 v4, v18, v8, v4
	v_fma_f32 v5, v18, v9, v5
	v_fma_f32 v2, v18, v6, v2
	v_fma_f32 v3, v18, v7, v3
.LBB0_765:
	s_and_b64 vcc, exec, s[48:49]
	s_cbranch_vccnz .LBB0_767
	v_mad_u64_u32 v[6:7], s[4:5], v145, s10, v[114:115]
	v_mov_b32_e32 v8, v7
	v_mad_u64_u32 v[8:9], s[4:5], v123, s10, v[8:9]
	v_mov_b32_e32 v7, v8
	global_load_dwordx2 v[6:7], v[6:7], off offset:256
	s_waitcnt vmcnt(0)
	v_lshlrev_b32_e32 v8, 16, v6
	v_and_b32_e32 v9, 0xffff0000, v6
	v_lshlrev_b32_e32 v6, 16, v7
	v_and_b32_e32 v7, 0xffff0000, v7
	v_fma_f32 v4, v20, v8, v4
	v_fma_f32 v5, v20, v9, v5
	v_fma_f32 v2, v20, v6, v2
	v_fma_f32 v3, v20, v7, v3
.LBB0_767:
	v_mul_f32_e32 v4, v34, v4
	v_mul_f32_e32 v5, v35, v5
	v_lshlrev_b32_e32 v6, 16, v124
	v_and_b32_e32 v7, 0xffff0000, v124
	v_mul_f32_e32 v4, v4, v6
	v_mul_f32_e32 v5, v5, v7
	v_mul_f32_e32 v2, v34, v2
	v_mul_f32_e32 v3, v35, v3
	v_lshlrev_b32_e32 v6, 16, v125
	v_and_b32_e32 v7, 0xffff0000, v125
	v_mul_f32_e32 v2, v2, v6
	v_mul_f32_e32 v3, v3, v7
	v_cvt_pk_bf16_f32 v4, v4, v5
	v_cvt_pk_bf16_f32 v5, v2, v3
	global_store_dwordx2 v[22:23], v[4:5], off offset:96
	v_mul_f32_e32 v4, v14, v38
	v_mul_f32_e32 v5, v15, v39
	s_and_b64 vcc, exec, s[42:43]
	v_mul_f32_e32 v2, v16, v38
	v_mul_f32_e32 v3, v17, v39
	s_cbranch_vccnz .LBB0_769
	v_mad_u64_u32 v[6:7], s[4:5], v145, s10, v[116:117]
	v_mov_b32_e32 v8, v7
	v_mad_u64_u32 v[8:9], s[4:5], v123, s10, v[8:9]
	v_mov_b32_e32 v7, v8
	global_load_dwordx2 v[6:7], v[6:7], off
	s_waitcnt vmcnt(0)
	v_lshlrev_b32_e32 v8, 16, v6
	v_and_b32_e32 v9, 0xffff0000, v6
	v_lshlrev_b32_e32 v6, 16, v7
	v_and_b32_e32 v7, 0xffff0000, v7
	v_fma_f32 v4, v36, v8, v4
	v_fma_f32 v5, v36, v9, v5
	v_fma_f32 v2, v36, v6, v2
	v_fma_f32 v3, v36, v7, v3
.LBB0_769:
	s_and_b64 vcc, exec, s[46:47]
	s_cbranch_vccnz .LBB0_771
	v_mad_u64_u32 v[6:7], s[4:5], v145, s10, v[116:117]
	v_mov_b32_e32 v8, v7
	v_mad_u64_u32 v[8:9], s[4:5], v123, s10, v[8:9]
	v_mov_b32_e32 v7, v8
	global_load_dwordx2 v[6:7], v[6:7], off offset:128
	s_waitcnt vmcnt(0)
	v_lshlrev_b32_e32 v8, 16, v6
	v_and_b32_e32 v9, 0xffff0000, v6
	v_lshlrev_b32_e32 v6, 16, v7
	v_and_b32_e32 v7, 0xffff0000, v7
	v_fma_f32 v4, v18, v8, v4
	v_fma_f32 v5, v18, v9, v5
	v_fma_f32 v2, v18, v6, v2
	v_fma_f32 v3, v18, v7, v3
.LBB0_771:
	s_and_b64 vcc, exec, s[48:49]
	s_cbranch_vccnz .LBB0_631
	v_mad_u64_u32 v[6:7], s[4:5], v145, s10, v[116:117]
	v_mov_b32_e32 v8, v7
	v_mad_u64_u32 v[8:9], s[4:5], v123, s10, v[8:9]
	v_mov_b32_e32 v7, v8
	global_load_dwordx2 v[6:7], v[6:7], off offset:256
	s_waitcnt vmcnt(0)
	v_lshlrev_b32_e32 v8, 16, v6
	v_and_b32_e32 v9, 0xffff0000, v6
	v_lshlrev_b32_e32 v6, 16, v7
	v_and_b32_e32 v7, 0xffff0000, v7
	v_fma_f32 v4, v20, v8, v4
	v_fma_f32 v5, v20, v9, v5
	v_fma_f32 v2, v20, v6, v2
	v_fma_f32 v3, v20, v7, v3
	s_branch .LBB0_631
